# v105 + k-loop: s_setprio 1 hoisted before the segment barrier and s_setprio 0 sunk after it (off the wave hand-over path, 68 segments)
# baseline (speedup 1.0000x reference)
; #define PG8_STAGE(bufoff, gbase, voff) do { _Pragma("unroll") for (int _i = 0; _i < 2; ++_i) \
;         __builtin_amdgcn_global_load_lds((const unsigned*)((const char*)(gbase) + (voff)[_i]), (PG8_LAS unsigned*)(lds + (bufoff) + ldsw + _i * 8192), 16, 0, 0); } while (0)
; #define PG8_LDA(dst, b, h) do { _Pragma("unroll") for (int m = 0; m < 4; ++m) _Pragma("unroll") for (int k = 0; k < 2; ++k) dst[m][k] = *(const PG8_LAS bf16x8*)(lds + PG8_SA(b, h) + aoff + m * 2048 + k * 1024); } while (0)
; #define PG8_LDB(dst, b, h) do { _Pragma("unroll") for (int n = 0; n < 2; ++n) _Pragma("unroll") for (int k = 0; k < 2; ++k) dst[n][k] = *(const PG8_LAS bf16x8*)(lds + PG8_SB(b, h) + boff + n * 2048 + k * 1024); } while (0)
; #define PG8_MMA(ai, bj, At, Bt) do { __builtin_amdgcn_s_setprio(1); _Pragma("unroll") for (int m = 0; m < 4; ++m) _Pragma("unroll") for (int n = 0; n < 2; ++n) _Pragma("unroll") for (int k = 0; k < 2; ++k) \
;         acc[ai][bj][m][n] = __builtin_amdgcn_mfma_f32_16x16x32_bf16(Bt[n][k], At[m][k], acc[ai][bj][m][n], 0, 0, 0); __builtin_amdgcn_s_setprio(0); } while (0)
; #define PG8_BAR __builtin_amdgcn_s_barrier()
; template <class Epi, class Sched>
; __device__ __forceinline__ void gemm_phase(PG8_LAS unsigned char* lds, PG8_LAS unsigned char* xl, const Gemm g, const Sched& S, const Epi& E) {
;     ...
;         const bool has_next = S.next(ui + 1, nxt);
;         const char* nA = has_next ? (const char*)g.A + nxt.aoff : cA; const char* nB = has_next ? (const char*)g.Bt + nxt.boff : cB;
; #pragma unroll 1
;         for (int t = 0; t < nt; t += 2) {
;             const bool last = (t == nt - 2);
;             const char* a1 = cA + (size_t)(t + 1) * kstep;
;             const char* a2 = last ? nA : cA + (size_t)(t + 2) * kstep; const char* b2 = last ? nB : cB + (size_t)(t + 2) * kstep;
;             const char* a3 = a2 + kstep; const char* b3 = b2 + kstep;
;             PG8_LDB(B0, 0, 0); PG8_LDB(B1, 0, 1); PG8_SCHED; PG8_LDA(At, 0, 0); PG8_STAGE(PG8_SA(1, 1), a1 + hsA, voffA);
;             PG8_WAIT_V(8); PG8_WAIT_L(0); PG8_BAR; PG8_MMA(0, 0, At, B0); PG8_MMA(0, 1, At, B1); PG8_BAR; PG8_SCHED;
;             PG8_LDA(At, 0, 1); PG8_STAGE(PG8_SB(0, 0), b2, voffB); PG8_STAGE(PG8_SB(0, 1), b2 + hsB, voffB); PG8_STAGE(PG8_SA(0, 0), a2, voffA);
;             PG8_WAIT_V(8); PG8_WAIT_L(0); PG8_BAR; PG8_MMA(1, 0, At, B0); PG8_MMA(1, 1, At, B1); PG8_BAR; PG8_SCHED;
.LBB0_101:
	s_add_u32 s20, s35, s16
	s_addc_u32 s21, s36, s17
	s_and_b64 s[22:23], s[4:5], exec
	s_cselect_b32 s73, s21, s29
	s_cselect_b32 s74, s20, s28
	s_add_u32 s22, s2, s18
	s_addc_u32 s23, s3, s19
	s_and_b64 s[30:31], s[4:5], exec
	s_cselect_b32 s75, s23, s27
	s_cselect_b32 s76, s22, s26
	s_add_u32 s77, s26, 0x100
	s_addc_u32 s78, s27, 0
	s_add_u32 s26, s28, 0x40080
	v_mov_b32_e32 v0, 0
	s_addc_u32 s27, s29, 0
	s_mov_b32 s79, -2
	ds_read_b128 v[148:151], v153
	ds_read_b128 v[158:161], v153 offset:1024
	ds_read_b128 v[162:165], v153 offset:2048
	ds_read_b128 v[166:169], v153 offset:3072
	ds_read_b128 v[170:173], v154
	ds_read_b128 v[174:177], v154 offset:1024
	ds_read_b128 v[178:181], v154 offset:2048
	ds_read_b128 v[182:185], v154 offset:3072
	s_add_u32 s28, s26, 0xfffc0080
	s_addc_u32 s29, s27, -1
	s_cmp_eq_u32 s79, 12
	s_cselect_b32 s31, s73, s29
	s_cselect_b32 s30, s74, s28
	s_cselect_b32 s29, s75, s78
	s_cselect_b32 s28, s76, s77
	v_lshl_add_u64 v[218:219], s[26:27], 0, v[142:143]
	s_add_i32 m0, s52, 0xc000
	ds_read_b128 v[186:189], v155
	ds_read_b128 v[190:193], v155 offset:1024
	ds_read_b128 v[194:197], v155 offset:2048
	ds_read_b128 v[198:201], v155 offset:3072
	ds_read_b128 v[202:205], v155 offset:4096
	ds_read_b128 v[206:209], v155 offset:5120
	ds_read_b128 v[210:213], v155 offset:6144
	ds_read_b128 v[214:217], v155 offset:7168
	global_load_lds_dwordx4 v[218:219], off
	v_lshl_add_u64 v[218:219], s[26:27], 0, v[140:141]
	s_add_i32 m0, s52, 0xe000
	s_nop 0
	global_load_lds_dwordx4 v[218:219], off
	s_waitcnt vmcnt(8) lgkmcnt(0)
	s_setprio 1
	s_barrier
	v_mfma_f32_16x16x32_bf16 v[124:127], v[148:151], v[186:189], 0
	v_mfma_f32_16x16x32_bf16 v[116:119], v[162:165], v[186:189], 0
	v_mfma_f32_16x16x32_bf16 v[108:111], v[148:151], v[194:197], 0
	v_mfma_f32_16x16x32_bf16 v[100:103], v[162:165], v[194:197], 0
	v_mfma_f32_16x16x32_bf16 v[92:95], v[148:151], v[202:205], 0
	v_mfma_f32_16x16x32_bf16 v[84:87], v[162:165], v[202:205], 0
	v_mfma_f32_16x16x32_bf16 v[76:79], v[148:151], v[210:213], 0
	v_mfma_f32_16x16x32_bf16 v[68:71], v[162:165], v[210:213], 0
	v_mfma_f32_16x16x32_bf16 v[124:127], v[158:161], v[190:193], v[124:127]
	v_mfma_f32_16x16x32_bf16 v[116:119], v[166:169], v[190:193], v[116:119]
	v_mfma_f32_16x16x32_bf16 v[108:111], v[158:161], v[198:201], v[108:111]
	v_mfma_f32_16x16x32_bf16 v[100:103], v[166:169], v[198:201], v[100:103]
	v_mfma_f32_16x16x32_bf16 v[92:95], v[158:161], v[206:209], v[92:95]
	v_mfma_f32_16x16x32_bf16 v[84:87], v[166:169], v[206:209], v[84:87]
	v_mfma_f32_16x16x32_bf16 v[76:79], v[158:161], v[214:217], v[76:79]
	v_mfma_f32_16x16x32_bf16 v[68:71], v[166:169], v[214:217], v[68:71]
	s_setprio 0
	s_setprio 1
	v_mfma_f32_16x16x32_bf16 v[120:123], v[170:173], v[186:189], 0
	v_mfma_f32_16x16x32_bf16 v[112:115], v[178:181], v[186:189], 0
	v_mfma_f32_16x16x32_bf16 v[104:107], v[170:173], v[194:197], 0
	v_mfma_f32_16x16x32_bf16 v[96:99], v[178:181], v[194:197], 0
	v_mfma_f32_16x16x32_bf16 v[88:91], v[170:173], v[202:205], 0
	v_mfma_f32_16x16x32_bf16 v[80:83], v[178:181], v[202:205], 0
	v_mfma_f32_16x16x32_bf16 v[72:75], v[170:173], v[210:213], 0
	v_mfma_f32_16x16x32_bf16 v[64:67], v[178:181], v[210:213], 0
	v_mfma_f32_16x16x32_bf16 v[120:123], v[174:177], v[190:193], v[120:123]
	v_mfma_f32_16x16x32_bf16 v[112:115], v[182:185], v[190:193], v[112:115]
	v_mfma_f32_16x16x32_bf16 v[104:107], v[174:177], v[198:201], v[104:107]
	v_mfma_f32_16x16x32_bf16 v[96:99], v[182:185], v[198:201], v[96:99]
	v_mfma_f32_16x16x32_bf16 v[88:91], v[174:177], v[206:209], v[88:91]
	v_mfma_f32_16x16x32_bf16 v[80:83], v[182:185], v[206:209], v[80:83]
	v_mfma_f32_16x16x32_bf16 v[72:75], v[174:177], v[214:217], v[72:75]
	v_mfma_f32_16x16x32_bf16 v[64:67], v[182:185], v[214:217], v[64:67]
	s_barrier
	s_setprio 0
	s_add_i32 s68, s60, s42
	v_lshl_add_u64 v[218:219], s[28:29], 0, v[132:133]
	s_mov_b32 m0, s68
	ds_read_b128 v[186:189], v155 offset:16384
	ds_read_b128 v[190:193], v155 offset:17408
	ds_read_b128 v[194:197], v155 offset:18432
	ds_read_b128 v[198:201], v155 offset:19456
	ds_read_b128 v[202:205], v155 offset:20480
	ds_read_b128 v[206:209], v155 offset:21504
	ds_read_b128 v[210:213], v155 offset:22528
	ds_read_b128 v[214:217], v155 offset:23552
	global_load_lds_dwordx4 v[218:219], off
	s_add_i32 m0, s68, 0x2000
	s_add_u32 s80, s28, 0x40000
	v_lshl_add_u64 v[222:223], s[28:29], 0, v[128:129]
	s_addc_u32 s81, s29, 0
	s_add_i32 s68, s61, s42
	global_load_lds_dwordx4 v[222:223], off
	v_lshl_add_u64 v[224:225], s[80:81], 0, v[132:133]
	s_mov_b32 m0, s68
	v_lshl_add_u64 v[226:227], s[30:31], 0, v[130:131]
	global_load_lds_dwordx4 v[224:225], off
	v_lshl_add_u64 v[224:225], s[80:81], 0, v[128:129]
	s_add_i32 m0, s68, 0x2000
	s_nop 0
	global_load_lds_dwordx4 v[224:225], off
	v_lshl_add_u64 v[224:225], s[30:31], 0, v[134:135]
	s_mov_b32 m0, s52
	s_nop 0
	global_load_lds_dwordx4 v[224:225], off
	s_mov_b32 m0, s53
	s_nop 0
	global_load_lds_dwordx4 v[226:227], off
	s_waitcnt vmcnt(8) lgkmcnt(0)
	s_setprio 1
	s_barrier
; #define PG8_STAGE(bufoff, gbase, voff) do { _Pragma("unroll") for (int _i = 0; _i < 2; ++_i) \
;         __builtin_amdgcn_global_load_lds((const unsigned*)((const char*)(gbase) + (voff)[_i]), (PG8_LAS unsigned*)(lds + (bufoff) + ldsw + _i * 8192), 16, 0, 0); } while (0)
; #define PG8_LDA(dst, b, h) do { _Pragma("unroll") for (int m = 0; m < 4; ++m) _Pragma("unroll") for (int k = 0; k < 2; ++k) dst[m][k] = *(const PG8_LAS bf16x8*)(lds + PG8_SA(b, h) + aoff + m * 2048 + k * 1024); } while (0)
; #define PG8_LDB(dst, b, h) do { _Pragma("unroll") for (int n = 0; n < 2; ++n) _Pragma("unroll") for (int k = 0; k < 2; ++k) dst[n][k] = *(const PG8_LAS bf16x8*)(lds + PG8_SB(b, h) + boff + n * 2048 + k * 1024); } while (0)
; #define PG8_MMA(ai, bj, At, Bt) do { __builtin_amdgcn_s_setprio(1); _Pragma("unroll") for (int m = 0; m < 4; ++m) _Pragma("unroll") for (int n = 0; n < 2; ++n) _Pragma("unroll") for (int k = 0; k < 2; ++k) \
;         acc[ai][bj][m][n] = __builtin_amdgcn_mfma_f32_16x16x32_bf16(Bt[n][k], At[m][k], acc[ai][bj][m][n], 0, 0, 0); __builtin_amdgcn_s_setprio(0); } while (0)
; #define PG8_WAIT_V(n) asm volatile("s_waitcnt vmcnt(" #n ")" ::: "memory")
; #define PG8_WAIT_L(n) asm volatile("s_waitcnt lgkmcnt(" #n ")" ::: "memory")
; #define PG8_BAR __builtin_amdgcn_s_barrier()
; #define PG8_SCHED __builtin_amdgcn_sched_barrier(0)
; template <class Epi, class Sched>
; __device__ __forceinline__ void gemm_phase(PG8_LAS unsigned char* lds, PG8_LAS unsigned char* xl, const Gemm g, const Sched& S, const Epi& E) {
;     ...
;             PG8_WAIT_V(8); PG8_WAIT_L(0); PG8_BAR; PG8_MMA(1, 0, At, B0); PG8_MMA(1, 1, At, B1); PG8_BAR; PG8_SCHED;
;             PG8_LDB(B0, 1, 0); PG8_LDB(B1, 1, 1); PG8_SCHED; PG8_LDA(At, 1, 0); PG8_STAGE(PG8_SA(0, 1), a2 + hsA, voffA);
;             PG8_WAIT_V(8); PG8_WAIT_L(0); PG8_BAR; PG8_MMA(0, 0, At, B0); PG8_MMA(0, 1, At, B1); PG8_BAR; PG8_SCHED;
	v_mfma_f32_16x16x32_bf16 v[60:63], v[148:151], v[186:189], 0
	v_mfma_f32_16x16x32_bf16 v[52:55], v[162:165], v[186:189], 0
	v_mfma_f32_16x16x32_bf16 v[44:47], v[148:151], v[194:197], 0
	v_mfma_f32_16x16x32_bf16 v[36:39], v[162:165], v[194:197], 0
	v_mfma_f32_16x16x32_bf16 v[28:31], v[148:151], v[202:205], 0
	v_mfma_f32_16x16x32_bf16 v[20:23], v[162:165], v[202:205], 0
	v_mfma_f32_16x16x32_bf16 v[12:15], v[148:151], v[210:213], 0
	v_mfma_f32_16x16x32_bf16 v[4:7], v[162:165], v[210:213], 0
	v_mfma_f32_16x16x32_bf16 v[60:63], v[158:161], v[190:193], v[60:63]
	v_mfma_f32_16x16x32_bf16 v[52:55], v[166:169], v[190:193], v[52:55]
	v_mfma_f32_16x16x32_bf16 v[44:47], v[158:161], v[198:201], v[44:47]
	v_mfma_f32_16x16x32_bf16 v[36:39], v[166:169], v[198:201], v[36:39]
	v_mfma_f32_16x16x32_bf16 v[28:31], v[158:161], v[206:209], v[28:31]
	v_mfma_f32_16x16x32_bf16 v[20:23], v[166:169], v[206:209], v[20:23]
	v_mfma_f32_16x16x32_bf16 v[12:15], v[158:161], v[214:217], v[12:15]
	v_mfma_f32_16x16x32_bf16 v[4:7], v[166:169], v[214:217], v[4:7]
	s_setprio 0
	s_setprio 1
	v_mfma_f32_16x16x32_bf16 v[56:59], v[170:173], v[186:189], 0
	v_mfma_f32_16x16x32_bf16 v[48:51], v[178:181], v[186:189], 0
	v_mfma_f32_16x16x32_bf16 v[40:43], v[170:173], v[194:197], 0
	v_mfma_f32_16x16x32_bf16 v[32:35], v[178:181], v[194:197], 0
	v_mfma_f32_16x16x32_bf16 v[24:27], v[170:173], v[202:205], 0
	v_mfma_f32_16x16x32_bf16 v[16:19], v[178:181], v[202:205], 0
	v_mfma_f32_16x16x32_bf16 v[8:11], v[170:173], v[210:213], 0
	v_mfma_f32_16x16x32_bf16 v[0:3], v[178:181], v[210:213], 0
	v_mfma_f32_16x16x32_bf16 v[56:59], v[174:177], v[190:193], v[56:59]
	v_mfma_f32_16x16x32_bf16 v[48:51], v[182:185], v[190:193], v[48:51]
	v_mfma_f32_16x16x32_bf16 v[40:43], v[174:177], v[198:201], v[40:43]
	v_mfma_f32_16x16x32_bf16 v[32:35], v[182:185], v[198:201], v[32:35]
	v_mfma_f32_16x16x32_bf16 v[24:27], v[174:177], v[206:209], v[24:27]
	v_mfma_f32_16x16x32_bf16 v[16:19], v[182:185], v[206:209], v[16:19]
	v_mfma_f32_16x16x32_bf16 v[8:11], v[174:177], v[214:217], v[8:11]
	v_mfma_f32_16x16x32_bf16 v[0:3], v[182:185], v[214:217], v[0:3]
	s_barrier
	s_setprio 0
	s_add_i32 s68, 0, 0x18000
	v_add_u32_e32 v136, s68, v152
	s_add_i32 s80, 0, 0x1c000
	ds_read_b128 v[148:151], v136
	ds_read_b128 v[158:161], v136 offset:1024
	ds_read_b128 v[162:165], v136 offset:2048
	ds_read_b128 v[166:169], v136 offset:3072
	v_add_u32_e32 v136, s80, v152
	ds_read_b128 v[170:173], v136
	ds_read_b128 v[174:177], v136 offset:1024
	ds_read_b128 v[178:181], v136 offset:2048
	ds_read_b128 v[182:185], v136 offset:3072
	s_add_u32 s30, s30, 0x40000
	s_addc_u32 s31, s31, 0
	s_mov_b32 m0, s54
	v_lshl_add_u64 v[228:229], s[30:31], 0, v[134:135]
	ds_read_b128 v[186:189], v155 offset:32768
	ds_read_b128 v[190:193], v155 offset:33792
	ds_read_b128 v[194:197], v155 offset:34816
	ds_read_b128 v[198:201], v155 offset:35840
	ds_read_b128 v[202:205], v155 offset:36864
	ds_read_b128 v[206:209], v155 offset:37888
	ds_read_b128 v[210:213], v155 offset:38912
	ds_read_b128 v[214:217], v155 offset:39936
	global_load_lds_dwordx4 v[228:229], off
	v_lshl_add_u64 v[228:229], s[30:31], 0, v[130:131]
	s_mov_b32 m0, s55
	s_nop 0
	global_load_lds_dwordx4 v[228:229], off
	s_waitcnt vmcnt(8) lgkmcnt(0)
	s_setprio 1
	s_barrier
	v_mfma_f32_16x16x32_bf16 v[124:127], v[148:151], v[186:189], v[124:127]
	v_mfma_f32_16x16x32_bf16 v[116:119], v[162:165], v[186:189], v[116:119]
	v_mfma_f32_16x16x32_bf16 v[108:111], v[148:151], v[194:197], v[108:111]
	v_mfma_f32_16x16x32_bf16 v[100:103], v[162:165], v[194:197], v[100:103]
	v_mfma_f32_16x16x32_bf16 v[92:95], v[148:151], v[202:205], v[92:95]
	v_mfma_f32_16x16x32_bf16 v[84:87], v[162:165], v[202:205], v[84:87]
	v_mfma_f32_16x16x32_bf16 v[76:79], v[148:151], v[210:213], v[76:79]
	v_mfma_f32_16x16x32_bf16 v[68:71], v[162:165], v[210:213], v[68:71]
	v_mfma_f32_16x16x32_bf16 v[124:127], v[158:161], v[190:193], v[124:127]
	v_mfma_f32_16x16x32_bf16 v[116:119], v[166:169], v[190:193], v[116:119]
	v_mfma_f32_16x16x32_bf16 v[108:111], v[158:161], v[198:201], v[108:111]
	v_mfma_f32_16x16x32_bf16 v[100:103], v[166:169], v[198:201], v[100:103]
	v_mfma_f32_16x16x32_bf16 v[92:95], v[158:161], v[206:209], v[92:95]
	v_mfma_f32_16x16x32_bf16 v[84:87], v[166:169], v[206:209], v[84:87]
	v_mfma_f32_16x16x32_bf16 v[76:79], v[158:161], v[214:217], v[76:79]
	v_mfma_f32_16x16x32_bf16 v[68:71], v[166:169], v[214:217], v[68:71]
	s_setprio 0
	s_setprio 1
	v_mfma_f32_16x16x32_bf16 v[120:123], v[170:173], v[186:189], v[120:123]
	v_mfma_f32_16x16x32_bf16 v[112:115], v[178:181], v[186:189], v[112:115]
	v_mfma_f32_16x16x32_bf16 v[104:107], v[170:173], v[194:197], v[104:107]
	v_mfma_f32_16x16x32_bf16 v[96:99], v[178:181], v[194:197], v[96:99]
	v_mfma_f32_16x16x32_bf16 v[88:91], v[170:173], v[202:205], v[88:91]
	v_mfma_f32_16x16x32_bf16 v[80:83], v[178:181], v[202:205], v[80:83]
	v_mfma_f32_16x16x32_bf16 v[72:75], v[170:173], v[210:213], v[72:75]
	v_mfma_f32_16x16x32_bf16 v[64:67], v[178:181], v[210:213], v[64:67]
	v_mfma_f32_16x16x32_bf16 v[120:123], v[174:177], v[190:193], v[120:123]
	v_mfma_f32_16x16x32_bf16 v[112:115], v[182:185], v[190:193], v[112:115]
	v_mfma_f32_16x16x32_bf16 v[104:107], v[174:177], v[198:201], v[104:107]
	v_mfma_f32_16x16x32_bf16 v[96:99], v[182:185], v[198:201], v[96:99]
	v_mfma_f32_16x16x32_bf16 v[88:91], v[174:177], v[206:209], v[88:91]
	v_mfma_f32_16x16x32_bf16 v[80:83], v[182:185], v[206:209], v[80:83]
	v_mfma_f32_16x16x32_bf16 v[72:75], v[174:177], v[214:217], v[72:75]
	v_mfma_f32_16x16x32_bf16 v[64:67], v[182:185], v[214:217], v[64:67]
	s_barrier
; #define PG8_STAGE(bufoff, gbase, voff) do { _Pragma("unroll") for (int _i = 0; _i < 2; ++_i) \
;         __builtin_amdgcn_global_load_lds((const unsigned*)((const char*)(gbase) + (voff)[_i]), (PG8_LAS unsigned*)(lds + (bufoff) + ldsw + _i * 8192), 16, 0, 0); } while (0)
; #define PG8_LDA(dst, b, h) do { _Pragma("unroll") for (int m = 0; m < 4; ++m) _Pragma("unroll") for (int k = 0; k < 2; ++k) dst[m][k] = *(const PG8_LAS bf16x8*)(lds + PG8_SA(b, h) + aoff + m * 2048 + k * 1024); } while (0)
; #define PG8_LDB(dst, b, h) do { _Pragma("unroll") for (int n = 0; n < 2; ++n) _Pragma("unroll") for (int k = 0; k < 2; ++k) dst[n][k] = *(const PG8_LAS bf16x8*)(lds + PG8_SB(b, h) + boff + n * 2048 + k * 1024); } while (0)
; #define PG8_MMA(ai, bj, At, Bt) do { __builtin_amdgcn_s_setprio(1); _Pragma("unroll") for (int m = 0; m < 4; ++m) _Pragma("unroll") for (int n = 0; n < 2; ++n) _Pragma("unroll") for (int k = 0; k < 2; ++k) \
;         acc[ai][bj][m][n] = __builtin_amdgcn_mfma_f32_16x16x32_bf16(Bt[n][k], At[m][k], acc[ai][bj][m][n], 0, 0, 0); __builtin_amdgcn_s_setprio(0); } while (0)
; #define PG8_WAIT_V(n) asm volatile("s_waitcnt vmcnt(" #n ")" ::: "memory")
; #define PG8_WAIT_L(n) asm volatile("s_waitcnt lgkmcnt(" #n ")" ::: "memory")
; #define PG8_BAR __builtin_amdgcn_s_barrier()
; #define PG8_SCHED __builtin_amdgcn_sched_barrier(0)
; template <class Epi, class Sched>
; __device__ __forceinline__ void gemm_phase(PG8_LAS unsigned char* lds, PG8_LAS unsigned char* xl, const Gemm g, const Sched& S, const Epi& E) {
;     ...
;             PG8_LDB(B0, 0, 0); PG8_LDB(B1, 0, 1); PG8_SCHED; PG8_LDA(At, 0, 0); PG8_STAGE(PG8_SA(1, 1), a1 + hsA, voffA);
;             PG8_WAIT_V(8); PG8_WAIT_L(0); PG8_BAR; PG8_MMA(0, 0, At, B0); PG8_MMA(0, 1, At, B1); PG8_BAR; PG8_SCHED;
;     ...
;             PG8_LDA(At, 1, 1); PG8_STAGE(PG8_SB(1, 0), b3, voffB); PG8_STAGE(PG8_SB(1, 1), b3 + hsB, voffB); PG8_STAGE(PG8_SA(1, 0), a3, voffA);
;             PG8_WAIT_V(8); PG8_WAIT_L(0); PG8_BAR; PG8_MMA(1, 0, At, B0); PG8_MMA(1, 1, At, B1); PG8_BAR; PG8_SCHED;
	s_setprio 0
	s_add_i32 s30, s68, s42
	v_lshl_add_u64 v[218:219], v[218:219], 0, s[12:13]
	s_mov_b32 m0, s30
	ds_read_b128 v[186:189], v155 offset:49152
	ds_read_b128 v[190:193], v155 offset:50176
	ds_read_b128 v[194:197], v155 offset:51200
	ds_read_b128 v[198:201], v155 offset:52224
	ds_read_b128 v[202:205], v155 offset:53248
	ds_read_b128 v[206:209], v155 offset:54272
	ds_read_b128 v[210:213], v155 offset:55296
	ds_read_b128 v[214:217], v155 offset:56320
	global_load_lds_dwordx4 v[218:219], off
	s_add_i32 m0, s30, 0x2000
	s_add_u32 s28, s28, 0x40080
	v_lshl_add_u64 v[218:219], v[222:223], 0, s[12:13]
	s_addc_u32 s29, s29, 0
	s_add_i32 s30, s80, s42
	global_load_lds_dwordx4 v[218:219], off
	v_lshl_add_u64 v[218:219], s[28:29], 0, v[132:133]
	s_mov_b32 m0, s30
	s_nop 0
	global_load_lds_dwordx4 v[218:219], off
	v_lshl_add_u64 v[218:219], s[28:29], 0, v[128:129]
	s_add_i32 m0, s30, 0x2000
	s_nop 0
	global_load_lds_dwordx4 v[218:219], off
	v_lshl_add_u64 v[218:219], v[224:225], 0, s[12:13]
	s_mov_b32 m0, s58
	s_nop 0
	global_load_lds_dwordx4 v[218:219], off
	v_lshl_add_u64 v[218:219], v[226:227], 0, s[12:13]
	s_mov_b32 m0, s59
	s_nop 0
	global_load_lds_dwordx4 v[218:219], off
	s_waitcnt vmcnt(8) lgkmcnt(0)
	s_setprio 1
	s_barrier
	v_mfma_f32_16x16x32_bf16 v[60:63], v[148:151], v[186:189], v[60:63]
	v_mfma_f32_16x16x32_bf16 v[52:55], v[162:165], v[186:189], v[52:55]
	v_mfma_f32_16x16x32_bf16 v[44:47], v[148:151], v[194:197], v[44:47]
	v_mfma_f32_16x16x32_bf16 v[36:39], v[162:165], v[194:197], v[36:39]
	v_mfma_f32_16x16x32_bf16 v[28:31], v[148:151], v[202:205], v[28:31]
	v_mfma_f32_16x16x32_bf16 v[20:23], v[162:165], v[202:205], v[20:23]
	v_mfma_f32_16x16x32_bf16 v[12:15], v[148:151], v[210:213], v[12:15]
	v_mfma_f32_16x16x32_bf16 v[4:7], v[162:165], v[210:213], v[4:7]
	v_mfma_f32_16x16x32_bf16 v[60:63], v[158:161], v[190:193], v[60:63]
	v_mfma_f32_16x16x32_bf16 v[52:55], v[166:169], v[190:193], v[52:55]
	v_mfma_f32_16x16x32_bf16 v[44:47], v[158:161], v[198:201], v[44:47]
	v_mfma_f32_16x16x32_bf16 v[36:39], v[166:169], v[198:201], v[36:39]
	v_mfma_f32_16x16x32_bf16 v[28:31], v[158:161], v[206:209], v[28:31]
	v_mfma_f32_16x16x32_bf16 v[20:23], v[166:169], v[206:209], v[20:23]
	v_mfma_f32_16x16x32_bf16 v[12:15], v[158:161], v[214:217], v[12:15]
	v_mfma_f32_16x16x32_bf16 v[4:7], v[166:169], v[214:217], v[4:7]
	s_setprio 0
	s_setprio 1
	v_mfma_f32_16x16x32_bf16 v[56:59], v[170:173], v[186:189], v[56:59]
	s_add_i32 s79, s79, 2
	v_mfma_f32_16x16x32_bf16 v[48:51], v[178:181], v[186:189], v[48:51]
	s_add_u32 s77, s77, 0x100
	v_mfma_f32_16x16x32_bf16 v[40:43], v[170:173], v[194:197], v[40:43]
	s_addc_u32 s78, s78, 0
	v_mfma_f32_16x16x32_bf16 v[32:35], v[178:181], v[194:197], v[32:35]
	s_add_u32 s26, s26, 0x100
	v_mfma_f32_16x16x32_bf16 v[24:27], v[170:173], v[202:205], v[24:27]
	s_addc_u32 s27, s27, 0
	v_mfma_f32_16x16x32_bf16 v[16:19], v[178:181], v[202:205], v[16:19]
	s_cmp_gt_u32 s79, 13
	v_mfma_f32_16x16x32_bf16 v[8:11], v[170:173], v[210:213], v[8:11]
	v_mfma_f32_16x16x32_bf16 v[0:3], v[178:181], v[210:213], v[0:3]
	v_mfma_f32_16x16x32_bf16 v[56:59], v[174:177], v[190:193], v[56:59]
	v_mfma_f32_16x16x32_bf16 v[48:51], v[182:185], v[190:193], v[48:51]
	v_mfma_f32_16x16x32_bf16 v[40:43], v[174:177], v[198:201], v[40:43]
	v_mfma_f32_16x16x32_bf16 v[32:35], v[182:185], v[198:201], v[32:35]
	v_mfma_f32_16x16x32_bf16 v[24:27], v[174:177], v[206:209], v[24:27]
	v_mfma_f32_16x16x32_bf16 v[16:19], v[182:185], v[206:209], v[16:19]
	v_mfma_f32_16x16x32_bf16 v[8:11], v[174:177], v[214:217], v[8:11]
	v_mfma_f32_16x16x32_bf16 v[0:3], v[182:185], v[214:217], v[0:3]
	s_barrier
	s_setprio 0
	s_cbranch_scc1 .Lpeel_after_P1
.LBB0_102:
	ds_read_b128 v[148:151], v153
	ds_read_b128 v[158:161], v153 offset:1024
	ds_read_b128 v[162:165], v153 offset:2048
	ds_read_b128 v[166:169], v153 offset:3072
	ds_read_b128 v[170:173], v154
	ds_read_b128 v[174:177], v154 offset:1024
	ds_read_b128 v[178:181], v154 offset:2048
	ds_read_b128 v[182:185], v154 offset:3072
	s_add_u32 s28, s26, 0xfffc0080
	s_addc_u32 s29, s27, -1
	s_cmp_eq_u32 s79, 12
	s_cselect_b32 s31, s73, s29
	s_cselect_b32 s30, s74, s28
	s_cselect_b32 s29, s75, s78
	s_cselect_b32 s28, s76, s77
	v_lshl_add_u64 v[218:219], s[26:27], 0, v[142:143]
	s_add_i32 m0, s52, 0xc000
	ds_read_b128 v[186:189], v155
	ds_read_b128 v[190:193], v155 offset:1024
	ds_read_b128 v[194:197], v155 offset:2048
	ds_read_b128 v[198:201], v155 offset:3072
	ds_read_b128 v[202:205], v155 offset:4096
	ds_read_b128 v[206:209], v155 offset:5120
	ds_read_b128 v[210:213], v155 offset:6144
	ds_read_b128 v[214:217], v155 offset:7168
	global_load_lds_dwordx4 v[218:219], off
	v_lshl_add_u64 v[218:219], s[26:27], 0, v[140:141]
	s_add_i32 m0, s52, 0xe000
	s_nop 0
	global_load_lds_dwordx4 v[218:219], off
	s_waitcnt vmcnt(8) lgkmcnt(0)
	s_setprio 1
	s_barrier
; #define PG8_STAGE(bufoff, gbase, voff) do { _Pragma("unroll") for (int _i = 0; _i < 2; ++_i) \
;         __builtin_amdgcn_global_load_lds((const unsigned*)((const char*)(gbase) + (voff)[_i]), (PG8_LAS unsigned*)(lds + (bufoff) + ldsw + _i * 8192), 16, 0, 0); } while (0)
; #define PG8_LDA(dst, b, h) do { _Pragma("unroll") for (int m = 0; m < 4; ++m) _Pragma("unroll") for (int k = 0; k < 2; ++k) dst[m][k] = *(const PG8_LAS bf16x8*)(lds + PG8_SA(b, h) + aoff + m * 2048 + k * 1024); } while (0)
; #define PG8_LDB(dst, b, h) do { _Pragma("unroll") for (int n = 0; n < 2; ++n) _Pragma("unroll") for (int k = 0; k < 2; ++k) dst[n][k] = *(const PG8_LAS bf16x8*)(lds + PG8_SB(b, h) + boff + n * 2048 + k * 1024); } while (0)
; #define PG8_MMA(ai, bj, At, Bt) do { __builtin_amdgcn_s_setprio(1); _Pragma("unroll") for (int m = 0; m < 4; ++m) _Pragma("unroll") for (int n = 0; n < 2; ++n) _Pragma("unroll") for (int k = 0; k < 2; ++k) \
;         acc[ai][bj][m][n] = __builtin_amdgcn_mfma_f32_16x16x32_bf16(Bt[n][k], At[m][k], acc[ai][bj][m][n], 0, 0, 0); __builtin_amdgcn_s_setprio(0); } while (0)
; #define PG8_WAIT_V(n) asm volatile("s_waitcnt vmcnt(" #n ")" ::: "memory")
; #define PG8_WAIT_L(n) asm volatile("s_waitcnt lgkmcnt(" #n ")" ::: "memory")
; #define PG8_BAR __builtin_amdgcn_s_barrier()
; #define PG8_SCHED __builtin_amdgcn_sched_barrier(0)
; template <class Epi, class Sched>
; __device__ __forceinline__ void gemm_phase(PG8_LAS unsigned char* lds, PG8_LAS unsigned char* xl, const Gemm g, const Sched& S, const Epi& E) {
;     ...
;             PG8_LDB(B0, 0, 0); PG8_LDB(B1, 0, 1); PG8_SCHED; PG8_LDA(At, 0, 0); PG8_STAGE(PG8_SA(1, 1), a1 + hsA, voffA);
;             PG8_WAIT_V(8); PG8_WAIT_L(0); PG8_BAR; PG8_MMA(0, 0, At, B0); PG8_MMA(0, 1, At, B1); PG8_BAR; PG8_SCHED;
;             PG8_LDA(At, 0, 1); PG8_STAGE(PG8_SB(0, 0), b2, voffB); PG8_STAGE(PG8_SB(0, 1), b2 + hsB, voffB); PG8_STAGE(PG8_SA(0, 0), a2, voffA);
;             PG8_WAIT_V(8); PG8_WAIT_L(0); PG8_BAR; PG8_MMA(1, 0, At, B0); PG8_MMA(1, 1, At, B1); PG8_BAR; PG8_SCHED;
	v_mfma_f32_16x16x32_bf16 v[124:127], v[148:151], v[186:189], v[124:127]
	v_mfma_f32_16x16x32_bf16 v[116:119], v[162:165], v[186:189], v[116:119]
	v_mfma_f32_16x16x32_bf16 v[108:111], v[148:151], v[194:197], v[108:111]
	v_mfma_f32_16x16x32_bf16 v[100:103], v[162:165], v[194:197], v[100:103]
	v_mfma_f32_16x16x32_bf16 v[92:95], v[148:151], v[202:205], v[92:95]
	v_mfma_f32_16x16x32_bf16 v[84:87], v[162:165], v[202:205], v[84:87]
	v_mfma_f32_16x16x32_bf16 v[76:79], v[148:151], v[210:213], v[76:79]
	v_mfma_f32_16x16x32_bf16 v[68:71], v[162:165], v[210:213], v[68:71]
	v_mfma_f32_16x16x32_bf16 v[124:127], v[158:161], v[190:193], v[124:127]
	v_mfma_f32_16x16x32_bf16 v[116:119], v[166:169], v[190:193], v[116:119]
	v_mfma_f32_16x16x32_bf16 v[108:111], v[158:161], v[198:201], v[108:111]
	v_mfma_f32_16x16x32_bf16 v[100:103], v[166:169], v[198:201], v[100:103]
	v_mfma_f32_16x16x32_bf16 v[92:95], v[158:161], v[206:209], v[92:95]
	v_mfma_f32_16x16x32_bf16 v[84:87], v[166:169], v[206:209], v[84:87]
	v_mfma_f32_16x16x32_bf16 v[76:79], v[158:161], v[214:217], v[76:79]
	v_mfma_f32_16x16x32_bf16 v[68:71], v[166:169], v[214:217], v[68:71]
	s_setprio 0
	s_setprio 1
	v_mfma_f32_16x16x32_bf16 v[120:123], v[170:173], v[186:189], v[120:123]
	v_mfma_f32_16x16x32_bf16 v[112:115], v[178:181], v[186:189], v[112:115]
	v_mfma_f32_16x16x32_bf16 v[104:107], v[170:173], v[194:197], v[104:107]
	v_mfma_f32_16x16x32_bf16 v[96:99], v[178:181], v[194:197], v[96:99]
	v_mfma_f32_16x16x32_bf16 v[88:91], v[170:173], v[202:205], v[88:91]
	v_mfma_f32_16x16x32_bf16 v[80:83], v[178:181], v[202:205], v[80:83]
	v_mfma_f32_16x16x32_bf16 v[72:75], v[170:173], v[210:213], v[72:75]
	v_mfma_f32_16x16x32_bf16 v[64:67], v[178:181], v[210:213], v[64:67]
	v_mfma_f32_16x16x32_bf16 v[120:123], v[174:177], v[190:193], v[120:123]
	v_mfma_f32_16x16x32_bf16 v[112:115], v[182:185], v[190:193], v[112:115]
	v_mfma_f32_16x16x32_bf16 v[104:107], v[174:177], v[198:201], v[104:107]
	v_mfma_f32_16x16x32_bf16 v[96:99], v[182:185], v[198:201], v[96:99]
	v_mfma_f32_16x16x32_bf16 v[88:91], v[174:177], v[206:209], v[88:91]
	v_mfma_f32_16x16x32_bf16 v[80:83], v[182:185], v[206:209], v[80:83]
	v_mfma_f32_16x16x32_bf16 v[72:75], v[174:177], v[214:217], v[72:75]
	v_mfma_f32_16x16x32_bf16 v[64:67], v[182:185], v[214:217], v[64:67]
	s_barrier
	s_setprio 0
	s_add_i32 s68, s60, s42
	v_lshl_add_u64 v[218:219], s[28:29], 0, v[132:133]
	s_mov_b32 m0, s68
	ds_read_b128 v[186:189], v155 offset:16384
	ds_read_b128 v[190:193], v155 offset:17408
	ds_read_b128 v[194:197], v155 offset:18432
	ds_read_b128 v[198:201], v155 offset:19456
	ds_read_b128 v[202:205], v155 offset:20480
	ds_read_b128 v[206:209], v155 offset:21504
	ds_read_b128 v[210:213], v155 offset:22528
	ds_read_b128 v[214:217], v155 offset:23552
	global_load_lds_dwordx4 v[218:219], off
	s_add_i32 m0, s68, 0x2000
	s_add_u32 s80, s28, 0x40000
	v_lshl_add_u64 v[222:223], s[28:29], 0, v[128:129]
	s_addc_u32 s81, s29, 0
	s_add_i32 s68, s61, s42
	global_load_lds_dwordx4 v[222:223], off
	v_lshl_add_u64 v[224:225], s[80:81], 0, v[132:133]
	s_mov_b32 m0, s68
	v_lshl_add_u64 v[226:227], s[30:31], 0, v[130:131]
	global_load_lds_dwordx4 v[224:225], off
	v_lshl_add_u64 v[224:225], s[80:81], 0, v[128:129]
	s_add_i32 m0, s68, 0x2000
	s_nop 0
	global_load_lds_dwordx4 v[224:225], off
	v_lshl_add_u64 v[224:225], s[30:31], 0, v[134:135]
	s_mov_b32 m0, s52
	s_nop 0
	global_load_lds_dwordx4 v[224:225], off
	s_mov_b32 m0, s53
	s_nop 0
	global_load_lds_dwordx4 v[226:227], off
	s_waitcnt vmcnt(8) lgkmcnt(0)
	s_setprio 1
	s_barrier
	v_mfma_f32_16x16x32_bf16 v[60:63], v[148:151], v[186:189], v[60:63]
	v_mfma_f32_16x16x32_bf16 v[52:55], v[162:165], v[186:189], v[52:55]
	v_mfma_f32_16x16x32_bf16 v[44:47], v[148:151], v[194:197], v[44:47]
	v_mfma_f32_16x16x32_bf16 v[36:39], v[162:165], v[194:197], v[36:39]
	v_mfma_f32_16x16x32_bf16 v[28:31], v[148:151], v[202:205], v[28:31]
	v_mfma_f32_16x16x32_bf16 v[20:23], v[162:165], v[202:205], v[20:23]
	v_mfma_f32_16x16x32_bf16 v[12:15], v[148:151], v[210:213], v[12:15]
	v_mfma_f32_16x16x32_bf16 v[4:7], v[162:165], v[210:213], v[4:7]
	v_mfma_f32_16x16x32_bf16 v[60:63], v[158:161], v[190:193], v[60:63]
	v_mfma_f32_16x16x32_bf16 v[52:55], v[166:169], v[190:193], v[52:55]
	v_mfma_f32_16x16x32_bf16 v[44:47], v[158:161], v[198:201], v[44:47]
	v_mfma_f32_16x16x32_bf16 v[36:39], v[166:169], v[198:201], v[36:39]
	v_mfma_f32_16x16x32_bf16 v[28:31], v[158:161], v[206:209], v[28:31]
	v_mfma_f32_16x16x32_bf16 v[20:23], v[166:169], v[206:209], v[20:23]
	v_mfma_f32_16x16x32_bf16 v[12:15], v[158:161], v[214:217], v[12:15]
	v_mfma_f32_16x16x32_bf16 v[4:7], v[166:169], v[214:217], v[4:7]
	s_setprio 0
	s_setprio 1
	v_mfma_f32_16x16x32_bf16 v[56:59], v[170:173], v[186:189], v[56:59]
	v_mfma_f32_16x16x32_bf16 v[48:51], v[178:181], v[186:189], v[48:51]
	v_mfma_f32_16x16x32_bf16 v[40:43], v[170:173], v[194:197], v[40:43]
	v_mfma_f32_16x16x32_bf16 v[32:35], v[178:181], v[194:197], v[32:35]
	v_mfma_f32_16x16x32_bf16 v[24:27], v[170:173], v[202:205], v[24:27]
	v_mfma_f32_16x16x32_bf16 v[16:19], v[178:181], v[202:205], v[16:19]
	v_mfma_f32_16x16x32_bf16 v[8:11], v[170:173], v[210:213], v[8:11]
	v_mfma_f32_16x16x32_bf16 v[0:3], v[178:181], v[210:213], v[0:3]
	v_mfma_f32_16x16x32_bf16 v[56:59], v[174:177], v[190:193], v[56:59]
	v_mfma_f32_16x16x32_bf16 v[48:51], v[182:185], v[190:193], v[48:51]
	v_mfma_f32_16x16x32_bf16 v[40:43], v[174:177], v[198:201], v[40:43]
	v_mfma_f32_16x16x32_bf16 v[32:35], v[182:185], v[198:201], v[32:35]
	v_mfma_f32_16x16x32_bf16 v[24:27], v[174:177], v[206:209], v[24:27]
	v_mfma_f32_16x16x32_bf16 v[16:19], v[182:185], v[206:209], v[16:19]
	v_mfma_f32_16x16x32_bf16 v[8:11], v[174:177], v[214:217], v[8:11]
	v_mfma_f32_16x16x32_bf16 v[0:3], v[182:185], v[214:217], v[0:3]
	s_barrier
; #define PG8_STAGE(bufoff, gbase, voff) do { _Pragma("unroll") for (int _i = 0; _i < 2; ++_i) \
;         __builtin_amdgcn_global_load_lds((const unsigned*)((const char*)(gbase) + (voff)[_i]), (PG8_LAS unsigned*)(lds + (bufoff) + ldsw + _i * 8192), 16, 0, 0); } while (0)
; #define PG8_LDA(dst, b, h) do { _Pragma("unroll") for (int m = 0; m < 4; ++m) _Pragma("unroll") for (int k = 0; k < 2; ++k) dst[m][k] = *(const PG8_LAS bf16x8*)(lds + PG8_SA(b, h) + aoff + m * 2048 + k * 1024); } while (0)
; #define PG8_LDB(dst, b, h) do { _Pragma("unroll") for (int n = 0; n < 2; ++n) _Pragma("unroll") for (int k = 0; k < 2; ++k) dst[n][k] = *(const PG8_LAS bf16x8*)(lds + PG8_SB(b, h) + boff + n * 2048 + k * 1024); } while (0)
; #define PG8_MMA(ai, bj, At, Bt) do { __builtin_amdgcn_s_setprio(1); _Pragma("unroll") for (int m = 0; m < 4; ++m) _Pragma("unroll") for (int n = 0; n < 2; ++n) _Pragma("unroll") for (int k = 0; k < 2; ++k) \
;         acc[ai][bj][m][n] = __builtin_amdgcn_mfma_f32_16x16x32_bf16(Bt[n][k], At[m][k], acc[ai][bj][m][n], 0, 0, 0); __builtin_amdgcn_s_setprio(0); } while (0)
; #define PG8_WAIT_V(n) asm volatile("s_waitcnt vmcnt(" #n ")" ::: "memory")
; #define PG8_WAIT_L(n) asm volatile("s_waitcnt lgkmcnt(" #n ")" ::: "memory")
; #define PG8_BAR __builtin_amdgcn_s_barrier()
; #define PG8_SCHED __builtin_amdgcn_sched_barrier(0)
; template <class Epi, class Sched>
; __device__ __forceinline__ void gemm_phase(PG8_LAS unsigned char* lds, PG8_LAS unsigned char* xl, const Gemm g, const Sched& S, const Epi& E) {
;     ...
;             PG8_LDB(B0, 1, 0); PG8_LDB(B1, 1, 1); PG8_SCHED; PG8_LDA(At, 1, 0); PG8_STAGE(PG8_SA(0, 1), a2 + hsA, voffA);
;             PG8_WAIT_V(8); PG8_WAIT_L(0); PG8_BAR; PG8_MMA(0, 0, At, B0); PG8_MMA(0, 1, At, B1); PG8_BAR; PG8_SCHED;
	s_setprio 0
	s_add_i32 s68, 0, 0x18000
	v_add_u32_e32 v136, s68, v152
	s_add_i32 s80, 0, 0x1c000
	ds_read_b128 v[148:151], v136
	ds_read_b128 v[158:161], v136 offset:1024
	ds_read_b128 v[162:165], v136 offset:2048
	ds_read_b128 v[166:169], v136 offset:3072
	v_add_u32_e32 v136, s80, v152
	ds_read_b128 v[170:173], v136
	ds_read_b128 v[174:177], v136 offset:1024
	ds_read_b128 v[178:181], v136 offset:2048
	ds_read_b128 v[182:185], v136 offset:3072
	s_add_u32 s30, s30, 0x40000
	s_addc_u32 s31, s31, 0
	s_mov_b32 m0, s54
	v_lshl_add_u64 v[228:229], s[30:31], 0, v[134:135]
	ds_read_b128 v[186:189], v155 offset:32768
	ds_read_b128 v[190:193], v155 offset:33792
	ds_read_b128 v[194:197], v155 offset:34816
	ds_read_b128 v[198:201], v155 offset:35840
	ds_read_b128 v[202:205], v155 offset:36864
	ds_read_b128 v[206:209], v155 offset:37888
	ds_read_b128 v[210:213], v155 offset:38912
	ds_read_b128 v[214:217], v155 offset:39936
	global_load_lds_dwordx4 v[228:229], off
	v_lshl_add_u64 v[228:229], s[30:31], 0, v[130:131]
	s_mov_b32 m0, s55
	s_nop 0
	global_load_lds_dwordx4 v[228:229], off
	s_waitcnt vmcnt(8) lgkmcnt(0)
	s_setprio 1
	s_barrier
	v_mfma_f32_16x16x32_bf16 v[124:127], v[148:151], v[186:189], v[124:127]
	v_mfma_f32_16x16x32_bf16 v[116:119], v[162:165], v[186:189], v[116:119]
	v_mfma_f32_16x16x32_bf16 v[108:111], v[148:151], v[194:197], v[108:111]
	v_mfma_f32_16x16x32_bf16 v[100:103], v[162:165], v[194:197], v[100:103]
	v_mfma_f32_16x16x32_bf16 v[92:95], v[148:151], v[202:205], v[92:95]
	v_mfma_f32_16x16x32_bf16 v[84:87], v[162:165], v[202:205], v[84:87]
	v_mfma_f32_16x16x32_bf16 v[76:79], v[148:151], v[210:213], v[76:79]
	v_mfma_f32_16x16x32_bf16 v[68:71], v[162:165], v[210:213], v[68:71]
	v_mfma_f32_16x16x32_bf16 v[124:127], v[158:161], v[190:193], v[124:127]
	v_mfma_f32_16x16x32_bf16 v[116:119], v[166:169], v[190:193], v[116:119]
	v_mfma_f32_16x16x32_bf16 v[108:111], v[158:161], v[198:201], v[108:111]
	v_mfma_f32_16x16x32_bf16 v[100:103], v[166:169], v[198:201], v[100:103]
	v_mfma_f32_16x16x32_bf16 v[92:95], v[158:161], v[206:209], v[92:95]
	v_mfma_f32_16x16x32_bf16 v[84:87], v[166:169], v[206:209], v[84:87]
	v_mfma_f32_16x16x32_bf16 v[76:79], v[158:161], v[214:217], v[76:79]
	v_mfma_f32_16x16x32_bf16 v[68:71], v[166:169], v[214:217], v[68:71]
	s_setprio 0
	s_setprio 1
	v_mfma_f32_16x16x32_bf16 v[120:123], v[170:173], v[186:189], v[120:123]
	v_mfma_f32_16x16x32_bf16 v[112:115], v[178:181], v[186:189], v[112:115]
	v_mfma_f32_16x16x32_bf16 v[104:107], v[170:173], v[194:197], v[104:107]
	v_mfma_f32_16x16x32_bf16 v[96:99], v[178:181], v[194:197], v[96:99]
	v_mfma_f32_16x16x32_bf16 v[88:91], v[170:173], v[202:205], v[88:91]
	v_mfma_f32_16x16x32_bf16 v[80:83], v[178:181], v[202:205], v[80:83]
	v_mfma_f32_16x16x32_bf16 v[72:75], v[170:173], v[210:213], v[72:75]
	v_mfma_f32_16x16x32_bf16 v[64:67], v[178:181], v[210:213], v[64:67]
	v_mfma_f32_16x16x32_bf16 v[120:123], v[174:177], v[190:193], v[120:123]
	v_mfma_f32_16x16x32_bf16 v[112:115], v[182:185], v[190:193], v[112:115]
	v_mfma_f32_16x16x32_bf16 v[104:107], v[174:177], v[198:201], v[104:107]
	v_mfma_f32_16x16x32_bf16 v[96:99], v[182:185], v[198:201], v[96:99]
	v_mfma_f32_16x16x32_bf16 v[88:91], v[174:177], v[206:209], v[88:91]
	v_mfma_f32_16x16x32_bf16 v[80:83], v[182:185], v[206:209], v[80:83]
	v_mfma_f32_16x16x32_bf16 v[72:75], v[174:177], v[214:217], v[72:75]
	v_mfma_f32_16x16x32_bf16 v[64:67], v[182:185], v[214:217], v[64:67]
	s_barrier
; #define PG8_STAGE(bufoff, gbase, voff) do { _Pragma("unroll") for (int _i = 0; _i < 2; ++_i) \
;         __builtin_amdgcn_global_load_lds((const unsigned*)((const char*)(gbase) + (voff)[_i]), (PG8_LAS unsigned*)(lds + (bufoff) + ldsw + _i * 8192), 16, 0, 0); } while (0)
; #define PG8_LDA(dst, b, h) do { _Pragma("unroll") for (int m = 0; m < 4; ++m) _Pragma("unroll") for (int k = 0; k < 2; ++k) dst[m][k] = *(const PG8_LAS bf16x8*)(lds + PG8_SA(b, h) + aoff + m * 2048 + k * 1024); } while (0)
; #define PG8_MMA(ai, bj, At, Bt) do { __builtin_amdgcn_s_setprio(1); _Pragma("unroll") for (int m = 0; m < 4; ++m) _Pragma("unroll") for (int n = 0; n < 2; ++n) _Pragma("unroll") for (int k = 0; k < 2; ++k) \
;         acc[ai][bj][m][n] = __builtin_amdgcn_mfma_f32_16x16x32_bf16(Bt[n][k], At[m][k], acc[ai][bj][m][n], 0, 0, 0); __builtin_amdgcn_s_setprio(0); } while (0)
; #define PG8_WAIT_V(n) asm volatile("s_waitcnt vmcnt(" #n ")" ::: "memory")
; #define PG8_WAIT_L(n) asm volatile("s_waitcnt lgkmcnt(" #n ")" ::: "memory")
; #define PG8_BAR __builtin_amdgcn_s_barrier()
; #define PG8_SCHED __builtin_amdgcn_sched_barrier(0)
; template <class Epi, class Sched>
; __device__ __forceinline__ void gemm_phase(PG8_LAS unsigned char* lds, PG8_LAS unsigned char* xl, const Gemm g, const Sched& S, const Epi& E) {
;     ...
;             PG8_LDA(At, 1, 1); PG8_STAGE(PG8_SB(1, 0), b3, voffB); PG8_STAGE(PG8_SB(1, 1), b3 + hsB, voffB); PG8_STAGE(PG8_SA(1, 0), a3, voffA);
;             PG8_WAIT_V(8); PG8_WAIT_L(0); PG8_BAR; PG8_MMA(1, 0, At, B0); PG8_MMA(1, 1, At, B1); PG8_BAR; PG8_SCHED;
	s_setprio 0
	s_add_i32 s30, s68, s42
	v_lshl_add_u64 v[218:219], v[218:219], 0, s[12:13]
	s_mov_b32 m0, s30
	ds_read_b128 v[186:189], v155 offset:49152
	ds_read_b128 v[190:193], v155 offset:50176
	ds_read_b128 v[194:197], v155 offset:51200
	ds_read_b128 v[198:201], v155 offset:52224
	ds_read_b128 v[202:205], v155 offset:53248
	ds_read_b128 v[206:209], v155 offset:54272
	ds_read_b128 v[210:213], v155 offset:55296
	ds_read_b128 v[214:217], v155 offset:56320
	global_load_lds_dwordx4 v[218:219], off
	s_add_i32 m0, s30, 0x2000
	s_add_u32 s28, s28, 0x40080
	v_lshl_add_u64 v[218:219], v[222:223], 0, s[12:13]
	s_addc_u32 s29, s29, 0
	s_add_i32 s30, s80, s42
	global_load_lds_dwordx4 v[218:219], off
	v_lshl_add_u64 v[218:219], s[28:29], 0, v[132:133]
	s_mov_b32 m0, s30
	s_nop 0
	global_load_lds_dwordx4 v[218:219], off
	v_lshl_add_u64 v[218:219], s[28:29], 0, v[128:129]
	s_add_i32 m0, s30, 0x2000
	s_nop 0
	global_load_lds_dwordx4 v[218:219], off
	v_lshl_add_u64 v[218:219], v[224:225], 0, s[12:13]
	s_mov_b32 m0, s58
	s_nop 0
	global_load_lds_dwordx4 v[218:219], off
	v_lshl_add_u64 v[218:219], v[226:227], 0, s[12:13]
	s_mov_b32 m0, s59
	s_nop 0
	global_load_lds_dwordx4 v[218:219], off
	s_waitcnt vmcnt(8) lgkmcnt(0)
	s_setprio 1
	s_barrier
	v_mfma_f32_16x16x32_bf16 v[60:63], v[148:151], v[186:189], v[60:63]
	v_mfma_f32_16x16x32_bf16 v[52:55], v[162:165], v[186:189], v[52:55]
	v_mfma_f32_16x16x32_bf16 v[44:47], v[148:151], v[194:197], v[44:47]
	v_mfma_f32_16x16x32_bf16 v[36:39], v[162:165], v[194:197], v[36:39]
	v_mfma_f32_16x16x32_bf16 v[28:31], v[148:151], v[202:205], v[28:31]
	v_mfma_f32_16x16x32_bf16 v[20:23], v[162:165], v[202:205], v[20:23]
	v_mfma_f32_16x16x32_bf16 v[12:15], v[148:151], v[210:213], v[12:15]
	v_mfma_f32_16x16x32_bf16 v[4:7], v[162:165], v[210:213], v[4:7]
	v_mfma_f32_16x16x32_bf16 v[60:63], v[158:161], v[190:193], v[60:63]
	v_mfma_f32_16x16x32_bf16 v[52:55], v[166:169], v[190:193], v[52:55]
	v_mfma_f32_16x16x32_bf16 v[44:47], v[158:161], v[198:201], v[44:47]
	v_mfma_f32_16x16x32_bf16 v[36:39], v[166:169], v[198:201], v[36:39]
	v_mfma_f32_16x16x32_bf16 v[28:31], v[158:161], v[206:209], v[28:31]
	v_mfma_f32_16x16x32_bf16 v[20:23], v[166:169], v[206:209], v[20:23]
	v_mfma_f32_16x16x32_bf16 v[12:15], v[158:161], v[214:217], v[12:15]
	v_mfma_f32_16x16x32_bf16 v[4:7], v[166:169], v[214:217], v[4:7]
	s_setprio 0
	s_setprio 1
	v_mfma_f32_16x16x32_bf16 v[56:59], v[170:173], v[186:189], v[56:59]
	s_add_i32 s79, s79, 2
	v_mfma_f32_16x16x32_bf16 v[48:51], v[178:181], v[186:189], v[48:51]
	s_add_u32 s77, s77, 0x100
	v_mfma_f32_16x16x32_bf16 v[40:43], v[170:173], v[194:197], v[40:43]
	s_addc_u32 s78, s78, 0
	v_mfma_f32_16x16x32_bf16 v[32:35], v[178:181], v[194:197], v[32:35]
	s_add_u32 s26, s26, 0x100
	v_mfma_f32_16x16x32_bf16 v[24:27], v[170:173], v[202:205], v[24:27]
	s_addc_u32 s27, s27, 0
	v_mfma_f32_16x16x32_bf16 v[16:19], v[178:181], v[202:205], v[16:19]
	s_cmp_gt_u32 s79, 13
	v_mfma_f32_16x16x32_bf16 v[8:11], v[170:173], v[210:213], v[8:11]
	v_mfma_f32_16x16x32_bf16 v[0:3], v[178:181], v[210:213], v[0:3]
	v_mfma_f32_16x16x32_bf16 v[56:59], v[174:177], v[190:193], v[56:59]
	v_mfma_f32_16x16x32_bf16 v[48:51], v[182:185], v[190:193], v[48:51]
	v_mfma_f32_16x16x32_bf16 v[40:43], v[174:177], v[198:201], v[40:43]
	v_mfma_f32_16x16x32_bf16 v[32:35], v[182:185], v[198:201], v[32:35]
	v_mfma_f32_16x16x32_bf16 v[24:27], v[174:177], v[206:209], v[24:27]
	v_mfma_f32_16x16x32_bf16 v[16:19], v[182:185], v[206:209], v[16:19]
	v_mfma_f32_16x16x32_bf16 v[8:11], v[174:177], v[214:217], v[8:11]
	v_mfma_f32_16x16x32_bf16 v[0:3], v[182:185], v[214:217], v[0:3]
	s_barrier
	s_setprio 0
	s_cbranch_scc0 .LBB0_102

; #define PG8_STAGE(bufoff, gbase, voff) do { _Pragma("unroll") for (int _i = 0; _i < 2; ++_i) \
;         __builtin_amdgcn_global_load_lds((const unsigned*)((const char*)(gbase) + (voff)[_i]), (PG8_LAS unsigned*)(lds + (bufoff) + ldsw + _i * 8192), 16, 0, 0); } while (0)
; #define PG8_LDA(dst, b, h) do { _Pragma("unroll") for (int m = 0; m < 4; ++m) _Pragma("unroll") for (int k = 0; k < 2; ++k) dst[m][k] = *(const PG8_LAS bf16x8*)(lds + PG8_SA(b, h) + aoff + m * 2048 + k * 1024); } while (0)
; #define PG8_LDB(dst, b, h) do { _Pragma("unroll") for (int n = 0; n < 2; ++n) _Pragma("unroll") for (int k = 0; k < 2; ++k) dst[n][k] = *(const PG8_LAS bf16x8*)(lds + PG8_SB(b, h) + boff + n * 2048 + k * 1024); } while (0)
; #define PG8_MMA(ai, bj, At, Bt) do { __builtin_amdgcn_s_setprio(1); _Pragma("unroll") for (int m = 0; m < 4; ++m) _Pragma("unroll") for (int n = 0; n < 2; ++n) _Pragma("unroll") for (int k = 0; k < 2; ++k) \
;         acc[ai][bj][m][n] = __builtin_amdgcn_mfma_f32_16x16x32_bf16(Bt[n][k], At[m][k], acc[ai][bj][m][n], 0, 0, 0); __builtin_amdgcn_s_setprio(0); } while (0)
; #define PG8_BAR __builtin_amdgcn_s_barrier()
; template <class Epi, class Sched>
; __device__ __forceinline__ void gemm_phase(PG8_LAS unsigned char* lds, PG8_LAS unsigned char* xl, const Gemm g, const Sched& S, const Epi& E) {
;     ...
;         const bool has_next = S.next(ui + 1, nxt);
;         const char* nA = has_next ? (const char*)g.A + nxt.aoff : cA; const char* nB = has_next ? (const char*)g.Bt + nxt.boff : cB;
; #pragma unroll 1
;         for (int t = 0; t < nt; t += 2) {
;             const bool last = (t == nt - 2);
;             const char* a1 = cA + (size_t)(t + 1) * kstep;
;             const char* a2 = last ? nA : cA + (size_t)(t + 2) * kstep; const char* b2 = last ? nB : cB + (size_t)(t + 2) * kstep;
;             const char* a3 = a2 + kstep; const char* b3 = b2 + kstep;
;             PG8_LDB(B0, 0, 0); PG8_LDB(B1, 0, 1); PG8_SCHED; PG8_LDA(At, 0, 0); PG8_STAGE(PG8_SA(1, 1), a1 + hsA, voffA);
;             PG8_WAIT_V(8); PG8_WAIT_L(0); PG8_BAR; PG8_MMA(0, 0, At, B0); PG8_MMA(0, 1, At, B1); PG8_BAR; PG8_SCHED;
;             PG8_LDA(At, 0, 1); PG8_STAGE(PG8_SB(0, 0), b2, voffB); PG8_STAGE(PG8_SB(0, 1), b2 + hsB, voffB); PG8_STAGE(PG8_SA(0, 0), a2, voffA);
;             PG8_WAIT_V(8); PG8_WAIT_L(0); PG8_BAR; PG8_MMA(1, 0, At, B0); PG8_MMA(1, 1, At, B1); PG8_BAR; PG8_SCHED;
.LBB0_129:
	s_add_u32 s18, s35, s14
	s_addc_u32 s19, s36, s15
	s_and_b64 s[20:21], s[4:5], exec
	s_cselect_b32 s70, s19, s29
	s_cselect_b32 s72, s18, s28
	s_add_u32 s20, s37, s16
	s_addc_u32 s21, s42, s17
	s_and_b64 s[30:31], s[4:5], exec
	s_cselect_b32 s73, s21, s27
	s_cselect_b32 s74, s20, s26
	s_add_u32 s75, s26, 0x100
	s_addc_u32 s76, s27, 0
	s_add_u32 s26, s28, 0x40080
	v_mov_b32_e32 v0, 0
	s_addc_u32 s27, s29, 0
	s_mov_b32 s77, -2
	ds_read_b128 v[154:157], v150
	ds_read_b128 v[158:161], v150 offset:1024
	ds_read_b128 v[162:165], v150 offset:2048
	ds_read_b128 v[166:169], v150 offset:3072
	ds_read_b128 v[170:173], v151
	ds_read_b128 v[174:177], v151 offset:1024
	ds_read_b128 v[178:181], v151 offset:2048
	ds_read_b128 v[182:185], v151 offset:3072
	s_add_u32 s28, s26, 0xfffc0080
	s_addc_u32 s29, s27, -1
	s_cmp_eq_u32 s77, 12
	s_cselect_b32 s31, s70, s29
	s_cselect_b32 s30, s72, s28
	s_cselect_b32 s29, s73, s76
	s_cselect_b32 s28, s74, s75
	v_lshl_add_u64 v[146:147], s[26:27], 0, v[140:141]
	s_add_i32 m0, s46, 0xc000
	ds_read_b128 v[186:189], v152
	ds_read_b128 v[190:193], v152 offset:1024
	ds_read_b128 v[194:197], v152 offset:2048
	ds_read_b128 v[198:201], v152 offset:3072
	ds_read_b128 v[202:205], v152 offset:4096
	ds_read_b128 v[206:209], v152 offset:5120
	ds_read_b128 v[210:213], v152 offset:6144
	ds_read_b128 v[214:217], v152 offset:7168
	global_load_lds_dwordx4 v[146:147], off
	v_lshl_add_u64 v[146:147], s[26:27], 0, v[138:139]
	s_add_i32 m0, s46, 0xe000
	s_nop 0
	global_load_lds_dwordx4 v[146:147], off
	s_waitcnt vmcnt(8) lgkmcnt(0)
	s_setprio 1
	s_barrier
	v_mfma_f32_16x16x32_bf16 v[124:127], v[154:157], v[186:189], 0
	v_mfma_f32_16x16x32_bf16 v[120:123], v[162:165], v[186:189], 0
	v_mfma_f32_16x16x32_bf16 v[116:119], v[154:157], v[194:197], 0
	v_mfma_f32_16x16x32_bf16 v[108:111], v[162:165], v[194:197], 0
	v_mfma_f32_16x16x32_bf16 v[100:103], v[154:157], v[202:205], 0
	v_mfma_f32_16x16x32_bf16 v[92:95], v[162:165], v[202:205], 0
	v_mfma_f32_16x16x32_bf16 v[84:87], v[154:157], v[210:213], 0
	v_mfma_f32_16x16x32_bf16 v[76:79], v[162:165], v[210:213], 0
	v_mfma_f32_16x16x32_bf16 v[124:127], v[158:161], v[190:193], v[124:127]
	v_mfma_f32_16x16x32_bf16 v[120:123], v[166:169], v[190:193], v[120:123]
	v_mfma_f32_16x16x32_bf16 v[116:119], v[158:161], v[198:201], v[116:119]
	v_mfma_f32_16x16x32_bf16 v[108:111], v[166:169], v[198:201], v[108:111]
	v_mfma_f32_16x16x32_bf16 v[100:103], v[158:161], v[206:209], v[100:103]
	v_mfma_f32_16x16x32_bf16 v[92:95], v[166:169], v[206:209], v[92:95]
	v_mfma_f32_16x16x32_bf16 v[84:87], v[158:161], v[214:217], v[84:87]
	v_mfma_f32_16x16x32_bf16 v[76:79], v[166:169], v[214:217], v[76:79]
	s_setprio 0
	s_setprio 1
	v_mfma_f32_16x16x32_bf16 v[112:115], v[170:173], v[186:189], 0
	v_mfma_f32_16x16x32_bf16 v[104:107], v[178:181], v[186:189], 0
	v_mfma_f32_16x16x32_bf16 v[96:99], v[170:173], v[194:197], 0
	v_mfma_f32_16x16x32_bf16 v[88:91], v[178:181], v[194:197], 0
	v_mfma_f32_16x16x32_bf16 v[80:83], v[170:173], v[202:205], 0
	v_mfma_f32_16x16x32_bf16 v[72:75], v[178:181], v[202:205], 0
	v_mfma_f32_16x16x32_bf16 v[68:71], v[170:173], v[210:213], 0
	v_mfma_f32_16x16x32_bf16 v[64:67], v[178:181], v[210:213], 0
	v_mfma_f32_16x16x32_bf16 v[112:115], v[174:177], v[190:193], v[112:115]
	v_mfma_f32_16x16x32_bf16 v[104:107], v[182:185], v[190:193], v[104:107]
	v_mfma_f32_16x16x32_bf16 v[96:99], v[174:177], v[198:201], v[96:99]
	v_mfma_f32_16x16x32_bf16 v[88:91], v[182:185], v[198:201], v[88:91]
	v_mfma_f32_16x16x32_bf16 v[80:83], v[174:177], v[206:209], v[80:83]
	v_mfma_f32_16x16x32_bf16 v[72:75], v[182:185], v[206:209], v[72:75]
	v_mfma_f32_16x16x32_bf16 v[68:71], v[174:177], v[214:217], v[68:71]
	v_mfma_f32_16x16x32_bf16 v[64:67], v[182:185], v[214:217], v[64:67]
	s_barrier
	s_setprio 0
	s_add_i32 s68, s57, s43
	v_lshl_add_u64 v[146:147], s[28:29], 0, v[130:131]
	s_mov_b32 m0, s68
	ds_read_b128 v[186:189], v152 offset:16384
	ds_read_b128 v[190:193], v152 offset:17408
	ds_read_b128 v[194:197], v152 offset:18432
	ds_read_b128 v[198:201], v152 offset:19456
	ds_read_b128 v[202:205], v152 offset:20480
	ds_read_b128 v[206:209], v152 offset:21504
	ds_read_b128 v[210:213], v152 offset:22528
	ds_read_b128 v[214:217], v152 offset:23552
	global_load_lds_dwordx4 v[146:147], off
	s_add_i32 m0, s68, 0x2000
	s_add_u32 s78, s28, 0x40000
	v_lshl_add_u64 v[218:219], s[28:29], 0, v[134:135]
	s_addc_u32 s79, s29, 0
	s_add_i32 s68, s58, s43
	global_load_lds_dwordx4 v[218:219], off
	v_lshl_add_u64 v[222:223], s[78:79], 0, v[130:131]
	s_mov_b32 m0, s68
	v_lshl_add_u64 v[224:225], s[30:31], 0, v[132:133]
	global_load_lds_dwordx4 v[222:223], off
	v_lshl_add_u64 v[222:223], s[78:79], 0, v[134:135]
	s_add_i32 m0, s68, 0x2000
	s_nop 0
	global_load_lds_dwordx4 v[222:223], off
	v_lshl_add_u64 v[222:223], s[30:31], 0, v[128:129]
	s_mov_b32 m0, s46
	s_nop 0
	global_load_lds_dwordx4 v[222:223], off
	s_mov_b32 m0, s47
	s_nop 0
	global_load_lds_dwordx4 v[224:225], off
	s_waitcnt vmcnt(8) lgkmcnt(0)
	s_setprio 1
	s_barrier
; #define PG8_STAGE(bufoff, gbase, voff) do { _Pragma("unroll") for (int _i = 0; _i < 2; ++_i) \
;         __builtin_amdgcn_global_load_lds((const unsigned*)((const char*)(gbase) + (voff)[_i]), (PG8_LAS unsigned*)(lds + (bufoff) + ldsw + _i * 8192), 16, 0, 0); } while (0)
; #define PG8_LDA(dst, b, h) do { _Pragma("unroll") for (int m = 0; m < 4; ++m) _Pragma("unroll") for (int k = 0; k < 2; ++k) dst[m][k] = *(const PG8_LAS bf16x8*)(lds + PG8_SA(b, h) + aoff + m * 2048 + k * 1024); } while (0)
; #define PG8_LDB(dst, b, h) do { _Pragma("unroll") for (int n = 0; n < 2; ++n) _Pragma("unroll") for (int k = 0; k < 2; ++k) dst[n][k] = *(const PG8_LAS bf16x8*)(lds + PG8_SB(b, h) + boff + n * 2048 + k * 1024); } while (0)
; #define PG8_MMA(ai, bj, At, Bt) do { __builtin_amdgcn_s_setprio(1); _Pragma("unroll") for (int m = 0; m < 4; ++m) _Pragma("unroll") for (int n = 0; n < 2; ++n) _Pragma("unroll") for (int k = 0; k < 2; ++k) \
;         acc[ai][bj][m][n] = __builtin_amdgcn_mfma_f32_16x16x32_bf16(Bt[n][k], At[m][k], acc[ai][bj][m][n], 0, 0, 0); __builtin_amdgcn_s_setprio(0); } while (0)
; #define PG8_WAIT_V(n) asm volatile("s_waitcnt vmcnt(" #n ")" ::: "memory")
; #define PG8_WAIT_L(n) asm volatile("s_waitcnt lgkmcnt(" #n ")" ::: "memory")
; #define PG8_BAR __builtin_amdgcn_s_barrier()
; #define PG8_SCHED __builtin_amdgcn_sched_barrier(0)
; template <class Epi, class Sched>
; __device__ __forceinline__ void gemm_phase(PG8_LAS unsigned char* lds, PG8_LAS unsigned char* xl, const Gemm g, const Sched& S, const Epi& E) {
;     ...
;             PG8_WAIT_V(8); PG8_WAIT_L(0); PG8_BAR; PG8_MMA(1, 0, At, B0); PG8_MMA(1, 1, At, B1); PG8_BAR; PG8_SCHED;
;             PG8_LDB(B0, 1, 0); PG8_LDB(B1, 1, 1); PG8_SCHED; PG8_LDA(At, 1, 0); PG8_STAGE(PG8_SA(0, 1), a2 + hsA, voffA);
;             PG8_WAIT_V(8); PG8_WAIT_L(0); PG8_BAR; PG8_MMA(0, 0, At, B0); PG8_MMA(0, 1, At, B1); PG8_BAR; PG8_SCHED;
	v_mfma_f32_16x16x32_bf16 v[60:63], v[154:157], v[186:189], 0
	v_mfma_f32_16x16x32_bf16 v[56:59], v[162:165], v[186:189], 0
	v_mfma_f32_16x16x32_bf16 v[52:55], v[154:157], v[194:197], 0
	v_mfma_f32_16x16x32_bf16 v[44:47], v[162:165], v[194:197], 0
	v_mfma_f32_16x16x32_bf16 v[36:39], v[154:157], v[202:205], 0
	v_mfma_f32_16x16x32_bf16 v[28:31], v[162:165], v[202:205], 0
	v_mfma_f32_16x16x32_bf16 v[20:23], v[154:157], v[210:213], 0
	v_mfma_f32_16x16x32_bf16 v[12:15], v[162:165], v[210:213], 0
	v_mfma_f32_16x16x32_bf16 v[60:63], v[158:161], v[190:193], v[60:63]
	v_mfma_f32_16x16x32_bf16 v[56:59], v[166:169], v[190:193], v[56:59]
	v_mfma_f32_16x16x32_bf16 v[52:55], v[158:161], v[198:201], v[52:55]
	v_mfma_f32_16x16x32_bf16 v[44:47], v[166:169], v[198:201], v[44:47]
	v_mfma_f32_16x16x32_bf16 v[36:39], v[158:161], v[206:209], v[36:39]
	v_mfma_f32_16x16x32_bf16 v[28:31], v[166:169], v[206:209], v[28:31]
	v_mfma_f32_16x16x32_bf16 v[20:23], v[158:161], v[214:217], v[20:23]
	v_mfma_f32_16x16x32_bf16 v[12:15], v[166:169], v[214:217], v[12:15]
	s_setprio 0
	s_setprio 1
	v_mfma_f32_16x16x32_bf16 v[48:51], v[170:173], v[186:189], 0
	v_mfma_f32_16x16x32_bf16 v[40:43], v[178:181], v[186:189], 0
	v_mfma_f32_16x16x32_bf16 v[32:35], v[170:173], v[194:197], 0
	v_mfma_f32_16x16x32_bf16 v[24:27], v[178:181], v[194:197], 0
	v_mfma_f32_16x16x32_bf16 v[16:19], v[170:173], v[202:205], 0
	v_mfma_f32_16x16x32_bf16 v[8:11], v[178:181], v[202:205], 0
	v_mfma_f32_16x16x32_bf16 v[4:7], v[170:173], v[210:213], 0
	v_mfma_f32_16x16x32_bf16 v[0:3], v[178:181], v[210:213], 0
	v_mfma_f32_16x16x32_bf16 v[48:51], v[174:177], v[190:193], v[48:51]
	v_mfma_f32_16x16x32_bf16 v[40:43], v[182:185], v[190:193], v[40:43]
	v_mfma_f32_16x16x32_bf16 v[32:35], v[174:177], v[198:201], v[32:35]
	v_mfma_f32_16x16x32_bf16 v[24:27], v[182:185], v[198:201], v[24:27]
	v_mfma_f32_16x16x32_bf16 v[16:19], v[174:177], v[206:209], v[16:19]
	v_mfma_f32_16x16x32_bf16 v[8:11], v[182:185], v[206:209], v[8:11]
	v_mfma_f32_16x16x32_bf16 v[4:7], v[174:177], v[214:217], v[4:7]
	v_mfma_f32_16x16x32_bf16 v[0:3], v[182:185], v[214:217], v[0:3]
	s_barrier
	s_setprio 0
	s_add_i32 s68, 0, 0x18000
	v_add_u32_e32 v153, s68, v149
	s_add_i32 s78, 0, 0x1c000
	ds_read_b128 v[154:157], v153
	ds_read_b128 v[158:161], v153 offset:1024
	ds_read_b128 v[162:165], v153 offset:2048
	ds_read_b128 v[166:169], v153 offset:3072
	v_add_u32_e32 v153, s78, v149
	ds_read_b128 v[170:173], v153
	ds_read_b128 v[174:177], v153 offset:1024
	ds_read_b128 v[178:181], v153 offset:2048
	ds_read_b128 v[182:185], v153 offset:3072
	s_add_u32 s30, s30, 0x40000
	s_addc_u32 s31, s31, 0
	s_mov_b32 m0, s52
	v_lshl_add_u64 v[226:227], s[30:31], 0, v[128:129]
	ds_read_b128 v[186:189], v152 offset:32768
	ds_read_b128 v[190:193], v152 offset:33792
	ds_read_b128 v[194:197], v152 offset:34816
	ds_read_b128 v[198:201], v152 offset:35840
	ds_read_b128 v[202:205], v152 offset:36864
	ds_read_b128 v[206:209], v152 offset:37888
	ds_read_b128 v[210:213], v152 offset:38912
	ds_read_b128 v[214:217], v152 offset:39936
	global_load_lds_dwordx4 v[226:227], off
	v_lshl_add_u64 v[226:227], s[30:31], 0, v[132:133]
	s_mov_b32 m0, s53
	s_nop 0
	global_load_lds_dwordx4 v[226:227], off
	s_waitcnt vmcnt(8) lgkmcnt(0)
	s_setprio 1
	s_barrier
	v_mfma_f32_16x16x32_bf16 v[124:127], v[154:157], v[186:189], v[124:127]
	v_mfma_f32_16x16x32_bf16 v[120:123], v[162:165], v[186:189], v[120:123]
	v_mfma_f32_16x16x32_bf16 v[116:119], v[154:157], v[194:197], v[116:119]
	v_mfma_f32_16x16x32_bf16 v[108:111], v[162:165], v[194:197], v[108:111]
	v_mfma_f32_16x16x32_bf16 v[100:103], v[154:157], v[202:205], v[100:103]
	v_mfma_f32_16x16x32_bf16 v[92:95], v[162:165], v[202:205], v[92:95]
	v_mfma_f32_16x16x32_bf16 v[84:87], v[154:157], v[210:213], v[84:87]
	v_mfma_f32_16x16x32_bf16 v[76:79], v[162:165], v[210:213], v[76:79]
	v_mfma_f32_16x16x32_bf16 v[124:127], v[158:161], v[190:193], v[124:127]
	v_mfma_f32_16x16x32_bf16 v[120:123], v[166:169], v[190:193], v[120:123]
	v_mfma_f32_16x16x32_bf16 v[116:119], v[158:161], v[198:201], v[116:119]
	v_mfma_f32_16x16x32_bf16 v[108:111], v[166:169], v[198:201], v[108:111]
	v_mfma_f32_16x16x32_bf16 v[100:103], v[158:161], v[206:209], v[100:103]
	v_mfma_f32_16x16x32_bf16 v[92:95], v[166:169], v[206:209], v[92:95]
	v_mfma_f32_16x16x32_bf16 v[84:87], v[158:161], v[214:217], v[84:87]
	v_mfma_f32_16x16x32_bf16 v[76:79], v[166:169], v[214:217], v[76:79]
	s_setprio 0
	s_setprio 1
	v_mfma_f32_16x16x32_bf16 v[112:115], v[170:173], v[186:189], v[112:115]
	v_mfma_f32_16x16x32_bf16 v[104:107], v[178:181], v[186:189], v[104:107]
	v_mfma_f32_16x16x32_bf16 v[96:99], v[170:173], v[194:197], v[96:99]
	v_mfma_f32_16x16x32_bf16 v[88:91], v[178:181], v[194:197], v[88:91]
	v_mfma_f32_16x16x32_bf16 v[80:83], v[170:173], v[202:205], v[80:83]
	v_mfma_f32_16x16x32_bf16 v[72:75], v[178:181], v[202:205], v[72:75]
	v_mfma_f32_16x16x32_bf16 v[68:71], v[170:173], v[210:213], v[68:71]
	v_mfma_f32_16x16x32_bf16 v[64:67], v[178:181], v[210:213], v[64:67]
	v_mfma_f32_16x16x32_bf16 v[112:115], v[174:177], v[190:193], v[112:115]
	v_mfma_f32_16x16x32_bf16 v[104:107], v[182:185], v[190:193], v[104:107]
	v_mfma_f32_16x16x32_bf16 v[96:99], v[174:177], v[198:201], v[96:99]
	v_mfma_f32_16x16x32_bf16 v[88:91], v[182:185], v[198:201], v[88:91]
	v_mfma_f32_16x16x32_bf16 v[80:83], v[174:177], v[206:209], v[80:83]
	v_mfma_f32_16x16x32_bf16 v[72:75], v[182:185], v[206:209], v[72:75]
	v_mfma_f32_16x16x32_bf16 v[68:71], v[174:177], v[214:217], v[68:71]
	v_mfma_f32_16x16x32_bf16 v[64:67], v[182:185], v[214:217], v[64:67]
	s_barrier
; #define PG8_STAGE(bufoff, gbase, voff) do { _Pragma("unroll") for (int _i = 0; _i < 2; ++_i) \
;         __builtin_amdgcn_global_load_lds((const unsigned*)((const char*)(gbase) + (voff)[_i]), (PG8_LAS unsigned*)(lds + (bufoff) + ldsw + _i * 8192), 16, 0, 0); } while (0)
; #define PG8_LDA(dst, b, h) do { _Pragma("unroll") for (int m = 0; m < 4; ++m) _Pragma("unroll") for (int k = 0; k < 2; ++k) dst[m][k] = *(const PG8_LAS bf16x8*)(lds + PG8_SA(b, h) + aoff + m * 2048 + k * 1024); } while (0)
; #define PG8_LDB(dst, b, h) do { _Pragma("unroll") for (int n = 0; n < 2; ++n) _Pragma("unroll") for (int k = 0; k < 2; ++k) dst[n][k] = *(const PG8_LAS bf16x8*)(lds + PG8_SB(b, h) + boff + n * 2048 + k * 1024); } while (0)
; #define PG8_MMA(ai, bj, At, Bt) do { __builtin_amdgcn_s_setprio(1); _Pragma("unroll") for (int m = 0; m < 4; ++m) _Pragma("unroll") for (int n = 0; n < 2; ++n) _Pragma("unroll") for (int k = 0; k < 2; ++k) \
;         acc[ai][bj][m][n] = __builtin_amdgcn_mfma_f32_16x16x32_bf16(Bt[n][k], At[m][k], acc[ai][bj][m][n], 0, 0, 0); __builtin_amdgcn_s_setprio(0); } while (0)
; #define PG8_WAIT_V(n) asm volatile("s_waitcnt vmcnt(" #n ")" ::: "memory")
; #define PG8_WAIT_L(n) asm volatile("s_waitcnt lgkmcnt(" #n ")" ::: "memory")
; #define PG8_BAR __builtin_amdgcn_s_barrier()
; #define PG8_SCHED __builtin_amdgcn_sched_barrier(0)
; template <class Epi, class Sched>
; __device__ __forceinline__ void gemm_phase(PG8_LAS unsigned char* lds, PG8_LAS unsigned char* xl, const Gemm g, const Sched& S, const Epi& E) {
;     ...
;             PG8_LDB(B0, 0, 0); PG8_LDB(B1, 0, 1); PG8_SCHED; PG8_LDA(At, 0, 0); PG8_STAGE(PG8_SA(1, 1), a1 + hsA, voffA);
;             PG8_WAIT_V(8); PG8_WAIT_L(0); PG8_BAR; PG8_MMA(0, 0, At, B0); PG8_MMA(0, 1, At, B1); PG8_BAR; PG8_SCHED;
;     ...
;             PG8_LDA(At, 1, 1); PG8_STAGE(PG8_SB(1, 0), b3, voffB); PG8_STAGE(PG8_SB(1, 1), b3 + hsB, voffB); PG8_STAGE(PG8_SA(1, 0), a3, voffA);
;             PG8_WAIT_V(8); PG8_WAIT_L(0); PG8_BAR; PG8_MMA(1, 0, At, B0); PG8_MMA(1, 1, At, B1); PG8_BAR; PG8_SCHED;
	s_setprio 0
	s_add_i32 s30, s68, s43
	v_lshl_add_u64 v[146:147], v[146:147], 0, s[10:11]
	s_mov_b32 m0, s30
	ds_read_b128 v[186:189], v152 offset:49152
	ds_read_b128 v[190:193], v152 offset:50176
	ds_read_b128 v[194:197], v152 offset:51200
	ds_read_b128 v[198:201], v152 offset:52224
	ds_read_b128 v[202:205], v152 offset:53248
	ds_read_b128 v[206:209], v152 offset:54272
	ds_read_b128 v[210:213], v152 offset:55296
	ds_read_b128 v[214:217], v152 offset:56320
	global_load_lds_dwordx4 v[146:147], off
	s_add_i32 m0, s30, 0x2000
	s_add_u32 s28, s28, 0x40080
	v_lshl_add_u64 v[146:147], v[218:219], 0, s[10:11]
	s_addc_u32 s29, s29, 0
	s_add_i32 s30, s78, s43
	global_load_lds_dwordx4 v[146:147], off
	v_lshl_add_u64 v[146:147], s[28:29], 0, v[130:131]
	s_mov_b32 m0, s30
	s_nop 0
	global_load_lds_dwordx4 v[146:147], off
	v_lshl_add_u64 v[146:147], s[28:29], 0, v[134:135]
	s_add_i32 m0, s30, 0x2000
	s_nop 0
	global_load_lds_dwordx4 v[146:147], off
	v_lshl_add_u64 v[146:147], v[222:223], 0, s[10:11]
	s_mov_b32 m0, s55
	s_nop 0
	global_load_lds_dwordx4 v[146:147], off
	v_lshl_add_u64 v[146:147], v[224:225], 0, s[10:11]
	s_mov_b32 m0, s56
	s_nop 0
	global_load_lds_dwordx4 v[146:147], off
	s_waitcnt vmcnt(8) lgkmcnt(0)
	s_setprio 1
	s_barrier
	v_mfma_f32_16x16x32_bf16 v[60:63], v[154:157], v[186:189], v[60:63]
	v_mfma_f32_16x16x32_bf16 v[56:59], v[162:165], v[186:189], v[56:59]
	v_mfma_f32_16x16x32_bf16 v[52:55], v[154:157], v[194:197], v[52:55]
	v_mfma_f32_16x16x32_bf16 v[44:47], v[162:165], v[194:197], v[44:47]
	v_mfma_f32_16x16x32_bf16 v[36:39], v[154:157], v[202:205], v[36:39]
	v_mfma_f32_16x16x32_bf16 v[28:31], v[162:165], v[202:205], v[28:31]
	v_mfma_f32_16x16x32_bf16 v[20:23], v[154:157], v[210:213], v[20:23]
	v_mfma_f32_16x16x32_bf16 v[12:15], v[162:165], v[210:213], v[12:15]
	v_mfma_f32_16x16x32_bf16 v[60:63], v[158:161], v[190:193], v[60:63]
	v_mfma_f32_16x16x32_bf16 v[56:59], v[166:169], v[190:193], v[56:59]
	v_mfma_f32_16x16x32_bf16 v[52:55], v[158:161], v[198:201], v[52:55]
	v_mfma_f32_16x16x32_bf16 v[44:47], v[166:169], v[198:201], v[44:47]
	v_mfma_f32_16x16x32_bf16 v[36:39], v[158:161], v[206:209], v[36:39]
	v_mfma_f32_16x16x32_bf16 v[28:31], v[166:169], v[206:209], v[28:31]
	v_mfma_f32_16x16x32_bf16 v[20:23], v[158:161], v[214:217], v[20:23]
	v_mfma_f32_16x16x32_bf16 v[12:15], v[166:169], v[214:217], v[12:15]
	s_setprio 0
	s_setprio 1
	v_mfma_f32_16x16x32_bf16 v[48:51], v[170:173], v[186:189], v[48:51]
	s_add_i32 s77, s77, 2
	v_mfma_f32_16x16x32_bf16 v[40:43], v[178:181], v[186:189], v[40:43]
	s_add_u32 s75, s75, 0x100
	v_mfma_f32_16x16x32_bf16 v[32:35], v[170:173], v[194:197], v[32:35]
	s_addc_u32 s76, s76, 0
	v_mfma_f32_16x16x32_bf16 v[24:27], v[178:181], v[194:197], v[24:27]
	s_add_u32 s26, s26, 0x100
	v_mfma_f32_16x16x32_bf16 v[16:19], v[170:173], v[202:205], v[16:19]
	s_addc_u32 s27, s27, 0
	v_mfma_f32_16x16x32_bf16 v[8:11], v[178:181], v[202:205], v[8:11]
	s_cmp_gt_u32 s77, 13
	v_mfma_f32_16x16x32_bf16 v[4:7], v[170:173], v[210:213], v[4:7]
	v_mfma_f32_16x16x32_bf16 v[0:3], v[178:181], v[210:213], v[0:3]
	v_mfma_f32_16x16x32_bf16 v[48:51], v[174:177], v[190:193], v[48:51]
	v_mfma_f32_16x16x32_bf16 v[40:43], v[182:185], v[190:193], v[40:43]
	v_mfma_f32_16x16x32_bf16 v[32:35], v[174:177], v[198:201], v[32:35]
	v_mfma_f32_16x16x32_bf16 v[24:27], v[182:185], v[198:201], v[24:27]
	v_mfma_f32_16x16x32_bf16 v[16:19], v[174:177], v[206:209], v[16:19]
	v_mfma_f32_16x16x32_bf16 v[8:11], v[182:185], v[206:209], v[8:11]
	v_mfma_f32_16x16x32_bf16 v[4:7], v[174:177], v[214:217], v[4:7]
	v_mfma_f32_16x16x32_bf16 v[0:3], v[182:185], v[214:217], v[0:3]
	s_barrier
	s_setprio 0
	s_cbranch_scc1 .Lpeel_after_P11
.LBB0_130:
	ds_read_b128 v[154:157], v150
	ds_read_b128 v[158:161], v150 offset:1024
	ds_read_b128 v[162:165], v150 offset:2048
	ds_read_b128 v[166:169], v150 offset:3072
	ds_read_b128 v[170:173], v151
	ds_read_b128 v[174:177], v151 offset:1024
	ds_read_b128 v[178:181], v151 offset:2048
	ds_read_b128 v[182:185], v151 offset:3072
	s_add_u32 s28, s26, 0xfffc0080
	s_addc_u32 s29, s27, -1
	s_cmp_eq_u32 s77, 12
	s_cselect_b32 s31, s70, s29
	s_cselect_b32 s30, s72, s28
	s_cselect_b32 s29, s73, s76
	s_cselect_b32 s28, s74, s75
	v_lshl_add_u64 v[146:147], s[26:27], 0, v[140:141]
	s_add_i32 m0, s46, 0xc000
	ds_read_b128 v[186:189], v152
	ds_read_b128 v[190:193], v152 offset:1024
	ds_read_b128 v[194:197], v152 offset:2048
	ds_read_b128 v[198:201], v152 offset:3072
	ds_read_b128 v[202:205], v152 offset:4096
	ds_read_b128 v[206:209], v152 offset:5120
	ds_read_b128 v[210:213], v152 offset:6144
	ds_read_b128 v[214:217], v152 offset:7168
	global_load_lds_dwordx4 v[146:147], off
	v_lshl_add_u64 v[146:147], s[26:27], 0, v[138:139]
	s_add_i32 m0, s46, 0xe000
	s_nop 0
	global_load_lds_dwordx4 v[146:147], off
	s_waitcnt vmcnt(8) lgkmcnt(0)
	s_setprio 1
	s_barrier
; #define PG8_STAGE(bufoff, gbase, voff) do { _Pragma("unroll") for (int _i = 0; _i < 2; ++_i) \
;         __builtin_amdgcn_global_load_lds((const unsigned*)((const char*)(gbase) + (voff)[_i]), (PG8_LAS unsigned*)(lds + (bufoff) + ldsw + _i * 8192), 16, 0, 0); } while (0)
; #define PG8_LDA(dst, b, h) do { _Pragma("unroll") for (int m = 0; m < 4; ++m) _Pragma("unroll") for (int k = 0; k < 2; ++k) dst[m][k] = *(const PG8_LAS bf16x8*)(lds + PG8_SA(b, h) + aoff + m * 2048 + k * 1024); } while (0)
; #define PG8_LDB(dst, b, h) do { _Pragma("unroll") for (int n = 0; n < 2; ++n) _Pragma("unroll") for (int k = 0; k < 2; ++k) dst[n][k] = *(const PG8_LAS bf16x8*)(lds + PG8_SB(b, h) + boff + n * 2048 + k * 1024); } while (0)
; #define PG8_MMA(ai, bj, At, Bt) do { __builtin_amdgcn_s_setprio(1); _Pragma("unroll") for (int m = 0; m < 4; ++m) _Pragma("unroll") for (int n = 0; n < 2; ++n) _Pragma("unroll") for (int k = 0; k < 2; ++k) \
;         acc[ai][bj][m][n] = __builtin_amdgcn_mfma_f32_16x16x32_bf16(Bt[n][k], At[m][k], acc[ai][bj][m][n], 0, 0, 0); __builtin_amdgcn_s_setprio(0); } while (0)
; #define PG8_WAIT_V(n) asm volatile("s_waitcnt vmcnt(" #n ")" ::: "memory")
; #define PG8_WAIT_L(n) asm volatile("s_waitcnt lgkmcnt(" #n ")" ::: "memory")
; #define PG8_BAR __builtin_amdgcn_s_barrier()
; #define PG8_SCHED __builtin_amdgcn_sched_barrier(0)
; template <class Epi, class Sched>
; __device__ __forceinline__ void gemm_phase(PG8_LAS unsigned char* lds, PG8_LAS unsigned char* xl, const Gemm g, const Sched& S, const Epi& E) {
;     ...
;             PG8_LDB(B0, 0, 0); PG8_LDB(B1, 0, 1); PG8_SCHED; PG8_LDA(At, 0, 0); PG8_STAGE(PG8_SA(1, 1), a1 + hsA, voffA);
;             PG8_WAIT_V(8); PG8_WAIT_L(0); PG8_BAR; PG8_MMA(0, 0, At, B0); PG8_MMA(0, 1, At, B1); PG8_BAR; PG8_SCHED;
;             PG8_LDA(At, 0, 1); PG8_STAGE(PG8_SB(0, 0), b2, voffB); PG8_STAGE(PG8_SB(0, 1), b2 + hsB, voffB); PG8_STAGE(PG8_SA(0, 0), a2, voffA);
;             PG8_WAIT_V(8); PG8_WAIT_L(0); PG8_BAR; PG8_MMA(1, 0, At, B0); PG8_MMA(1, 1, At, B1); PG8_BAR; PG8_SCHED;
	v_mfma_f32_16x16x32_bf16 v[124:127], v[154:157], v[186:189], v[124:127]
	v_mfma_f32_16x16x32_bf16 v[120:123], v[162:165], v[186:189], v[120:123]
	v_mfma_f32_16x16x32_bf16 v[116:119], v[154:157], v[194:197], v[116:119]
	v_mfma_f32_16x16x32_bf16 v[108:111], v[162:165], v[194:197], v[108:111]
	v_mfma_f32_16x16x32_bf16 v[100:103], v[154:157], v[202:205], v[100:103]
	v_mfma_f32_16x16x32_bf16 v[92:95], v[162:165], v[202:205], v[92:95]
	v_mfma_f32_16x16x32_bf16 v[84:87], v[154:157], v[210:213], v[84:87]
	v_mfma_f32_16x16x32_bf16 v[76:79], v[162:165], v[210:213], v[76:79]
	v_mfma_f32_16x16x32_bf16 v[124:127], v[158:161], v[190:193], v[124:127]
	v_mfma_f32_16x16x32_bf16 v[120:123], v[166:169], v[190:193], v[120:123]
	v_mfma_f32_16x16x32_bf16 v[116:119], v[158:161], v[198:201], v[116:119]
	v_mfma_f32_16x16x32_bf16 v[108:111], v[166:169], v[198:201], v[108:111]
	v_mfma_f32_16x16x32_bf16 v[100:103], v[158:161], v[206:209], v[100:103]
	v_mfma_f32_16x16x32_bf16 v[92:95], v[166:169], v[206:209], v[92:95]
	v_mfma_f32_16x16x32_bf16 v[84:87], v[158:161], v[214:217], v[84:87]
	v_mfma_f32_16x16x32_bf16 v[76:79], v[166:169], v[214:217], v[76:79]
	s_setprio 0
	s_setprio 1
	v_mfma_f32_16x16x32_bf16 v[112:115], v[170:173], v[186:189], v[112:115]
	v_mfma_f32_16x16x32_bf16 v[104:107], v[178:181], v[186:189], v[104:107]
	v_mfma_f32_16x16x32_bf16 v[96:99], v[170:173], v[194:197], v[96:99]
	v_mfma_f32_16x16x32_bf16 v[88:91], v[178:181], v[194:197], v[88:91]
	v_mfma_f32_16x16x32_bf16 v[80:83], v[170:173], v[202:205], v[80:83]
	v_mfma_f32_16x16x32_bf16 v[72:75], v[178:181], v[202:205], v[72:75]
	v_mfma_f32_16x16x32_bf16 v[68:71], v[170:173], v[210:213], v[68:71]
	v_mfma_f32_16x16x32_bf16 v[64:67], v[178:181], v[210:213], v[64:67]
	v_mfma_f32_16x16x32_bf16 v[112:115], v[174:177], v[190:193], v[112:115]
	v_mfma_f32_16x16x32_bf16 v[104:107], v[182:185], v[190:193], v[104:107]
	v_mfma_f32_16x16x32_bf16 v[96:99], v[174:177], v[198:201], v[96:99]
	v_mfma_f32_16x16x32_bf16 v[88:91], v[182:185], v[198:201], v[88:91]
	v_mfma_f32_16x16x32_bf16 v[80:83], v[174:177], v[206:209], v[80:83]
	v_mfma_f32_16x16x32_bf16 v[72:75], v[182:185], v[206:209], v[72:75]
	v_mfma_f32_16x16x32_bf16 v[68:71], v[174:177], v[214:217], v[68:71]
	v_mfma_f32_16x16x32_bf16 v[64:67], v[182:185], v[214:217], v[64:67]
	s_barrier
	s_setprio 0
	s_add_i32 s68, s57, s43
	v_lshl_add_u64 v[146:147], s[28:29], 0, v[130:131]
	s_mov_b32 m0, s68
	ds_read_b128 v[186:189], v152 offset:16384
	ds_read_b128 v[190:193], v152 offset:17408
	ds_read_b128 v[194:197], v152 offset:18432
	ds_read_b128 v[198:201], v152 offset:19456
	ds_read_b128 v[202:205], v152 offset:20480
	ds_read_b128 v[206:209], v152 offset:21504
	ds_read_b128 v[210:213], v152 offset:22528
	ds_read_b128 v[214:217], v152 offset:23552
	global_load_lds_dwordx4 v[146:147], off
	s_add_i32 m0, s68, 0x2000
	s_add_u32 s78, s28, 0x40000
	v_lshl_add_u64 v[218:219], s[28:29], 0, v[134:135]
	s_addc_u32 s79, s29, 0
	s_add_i32 s68, s58, s43
	global_load_lds_dwordx4 v[218:219], off
	v_lshl_add_u64 v[222:223], s[78:79], 0, v[130:131]
	s_mov_b32 m0, s68
	v_lshl_add_u64 v[224:225], s[30:31], 0, v[132:133]
	global_load_lds_dwordx4 v[222:223], off
	v_lshl_add_u64 v[222:223], s[78:79], 0, v[134:135]
	s_add_i32 m0, s68, 0x2000
	s_nop 0
	global_load_lds_dwordx4 v[222:223], off
	v_lshl_add_u64 v[222:223], s[30:31], 0, v[128:129]
	s_mov_b32 m0, s46
	s_nop 0
	global_load_lds_dwordx4 v[222:223], off
	s_mov_b32 m0, s47
	s_nop 0
	global_load_lds_dwordx4 v[224:225], off
	s_waitcnt vmcnt(8) lgkmcnt(0)
	s_setprio 1
	s_barrier
	v_mfma_f32_16x16x32_bf16 v[60:63], v[154:157], v[186:189], v[60:63]
	v_mfma_f32_16x16x32_bf16 v[56:59], v[162:165], v[186:189], v[56:59]
	v_mfma_f32_16x16x32_bf16 v[52:55], v[154:157], v[194:197], v[52:55]
	v_mfma_f32_16x16x32_bf16 v[44:47], v[162:165], v[194:197], v[44:47]
	v_mfma_f32_16x16x32_bf16 v[36:39], v[154:157], v[202:205], v[36:39]
	v_mfma_f32_16x16x32_bf16 v[28:31], v[162:165], v[202:205], v[28:31]
	v_mfma_f32_16x16x32_bf16 v[20:23], v[154:157], v[210:213], v[20:23]
	v_mfma_f32_16x16x32_bf16 v[12:15], v[162:165], v[210:213], v[12:15]
	v_mfma_f32_16x16x32_bf16 v[60:63], v[158:161], v[190:193], v[60:63]
	v_mfma_f32_16x16x32_bf16 v[56:59], v[166:169], v[190:193], v[56:59]
	v_mfma_f32_16x16x32_bf16 v[52:55], v[158:161], v[198:201], v[52:55]
	v_mfma_f32_16x16x32_bf16 v[44:47], v[166:169], v[198:201], v[44:47]
	v_mfma_f32_16x16x32_bf16 v[36:39], v[158:161], v[206:209], v[36:39]
	v_mfma_f32_16x16x32_bf16 v[28:31], v[166:169], v[206:209], v[28:31]
	v_mfma_f32_16x16x32_bf16 v[20:23], v[158:161], v[214:217], v[20:23]
	v_mfma_f32_16x16x32_bf16 v[12:15], v[166:169], v[214:217], v[12:15]
	s_setprio 0
	s_setprio 1
	v_mfma_f32_16x16x32_bf16 v[48:51], v[170:173], v[186:189], v[48:51]
	v_mfma_f32_16x16x32_bf16 v[40:43], v[178:181], v[186:189], v[40:43]
	v_mfma_f32_16x16x32_bf16 v[32:35], v[170:173], v[194:197], v[32:35]
	v_mfma_f32_16x16x32_bf16 v[24:27], v[178:181], v[194:197], v[24:27]
	v_mfma_f32_16x16x32_bf16 v[16:19], v[170:173], v[202:205], v[16:19]
	v_mfma_f32_16x16x32_bf16 v[8:11], v[178:181], v[202:205], v[8:11]
	v_mfma_f32_16x16x32_bf16 v[4:7], v[170:173], v[210:213], v[4:7]
	v_mfma_f32_16x16x32_bf16 v[0:3], v[178:181], v[210:213], v[0:3]
	v_mfma_f32_16x16x32_bf16 v[48:51], v[174:177], v[190:193], v[48:51]
	v_mfma_f32_16x16x32_bf16 v[40:43], v[182:185], v[190:193], v[40:43]
	v_mfma_f32_16x16x32_bf16 v[32:35], v[174:177], v[198:201], v[32:35]
	v_mfma_f32_16x16x32_bf16 v[24:27], v[182:185], v[198:201], v[24:27]
	v_mfma_f32_16x16x32_bf16 v[16:19], v[174:177], v[206:209], v[16:19]
	v_mfma_f32_16x16x32_bf16 v[8:11], v[182:185], v[206:209], v[8:11]
	v_mfma_f32_16x16x32_bf16 v[4:7], v[174:177], v[214:217], v[4:7]
	v_mfma_f32_16x16x32_bf16 v[0:3], v[182:185], v[214:217], v[0:3]
	s_barrier
; #define PG8_STAGE(bufoff, gbase, voff) do { _Pragma("unroll") for (int _i = 0; _i < 2; ++_i) \
;         __builtin_amdgcn_global_load_lds((const unsigned*)((const char*)(gbase) + (voff)[_i]), (PG8_LAS unsigned*)(lds + (bufoff) + ldsw + _i * 8192), 16, 0, 0); } while (0)
; #define PG8_LDA(dst, b, h) do { _Pragma("unroll") for (int m = 0; m < 4; ++m) _Pragma("unroll") for (int k = 0; k < 2; ++k) dst[m][k] = *(const PG8_LAS bf16x8*)(lds + PG8_SA(b, h) + aoff + m * 2048 + k * 1024); } while (0)
; #define PG8_LDB(dst, b, h) do { _Pragma("unroll") for (int n = 0; n < 2; ++n) _Pragma("unroll") for (int k = 0; k < 2; ++k) dst[n][k] = *(const PG8_LAS bf16x8*)(lds + PG8_SB(b, h) + boff + n * 2048 + k * 1024); } while (0)
; #define PG8_MMA(ai, bj, At, Bt) do { __builtin_amdgcn_s_setprio(1); _Pragma("unroll") for (int m = 0; m < 4; ++m) _Pragma("unroll") for (int n = 0; n < 2; ++n) _Pragma("unroll") for (int k = 0; k < 2; ++k) \
;         acc[ai][bj][m][n] = __builtin_amdgcn_mfma_f32_16x16x32_bf16(Bt[n][k], At[m][k], acc[ai][bj][m][n], 0, 0, 0); __builtin_amdgcn_s_setprio(0); } while (0)
; #define PG8_WAIT_V(n) asm volatile("s_waitcnt vmcnt(" #n ")" ::: "memory")
; #define PG8_WAIT_L(n) asm volatile("s_waitcnt lgkmcnt(" #n ")" ::: "memory")
; #define PG8_BAR __builtin_amdgcn_s_barrier()
; #define PG8_SCHED __builtin_amdgcn_sched_barrier(0)
; template <class Epi, class Sched>
; __device__ __forceinline__ void gemm_phase(PG8_LAS unsigned char* lds, PG8_LAS unsigned char* xl, const Gemm g, const Sched& S, const Epi& E) {
;     ...
;             PG8_LDB(B0, 1, 0); PG8_LDB(B1, 1, 1); PG8_SCHED; PG8_LDA(At, 1, 0); PG8_STAGE(PG8_SA(0, 1), a2 + hsA, voffA);
;             PG8_WAIT_V(8); PG8_WAIT_L(0); PG8_BAR; PG8_MMA(0, 0, At, B0); PG8_MMA(0, 1, At, B1); PG8_BAR; PG8_SCHED;
	s_setprio 0
	s_add_i32 s68, 0, 0x18000
	v_add_u32_e32 v153, s68, v149
	s_add_i32 s78, 0, 0x1c000
	ds_read_b128 v[154:157], v153
	ds_read_b128 v[158:161], v153 offset:1024
	ds_read_b128 v[162:165], v153 offset:2048
	ds_read_b128 v[166:169], v153 offset:3072
	v_add_u32_e32 v153, s78, v149
	ds_read_b128 v[170:173], v153
	ds_read_b128 v[174:177], v153 offset:1024
	ds_read_b128 v[178:181], v153 offset:2048
	ds_read_b128 v[182:185], v153 offset:3072
	s_add_u32 s30, s30, 0x40000
	s_addc_u32 s31, s31, 0
	s_mov_b32 m0, s52
	v_lshl_add_u64 v[226:227], s[30:31], 0, v[128:129]
	ds_read_b128 v[186:189], v152 offset:32768
	ds_read_b128 v[190:193], v152 offset:33792
	ds_read_b128 v[194:197], v152 offset:34816
	ds_read_b128 v[198:201], v152 offset:35840
	ds_read_b128 v[202:205], v152 offset:36864
	ds_read_b128 v[206:209], v152 offset:37888
	ds_read_b128 v[210:213], v152 offset:38912
	ds_read_b128 v[214:217], v152 offset:39936
	global_load_lds_dwordx4 v[226:227], off
	v_lshl_add_u64 v[226:227], s[30:31], 0, v[132:133]
	s_mov_b32 m0, s53
	s_nop 0
	global_load_lds_dwordx4 v[226:227], off
	s_waitcnt vmcnt(8) lgkmcnt(0)
	s_setprio 1
	s_barrier
	v_mfma_f32_16x16x32_bf16 v[124:127], v[154:157], v[186:189], v[124:127]
	v_mfma_f32_16x16x32_bf16 v[120:123], v[162:165], v[186:189], v[120:123]
	v_mfma_f32_16x16x32_bf16 v[116:119], v[154:157], v[194:197], v[116:119]
	v_mfma_f32_16x16x32_bf16 v[108:111], v[162:165], v[194:197], v[108:111]
	v_mfma_f32_16x16x32_bf16 v[100:103], v[154:157], v[202:205], v[100:103]
	v_mfma_f32_16x16x32_bf16 v[92:95], v[162:165], v[202:205], v[92:95]
	v_mfma_f32_16x16x32_bf16 v[84:87], v[154:157], v[210:213], v[84:87]
	v_mfma_f32_16x16x32_bf16 v[76:79], v[162:165], v[210:213], v[76:79]
	v_mfma_f32_16x16x32_bf16 v[124:127], v[158:161], v[190:193], v[124:127]
	v_mfma_f32_16x16x32_bf16 v[120:123], v[166:169], v[190:193], v[120:123]
	v_mfma_f32_16x16x32_bf16 v[116:119], v[158:161], v[198:201], v[116:119]
	v_mfma_f32_16x16x32_bf16 v[108:111], v[166:169], v[198:201], v[108:111]
	v_mfma_f32_16x16x32_bf16 v[100:103], v[158:161], v[206:209], v[100:103]
	v_mfma_f32_16x16x32_bf16 v[92:95], v[166:169], v[206:209], v[92:95]
	v_mfma_f32_16x16x32_bf16 v[84:87], v[158:161], v[214:217], v[84:87]
	v_mfma_f32_16x16x32_bf16 v[76:79], v[166:169], v[214:217], v[76:79]
	s_setprio 0
	s_setprio 1
	v_mfma_f32_16x16x32_bf16 v[112:115], v[170:173], v[186:189], v[112:115]
	v_mfma_f32_16x16x32_bf16 v[104:107], v[178:181], v[186:189], v[104:107]
	v_mfma_f32_16x16x32_bf16 v[96:99], v[170:173], v[194:197], v[96:99]
	v_mfma_f32_16x16x32_bf16 v[88:91], v[178:181], v[194:197], v[88:91]
	v_mfma_f32_16x16x32_bf16 v[80:83], v[170:173], v[202:205], v[80:83]
	v_mfma_f32_16x16x32_bf16 v[72:75], v[178:181], v[202:205], v[72:75]
	v_mfma_f32_16x16x32_bf16 v[68:71], v[170:173], v[210:213], v[68:71]
	v_mfma_f32_16x16x32_bf16 v[64:67], v[178:181], v[210:213], v[64:67]
	v_mfma_f32_16x16x32_bf16 v[112:115], v[174:177], v[190:193], v[112:115]
	v_mfma_f32_16x16x32_bf16 v[104:107], v[182:185], v[190:193], v[104:107]
	v_mfma_f32_16x16x32_bf16 v[96:99], v[174:177], v[198:201], v[96:99]
	v_mfma_f32_16x16x32_bf16 v[88:91], v[182:185], v[198:201], v[88:91]
	v_mfma_f32_16x16x32_bf16 v[80:83], v[174:177], v[206:209], v[80:83]
	v_mfma_f32_16x16x32_bf16 v[72:75], v[182:185], v[206:209], v[72:75]
	v_mfma_f32_16x16x32_bf16 v[68:71], v[174:177], v[214:217], v[68:71]
	v_mfma_f32_16x16x32_bf16 v[64:67], v[182:185], v[214:217], v[64:67]
	s_barrier
; #define PG8_STAGE(bufoff, gbase, voff) do { _Pragma("unroll") for (int _i = 0; _i < 2; ++_i) \
;         __builtin_amdgcn_global_load_lds((const unsigned*)((const char*)(gbase) + (voff)[_i]), (PG8_LAS unsigned*)(lds + (bufoff) + ldsw + _i * 8192), 16, 0, 0); } while (0)
; #define PG8_LDA(dst, b, h) do { _Pragma("unroll") for (int m = 0; m < 4; ++m) _Pragma("unroll") for (int k = 0; k < 2; ++k) dst[m][k] = *(const PG8_LAS bf16x8*)(lds + PG8_SA(b, h) + aoff + m * 2048 + k * 1024); } while (0)
; #define PG8_MMA(ai, bj, At, Bt) do { __builtin_amdgcn_s_setprio(1); _Pragma("unroll") for (int m = 0; m < 4; ++m) _Pragma("unroll") for (int n = 0; n < 2; ++n) _Pragma("unroll") for (int k = 0; k < 2; ++k) \
;         acc[ai][bj][m][n] = __builtin_amdgcn_mfma_f32_16x16x32_bf16(Bt[n][k], At[m][k], acc[ai][bj][m][n], 0, 0, 0); __builtin_amdgcn_s_setprio(0); } while (0)
; #define PG8_WAIT_V(n) asm volatile("s_waitcnt vmcnt(" #n ")" ::: "memory")
; #define PG8_WAIT_L(n) asm volatile("s_waitcnt lgkmcnt(" #n ")" ::: "memory")
; #define PG8_BAR __builtin_amdgcn_s_barrier()
; #define PG8_SCHED __builtin_amdgcn_sched_barrier(0)
; template <class Epi, class Sched>
; __device__ __forceinline__ void gemm_phase(PG8_LAS unsigned char* lds, PG8_LAS unsigned char* xl, const Gemm g, const Sched& S, const Epi& E) {
;     ...
;             PG8_LDA(At, 1, 1); PG8_STAGE(PG8_SB(1, 0), b3, voffB); PG8_STAGE(PG8_SB(1, 1), b3 + hsB, voffB); PG8_STAGE(PG8_SA(1, 0), a3, voffA);
;             PG8_WAIT_V(8); PG8_WAIT_L(0); PG8_BAR; PG8_MMA(1, 0, At, B0); PG8_MMA(1, 1, At, B1); PG8_BAR; PG8_SCHED;
	s_setprio 0
	s_add_i32 s30, s68, s43
	v_lshl_add_u64 v[146:147], v[146:147], 0, s[10:11]
	s_mov_b32 m0, s30
	ds_read_b128 v[186:189], v152 offset:49152
	ds_read_b128 v[190:193], v152 offset:50176
	ds_read_b128 v[194:197], v152 offset:51200
	ds_read_b128 v[198:201], v152 offset:52224
	ds_read_b128 v[202:205], v152 offset:53248
	ds_read_b128 v[206:209], v152 offset:54272
	ds_read_b128 v[210:213], v152 offset:55296
	ds_read_b128 v[214:217], v152 offset:56320
	global_load_lds_dwordx4 v[146:147], off
	s_add_i32 m0, s30, 0x2000
	s_add_u32 s28, s28, 0x40080
	v_lshl_add_u64 v[146:147], v[218:219], 0, s[10:11]
	s_addc_u32 s29, s29, 0
	s_add_i32 s30, s78, s43
	global_load_lds_dwordx4 v[146:147], off
	v_lshl_add_u64 v[146:147], s[28:29], 0, v[130:131]
	s_mov_b32 m0, s30
	s_nop 0
	global_load_lds_dwordx4 v[146:147], off
	v_lshl_add_u64 v[146:147], s[28:29], 0, v[134:135]
	s_add_i32 m0, s30, 0x2000
	s_nop 0
	global_load_lds_dwordx4 v[146:147], off
	v_lshl_add_u64 v[146:147], v[222:223], 0, s[10:11]
	s_mov_b32 m0, s55
	s_nop 0
	global_load_lds_dwordx4 v[146:147], off
	v_lshl_add_u64 v[146:147], v[224:225], 0, s[10:11]
	s_mov_b32 m0, s56
	s_nop 0
	global_load_lds_dwordx4 v[146:147], off
	s_waitcnt vmcnt(8) lgkmcnt(0)
	s_setprio 1
	s_barrier
	v_mfma_f32_16x16x32_bf16 v[60:63], v[154:157], v[186:189], v[60:63]
	v_mfma_f32_16x16x32_bf16 v[56:59], v[162:165], v[186:189], v[56:59]
	v_mfma_f32_16x16x32_bf16 v[52:55], v[154:157], v[194:197], v[52:55]
	v_mfma_f32_16x16x32_bf16 v[44:47], v[162:165], v[194:197], v[44:47]
	v_mfma_f32_16x16x32_bf16 v[36:39], v[154:157], v[202:205], v[36:39]
	v_mfma_f32_16x16x32_bf16 v[28:31], v[162:165], v[202:205], v[28:31]
	v_mfma_f32_16x16x32_bf16 v[20:23], v[154:157], v[210:213], v[20:23]
	v_mfma_f32_16x16x32_bf16 v[12:15], v[162:165], v[210:213], v[12:15]
	v_mfma_f32_16x16x32_bf16 v[60:63], v[158:161], v[190:193], v[60:63]
	v_mfma_f32_16x16x32_bf16 v[56:59], v[166:169], v[190:193], v[56:59]
	v_mfma_f32_16x16x32_bf16 v[52:55], v[158:161], v[198:201], v[52:55]
	v_mfma_f32_16x16x32_bf16 v[44:47], v[166:169], v[198:201], v[44:47]
	v_mfma_f32_16x16x32_bf16 v[36:39], v[158:161], v[206:209], v[36:39]
	v_mfma_f32_16x16x32_bf16 v[28:31], v[166:169], v[206:209], v[28:31]
	v_mfma_f32_16x16x32_bf16 v[20:23], v[158:161], v[214:217], v[20:23]
	v_mfma_f32_16x16x32_bf16 v[12:15], v[166:169], v[214:217], v[12:15]
	s_setprio 0
	s_setprio 1
	v_mfma_f32_16x16x32_bf16 v[48:51], v[170:173], v[186:189], v[48:51]
	s_add_i32 s77, s77, 2
	v_mfma_f32_16x16x32_bf16 v[40:43], v[178:181], v[186:189], v[40:43]
	s_add_u32 s75, s75, 0x100
	v_mfma_f32_16x16x32_bf16 v[32:35], v[170:173], v[194:197], v[32:35]
	s_addc_u32 s76, s76, 0
	v_mfma_f32_16x16x32_bf16 v[24:27], v[178:181], v[194:197], v[24:27]
	s_add_u32 s26, s26, 0x100
	v_mfma_f32_16x16x32_bf16 v[16:19], v[170:173], v[202:205], v[16:19]
	s_addc_u32 s27, s27, 0
	v_mfma_f32_16x16x32_bf16 v[8:11], v[178:181], v[202:205], v[8:11]
	s_cmp_gt_u32 s77, 13
	v_mfma_f32_16x16x32_bf16 v[4:7], v[170:173], v[210:213], v[4:7]
	v_mfma_f32_16x16x32_bf16 v[0:3], v[178:181], v[210:213], v[0:3]
	v_mfma_f32_16x16x32_bf16 v[48:51], v[174:177], v[190:193], v[48:51]
	v_mfma_f32_16x16x32_bf16 v[40:43], v[182:185], v[190:193], v[40:43]
	v_mfma_f32_16x16x32_bf16 v[32:35], v[174:177], v[198:201], v[32:35]
	v_mfma_f32_16x16x32_bf16 v[24:27], v[182:185], v[198:201], v[24:27]
	v_mfma_f32_16x16x32_bf16 v[16:19], v[174:177], v[206:209], v[16:19]
	v_mfma_f32_16x16x32_bf16 v[8:11], v[182:185], v[206:209], v[8:11]
	v_mfma_f32_16x16x32_bf16 v[4:7], v[174:177], v[214:217], v[4:7]
	v_mfma_f32_16x16x32_bf16 v[0:3], v[182:185], v[214:217], v[0:3]
	s_barrier
	s_setprio 0
	s_cbranch_scc0 .LBB0_130

; #define PG8_STAGE(bufoff, gbase, voff) do { _Pragma("unroll") for (int _i = 0; _i < 2; ++_i) \
;         __builtin_amdgcn_global_load_lds((const unsigned*)((const char*)(gbase) + (voff)[_i]), (PG8_LAS unsigned*)(lds + (bufoff) + ldsw + _i * 8192), 16, 0, 0); } while (0)
; #define PG8_LDA(dst, b, h) do { _Pragma("unroll") for (int m = 0; m < 4; ++m) _Pragma("unroll") for (int k = 0; k < 2; ++k) dst[m][k] = *(const PG8_LAS bf16x8*)(lds + PG8_SA(b, h) + aoff + m * 2048 + k * 1024); } while (0)
; #define PG8_LDB(dst, b, h) do { _Pragma("unroll") for (int n = 0; n < 2; ++n) _Pragma("unroll") for (int k = 0; k < 2; ++k) dst[n][k] = *(const PG8_LAS bf16x8*)(lds + PG8_SB(b, h) + boff + n * 2048 + k * 1024); } while (0)
; #define PG8_MMA(ai, bj, At, Bt) do { __builtin_amdgcn_s_setprio(1); _Pragma("unroll") for (int m = 0; m < 4; ++m) _Pragma("unroll") for (int n = 0; n < 2; ++n) _Pragma("unroll") for (int k = 0; k < 2; ++k) \
;         acc[ai][bj][m][n] = __builtin_amdgcn_mfma_f32_16x16x32_bf16(Bt[n][k], At[m][k], acc[ai][bj][m][n], 0, 0, 0); __builtin_amdgcn_s_setprio(0); } while (0)
; template <class Epi, class Sched>
; __device__ __forceinline__ void gemm_phase(PG8_LAS unsigned char* lds, PG8_LAS unsigned char* xl, const Gemm g, const Sched& S, const Epi& E) {
;     ...
;     for (;;) {
;         const bool has_next = S.next(ui + 1, nxt);
;         const char* nA = has_next ? (const char*)g.A + nxt.aoff : cA; const char* nB = has_next ? (const char*)g.Bt + nxt.boff : cB;
; #pragma unroll 1
;         for (int t = 0; t < nt; t += 2) {
;             const bool last = (t == nt - 2);
;             const char* a1 = cA + (size_t)(t + 1) * kstep;
;             const char* a2 = last ? nA : cA + (size_t)(t + 2) * kstep; const char* b2 = last ? nB : cB + (size_t)(t + 2) * kstep;
;             const char* a3 = a2 + kstep; const char* b3 = b2 + kstep;
;             PG8_LDB(B0, 0, 0); PG8_LDB(B1, 0, 1); PG8_SCHED; PG8_LDA(At, 0, 0); PG8_STAGE(PG8_SA(1, 1), a1 + hsA, voffA);
;             PG8_WAIT_V(8); PG8_WAIT_L(0); PG8_BAR; PG8_MMA(0, 0, At, B0); PG8_MMA(0, 1, At, B1); PG8_BAR; PG8_SCHED;
;             PG8_LDA(At, 0, 1); PG8_STAGE(PG8_SB(0, 0), b2, voffB); PG8_STAGE(PG8_SB(0, 1), b2 + hsB, voffB); PG8_STAGE(PG8_SA(0, 0), a2, voffA);
;             PG8_WAIT_V(8); PG8_WAIT_L(0); PG8_BAR; PG8_MMA(1, 0, At, B0); PG8_MMA(1, 1, At, B1); PG8_BAR; PG8_SCHED;
.LBB0_376:
	s_add_u32 s20, s2, s16
	s_addc_u32 s21, s3, s17
	s_and_b64 s[22:23], s[4:5], exec
	s_cselect_b32 s82, s21, s31
	s_cselect_b32 s83, s20, s30
	s_add_u32 s22, s2, s18
	s_addc_u32 s23, s3, s19
	s_and_b64 s[34:35], s[4:5], exec
	v_mov_b32_e32 v0, 0
	s_cselect_b32 s84, s23, s29
	s_cselect_b32 s85, s22, s28
	s_mov_b64 s[50:51], 0
	s_mov_b64 s[34:35], -1
	s_mov_b64 s[36:37], 0
	s_add_u32 s56, s30, s50
	s_addc_u32 s57, s31, s51
	s_add_u32 s54, s56, 0x100
	s_addc_u32 s55, s57, 0
	s_and_b64 s[52:53], s[36:37], exec
	s_cselect_b32 s53, s82, s55
	s_cselect_b32 s52, s83, s54
	s_add_u32 s50, s28, s50
	s_addc_u32 s51, s29, s51
	s_add_u32 s50, s50, 0x100
	s_addc_u32 s51, s51, 0
	s_and_b64 s[36:37], s[36:37], exec
	s_cselect_b32 s55, s84, s51
	s_cselect_b32 s54, s85, s50
	s_add_u32 s58, s56, 0x80080
	ds_read_b128 v[152:155], v147
	ds_read_b128 v[156:159], v147 offset:1024
	ds_read_b128 v[160:163], v147 offset:2048
	ds_read_b128 v[164:167], v147 offset:3072
	ds_read_b128 v[168:171], v148
	ds_read_b128 v[172:175], v148 offset:1024
	ds_read_b128 v[176:179], v148 offset:2048
	ds_read_b128 v[180:183], v148 offset:3072
	s_addc_u32 s59, s57, 0
	s_add_i32 s94, s73, s33
	s_add_i32 m0, s43, 0xc000
	s_add_i32 s95, s43, 0xe000
	s_add_i32 s91, s94, 0x2000
	s_add_u32 s56, s54, 0x80000
	s_addc_u32 s57, s55, 0
	s_add_i32 s93, s74, s33
	s_add_i32 s92, s93, 0x2000
	s_add_i32 s90, 0, 0x18000
	s_add_i32 s89, 0, 0x1c000
	s_add_u32 s50, s52, 0x80000
	s_addc_u32 s51, s53, 0
	s_add_i32 s88, s90, s33
	s_add_i32 s86, s88, 0x2000
	s_add_u32 s36, s54, 0x80080
	s_addc_u32 s37, s55, 0
	s_add_i32 s87, s89, s33
	s_add_i32 s68, s87, 0x2000
	v_lshl_add_u64 v[144:145], s[58:59], 0, v[128:129]
	ds_read_b128 v[184:187], v149
	ds_read_b128 v[188:191], v149 offset:1024
	ds_read_b128 v[192:195], v149 offset:2048
	ds_read_b128 v[196:199], v149 offset:3072
	ds_read_b128 v[200:203], v149 offset:4096
	ds_read_b128 v[204:207], v149 offset:5120
	ds_read_b128 v[208:211], v149 offset:6144
	ds_read_b128 v[212:215], v149 offset:7168
	global_load_lds_dwordx4 v[144:145], off
	v_lshl_add_u64 v[144:145], s[58:59], 0, v[132:133]
	s_mov_b32 m0, s95
	s_nop 0
	global_load_lds_dwordx4 v[144:145], off
	s_waitcnt vmcnt(8) lgkmcnt(0)
	s_setprio 1
	s_barrier
	v_mfma_f32_16x16x32_bf16 v[124:127], v[152:155], v[184:187], 0
	v_mfma_f32_16x16x32_bf16 v[120:123], v[160:163], v[184:187], 0
	v_mfma_f32_16x16x32_bf16 v[112:115], v[152:155], v[192:195], 0
	v_mfma_f32_16x16x32_bf16 v[104:107], v[160:163], v[192:195], 0
	v_mfma_f32_16x16x32_bf16 v[96:99], v[152:155], v[200:203], 0
	v_mfma_f32_16x16x32_bf16 v[88:91], v[160:163], v[200:203], 0
	v_mfma_f32_16x16x32_bf16 v[80:83], v[152:155], v[208:211], 0
	v_mfma_f32_16x16x32_bf16 v[72:75], v[160:163], v[208:211], 0
	v_mfma_f32_16x16x32_bf16 v[124:127], v[156:159], v[188:191], v[124:127]
	v_mfma_f32_16x16x32_bf16 v[120:123], v[164:167], v[188:191], v[120:123]
	v_mfma_f32_16x16x32_bf16 v[112:115], v[156:159], v[196:199], v[112:115]
	v_mfma_f32_16x16x32_bf16 v[104:107], v[164:167], v[196:199], v[104:107]
	v_mfma_f32_16x16x32_bf16 v[96:99], v[156:159], v[204:207], v[96:99]
	v_mfma_f32_16x16x32_bf16 v[88:91], v[164:167], v[204:207], v[88:91]
	v_mfma_f32_16x16x32_bf16 v[80:83], v[156:159], v[212:215], v[80:83]
	v_mfma_f32_16x16x32_bf16 v[72:75], v[164:167], v[212:215], v[72:75]
	s_setprio 0
	s_setprio 1
	v_mfma_f32_16x16x32_bf16 v[116:119], v[168:171], v[184:187], 0
	v_mfma_f32_16x16x32_bf16 v[108:111], v[176:179], v[184:187], 0
	v_mfma_f32_16x16x32_bf16 v[100:103], v[168:171], v[192:195], 0
	v_mfma_f32_16x16x32_bf16 v[92:95], v[176:179], v[192:195], 0
	v_mfma_f32_16x16x32_bf16 v[84:87], v[168:171], v[200:203], 0
	v_mfma_f32_16x16x32_bf16 v[76:79], v[176:179], v[200:203], 0
	v_mfma_f32_16x16x32_bf16 v[68:71], v[168:171], v[208:211], 0
	v_mfma_f32_16x16x32_bf16 v[64:67], v[176:179], v[208:211], 0
	v_mfma_f32_16x16x32_bf16 v[116:119], v[172:175], v[188:191], v[116:119]
	v_mfma_f32_16x16x32_bf16 v[108:111], v[180:183], v[188:191], v[108:111]
	v_mfma_f32_16x16x32_bf16 v[100:103], v[172:175], v[196:199], v[100:103]
	v_mfma_f32_16x16x32_bf16 v[92:95], v[180:183], v[196:199], v[92:95]
	v_mfma_f32_16x16x32_bf16 v[84:87], v[172:175], v[204:207], v[84:87]
	v_mfma_f32_16x16x32_bf16 v[76:79], v[180:183], v[204:207], v[76:79]
	v_mfma_f32_16x16x32_bf16 v[68:71], v[172:175], v[212:215], v[68:71]
	v_mfma_f32_16x16x32_bf16 v[64:67], v[180:183], v[212:215], v[64:67]
	s_barrier
	s_setprio 0
	s_mov_b32 m0, s94
	v_lshl_add_u64 v[144:145], s[54:55], 0, v[130:131]
	ds_read_b128 v[184:187], v149 offset:16384
	ds_read_b128 v[188:191], v149 offset:17408
	ds_read_b128 v[192:195], v149 offset:18432
	ds_read_b128 v[196:199], v149 offset:19456
	ds_read_b128 v[200:203], v149 offset:20480
	ds_read_b128 v[204:207], v149 offset:21504
	ds_read_b128 v[208:211], v149 offset:22528
	ds_read_b128 v[212:215], v149 offset:23552
	global_load_lds_dwordx4 v[144:145], off
	v_lshl_add_u64 v[216:217], s[54:55], 0, v[134:135]
	s_mov_b32 m0, s91
	v_lshl_add_u64 v[218:219], s[56:57], 0, v[130:131]
	global_load_lds_dwordx4 v[216:217], off
	s_mov_b32 m0, s93
	v_lshl_add_u64 v[222:223], s[52:53], 0, v[132:133]
	global_load_lds_dwordx4 v[218:219], off
	v_lshl_add_u64 v[218:219], s[56:57], 0, v[134:135]
	s_mov_b32 m0, s92
	s_nop 0
	global_load_lds_dwordx4 v[218:219], off
	v_lshl_add_u64 v[218:219], s[52:53], 0, v[128:129]
	s_mov_b32 m0, s43
	s_nop 0
	global_load_lds_dwordx4 v[218:219], off
	s_mov_b32 m0, s46
	s_nop 0
	global_load_lds_dwordx4 v[222:223], off
	s_waitcnt vmcnt(8) lgkmcnt(0)
	s_setprio 1
	s_barrier
; #define PG8_STAGE(bufoff, gbase, voff) do { _Pragma("unroll") for (int _i = 0; _i < 2; ++_i) \
;         __builtin_amdgcn_global_load_lds((const unsigned*)((const char*)(gbase) + (voff)[_i]), (PG8_LAS unsigned*)(lds + (bufoff) + ldsw + _i * 8192), 16, 0, 0); } while (0)
; #define PG8_LDA(dst, b, h) do { _Pragma("unroll") for (int m = 0; m < 4; ++m) _Pragma("unroll") for (int k = 0; k < 2; ++k) dst[m][k] = *(const PG8_LAS bf16x8*)(lds + PG8_SA(b, h) + aoff + m * 2048 + k * 1024); } while (0)
; #define PG8_LDB(dst, b, h) do { _Pragma("unroll") for (int n = 0; n < 2; ++n) _Pragma("unroll") for (int k = 0; k < 2; ++k) dst[n][k] = *(const PG8_LAS bf16x8*)(lds + PG8_SB(b, h) + boff + n * 2048 + k * 1024); } while (0)
; #define PG8_MMA(ai, bj, At, Bt) do { __builtin_amdgcn_s_setprio(1); _Pragma("unroll") for (int m = 0; m < 4; ++m) _Pragma("unroll") for (int n = 0; n < 2; ++n) _Pragma("unroll") for (int k = 0; k < 2; ++k) \
;         acc[ai][bj][m][n] = __builtin_amdgcn_mfma_f32_16x16x32_bf16(Bt[n][k], At[m][k], acc[ai][bj][m][n], 0, 0, 0); __builtin_amdgcn_s_setprio(0); } while (0)
; #define PG8_WAIT_V(n) asm volatile("s_waitcnt vmcnt(" #n ")" ::: "memory")
; template <class Epi, class Sched>
; __device__ __forceinline__ void gemm_phase(PG8_LAS unsigned char* lds, PG8_LAS unsigned char* xl, const Gemm g, const Sched& S, const Epi& E) {
;     ...
;             PG8_LDB(B0, 0, 0); PG8_LDB(B1, 0, 1); PG8_SCHED; PG8_LDA(At, 0, 0); PG8_STAGE(PG8_SA(1, 1), a1 + hsA, voffA);
;             PG8_WAIT_V(8); PG8_WAIT_L(0); PG8_BAR; PG8_MMA(0, 0, At, B0); PG8_MMA(0, 1, At, B1); PG8_BAR; PG8_SCHED;
;             PG8_LDA(At, 0, 1); PG8_STAGE(PG8_SB(0, 0), b2, voffB); PG8_STAGE(PG8_SB(0, 1), b2 + hsB, voffB); PG8_STAGE(PG8_SA(0, 0), a2, voffA);
;             PG8_WAIT_V(8); PG8_WAIT_L(0); PG8_BAR; PG8_MMA(1, 0, At, B0); PG8_MMA(1, 1, At, B1); PG8_BAR; PG8_SCHED;
;             PG8_LDB(B0, 1, 0); PG8_LDB(B1, 1, 1); PG8_SCHED; PG8_LDA(At, 1, 0); PG8_STAGE(PG8_SA(0, 1), a2 + hsA, voffA);
;             PG8_WAIT_V(8); PG8_WAIT_L(0); PG8_BAR; PG8_MMA(0, 0, At, B0); PG8_MMA(0, 1, At, B1); PG8_BAR; PG8_SCHED;
;             PG8_LDA(At, 1, 1); PG8_STAGE(PG8_SB(1, 0), b3, voffB); PG8_STAGE(PG8_SB(1, 1), b3 + hsB, voffB); PG8_STAGE(PG8_SA(1, 0), a3, voffA);
;             PG8_WAIT_V(8); PG8_WAIT_L(0); PG8_BAR; PG8_MMA(1, 0, At, B0); PG8_MMA(1, 1, At, B1); PG8_BAR; PG8_SCHED;
	v_mfma_f32_16x16x32_bf16 v[60:63], v[152:155], v[184:187], 0
	v_mfma_f32_16x16x32_bf16 v[56:59], v[160:163], v[184:187], 0
	v_mfma_f32_16x16x32_bf16 v[48:51], v[152:155], v[192:195], 0
	v_mfma_f32_16x16x32_bf16 v[40:43], v[160:163], v[192:195], 0
	v_mfma_f32_16x16x32_bf16 v[32:35], v[152:155], v[200:203], 0
	v_mfma_f32_16x16x32_bf16 v[24:27], v[160:163], v[200:203], 0
	v_mfma_f32_16x16x32_bf16 v[16:19], v[152:155], v[208:211], 0
	v_mfma_f32_16x16x32_bf16 v[8:11], v[160:163], v[208:211], 0
	v_mfma_f32_16x16x32_bf16 v[60:63], v[156:159], v[188:191], v[60:63]
	v_mfma_f32_16x16x32_bf16 v[56:59], v[164:167], v[188:191], v[56:59]
	v_mfma_f32_16x16x32_bf16 v[48:51], v[156:159], v[196:199], v[48:51]
	v_mfma_f32_16x16x32_bf16 v[40:43], v[164:167], v[196:199], v[40:43]
	v_mfma_f32_16x16x32_bf16 v[32:35], v[156:159], v[204:207], v[32:35]
	v_mfma_f32_16x16x32_bf16 v[24:27], v[164:167], v[204:207], v[24:27]
	v_mfma_f32_16x16x32_bf16 v[16:19], v[156:159], v[212:215], v[16:19]
	v_mfma_f32_16x16x32_bf16 v[8:11], v[164:167], v[212:215], v[8:11]
	s_setprio 0
	s_setprio 1
	v_mfma_f32_16x16x32_bf16 v[52:55], v[168:171], v[184:187], 0
	v_mfma_f32_16x16x32_bf16 v[44:47], v[176:179], v[184:187], 0
	v_mfma_f32_16x16x32_bf16 v[36:39], v[168:171], v[192:195], 0
	v_mfma_f32_16x16x32_bf16 v[28:31], v[176:179], v[192:195], 0
	v_mfma_f32_16x16x32_bf16 v[20:23], v[168:171], v[200:203], 0
	v_mfma_f32_16x16x32_bf16 v[12:15], v[176:179], v[200:203], 0
	v_mfma_f32_16x16x32_bf16 v[4:7], v[168:171], v[208:211], 0
	v_mfma_f32_16x16x32_bf16 v[0:3], v[176:179], v[208:211], 0
	v_mfma_f32_16x16x32_bf16 v[52:55], v[172:175], v[188:191], v[52:55]
	v_mfma_f32_16x16x32_bf16 v[44:47], v[180:183], v[188:191], v[44:47]
	v_mfma_f32_16x16x32_bf16 v[36:39], v[172:175], v[196:199], v[36:39]
	v_mfma_f32_16x16x32_bf16 v[28:31], v[180:183], v[196:199], v[28:31]
	v_mfma_f32_16x16x32_bf16 v[20:23], v[172:175], v[204:207], v[20:23]
	v_mfma_f32_16x16x32_bf16 v[12:15], v[180:183], v[204:207], v[12:15]
	v_mfma_f32_16x16x32_bf16 v[4:7], v[172:175], v[212:215], v[4:7]
	v_mfma_f32_16x16x32_bf16 v[0:3], v[180:183], v[212:215], v[0:3]
	s_barrier
	s_setprio 0
	v_add_u32_e32 v142, s90, v146
	ds_read_b128 v[152:155], v142
	ds_read_b128 v[156:159], v142 offset:1024
	ds_read_b128 v[160:163], v142 offset:2048
	ds_read_b128 v[164:167], v142 offset:3072
	v_add_u32_e32 v142, s89, v146
	ds_read_b128 v[168:171], v142
	ds_read_b128 v[172:175], v142 offset:1024
	ds_read_b128 v[176:179], v142 offset:2048
	ds_read_b128 v[180:183], v142 offset:3072
	s_mov_b32 m0, s47
	v_lshl_add_u64 v[224:225], s[50:51], 0, v[128:129]
	ds_read_b128 v[184:187], v149 offset:32768
	ds_read_b128 v[188:191], v149 offset:33792
	ds_read_b128 v[192:195], v149 offset:34816
	ds_read_b128 v[196:199], v149 offset:35840
	ds_read_b128 v[200:203], v149 offset:36864
	ds_read_b128 v[204:207], v149 offset:37888
	ds_read_b128 v[208:211], v149 offset:38912
	ds_read_b128 v[212:215], v149 offset:39936
	global_load_lds_dwordx4 v[224:225], off
	v_lshl_add_u64 v[224:225], s[50:51], 0, v[132:133]
	s_mov_b32 m0, s60
	s_nop 0
	global_load_lds_dwordx4 v[224:225], off
	s_waitcnt vmcnt(8) lgkmcnt(0)
	s_setprio 1
	s_barrier
	v_mfma_f32_16x16x32_bf16 v[124:127], v[152:155], v[184:187], v[124:127]
	v_mfma_f32_16x16x32_bf16 v[120:123], v[160:163], v[184:187], v[120:123]
	v_mfma_f32_16x16x32_bf16 v[112:115], v[152:155], v[192:195], v[112:115]
	v_mfma_f32_16x16x32_bf16 v[104:107], v[160:163], v[192:195], v[104:107]
	v_mfma_f32_16x16x32_bf16 v[96:99], v[152:155], v[200:203], v[96:99]
	v_mfma_f32_16x16x32_bf16 v[88:91], v[160:163], v[200:203], v[88:91]
	v_mfma_f32_16x16x32_bf16 v[80:83], v[152:155], v[208:211], v[80:83]
	v_mfma_f32_16x16x32_bf16 v[72:75], v[160:163], v[208:211], v[72:75]
	v_mfma_f32_16x16x32_bf16 v[124:127], v[156:159], v[188:191], v[124:127]
	v_mfma_f32_16x16x32_bf16 v[120:123], v[164:167], v[188:191], v[120:123]
	v_mfma_f32_16x16x32_bf16 v[112:115], v[156:159], v[196:199], v[112:115]
	v_mfma_f32_16x16x32_bf16 v[104:107], v[164:167], v[196:199], v[104:107]
	v_mfma_f32_16x16x32_bf16 v[96:99], v[156:159], v[204:207], v[96:99]
	v_mfma_f32_16x16x32_bf16 v[88:91], v[164:167], v[204:207], v[88:91]
	v_mfma_f32_16x16x32_bf16 v[80:83], v[156:159], v[212:215], v[80:83]
	v_mfma_f32_16x16x32_bf16 v[72:75], v[164:167], v[212:215], v[72:75]
	s_setprio 0
	s_setprio 1
	v_mfma_f32_16x16x32_bf16 v[116:119], v[168:171], v[184:187], v[116:119]
	v_mfma_f32_16x16x32_bf16 v[108:111], v[176:179], v[184:187], v[108:111]
	v_mfma_f32_16x16x32_bf16 v[100:103], v[168:171], v[192:195], v[100:103]
	v_mfma_f32_16x16x32_bf16 v[92:95], v[176:179], v[192:195], v[92:95]
	v_mfma_f32_16x16x32_bf16 v[84:87], v[168:171], v[200:203], v[84:87]
	v_mfma_f32_16x16x32_bf16 v[76:79], v[176:179], v[200:203], v[76:79]
	v_mfma_f32_16x16x32_bf16 v[68:71], v[168:171], v[208:211], v[68:71]
	v_mfma_f32_16x16x32_bf16 v[64:67], v[176:179], v[208:211], v[64:67]
	v_mfma_f32_16x16x32_bf16 v[116:119], v[172:175], v[188:191], v[116:119]
	v_mfma_f32_16x16x32_bf16 v[108:111], v[180:183], v[188:191], v[108:111]
	v_mfma_f32_16x16x32_bf16 v[100:103], v[172:175], v[196:199], v[100:103]
	v_mfma_f32_16x16x32_bf16 v[92:95], v[180:183], v[196:199], v[92:95]
	v_mfma_f32_16x16x32_bf16 v[84:87], v[172:175], v[204:207], v[84:87]
	v_mfma_f32_16x16x32_bf16 v[76:79], v[180:183], v[204:207], v[76:79]
	v_mfma_f32_16x16x32_bf16 v[68:71], v[172:175], v[212:215], v[68:71]
	v_mfma_f32_16x16x32_bf16 v[64:67], v[180:183], v[212:215], v[64:67]
	s_barrier
; #define PG8_STAGE(bufoff, gbase, voff) do { _Pragma("unroll") for (int _i = 0; _i < 2; ++_i) \
;         __builtin_amdgcn_global_load_lds((const unsigned*)((const char*)(gbase) + (voff)[_i]), (PG8_LAS unsigned*)(lds + (bufoff) + ldsw + _i * 8192), 16, 0, 0); } while (0)
; #define PG8_LDA(dst, b, h) do { _Pragma("unroll") for (int m = 0; m < 4; ++m) _Pragma("unroll") for (int k = 0; k < 2; ++k) dst[m][k] = *(const PG8_LAS bf16x8*)(lds + PG8_SA(b, h) + aoff + m * 2048 + k * 1024); } while (0)
; #define PG8_LDB(dst, b, h) do { _Pragma("unroll") for (int n = 0; n < 2; ++n) _Pragma("unroll") for (int k = 0; k < 2; ++k) dst[n][k] = *(const PG8_LAS bf16x8*)(lds + PG8_SB(b, h) + boff + n * 2048 + k * 1024); } while (0)
; #define PG8_WAIT_V(n) asm volatile("s_waitcnt vmcnt(" #n ")" ::: "memory")
; #define PG8_WAIT_L(n) asm volatile("s_waitcnt lgkmcnt(" #n ")" ::: "memory")
; template <class Epi, class Sched>
; __device__ __forceinline__ void gemm_phase(PG8_LAS unsigned char* lds, PG8_LAS unsigned char* xl, const Gemm g, const Sched& S, const Epi& E) {
;     ...
;             const bool last = (t == nt - 2);
;             const char* a1 = cA + (size_t)(t + 1) * kstep;
;             const char* a2 = last ? nA : cA + (size_t)(t + 2) * kstep; const char* b2 = last ? nB : cB + (size_t)(t + 2) * kstep;
;             const char* a3 = a2 + kstep; const char* b3 = b2 + kstep;
;             PG8_LDB(B0, 0, 0); PG8_LDB(B1, 0, 1); PG8_SCHED; PG8_LDA(At, 0, 0); PG8_STAGE(PG8_SA(1, 1), a1 + hsA, voffA);
;             PG8_WAIT_V(8); PG8_WAIT_L(0); PG8_BAR; PG8_MMA(0, 0, At, B0); PG8_MMA(0, 1, At, B1); PG8_BAR; PG8_SCHED;
;             PG8_LDA(At, 0, 1); PG8_STAGE(PG8_SB(0, 0), b2, voffB); PG8_STAGE(PG8_SB(0, 1), b2 + hsB, voffB); PG8_STAGE(PG8_SA(0, 0), a2, voffA);
;             PG8_WAIT_V(8); PG8_WAIT_L(0); PG8_BAR; PG8_MMA(1, 0, At, B0); PG8_MMA(1, 1, At, B1); PG8_BAR; PG8_SCHED;
;             PG8_LDB(B0, 1, 0); PG8_LDB(B1, 1, 1); PG8_SCHED; PG8_LDA(At, 1, 0); PG8_STAGE(PG8_SA(0, 1), a2 + hsA, voffA);
;             PG8_WAIT_V(8); PG8_WAIT_L(0); PG8_BAR; PG8_MMA(0, 0, At, B0); PG8_MMA(0, 1, At, B1); PG8_BAR; PG8_SCHED;
;             PG8_LDA(At, 1, 1); PG8_STAGE(PG8_SB(1, 0), b3, voffB); PG8_STAGE(PG8_SB(1, 1), b3 + hsB, voffB); PG8_STAGE(PG8_SA(1, 0), a3, voffA);
;             PG8_WAIT_V(8); PG8_WAIT_L(0); PG8_BAR; PG8_MMA(1, 0, At, B0); PG8_MMA(1, 1, At, B1); PG8_BAR; PG8_SCHED;
	s_setprio 0
	s_mov_b32 m0, s88
	v_lshl_add_u64 v[144:145], v[144:145], 0, s[10:11]
	ds_read_b128 v[184:187], v149 offset:49152
	ds_read_b128 v[188:191], v149 offset:50176
	ds_read_b128 v[192:195], v149 offset:51200
	ds_read_b128 v[196:199], v149 offset:52224
	ds_read_b128 v[200:203], v149 offset:53248
	ds_read_b128 v[204:207], v149 offset:54272
	ds_read_b128 v[208:211], v149 offset:55296
	ds_read_b128 v[212:215], v149 offset:56320
	global_load_lds_dwordx4 v[144:145], off
	v_lshl_add_u64 v[144:145], v[216:217], 0, s[10:11]
	s_mov_b32 m0, s86
	s_nop 0
	global_load_lds_dwordx4 v[144:145], off
	v_lshl_add_u64 v[144:145], s[36:37], 0, v[130:131]
	s_mov_b32 m0, s87
	s_nop 0
	global_load_lds_dwordx4 v[144:145], off
	v_lshl_add_u64 v[144:145], s[36:37], 0, v[134:135]
	s_mov_b32 m0, s68
	s_nop 0
	global_load_lds_dwordx4 v[144:145], off
	v_lshl_add_u64 v[144:145], v[218:219], 0, s[10:11]
	s_mov_b32 m0, s65
	s_nop 0
	global_load_lds_dwordx4 v[144:145], off
	v_lshl_add_u64 v[144:145], v[222:223], 0, s[10:11]
	s_mov_b32 m0, s66
	s_nop 0
	global_load_lds_dwordx4 v[144:145], off
	s_waitcnt vmcnt(8) lgkmcnt(0)
	s_setprio 1
	s_barrier
	v_mfma_f32_16x16x32_bf16 v[60:63], v[152:155], v[184:187], v[60:63]
	v_mfma_f32_16x16x32_bf16 v[56:59], v[160:163], v[184:187], v[56:59]
	v_mfma_f32_16x16x32_bf16 v[48:51], v[152:155], v[192:195], v[48:51]
	v_mfma_f32_16x16x32_bf16 v[40:43], v[160:163], v[192:195], v[40:43]
	v_mfma_f32_16x16x32_bf16 v[32:35], v[152:155], v[200:203], v[32:35]
	v_mfma_f32_16x16x32_bf16 v[24:27], v[160:163], v[200:203], v[24:27]
	v_mfma_f32_16x16x32_bf16 v[16:19], v[152:155], v[208:211], v[16:19]
	v_mfma_f32_16x16x32_bf16 v[8:11], v[160:163], v[208:211], v[8:11]
	v_mfma_f32_16x16x32_bf16 v[60:63], v[156:159], v[188:191], v[60:63]
	v_mfma_f32_16x16x32_bf16 v[56:59], v[164:167], v[188:191], v[56:59]
	v_mfma_f32_16x16x32_bf16 v[48:51], v[156:159], v[196:199], v[48:51]
	v_mfma_f32_16x16x32_bf16 v[40:43], v[164:167], v[196:199], v[40:43]
	v_mfma_f32_16x16x32_bf16 v[32:35], v[156:159], v[204:207], v[32:35]
	v_mfma_f32_16x16x32_bf16 v[24:27], v[164:167], v[204:207], v[24:27]
	v_mfma_f32_16x16x32_bf16 v[16:19], v[156:159], v[212:215], v[16:19]
	v_mfma_f32_16x16x32_bf16 v[8:11], v[164:167], v[212:215], v[8:11]
	s_setprio 0
	s_setprio 1
	v_mfma_f32_16x16x32_bf16 v[52:55], v[168:171], v[184:187], v[52:55]
	v_mfma_f32_16x16x32_bf16 v[44:47], v[176:179], v[184:187], v[44:47]
	v_mfma_f32_16x16x32_bf16 v[36:39], v[168:171], v[192:195], v[36:39]
	v_mfma_f32_16x16x32_bf16 v[28:31], v[176:179], v[192:195], v[28:31]
	v_mfma_f32_16x16x32_bf16 v[20:23], v[168:171], v[200:203], v[20:23]
	v_mfma_f32_16x16x32_bf16 v[12:15], v[176:179], v[200:203], v[12:15]
	v_mfma_f32_16x16x32_bf16 v[4:7], v[168:171], v[208:211], v[4:7]
	v_mfma_f32_16x16x32_bf16 v[0:3], v[176:179], v[208:211], v[0:3]
	v_mfma_f32_16x16x32_bf16 v[52:55], v[172:175], v[188:191], v[52:55]
	v_mfma_f32_16x16x32_bf16 v[44:47], v[180:183], v[188:191], v[44:47]
	v_mfma_f32_16x16x32_bf16 v[36:39], v[172:175], v[196:199], v[36:39]
	v_mfma_f32_16x16x32_bf16 v[28:31], v[180:183], v[196:199], v[28:31]
	v_mfma_f32_16x16x32_bf16 v[20:23], v[172:175], v[204:207], v[20:23]
	v_mfma_f32_16x16x32_bf16 v[12:15], v[180:183], v[204:207], v[12:15]
	v_mfma_f32_16x16x32_bf16 v[4:7], v[172:175], v[212:215], v[4:7]
	v_mfma_f32_16x16x32_bf16 v[0:3], v[180:183], v[212:215], v[0:3]
	s_barrier
	s_setprio 0
	s_andn2_b64 vcc, exec, s[34:35]
	s_mov_b64 s[36:37], -1
	s_mov_b64 s[34:35], 0
	s_mov_b64 s[50:51], 0x100
	s_cbranch_vccnz .Lpeel_after_PX
.LBB0_377:
	s_add_u32 s56, s30, s50
	s_addc_u32 s57, s31, s51
	s_add_u32 s54, s56, 0x100
	s_addc_u32 s55, s57, 0
	s_and_b64 s[52:53], s[36:37], exec
	s_cselect_b32 s53, s82, s55
	s_cselect_b32 s52, s83, s54
	s_add_u32 s50, s28, s50
	s_addc_u32 s51, s29, s51
	s_add_u32 s50, s50, 0x100
	s_addc_u32 s51, s51, 0
	s_and_b64 s[36:37], s[36:37], exec
	s_cselect_b32 s55, s84, s51
	s_cselect_b32 s54, s85, s50
	s_add_u32 s58, s56, 0x80080
	ds_read_b128 v[152:155], v147
	ds_read_b128 v[156:159], v147 offset:1024
	ds_read_b128 v[160:163], v147 offset:2048
	ds_read_b128 v[164:167], v147 offset:3072
	ds_read_b128 v[168:171], v148
	ds_read_b128 v[172:175], v148 offset:1024
	ds_read_b128 v[176:179], v148 offset:2048
	ds_read_b128 v[180:183], v148 offset:3072
	s_addc_u32 s59, s57, 0
	s_add_i32 s94, s73, s33
	s_add_i32 m0, s43, 0xc000
	s_add_i32 s95, s43, 0xe000
	s_add_i32 s91, s94, 0x2000
	s_add_u32 s56, s54, 0x80000
	s_addc_u32 s57, s55, 0
	s_add_i32 s93, s74, s33
	s_add_i32 s92, s93, 0x2000
	s_add_i32 s90, 0, 0x18000
	s_add_i32 s89, 0, 0x1c000
	s_add_u32 s50, s52, 0x80000
	s_addc_u32 s51, s53, 0
	s_add_i32 s88, s90, s33
	s_add_i32 s86, s88, 0x2000
	s_add_u32 s36, s54, 0x80080
	s_addc_u32 s37, s55, 0
	s_add_i32 s87, s89, s33
	s_add_i32 s68, s87, 0x2000
	v_lshl_add_u64 v[144:145], s[58:59], 0, v[128:129]
	ds_read_b128 v[184:187], v149
	ds_read_b128 v[188:191], v149 offset:1024
	ds_read_b128 v[192:195], v149 offset:2048
	ds_read_b128 v[196:199], v149 offset:3072
	ds_read_b128 v[200:203], v149 offset:4096
	ds_read_b128 v[204:207], v149 offset:5120
	ds_read_b128 v[208:211], v149 offset:6144
	ds_read_b128 v[212:215], v149 offset:7168
	global_load_lds_dwordx4 v[144:145], off
	v_lshl_add_u64 v[144:145], s[58:59], 0, v[132:133]
	s_mov_b32 m0, s95
	s_nop 0
	global_load_lds_dwordx4 v[144:145], off
	s_waitcnt vmcnt(8) lgkmcnt(0)
	s_setprio 1
	s_barrier
; #define PG8_STAGE(bufoff, gbase, voff) do { _Pragma("unroll") for (int _i = 0; _i < 2; ++_i) \
;         __builtin_amdgcn_global_load_lds((const unsigned*)((const char*)(gbase) + (voff)[_i]), (PG8_LAS unsigned*)(lds + (bufoff) + ldsw + _i * 8192), 16, 0, 0); } while (0)
; #define PG8_LDA(dst, b, h) do { _Pragma("unroll") for (int m = 0; m < 4; ++m) _Pragma("unroll") for (int k = 0; k < 2; ++k) dst[m][k] = *(const PG8_LAS bf16x8*)(lds + PG8_SA(b, h) + aoff + m * 2048 + k * 1024); } while (0)
; #define PG8_LDB(dst, b, h) do { _Pragma("unroll") for (int n = 0; n < 2; ++n) _Pragma("unroll") for (int k = 0; k < 2; ++k) dst[n][k] = *(const PG8_LAS bf16x8*)(lds + PG8_SB(b, h) + boff + n * 2048 + k * 1024); } while (0)
; #define PG8_MMA(ai, bj, At, Bt) do { __builtin_amdgcn_s_setprio(1); _Pragma("unroll") for (int m = 0; m < 4; ++m) _Pragma("unroll") for (int n = 0; n < 2; ++n) _Pragma("unroll") for (int k = 0; k < 2; ++k) \
;         acc[ai][bj][m][n] = __builtin_amdgcn_mfma_f32_16x16x32_bf16(Bt[n][k], At[m][k], acc[ai][bj][m][n], 0, 0, 0); __builtin_amdgcn_s_setprio(0); } while (0)
; #define PG8_WAIT_V(n) asm volatile("s_waitcnt vmcnt(" #n ")" ::: "memory")
; template <class Epi, class Sched>
; __device__ __forceinline__ void gemm_phase(PG8_LAS unsigned char* lds, PG8_LAS unsigned char* xl, const Gemm g, const Sched& S, const Epi& E) {
;     ...
;             PG8_LDB(B0, 0, 0); PG8_LDB(B1, 0, 1); PG8_SCHED; PG8_LDA(At, 0, 0); PG8_STAGE(PG8_SA(1, 1), a1 + hsA, voffA);
;             PG8_WAIT_V(8); PG8_WAIT_L(0); PG8_BAR; PG8_MMA(0, 0, At, B0); PG8_MMA(0, 1, At, B1); PG8_BAR; PG8_SCHED;
;             PG8_LDA(At, 0, 1); PG8_STAGE(PG8_SB(0, 0), b2, voffB); PG8_STAGE(PG8_SB(0, 1), b2 + hsB, voffB); PG8_STAGE(PG8_SA(0, 0), a2, voffA);
;             PG8_WAIT_V(8); PG8_WAIT_L(0); PG8_BAR; PG8_MMA(1, 0, At, B0); PG8_MMA(1, 1, At, B1); PG8_BAR; PG8_SCHED;
;             PG8_LDB(B0, 1, 0); PG8_LDB(B1, 1, 1); PG8_SCHED; PG8_LDA(At, 1, 0); PG8_STAGE(PG8_SA(0, 1), a2 + hsA, voffA);
;             PG8_WAIT_V(8); PG8_WAIT_L(0); PG8_BAR; PG8_MMA(0, 0, At, B0); PG8_MMA(0, 1, At, B1); PG8_BAR; PG8_SCHED;
;             PG8_LDA(At, 1, 1); PG8_STAGE(PG8_SB(1, 0), b3, voffB); PG8_STAGE(PG8_SB(1, 1), b3 + hsB, voffB); PG8_STAGE(PG8_SA(1, 0), a3, voffA);
;             PG8_WAIT_V(8); PG8_WAIT_L(0); PG8_BAR; PG8_MMA(1, 0, At, B0); PG8_MMA(1, 1, At, B1); PG8_BAR; PG8_SCHED;
	v_mfma_f32_16x16x32_bf16 v[124:127], v[152:155], v[184:187], v[124:127]
	v_mfma_f32_16x16x32_bf16 v[120:123], v[160:163], v[184:187], v[120:123]
	v_mfma_f32_16x16x32_bf16 v[112:115], v[152:155], v[192:195], v[112:115]
	v_mfma_f32_16x16x32_bf16 v[104:107], v[160:163], v[192:195], v[104:107]
	v_mfma_f32_16x16x32_bf16 v[96:99], v[152:155], v[200:203], v[96:99]
	v_mfma_f32_16x16x32_bf16 v[88:91], v[160:163], v[200:203], v[88:91]
	v_mfma_f32_16x16x32_bf16 v[80:83], v[152:155], v[208:211], v[80:83]
	v_mfma_f32_16x16x32_bf16 v[72:75], v[160:163], v[208:211], v[72:75]
	v_mfma_f32_16x16x32_bf16 v[124:127], v[156:159], v[188:191], v[124:127]
	v_mfma_f32_16x16x32_bf16 v[120:123], v[164:167], v[188:191], v[120:123]
	v_mfma_f32_16x16x32_bf16 v[112:115], v[156:159], v[196:199], v[112:115]
	v_mfma_f32_16x16x32_bf16 v[104:107], v[164:167], v[196:199], v[104:107]
	v_mfma_f32_16x16x32_bf16 v[96:99], v[156:159], v[204:207], v[96:99]
	v_mfma_f32_16x16x32_bf16 v[88:91], v[164:167], v[204:207], v[88:91]
	v_mfma_f32_16x16x32_bf16 v[80:83], v[156:159], v[212:215], v[80:83]
	v_mfma_f32_16x16x32_bf16 v[72:75], v[164:167], v[212:215], v[72:75]
	s_setprio 0
	s_setprio 1
	v_mfma_f32_16x16x32_bf16 v[116:119], v[168:171], v[184:187], v[116:119]
	v_mfma_f32_16x16x32_bf16 v[108:111], v[176:179], v[184:187], v[108:111]
	v_mfma_f32_16x16x32_bf16 v[100:103], v[168:171], v[192:195], v[100:103]
	v_mfma_f32_16x16x32_bf16 v[92:95], v[176:179], v[192:195], v[92:95]
	v_mfma_f32_16x16x32_bf16 v[84:87], v[168:171], v[200:203], v[84:87]
	v_mfma_f32_16x16x32_bf16 v[76:79], v[176:179], v[200:203], v[76:79]
	v_mfma_f32_16x16x32_bf16 v[68:71], v[168:171], v[208:211], v[68:71]
	v_mfma_f32_16x16x32_bf16 v[64:67], v[176:179], v[208:211], v[64:67]
	v_mfma_f32_16x16x32_bf16 v[116:119], v[172:175], v[188:191], v[116:119]
	v_mfma_f32_16x16x32_bf16 v[108:111], v[180:183], v[188:191], v[108:111]
	v_mfma_f32_16x16x32_bf16 v[100:103], v[172:175], v[196:199], v[100:103]
	v_mfma_f32_16x16x32_bf16 v[92:95], v[180:183], v[196:199], v[92:95]
	v_mfma_f32_16x16x32_bf16 v[84:87], v[172:175], v[204:207], v[84:87]
	v_mfma_f32_16x16x32_bf16 v[76:79], v[180:183], v[204:207], v[76:79]
	v_mfma_f32_16x16x32_bf16 v[68:71], v[172:175], v[212:215], v[68:71]
	v_mfma_f32_16x16x32_bf16 v[64:67], v[180:183], v[212:215], v[64:67]
	s_barrier
	s_setprio 0
	s_mov_b32 m0, s94
	v_lshl_add_u64 v[144:145], s[54:55], 0, v[130:131]
	ds_read_b128 v[184:187], v149 offset:16384
	ds_read_b128 v[188:191], v149 offset:17408
	ds_read_b128 v[192:195], v149 offset:18432
	ds_read_b128 v[196:199], v149 offset:19456
	ds_read_b128 v[200:203], v149 offset:20480
	ds_read_b128 v[204:207], v149 offset:21504
	ds_read_b128 v[208:211], v149 offset:22528
	ds_read_b128 v[212:215], v149 offset:23552
	global_load_lds_dwordx4 v[144:145], off
	v_lshl_add_u64 v[216:217], s[54:55], 0, v[134:135]
	s_mov_b32 m0, s91
	v_lshl_add_u64 v[218:219], s[56:57], 0, v[130:131]
	global_load_lds_dwordx4 v[216:217], off
	s_mov_b32 m0, s93
	v_lshl_add_u64 v[222:223], s[52:53], 0, v[132:133]
	global_load_lds_dwordx4 v[218:219], off
	v_lshl_add_u64 v[218:219], s[56:57], 0, v[134:135]
	s_mov_b32 m0, s92
	s_nop 0
	global_load_lds_dwordx4 v[218:219], off
	v_lshl_add_u64 v[218:219], s[52:53], 0, v[128:129]
	s_mov_b32 m0, s43
	s_nop 0
	global_load_lds_dwordx4 v[218:219], off
	s_mov_b32 m0, s46
	s_nop 0
	global_load_lds_dwordx4 v[222:223], off
	s_waitcnt vmcnt(8) lgkmcnt(0)
	s_setprio 1
	s_barrier
	v_mfma_f32_16x16x32_bf16 v[60:63], v[152:155], v[184:187], v[60:63]
	v_mfma_f32_16x16x32_bf16 v[56:59], v[160:163], v[184:187], v[56:59]
	v_mfma_f32_16x16x32_bf16 v[48:51], v[152:155], v[192:195], v[48:51]
	v_mfma_f32_16x16x32_bf16 v[40:43], v[160:163], v[192:195], v[40:43]
	v_mfma_f32_16x16x32_bf16 v[32:35], v[152:155], v[200:203], v[32:35]
	v_mfma_f32_16x16x32_bf16 v[24:27], v[160:163], v[200:203], v[24:27]
	v_mfma_f32_16x16x32_bf16 v[16:19], v[152:155], v[208:211], v[16:19]
	v_mfma_f32_16x16x32_bf16 v[8:11], v[160:163], v[208:211], v[8:11]
	v_mfma_f32_16x16x32_bf16 v[60:63], v[156:159], v[188:191], v[60:63]
	v_mfma_f32_16x16x32_bf16 v[56:59], v[164:167], v[188:191], v[56:59]
	v_mfma_f32_16x16x32_bf16 v[48:51], v[156:159], v[196:199], v[48:51]
	v_mfma_f32_16x16x32_bf16 v[40:43], v[164:167], v[196:199], v[40:43]
	v_mfma_f32_16x16x32_bf16 v[32:35], v[156:159], v[204:207], v[32:35]
	v_mfma_f32_16x16x32_bf16 v[24:27], v[164:167], v[204:207], v[24:27]
	v_mfma_f32_16x16x32_bf16 v[16:19], v[156:159], v[212:215], v[16:19]
	v_mfma_f32_16x16x32_bf16 v[8:11], v[164:167], v[212:215], v[8:11]
	s_setprio 0
	s_setprio 1
	v_mfma_f32_16x16x32_bf16 v[52:55], v[168:171], v[184:187], v[52:55]
	v_mfma_f32_16x16x32_bf16 v[44:47], v[176:179], v[184:187], v[44:47]
	v_mfma_f32_16x16x32_bf16 v[36:39], v[168:171], v[192:195], v[36:39]
	v_mfma_f32_16x16x32_bf16 v[28:31], v[176:179], v[192:195], v[28:31]
	v_mfma_f32_16x16x32_bf16 v[20:23], v[168:171], v[200:203], v[20:23]
	v_mfma_f32_16x16x32_bf16 v[12:15], v[176:179], v[200:203], v[12:15]
	v_mfma_f32_16x16x32_bf16 v[4:7], v[168:171], v[208:211], v[4:7]
	v_mfma_f32_16x16x32_bf16 v[0:3], v[176:179], v[208:211], v[0:3]
	v_mfma_f32_16x16x32_bf16 v[52:55], v[172:175], v[188:191], v[52:55]
	v_mfma_f32_16x16x32_bf16 v[44:47], v[180:183], v[188:191], v[44:47]
	v_mfma_f32_16x16x32_bf16 v[36:39], v[172:175], v[196:199], v[36:39]
	v_mfma_f32_16x16x32_bf16 v[28:31], v[180:183], v[196:199], v[28:31]
	v_mfma_f32_16x16x32_bf16 v[20:23], v[172:175], v[204:207], v[20:23]
	v_mfma_f32_16x16x32_bf16 v[12:15], v[180:183], v[204:207], v[12:15]
	v_mfma_f32_16x16x32_bf16 v[4:7], v[172:175], v[212:215], v[4:7]
	v_mfma_f32_16x16x32_bf16 v[0:3], v[180:183], v[212:215], v[0:3]
	s_barrier
; #define PG8_STAGE(bufoff, gbase, voff) do { _Pragma("unroll") for (int _i = 0; _i < 2; ++_i) \
;         __builtin_amdgcn_global_load_lds((const unsigned*)((const char*)(gbase) + (voff)[_i]), (PG8_LAS unsigned*)(lds + (bufoff) + ldsw + _i * 8192), 16, 0, 0); } while (0)
; #define PG8_LDA(dst, b, h) do { _Pragma("unroll") for (int m = 0; m < 4; ++m) _Pragma("unroll") for (int k = 0; k < 2; ++k) dst[m][k] = *(const PG8_LAS bf16x8*)(lds + PG8_SA(b, h) + aoff + m * 2048 + k * 1024); } while (0)
; #define PG8_LDB(dst, b, h) do { _Pragma("unroll") for (int n = 0; n < 2; ++n) _Pragma("unroll") for (int k = 0; k < 2; ++k) dst[n][k] = *(const PG8_LAS bf16x8*)(lds + PG8_SB(b, h) + boff + n * 2048 + k * 1024); } while (0)
; #define PG8_MMA(ai, bj, At, Bt) do { __builtin_amdgcn_s_setprio(1); _Pragma("unroll") for (int m = 0; m < 4; ++m) _Pragma("unroll") for (int n = 0; n < 2; ++n) _Pragma("unroll") for (int k = 0; k < 2; ++k) \
;         acc[ai][bj][m][n] = __builtin_amdgcn_mfma_f32_16x16x32_bf16(Bt[n][k], At[m][k], acc[ai][bj][m][n], 0, 0, 0); __builtin_amdgcn_s_setprio(0); } while (0)
; #define PG8_WAIT_V(n) asm volatile("s_waitcnt vmcnt(" #n ")" ::: "memory")
; #define PG8_WAIT_L(n) asm volatile("s_waitcnt lgkmcnt(" #n ")" ::: "memory")
; #define PG8_BAR __builtin_amdgcn_s_barrier()
; #define PG8_SCHED __builtin_amdgcn_sched_barrier(0)
; template <class Epi, class Sched>
; __device__ __forceinline__ void gemm_phase(PG8_LAS unsigned char* lds, PG8_LAS unsigned char* xl, const Gemm g, const Sched& S, const Epi& E) {
;     ...
;             PG8_LDB(B0, 1, 0); PG8_LDB(B1, 1, 1); PG8_SCHED; PG8_LDA(At, 1, 0); PG8_STAGE(PG8_SA(0, 1), a2 + hsA, voffA);
;             PG8_WAIT_V(8); PG8_WAIT_L(0); PG8_BAR; PG8_MMA(0, 0, At, B0); PG8_MMA(0, 1, At, B1); PG8_BAR; PG8_SCHED;
;             PG8_LDA(At, 1, 1); PG8_STAGE(PG8_SB(1, 0), b3, voffB); PG8_STAGE(PG8_SB(1, 1), b3 + hsB, voffB); PG8_STAGE(PG8_SA(1, 0), a3, voffA);
;             PG8_WAIT_V(8); PG8_WAIT_L(0); PG8_BAR; PG8_MMA(1, 0, At, B0); PG8_MMA(1, 1, At, B1); PG8_BAR; PG8_SCHED;
	s_setprio 0
	v_add_u32_e32 v142, s90, v146
	ds_read_b128 v[152:155], v142
	ds_read_b128 v[156:159], v142 offset:1024
	ds_read_b128 v[160:163], v142 offset:2048
	ds_read_b128 v[164:167], v142 offset:3072
	v_add_u32_e32 v142, s89, v146
	ds_read_b128 v[168:171], v142
	ds_read_b128 v[172:175], v142 offset:1024
	ds_read_b128 v[176:179], v142 offset:2048
	ds_read_b128 v[180:183], v142 offset:3072
	s_mov_b32 m0, s47
	v_lshl_add_u64 v[224:225], s[50:51], 0, v[128:129]
	ds_read_b128 v[184:187], v149 offset:32768
	ds_read_b128 v[188:191], v149 offset:33792
	ds_read_b128 v[192:195], v149 offset:34816
	ds_read_b128 v[196:199], v149 offset:35840
	ds_read_b128 v[200:203], v149 offset:36864
	ds_read_b128 v[204:207], v149 offset:37888
	ds_read_b128 v[208:211], v149 offset:38912
	ds_read_b128 v[212:215], v149 offset:39936
	global_load_lds_dwordx4 v[224:225], off
	v_lshl_add_u64 v[224:225], s[50:51], 0, v[132:133]
	s_mov_b32 m0, s60
	s_nop 0
	global_load_lds_dwordx4 v[224:225], off
	s_waitcnt vmcnt(8) lgkmcnt(0)
	s_setprio 1
	s_barrier
	v_mfma_f32_16x16x32_bf16 v[124:127], v[152:155], v[184:187], v[124:127]
	v_mfma_f32_16x16x32_bf16 v[120:123], v[160:163], v[184:187], v[120:123]
	v_mfma_f32_16x16x32_bf16 v[112:115], v[152:155], v[192:195], v[112:115]
	v_mfma_f32_16x16x32_bf16 v[104:107], v[160:163], v[192:195], v[104:107]
	v_mfma_f32_16x16x32_bf16 v[96:99], v[152:155], v[200:203], v[96:99]
	v_mfma_f32_16x16x32_bf16 v[88:91], v[160:163], v[200:203], v[88:91]
	v_mfma_f32_16x16x32_bf16 v[80:83], v[152:155], v[208:211], v[80:83]
	v_mfma_f32_16x16x32_bf16 v[72:75], v[160:163], v[208:211], v[72:75]
	v_mfma_f32_16x16x32_bf16 v[124:127], v[156:159], v[188:191], v[124:127]
	v_mfma_f32_16x16x32_bf16 v[120:123], v[164:167], v[188:191], v[120:123]
	v_mfma_f32_16x16x32_bf16 v[112:115], v[156:159], v[196:199], v[112:115]
	v_mfma_f32_16x16x32_bf16 v[104:107], v[164:167], v[196:199], v[104:107]
	v_mfma_f32_16x16x32_bf16 v[96:99], v[156:159], v[204:207], v[96:99]
	v_mfma_f32_16x16x32_bf16 v[88:91], v[164:167], v[204:207], v[88:91]
	v_mfma_f32_16x16x32_bf16 v[80:83], v[156:159], v[212:215], v[80:83]
	v_mfma_f32_16x16x32_bf16 v[72:75], v[164:167], v[212:215], v[72:75]
	s_setprio 0
	s_setprio 1
	v_mfma_f32_16x16x32_bf16 v[116:119], v[168:171], v[184:187], v[116:119]
	v_mfma_f32_16x16x32_bf16 v[108:111], v[176:179], v[184:187], v[108:111]
	v_mfma_f32_16x16x32_bf16 v[100:103], v[168:171], v[192:195], v[100:103]
	v_mfma_f32_16x16x32_bf16 v[92:95], v[176:179], v[192:195], v[92:95]
	v_mfma_f32_16x16x32_bf16 v[84:87], v[168:171], v[200:203], v[84:87]
	v_mfma_f32_16x16x32_bf16 v[76:79], v[176:179], v[200:203], v[76:79]
	v_mfma_f32_16x16x32_bf16 v[68:71], v[168:171], v[208:211], v[68:71]
	v_mfma_f32_16x16x32_bf16 v[64:67], v[176:179], v[208:211], v[64:67]
	v_mfma_f32_16x16x32_bf16 v[116:119], v[172:175], v[188:191], v[116:119]
	v_mfma_f32_16x16x32_bf16 v[108:111], v[180:183], v[188:191], v[108:111]
	v_mfma_f32_16x16x32_bf16 v[100:103], v[172:175], v[196:199], v[100:103]
	v_mfma_f32_16x16x32_bf16 v[92:95], v[180:183], v[196:199], v[92:95]
	v_mfma_f32_16x16x32_bf16 v[84:87], v[172:175], v[204:207], v[84:87]
	v_mfma_f32_16x16x32_bf16 v[76:79], v[180:183], v[204:207], v[76:79]
	v_mfma_f32_16x16x32_bf16 v[68:71], v[172:175], v[212:215], v[68:71]
	v_mfma_f32_16x16x32_bf16 v[64:67], v[180:183], v[212:215], v[64:67]
	s_barrier
	s_setprio 0
	s_mov_b32 m0, s88
	v_lshl_add_u64 v[144:145], v[144:145], 0, s[10:11]
	ds_read_b128 v[184:187], v149 offset:49152
	ds_read_b128 v[188:191], v149 offset:50176
	ds_read_b128 v[192:195], v149 offset:51200
	ds_read_b128 v[196:199], v149 offset:52224
	ds_read_b128 v[200:203], v149 offset:53248
	ds_read_b128 v[204:207], v149 offset:54272
	ds_read_b128 v[208:211], v149 offset:55296
	ds_read_b128 v[212:215], v149 offset:56320
	global_load_lds_dwordx4 v[144:145], off
	v_lshl_add_u64 v[144:145], v[216:217], 0, s[10:11]
	s_mov_b32 m0, s86
	s_nop 0
	global_load_lds_dwordx4 v[144:145], off
	v_lshl_add_u64 v[144:145], s[36:37], 0, v[130:131]
	s_mov_b32 m0, s87
	s_nop 0
	global_load_lds_dwordx4 v[144:145], off
	v_lshl_add_u64 v[144:145], s[36:37], 0, v[134:135]
	s_mov_b32 m0, s68
	s_nop 0
	global_load_lds_dwordx4 v[144:145], off
	v_lshl_add_u64 v[144:145], v[218:219], 0, s[10:11]
	s_mov_b32 m0, s65
	s_nop 0
	global_load_lds_dwordx4 v[144:145], off
	v_lshl_add_u64 v[144:145], v[222:223], 0, s[10:11]
	s_mov_b32 m0, s66
	s_nop 0
	global_load_lds_dwordx4 v[144:145], off
	s_waitcnt vmcnt(8) lgkmcnt(0)
	s_setprio 1
	s_barrier
	v_mfma_f32_16x16x32_bf16 v[60:63], v[152:155], v[184:187], v[60:63]
	v_mfma_f32_16x16x32_bf16 v[56:59], v[160:163], v[184:187], v[56:59]
	v_mfma_f32_16x16x32_bf16 v[48:51], v[152:155], v[192:195], v[48:51]
	v_mfma_f32_16x16x32_bf16 v[40:43], v[160:163], v[192:195], v[40:43]
	v_mfma_f32_16x16x32_bf16 v[32:35], v[152:155], v[200:203], v[32:35]
	v_mfma_f32_16x16x32_bf16 v[24:27], v[160:163], v[200:203], v[24:27]
	v_mfma_f32_16x16x32_bf16 v[16:19], v[152:155], v[208:211], v[16:19]
	v_mfma_f32_16x16x32_bf16 v[8:11], v[160:163], v[208:211], v[8:11]
	v_mfma_f32_16x16x32_bf16 v[60:63], v[156:159], v[188:191], v[60:63]
	v_mfma_f32_16x16x32_bf16 v[56:59], v[164:167], v[188:191], v[56:59]
	v_mfma_f32_16x16x32_bf16 v[48:51], v[156:159], v[196:199], v[48:51]
	v_mfma_f32_16x16x32_bf16 v[40:43], v[164:167], v[196:199], v[40:43]
	v_mfma_f32_16x16x32_bf16 v[32:35], v[156:159], v[204:207], v[32:35]
	v_mfma_f32_16x16x32_bf16 v[24:27], v[164:167], v[204:207], v[24:27]
	v_mfma_f32_16x16x32_bf16 v[16:19], v[156:159], v[212:215], v[16:19]
	v_mfma_f32_16x16x32_bf16 v[8:11], v[164:167], v[212:215], v[8:11]
	s_setprio 0
	s_setprio 1
	v_mfma_f32_16x16x32_bf16 v[52:55], v[168:171], v[184:187], v[52:55]
	v_mfma_f32_16x16x32_bf16 v[44:47], v[176:179], v[184:187], v[44:47]
	v_mfma_f32_16x16x32_bf16 v[36:39], v[168:171], v[192:195], v[36:39]
	v_mfma_f32_16x16x32_bf16 v[28:31], v[176:179], v[192:195], v[28:31]
	v_mfma_f32_16x16x32_bf16 v[20:23], v[168:171], v[200:203], v[20:23]
	v_mfma_f32_16x16x32_bf16 v[12:15], v[176:179], v[200:203], v[12:15]
	v_mfma_f32_16x16x32_bf16 v[4:7], v[168:171], v[208:211], v[4:7]
	v_mfma_f32_16x16x32_bf16 v[0:3], v[176:179], v[208:211], v[0:3]
	v_mfma_f32_16x16x32_bf16 v[52:55], v[172:175], v[188:191], v[52:55]
	v_mfma_f32_16x16x32_bf16 v[44:47], v[180:183], v[188:191], v[44:47]
	v_mfma_f32_16x16x32_bf16 v[36:39], v[172:175], v[196:199], v[36:39]
	v_mfma_f32_16x16x32_bf16 v[28:31], v[180:183], v[196:199], v[28:31]
	v_mfma_f32_16x16x32_bf16 v[20:23], v[172:175], v[204:207], v[20:23]
	v_mfma_f32_16x16x32_bf16 v[12:15], v[180:183], v[204:207], v[12:15]
	v_mfma_f32_16x16x32_bf16 v[4:7], v[172:175], v[212:215], v[4:7]
	v_mfma_f32_16x16x32_bf16 v[0:3], v[180:183], v[212:215], v[0:3]
	s_barrier
	s_setprio 0
	s_andn2_b64 vcc, exec, s[34:35]
	s_mov_b64 s[36:37], -1
	s_mov_b64 s[34:35], 0
	s_mov_b64 s[50:51], 0x100
	s_cbranch_vccz .LBB0_377

; #define PG8_STAGE(bufoff, gbase, voff) do { _Pragma("unroll") for (int _i = 0; _i < 2; ++_i) \
;         __builtin_amdgcn_global_load_lds((const unsigned*)((const char*)(gbase) + (voff)[_i]), (PG8_LAS unsigned*)(lds + (bufoff) + ldsw + _i * 8192), 16, 0, 0); } while (0)
; #define PG8_LDA(dst, b, h) do { _Pragma("unroll") for (int m = 0; m < 4; ++m) _Pragma("unroll") for (int k = 0; k < 2; ++k) dst[m][k] = *(const PG8_LAS bf16x8*)(lds + PG8_SA(b, h) + aoff + m * 2048 + k * 1024); } while (0)
; #define PG8_LDB(dst, b, h) do { _Pragma("unroll") for (int n = 0; n < 2; ++n) _Pragma("unroll") for (int k = 0; k < 2; ++k) dst[n][k] = *(const PG8_LAS bf16x8*)(lds + PG8_SB(b, h) + boff + n * 2048 + k * 1024); } while (0)
; #define PG8_WAIT_V(n) asm volatile("s_waitcnt vmcnt(" #n ")" ::: "memory")
; #define PG8_WAIT_L(n) asm volatile("s_waitcnt lgkmcnt(" #n ")" ::: "memory")
; template <class Epi, class Sched>
; __device__ __forceinline__ void gemm_phase(PG8_LAS unsigned char* lds, PG8_LAS unsigned char* xl, const Gemm g, const Sched& S, const Epi& E) {
;     ...
;             const bool last = (t == nt - 2);
;             const char* a1 = cA + (size_t)(t + 1) * kstep;
;             const char* a2 = last ? nA : cA + (size_t)(t + 2) * kstep; const char* b2 = last ? nB : cB + (size_t)(t + 2) * kstep;
;             const char* a3 = a2 + kstep; const char* b3 = b2 + kstep;
;             PG8_LDB(B0, 0, 0); PG8_LDB(B1, 0, 1); PG8_SCHED; PG8_LDA(At, 0, 0); PG8_STAGE(PG8_SA(1, 1), a1 + hsA, voffA);
;             PG8_WAIT_V(8); PG8_WAIT_L(0); PG8_BAR; PG8_MMA(0, 0, At, B0); PG8_MMA(0, 1, At, B1); PG8_BAR; PG8_SCHED;
;             PG8_LDA(At, 0, 1); PG8_STAGE(PG8_SB(0, 0), b2, voffB); PG8_STAGE(PG8_SB(0, 1), b2 + hsB, voffB); PG8_STAGE(PG8_SA(0, 0), a2, voffA);
;             PG8_WAIT_V(8); PG8_WAIT_L(0); PG8_BAR; PG8_MMA(1, 0, At, B0); PG8_MMA(1, 1, At, B1); PG8_BAR; PG8_SCHED;
;             PG8_LDB(B0, 1, 0); PG8_LDB(B1, 1, 1); PG8_SCHED; PG8_LDA(At, 1, 0); PG8_STAGE(PG8_SA(0, 1), a2 + hsA, voffA);
;             PG8_WAIT_V(8); PG8_WAIT_L(0); PG8_BAR; PG8_MMA(0, 0, At, B0); PG8_MMA(0, 1, At, B1); PG8_BAR; PG8_SCHED;
;             PG8_LDA(At, 1, 1); PG8_STAGE(PG8_SB(1, 0), b3, voffB); PG8_STAGE(PG8_SB(1, 1), b3 + hsB, voffB); PG8_STAGE(PG8_SA(1, 0), a3, voffA);
;             PG8_WAIT_V(8); PG8_WAIT_L(0); PG8_BAR; PG8_MMA(1, 0, At, B0); PG8_MMA(1, 1, At, B1); PG8_BAR; PG8_SCHED;
.LBB0_470:
	s_add_u32 s26, s43, s20
	s_addc_u32 s27, s50, s21
	s_and_b64 s[28:29], s[8:9], exec
	s_cselect_b32 s33, s27, s35
	s_cselect_b32 s46, s26, s34
	s_add_u32 s28, s51, s22
	s_addc_u32 s29, s52, s23
	s_and_b64 s[36:37], s[8:9], exec
	s_cselect_b32 s47, s29, s31
	s_cselect_b32 s70, s28, s30
	s_add_u32 s72, s30, 0x100
	s_addc_u32 s73, s31, 0
	s_add_u32 s30, s34, 0x40080
	v_mov_b32_e32 v0, 0
	s_addc_u32 s31, s35, 0
	s_mov_b32 s74, -2
	s_waitcnt lgkmcnt(0)
	ds_read_b128 v[168:171], v156
	ds_read_b128 v[172:175], v156 offset:1024
	ds_read_b128 v[180:183], v156 offset:2048
	ds_read_b128 v[184:187], v156 offset:3072
	ds_read_b128 v[188:191], v157
	ds_read_b128 v[192:195], v157 offset:1024
	ds_read_b128 v[196:199], v157 offset:2048
	ds_read_b128 v[200:203], v157 offset:3072
	s_add_u32 s34, s30, 0xfffc0080
	s_addc_u32 s35, s31, -1
	s_cmp_eq_u32 s74, 12
	s_cselect_b32 s37, s33, s35
	s_cselect_b32 s36, s46, s34
	s_cselect_b32 s35, s47, s73
	s_cselect_b32 s34, s70, s72
	v_lshl_add_u64 v[144:145], s[30:31], 0, v[138:139]
	s_add_i32 m0, s56, 0xc000
	ds_read_b128 v[204:207], v158
	ds_read_b128 v[208:211], v158 offset:1024
	ds_read_b128 v[212:215], v158 offset:2048
	ds_read_b128 v[216:219], v158 offset:3072
	ds_read_b128 v[222:225], v158 offset:4096
	ds_read_b128 v[226:229], v158 offset:5120
	ds_read_b128 v[230:233], v158 offset:6144
	ds_read_b128 v[234:237], v158 offset:7168
	global_load_lds_dwordx4 v[144:145], off
	v_lshl_add_u64 v[144:145], s[30:31], 0, v[136:137]
	s_add_i32 m0, s56, 0xe000
	s_nop 0
	global_load_lds_dwordx4 v[144:145], off
	s_waitcnt vmcnt(8) lgkmcnt(0)
	s_setprio 1
	s_barrier
	v_mfma_f32_16x16x32_bf16 v[124:127], v[168:171], v[204:207], 0
	v_mfma_f32_16x16x32_bf16 v[120:123], v[180:183], v[204:207], 0
	v_mfma_f32_16x16x32_bf16 v[108:111], v[168:171], v[212:215], 0
	v_mfma_f32_16x16x32_bf16 v[104:107], v[180:183], v[212:215], 0
	v_mfma_f32_16x16x32_bf16 v[92:95], v[168:171], v[222:225], 0
	v_mfma_f32_16x16x32_bf16 v[88:91], v[180:183], v[222:225], 0
	v_mfma_f32_16x16x32_bf16 v[76:79], v[168:171], v[230:233], 0
	v_mfma_f32_16x16x32_bf16 v[72:75], v[180:183], v[230:233], 0
	v_mfma_f32_16x16x32_bf16 v[124:127], v[172:175], v[208:211], v[124:127]
	v_mfma_f32_16x16x32_bf16 v[120:123], v[184:187], v[208:211], v[120:123]
	v_mfma_f32_16x16x32_bf16 v[108:111], v[172:175], v[216:219], v[108:111]
	v_mfma_f32_16x16x32_bf16 v[104:107], v[184:187], v[216:219], v[104:107]
	v_mfma_f32_16x16x32_bf16 v[92:95], v[172:175], v[226:229], v[92:95]
	v_mfma_f32_16x16x32_bf16 v[88:91], v[184:187], v[226:229], v[88:91]
	v_mfma_f32_16x16x32_bf16 v[76:79], v[172:175], v[234:237], v[76:79]
	v_mfma_f32_16x16x32_bf16 v[72:75], v[184:187], v[234:237], v[72:75]
	s_setprio 0
	s_setprio 1
	v_mfma_f32_16x16x32_bf16 v[116:119], v[188:191], v[204:207], 0
	v_mfma_f32_16x16x32_bf16 v[112:115], v[196:199], v[204:207], 0
	v_mfma_f32_16x16x32_bf16 v[100:103], v[188:191], v[212:215], 0
	v_mfma_f32_16x16x32_bf16 v[96:99], v[196:199], v[212:215], 0
	v_mfma_f32_16x16x32_bf16 v[84:87], v[188:191], v[222:225], 0
	v_mfma_f32_16x16x32_bf16 v[80:83], v[196:199], v[222:225], 0
	v_mfma_f32_16x16x32_bf16 v[68:71], v[188:191], v[230:233], 0
	v_mfma_f32_16x16x32_bf16 v[64:67], v[196:199], v[230:233], 0
	v_mfma_f32_16x16x32_bf16 v[116:119], v[192:195], v[208:211], v[116:119]
	v_mfma_f32_16x16x32_bf16 v[112:115], v[200:203], v[208:211], v[112:115]
	v_mfma_f32_16x16x32_bf16 v[100:103], v[192:195], v[216:219], v[100:103]
	v_mfma_f32_16x16x32_bf16 v[96:99], v[200:203], v[216:219], v[96:99]
	v_mfma_f32_16x16x32_bf16 v[84:87], v[192:195], v[226:229], v[84:87]
	v_mfma_f32_16x16x32_bf16 v[80:83], v[200:203], v[226:229], v[80:83]
	v_mfma_f32_16x16x32_bf16 v[68:71], v[192:195], v[234:237], v[68:71]
	v_mfma_f32_16x16x32_bf16 v[64:67], v[200:203], v[234:237], v[64:67]
	s_barrier
	s_setprio 0
	s_add_i32 s68, s64, s55
	v_lshl_add_u64 v[144:145], s[34:35], 0, v[130:131]
	s_mov_b32 m0, s68
	ds_read_b128 v[204:207], v158 offset:16384
	ds_read_b128 v[208:211], v158 offset:17408
	ds_read_b128 v[212:215], v158 offset:18432
	ds_read_b128 v[216:219], v158 offset:19456
	ds_read_b128 v[222:225], v158 offset:20480
	ds_read_b128 v[226:229], v158 offset:21504
	ds_read_b128 v[230:233], v158 offset:22528
	ds_read_b128 v[234:237], v158 offset:23552
	global_load_lds_dwordx4 v[144:145], off
	s_add_i32 m0, s68, 0x2000
	s_add_u32 s76, s34, 0x40000
	v_lshl_add_u64 v[176:177], s[34:35], 0, v[134:135]
	s_addc_u32 s77, s35, 0
	s_add_i32 s68, s65, s55
	global_load_lds_dwordx4 v[176:177], off
	v_lshl_add_u64 v[238:239], s[76:77], 0, v[130:131]
	s_mov_b32 m0, s68
	v_lshl_add_u64 v[240:241], s[36:37], 0, v[132:133]
	global_load_lds_dwordx4 v[238:239], off
	v_lshl_add_u64 v[238:239], s[76:77], 0, v[134:135]
	s_add_i32 m0, s68, 0x2000
	s_nop 0
	global_load_lds_dwordx4 v[238:239], off
	v_lshl_add_u64 v[238:239], s[36:37], 0, v[128:129]
	s_mov_b32 m0, s56
	s_nop 0
	global_load_lds_dwordx4 v[238:239], off
	s_mov_b32 m0, s57
	s_nop 0
	global_load_lds_dwordx4 v[240:241], off
	s_waitcnt vmcnt(8) lgkmcnt(0)
	s_setprio 1
	s_barrier
; #define PG8_STAGE(bufoff, gbase, voff) do { _Pragma("unroll") for (int _i = 0; _i < 2; ++_i) \
;         __builtin_amdgcn_global_load_lds((const unsigned*)((const char*)(gbase) + (voff)[_i]), (PG8_LAS unsigned*)(lds + (bufoff) + ldsw + _i * 8192), 16, 0, 0); } while (0)
; #define PG8_LDA(dst, b, h) do { _Pragma("unroll") for (int m = 0; m < 4; ++m) _Pragma("unroll") for (int k = 0; k < 2; ++k) dst[m][k] = *(const PG8_LAS bf16x8*)(lds + PG8_SA(b, h) + aoff + m * 2048 + k * 1024); } while (0)
; #define PG8_LDB(dst, b, h) do { _Pragma("unroll") for (int n = 0; n < 2; ++n) _Pragma("unroll") for (int k = 0; k < 2; ++k) dst[n][k] = *(const PG8_LAS bf16x8*)(lds + PG8_SB(b, h) + boff + n * 2048 + k * 1024); } while (0)
; #define PG8_MMA(ai, bj, At, Bt) do { __builtin_amdgcn_s_setprio(1); _Pragma("unroll") for (int m = 0; m < 4; ++m) _Pragma("unroll") for (int n = 0; n < 2; ++n) _Pragma("unroll") for (int k = 0; k < 2; ++k) \
;         acc[ai][bj][m][n] = __builtin_amdgcn_mfma_f32_16x16x32_bf16(Bt[n][k], At[m][k], acc[ai][bj][m][n], 0, 0, 0); __builtin_amdgcn_s_setprio(0); } while (0)
; #define PG8_WAIT_V(n) asm volatile("s_waitcnt vmcnt(" #n ")" ::: "memory")
; #define PG8_WAIT_L(n) asm volatile("s_waitcnt lgkmcnt(" #n ")" ::: "memory")
; #define PG8_BAR __builtin_amdgcn_s_barrier()
; #define PG8_SCHED __builtin_amdgcn_sched_barrier(0)
; template <class Epi, class Sched>
; __device__ __forceinline__ void gemm_phase(PG8_LAS unsigned char* lds, PG8_LAS unsigned char* xl, const Gemm g, const Sched& S, const Epi& E) {
;     ...
;             PG8_LDA(At, 0, 1); PG8_STAGE(PG8_SB(0, 0), b2, voffB); PG8_STAGE(PG8_SB(0, 1), b2 + hsB, voffB); PG8_STAGE(PG8_SA(0, 0), a2, voffA);
;             PG8_WAIT_V(8); PG8_WAIT_L(0); PG8_BAR; PG8_MMA(1, 0, At, B0); PG8_MMA(1, 1, At, B1); PG8_BAR; PG8_SCHED;
;             PG8_LDB(B0, 1, 0); PG8_LDB(B1, 1, 1); PG8_SCHED; PG8_LDA(At, 1, 0); PG8_STAGE(PG8_SA(0, 1), a2 + hsA, voffA);
;             PG8_WAIT_V(8); PG8_WAIT_L(0); PG8_BAR; PG8_MMA(0, 0, At, B0); PG8_MMA(0, 1, At, B1); PG8_BAR; PG8_SCHED;
;             PG8_LDA(At, 1, 1); PG8_STAGE(PG8_SB(1, 0), b3, voffB); PG8_STAGE(PG8_SB(1, 1), b3 + hsB, voffB); PG8_STAGE(PG8_SA(1, 0), a3, voffA);
;             PG8_WAIT_V(8); PG8_WAIT_L(0); PG8_BAR; PG8_MMA(1, 0, At, B0); PG8_MMA(1, 1, At, B1); PG8_BAR; PG8_SCHED;
	v_mfma_f32_16x16x32_bf16 v[60:63], v[168:171], v[204:207], 0
	v_mfma_f32_16x16x32_bf16 v[56:59], v[180:183], v[204:207], 0
	v_mfma_f32_16x16x32_bf16 v[44:47], v[168:171], v[212:215], 0
	v_mfma_f32_16x16x32_bf16 v[40:43], v[180:183], v[212:215], 0
	v_mfma_f32_16x16x32_bf16 v[28:31], v[168:171], v[222:225], 0
	v_mfma_f32_16x16x32_bf16 v[24:27], v[180:183], v[222:225], 0
	v_mfma_f32_16x16x32_bf16 v[12:15], v[168:171], v[230:233], 0
	v_mfma_f32_16x16x32_bf16 v[8:11], v[180:183], v[230:233], 0
	v_mfma_f32_16x16x32_bf16 v[60:63], v[172:175], v[208:211], v[60:63]
	v_mfma_f32_16x16x32_bf16 v[56:59], v[184:187], v[208:211], v[56:59]
	v_mfma_f32_16x16x32_bf16 v[44:47], v[172:175], v[216:219], v[44:47]
	v_mfma_f32_16x16x32_bf16 v[40:43], v[184:187], v[216:219], v[40:43]
	v_mfma_f32_16x16x32_bf16 v[28:31], v[172:175], v[226:229], v[28:31]
	v_mfma_f32_16x16x32_bf16 v[24:27], v[184:187], v[226:229], v[24:27]
	v_mfma_f32_16x16x32_bf16 v[12:15], v[172:175], v[234:237], v[12:15]
	v_mfma_f32_16x16x32_bf16 v[8:11], v[184:187], v[234:237], v[8:11]
	s_setprio 0
	s_setprio 1
	v_mfma_f32_16x16x32_bf16 v[52:55], v[188:191], v[204:207], 0
	v_mfma_f32_16x16x32_bf16 v[48:51], v[196:199], v[204:207], 0
	v_mfma_f32_16x16x32_bf16 v[36:39], v[188:191], v[212:215], 0
	v_mfma_f32_16x16x32_bf16 v[32:35], v[196:199], v[212:215], 0
	v_mfma_f32_16x16x32_bf16 v[20:23], v[188:191], v[222:225], 0
	v_mfma_f32_16x16x32_bf16 v[16:19], v[196:199], v[222:225], 0
	v_mfma_f32_16x16x32_bf16 v[4:7], v[188:191], v[230:233], 0
	v_mfma_f32_16x16x32_bf16 v[0:3], v[196:199], v[230:233], 0
	v_mfma_f32_16x16x32_bf16 v[52:55], v[192:195], v[208:211], v[52:55]
	v_mfma_f32_16x16x32_bf16 v[48:51], v[200:203], v[208:211], v[48:51]
	v_mfma_f32_16x16x32_bf16 v[36:39], v[192:195], v[216:219], v[36:39]
	v_mfma_f32_16x16x32_bf16 v[32:35], v[200:203], v[216:219], v[32:35]
	v_mfma_f32_16x16x32_bf16 v[20:23], v[192:195], v[226:229], v[20:23]
	v_mfma_f32_16x16x32_bf16 v[16:19], v[200:203], v[226:229], v[16:19]
	v_mfma_f32_16x16x32_bf16 v[4:7], v[192:195], v[234:237], v[4:7]
	v_mfma_f32_16x16x32_bf16 v[0:3], v[200:203], v[234:237], v[0:3]
	s_barrier
	s_setprio 0
	s_add_i32 s68, 0, 0x18000
	v_add_u32_e32 v179, s68, v147
	s_add_i32 s75, 0, 0x1c000
	ds_read_b128 v[168:171], v179
	ds_read_b128 v[172:175], v179 offset:1024
	ds_read_b128 v[180:183], v179 offset:2048
	ds_read_b128 v[184:187], v179 offset:3072
	v_add_u32_e32 v179, s75, v147
	ds_read_b128 v[188:191], v179
	ds_read_b128 v[192:195], v179 offset:1024
	ds_read_b128 v[196:199], v179 offset:2048
	ds_read_b128 v[200:203], v179 offset:3072
	s_add_u32 s36, s36, 0x40000
	s_addc_u32 s37, s37, 0
	s_mov_b32 m0, s58
	v_lshl_add_u64 v[242:243], s[36:37], 0, v[128:129]
	ds_read_b128 v[204:207], v158 offset:32768
	ds_read_b128 v[208:211], v158 offset:33792
	ds_read_b128 v[212:215], v158 offset:34816
	ds_read_b128 v[216:219], v158 offset:35840
	ds_read_b128 v[222:225], v158 offset:36864
	ds_read_b128 v[226:229], v158 offset:37888
	ds_read_b128 v[230:233], v158 offset:38912
	ds_read_b128 v[234:237], v158 offset:39936
	global_load_lds_dwordx4 v[242:243], off
	v_lshl_add_u64 v[242:243], s[36:37], 0, v[132:133]
	s_mov_b32 m0, s59
	s_nop 0
	global_load_lds_dwordx4 v[242:243], off
	s_waitcnt vmcnt(8) lgkmcnt(0)
	s_setprio 1
	s_barrier
	v_mfma_f32_16x16x32_bf16 v[124:127], v[168:171], v[204:207], v[124:127]
	v_mfma_f32_16x16x32_bf16 v[120:123], v[180:183], v[204:207], v[120:123]
	v_mfma_f32_16x16x32_bf16 v[108:111], v[168:171], v[212:215], v[108:111]
	v_mfma_f32_16x16x32_bf16 v[104:107], v[180:183], v[212:215], v[104:107]
	v_mfma_f32_16x16x32_bf16 v[92:95], v[168:171], v[222:225], v[92:95]
	v_mfma_f32_16x16x32_bf16 v[88:91], v[180:183], v[222:225], v[88:91]
	v_mfma_f32_16x16x32_bf16 v[76:79], v[168:171], v[230:233], v[76:79]
	v_mfma_f32_16x16x32_bf16 v[72:75], v[180:183], v[230:233], v[72:75]
	v_mfma_f32_16x16x32_bf16 v[124:127], v[172:175], v[208:211], v[124:127]
	v_mfma_f32_16x16x32_bf16 v[120:123], v[184:187], v[208:211], v[120:123]
	v_mfma_f32_16x16x32_bf16 v[108:111], v[172:175], v[216:219], v[108:111]
	v_mfma_f32_16x16x32_bf16 v[104:107], v[184:187], v[216:219], v[104:107]
	v_mfma_f32_16x16x32_bf16 v[92:95], v[172:175], v[226:229], v[92:95]
	v_mfma_f32_16x16x32_bf16 v[88:91], v[184:187], v[226:229], v[88:91]
	v_mfma_f32_16x16x32_bf16 v[76:79], v[172:175], v[234:237], v[76:79]
	v_mfma_f32_16x16x32_bf16 v[72:75], v[184:187], v[234:237], v[72:75]
	s_setprio 0
	s_setprio 1
	v_mfma_f32_16x16x32_bf16 v[116:119], v[188:191], v[204:207], v[116:119]
	v_mfma_f32_16x16x32_bf16 v[112:115], v[196:199], v[204:207], v[112:115]
	v_mfma_f32_16x16x32_bf16 v[100:103], v[188:191], v[212:215], v[100:103]
	v_mfma_f32_16x16x32_bf16 v[96:99], v[196:199], v[212:215], v[96:99]
	v_mfma_f32_16x16x32_bf16 v[84:87], v[188:191], v[222:225], v[84:87]
	v_mfma_f32_16x16x32_bf16 v[80:83], v[196:199], v[222:225], v[80:83]
	v_mfma_f32_16x16x32_bf16 v[68:71], v[188:191], v[230:233], v[68:71]
	v_mfma_f32_16x16x32_bf16 v[64:67], v[196:199], v[230:233], v[64:67]
	v_mfma_f32_16x16x32_bf16 v[116:119], v[192:195], v[208:211], v[116:119]
	v_mfma_f32_16x16x32_bf16 v[112:115], v[200:203], v[208:211], v[112:115]
	v_mfma_f32_16x16x32_bf16 v[100:103], v[192:195], v[216:219], v[100:103]
	v_mfma_f32_16x16x32_bf16 v[96:99], v[200:203], v[216:219], v[96:99]
	v_mfma_f32_16x16x32_bf16 v[84:87], v[192:195], v[226:229], v[84:87]
	v_mfma_f32_16x16x32_bf16 v[80:83], v[200:203], v[226:229], v[80:83]
	v_mfma_f32_16x16x32_bf16 v[68:71], v[192:195], v[234:237], v[68:71]
	v_mfma_f32_16x16x32_bf16 v[64:67], v[200:203], v[234:237], v[64:67]
	s_barrier
; #define PG8_STAGE(bufoff, gbase, voff) do { _Pragma("unroll") for (int _i = 0; _i < 2; ++_i) \
;         __builtin_amdgcn_global_load_lds((const unsigned*)((const char*)(gbase) + (voff)[_i]), (PG8_LAS unsigned*)(lds + (bufoff) + ldsw + _i * 8192), 16, 0, 0); } while (0)
; #define PG8_LDA(dst, b, h) do { _Pragma("unroll") for (int m = 0; m < 4; ++m) _Pragma("unroll") for (int k = 0; k < 2; ++k) dst[m][k] = *(const PG8_LAS bf16x8*)(lds + PG8_SA(b, h) + aoff + m * 2048 + k * 1024); } while (0)
; #define PG8_LDB(dst, b, h) do { _Pragma("unroll") for (int n = 0; n < 2; ++n) _Pragma("unroll") for (int k = 0; k < 2; ++k) dst[n][k] = *(const PG8_LAS bf16x8*)(lds + PG8_SB(b, h) + boff + n * 2048 + k * 1024); } while (0)
; #define PG8_MMA(ai, bj, At, Bt) do { __builtin_amdgcn_s_setprio(1); _Pragma("unroll") for (int m = 0; m < 4; ++m) _Pragma("unroll") for (int n = 0; n < 2; ++n) _Pragma("unroll") for (int k = 0; k < 2; ++k) \
;         acc[ai][bj][m][n] = __builtin_amdgcn_mfma_f32_16x16x32_bf16(Bt[n][k], At[m][k], acc[ai][bj][m][n], 0, 0, 0); __builtin_amdgcn_s_setprio(0); } while (0)
; #define PG8_WAIT_V(n) asm volatile("s_waitcnt vmcnt(" #n ")" ::: "memory")
; #define PG8_WAIT_L(n) asm volatile("s_waitcnt lgkmcnt(" #n ")" ::: "memory")
; #define PG8_BAR __builtin_amdgcn_s_barrier()
; #define PG8_SCHED __builtin_amdgcn_sched_barrier(0)
; template <class Epi, class Sched>
; __device__ __forceinline__ void gemm_phase(PG8_LAS unsigned char* lds, PG8_LAS unsigned char* xl, const Gemm g, const Sched& S, const Epi& E) {
;     ...
;             PG8_LDB(B0, 1, 0); PG8_LDB(B1, 1, 1); PG8_SCHED; PG8_LDA(At, 1, 0); PG8_STAGE(PG8_SA(0, 1), a2 + hsA, voffA);
;             PG8_WAIT_V(8); PG8_WAIT_L(0); PG8_BAR; PG8_MMA(0, 0, At, B0); PG8_MMA(0, 1, At, B1); PG8_BAR; PG8_SCHED;
;             PG8_LDA(At, 1, 1); PG8_STAGE(PG8_SB(1, 0), b3, voffB); PG8_STAGE(PG8_SB(1, 1), b3 + hsB, voffB); PG8_STAGE(PG8_SA(1, 0), a3, voffA);
;             PG8_WAIT_V(8); PG8_WAIT_L(0); PG8_BAR; PG8_MMA(1, 0, At, B0); PG8_MMA(1, 1, At, B1); PG8_BAR; PG8_SCHED;
;         }
	s_setprio 0
	s_add_i32 s36, s68, s55
	v_lshl_add_u64 v[144:145], v[144:145], 0, s[16:17]
	s_mov_b32 m0, s36
	ds_read_b128 v[204:207], v158 offset:49152
	ds_read_b128 v[208:211], v158 offset:50176
	ds_read_b128 v[212:215], v158 offset:51200
	ds_read_b128 v[216:219], v158 offset:52224
	ds_read_b128 v[222:225], v158 offset:53248
	ds_read_b128 v[226:229], v158 offset:54272
	ds_read_b128 v[230:233], v158 offset:55296
	ds_read_b128 v[234:237], v158 offset:56320
	global_load_lds_dwordx4 v[144:145], off
	s_add_i32 m0, s36, 0x2000
	s_add_u32 s34, s34, 0x40080
	v_lshl_add_u64 v[144:145], v[176:177], 0, s[16:17]
	s_addc_u32 s35, s35, 0
	s_add_i32 s36, s75, s55
	global_load_lds_dwordx4 v[144:145], off
	v_lshl_add_u64 v[144:145], s[34:35], 0, v[130:131]
	s_mov_b32 m0, s36
	s_nop 0
	global_load_lds_dwordx4 v[144:145], off
	v_lshl_add_u64 v[144:145], s[34:35], 0, v[134:135]
	s_add_i32 m0, s36, 0x2000
	s_nop 0
	global_load_lds_dwordx4 v[144:145], off
	v_lshl_add_u64 v[144:145], v[238:239], 0, s[16:17]
	s_mov_b32 m0, s61
	s_nop 0
	global_load_lds_dwordx4 v[144:145], off
	v_lshl_add_u64 v[144:145], v[240:241], 0, s[16:17]
	s_mov_b32 m0, s62
	s_nop 0
	global_load_lds_dwordx4 v[144:145], off
	s_waitcnt vmcnt(8) lgkmcnt(0)
	s_setprio 1
	s_barrier
	v_mfma_f32_16x16x32_bf16 v[60:63], v[168:171], v[204:207], v[60:63]
	v_mfma_f32_16x16x32_bf16 v[56:59], v[180:183], v[204:207], v[56:59]
	v_mfma_f32_16x16x32_bf16 v[44:47], v[168:171], v[212:215], v[44:47]
	v_mfma_f32_16x16x32_bf16 v[40:43], v[180:183], v[212:215], v[40:43]
	v_mfma_f32_16x16x32_bf16 v[28:31], v[168:171], v[222:225], v[28:31]
	v_mfma_f32_16x16x32_bf16 v[24:27], v[180:183], v[222:225], v[24:27]
	v_mfma_f32_16x16x32_bf16 v[12:15], v[168:171], v[230:233], v[12:15]
	v_mfma_f32_16x16x32_bf16 v[8:11], v[180:183], v[230:233], v[8:11]
	v_mfma_f32_16x16x32_bf16 v[60:63], v[172:175], v[208:211], v[60:63]
	v_mfma_f32_16x16x32_bf16 v[56:59], v[184:187], v[208:211], v[56:59]
	v_mfma_f32_16x16x32_bf16 v[44:47], v[172:175], v[216:219], v[44:47]
	v_mfma_f32_16x16x32_bf16 v[40:43], v[184:187], v[216:219], v[40:43]
	v_mfma_f32_16x16x32_bf16 v[28:31], v[172:175], v[226:229], v[28:31]
	v_mfma_f32_16x16x32_bf16 v[24:27], v[184:187], v[226:229], v[24:27]
	v_mfma_f32_16x16x32_bf16 v[12:15], v[172:175], v[234:237], v[12:15]
	v_mfma_f32_16x16x32_bf16 v[8:11], v[184:187], v[234:237], v[8:11]
	s_setprio 0
	s_setprio 1
	v_mfma_f32_16x16x32_bf16 v[52:55], v[188:191], v[204:207], v[52:55]
	s_add_i32 s74, s74, 2
	v_mfma_f32_16x16x32_bf16 v[48:51], v[196:199], v[204:207], v[48:51]
	s_add_u32 s72, s72, 0x100
	v_mfma_f32_16x16x32_bf16 v[36:39], v[188:191], v[212:215], v[36:39]
	s_addc_u32 s73, s73, 0
	v_mfma_f32_16x16x32_bf16 v[32:35], v[196:199], v[212:215], v[32:35]
	s_add_u32 s30, s30, 0x100
	v_mfma_f32_16x16x32_bf16 v[20:23], v[188:191], v[222:225], v[20:23]
	s_addc_u32 s31, s31, 0
	v_mfma_f32_16x16x32_bf16 v[16:19], v[196:199], v[222:225], v[16:19]
	s_cmp_gt_u32 s74, 13
	v_mfma_f32_16x16x32_bf16 v[4:7], v[188:191], v[230:233], v[4:7]
	v_mfma_f32_16x16x32_bf16 v[0:3], v[196:199], v[230:233], v[0:3]
	v_mfma_f32_16x16x32_bf16 v[52:55], v[192:195], v[208:211], v[52:55]
	v_mfma_f32_16x16x32_bf16 v[48:51], v[200:203], v[208:211], v[48:51]
	v_mfma_f32_16x16x32_bf16 v[36:39], v[192:195], v[216:219], v[36:39]
	v_mfma_f32_16x16x32_bf16 v[32:35], v[200:203], v[216:219], v[32:35]
	v_mfma_f32_16x16x32_bf16 v[20:23], v[192:195], v[226:229], v[20:23]
	v_mfma_f32_16x16x32_bf16 v[16:19], v[200:203], v[226:229], v[16:19]
	v_mfma_f32_16x16x32_bf16 v[4:7], v[192:195], v[234:237], v[4:7]
	v_mfma_f32_16x16x32_bf16 v[0:3], v[200:203], v[234:237], v[0:3]
	s_barrier
	s_setprio 0
	s_cbranch_scc1 .Lpeel_after_P3
.LBB0_471:
	ds_read_b128 v[168:171], v156
	ds_read_b128 v[172:175], v156 offset:1024
	ds_read_b128 v[180:183], v156 offset:2048
	ds_read_b128 v[184:187], v156 offset:3072
	ds_read_b128 v[188:191], v157
	ds_read_b128 v[192:195], v157 offset:1024
	ds_read_b128 v[196:199], v157 offset:2048
	ds_read_b128 v[200:203], v157 offset:3072
	s_add_u32 s34, s30, 0xfffc0080
	s_addc_u32 s35, s31, -1
	s_cmp_eq_u32 s74, 12
	s_cselect_b32 s37, s33, s35
	s_cselect_b32 s36, s46, s34
	s_cselect_b32 s35, s47, s73
	s_cselect_b32 s34, s70, s72
	v_lshl_add_u64 v[144:145], s[30:31], 0, v[138:139]
	s_add_i32 m0, s56, 0xc000
	ds_read_b128 v[204:207], v158
	ds_read_b128 v[208:211], v158 offset:1024
	ds_read_b128 v[212:215], v158 offset:2048
	ds_read_b128 v[216:219], v158 offset:3072
	ds_read_b128 v[222:225], v158 offset:4096
	ds_read_b128 v[226:229], v158 offset:5120
	ds_read_b128 v[230:233], v158 offset:6144
	ds_read_b128 v[234:237], v158 offset:7168
	global_load_lds_dwordx4 v[144:145], off
	v_lshl_add_u64 v[144:145], s[30:31], 0, v[136:137]
	s_add_i32 m0, s56, 0xe000
	s_nop 0
	global_load_lds_dwordx4 v[144:145], off
	s_waitcnt vmcnt(8) lgkmcnt(0)
	s_setprio 1
	s_barrier
; #define PG8_STAGE(bufoff, gbase, voff) do { _Pragma("unroll") for (int _i = 0; _i < 2; ++_i) \
;         __builtin_amdgcn_global_load_lds((const unsigned*)((const char*)(gbase) + (voff)[_i]), (PG8_LAS unsigned*)(lds + (bufoff) + ldsw + _i * 8192), 16, 0, 0); } while (0)
; #define PG8_LDA(dst, b, h) do { _Pragma("unroll") for (int m = 0; m < 4; ++m) _Pragma("unroll") for (int k = 0; k < 2; ++k) dst[m][k] = *(const PG8_LAS bf16x8*)(lds + PG8_SA(b, h) + aoff + m * 2048 + k * 1024); } while (0)
; #define PG8_LDB(dst, b, h) do { _Pragma("unroll") for (int n = 0; n < 2; ++n) _Pragma("unroll") for (int k = 0; k < 2; ++k) dst[n][k] = *(const PG8_LAS bf16x8*)(lds + PG8_SB(b, h) + boff + n * 2048 + k * 1024); } while (0)
; #define PG8_MMA(ai, bj, At, Bt) do { __builtin_amdgcn_s_setprio(1); _Pragma("unroll") for (int m = 0; m < 4; ++m) _Pragma("unroll") for (int n = 0; n < 2; ++n) _Pragma("unroll") for (int k = 0; k < 2; ++k) \
;         acc[ai][bj][m][n] = __builtin_amdgcn_mfma_f32_16x16x32_bf16(Bt[n][k], At[m][k], acc[ai][bj][m][n], 0, 0, 0); __builtin_amdgcn_s_setprio(0); } while (0)
; #define PG8_WAIT_V(n) asm volatile("s_waitcnt vmcnt(" #n ")" ::: "memory")
; #define PG8_WAIT_L(n) asm volatile("s_waitcnt lgkmcnt(" #n ")" ::: "memory")
; #define PG8_BAR __builtin_amdgcn_s_barrier()
; #define PG8_SCHED __builtin_amdgcn_sched_barrier(0)
; template <class Epi, class Sched>
; __device__ __forceinline__ void gemm_phase(PG8_LAS unsigned char* lds, PG8_LAS unsigned char* xl, const Gemm g, const Sched& S, const Epi& E) {
;     ...
;             PG8_WAIT_V(8); PG8_WAIT_L(0); PG8_BAR; PG8_MMA(0, 0, At, B0); PG8_MMA(0, 1, At, B1); PG8_BAR; PG8_SCHED;
;             PG8_LDA(At, 0, 1); PG8_STAGE(PG8_SB(0, 0), b2, voffB); PG8_STAGE(PG8_SB(0, 1), b2 + hsB, voffB); PG8_STAGE(PG8_SA(0, 0), a2, voffA);
;             PG8_WAIT_V(8); PG8_WAIT_L(0); PG8_BAR; PG8_MMA(1, 0, At, B0); PG8_MMA(1, 1, At, B1); PG8_BAR; PG8_SCHED;
;             PG8_LDB(B0, 1, 0); PG8_LDB(B1, 1, 1); PG8_SCHED; PG8_LDA(At, 1, 0); PG8_STAGE(PG8_SA(0, 1), a2 + hsA, voffA);
;             PG8_WAIT_V(8); PG8_WAIT_L(0); PG8_BAR; PG8_MMA(0, 0, At, B0); PG8_MMA(0, 1, At, B1); PG8_BAR; PG8_SCHED;
	v_mfma_f32_16x16x32_bf16 v[124:127], v[168:171], v[204:207], v[124:127]
	v_mfma_f32_16x16x32_bf16 v[120:123], v[180:183], v[204:207], v[120:123]
	v_mfma_f32_16x16x32_bf16 v[108:111], v[168:171], v[212:215], v[108:111]
	v_mfma_f32_16x16x32_bf16 v[104:107], v[180:183], v[212:215], v[104:107]
	v_mfma_f32_16x16x32_bf16 v[92:95], v[168:171], v[222:225], v[92:95]
	v_mfma_f32_16x16x32_bf16 v[88:91], v[180:183], v[222:225], v[88:91]
	v_mfma_f32_16x16x32_bf16 v[76:79], v[168:171], v[230:233], v[76:79]
	v_mfma_f32_16x16x32_bf16 v[72:75], v[180:183], v[230:233], v[72:75]
	v_mfma_f32_16x16x32_bf16 v[124:127], v[172:175], v[208:211], v[124:127]
	v_mfma_f32_16x16x32_bf16 v[120:123], v[184:187], v[208:211], v[120:123]
	v_mfma_f32_16x16x32_bf16 v[108:111], v[172:175], v[216:219], v[108:111]
	v_mfma_f32_16x16x32_bf16 v[104:107], v[184:187], v[216:219], v[104:107]
	v_mfma_f32_16x16x32_bf16 v[92:95], v[172:175], v[226:229], v[92:95]
	v_mfma_f32_16x16x32_bf16 v[88:91], v[184:187], v[226:229], v[88:91]
	v_mfma_f32_16x16x32_bf16 v[76:79], v[172:175], v[234:237], v[76:79]
	v_mfma_f32_16x16x32_bf16 v[72:75], v[184:187], v[234:237], v[72:75]
	s_setprio 0
	s_setprio 1
	v_mfma_f32_16x16x32_bf16 v[116:119], v[188:191], v[204:207], v[116:119]
	v_mfma_f32_16x16x32_bf16 v[112:115], v[196:199], v[204:207], v[112:115]
	v_mfma_f32_16x16x32_bf16 v[100:103], v[188:191], v[212:215], v[100:103]
	v_mfma_f32_16x16x32_bf16 v[96:99], v[196:199], v[212:215], v[96:99]
	v_mfma_f32_16x16x32_bf16 v[84:87], v[188:191], v[222:225], v[84:87]
	v_mfma_f32_16x16x32_bf16 v[80:83], v[196:199], v[222:225], v[80:83]
	v_mfma_f32_16x16x32_bf16 v[68:71], v[188:191], v[230:233], v[68:71]
	v_mfma_f32_16x16x32_bf16 v[64:67], v[196:199], v[230:233], v[64:67]
	v_mfma_f32_16x16x32_bf16 v[116:119], v[192:195], v[208:211], v[116:119]
	v_mfma_f32_16x16x32_bf16 v[112:115], v[200:203], v[208:211], v[112:115]
	v_mfma_f32_16x16x32_bf16 v[100:103], v[192:195], v[216:219], v[100:103]
	v_mfma_f32_16x16x32_bf16 v[96:99], v[200:203], v[216:219], v[96:99]
	v_mfma_f32_16x16x32_bf16 v[84:87], v[192:195], v[226:229], v[84:87]
	v_mfma_f32_16x16x32_bf16 v[80:83], v[200:203], v[226:229], v[80:83]
	v_mfma_f32_16x16x32_bf16 v[68:71], v[192:195], v[234:237], v[68:71]
	v_mfma_f32_16x16x32_bf16 v[64:67], v[200:203], v[234:237], v[64:67]
	s_barrier
	s_setprio 0
	s_add_i32 s68, s64, s55
	v_lshl_add_u64 v[144:145], s[34:35], 0, v[130:131]
	s_mov_b32 m0, s68
	ds_read_b128 v[204:207], v158 offset:16384
	ds_read_b128 v[208:211], v158 offset:17408
	ds_read_b128 v[212:215], v158 offset:18432
	ds_read_b128 v[216:219], v158 offset:19456
	ds_read_b128 v[222:225], v158 offset:20480
	ds_read_b128 v[226:229], v158 offset:21504
	ds_read_b128 v[230:233], v158 offset:22528
	ds_read_b128 v[234:237], v158 offset:23552
	global_load_lds_dwordx4 v[144:145], off
	s_add_i32 m0, s68, 0x2000
	s_add_u32 s76, s34, 0x40000
	v_lshl_add_u64 v[176:177], s[34:35], 0, v[134:135]
	s_addc_u32 s77, s35, 0
	s_add_i32 s68, s65, s55
	global_load_lds_dwordx4 v[176:177], off
	v_lshl_add_u64 v[238:239], s[76:77], 0, v[130:131]
	s_mov_b32 m0, s68
	v_lshl_add_u64 v[240:241], s[36:37], 0, v[132:133]
	global_load_lds_dwordx4 v[238:239], off
	v_lshl_add_u64 v[238:239], s[76:77], 0, v[134:135]
	s_add_i32 m0, s68, 0x2000
	s_nop 0
	global_load_lds_dwordx4 v[238:239], off
	v_lshl_add_u64 v[238:239], s[36:37], 0, v[128:129]
	s_mov_b32 m0, s56
	s_nop 0
	global_load_lds_dwordx4 v[238:239], off
	s_mov_b32 m0, s57
	s_nop 0
	global_load_lds_dwordx4 v[240:241], off
	s_waitcnt vmcnt(8) lgkmcnt(0)
	s_setprio 1
	s_barrier
	v_mfma_f32_16x16x32_bf16 v[60:63], v[168:171], v[204:207], v[60:63]
	v_mfma_f32_16x16x32_bf16 v[56:59], v[180:183], v[204:207], v[56:59]
	v_mfma_f32_16x16x32_bf16 v[44:47], v[168:171], v[212:215], v[44:47]
	v_mfma_f32_16x16x32_bf16 v[40:43], v[180:183], v[212:215], v[40:43]
	v_mfma_f32_16x16x32_bf16 v[28:31], v[168:171], v[222:225], v[28:31]
	v_mfma_f32_16x16x32_bf16 v[24:27], v[180:183], v[222:225], v[24:27]
	v_mfma_f32_16x16x32_bf16 v[12:15], v[168:171], v[230:233], v[12:15]
	v_mfma_f32_16x16x32_bf16 v[8:11], v[180:183], v[230:233], v[8:11]
	v_mfma_f32_16x16x32_bf16 v[60:63], v[172:175], v[208:211], v[60:63]
	v_mfma_f32_16x16x32_bf16 v[56:59], v[184:187], v[208:211], v[56:59]
	v_mfma_f32_16x16x32_bf16 v[44:47], v[172:175], v[216:219], v[44:47]
	v_mfma_f32_16x16x32_bf16 v[40:43], v[184:187], v[216:219], v[40:43]
	v_mfma_f32_16x16x32_bf16 v[28:31], v[172:175], v[226:229], v[28:31]
	v_mfma_f32_16x16x32_bf16 v[24:27], v[184:187], v[226:229], v[24:27]
	v_mfma_f32_16x16x32_bf16 v[12:15], v[172:175], v[234:237], v[12:15]
	v_mfma_f32_16x16x32_bf16 v[8:11], v[184:187], v[234:237], v[8:11]
	s_setprio 0
	s_setprio 1
	v_mfma_f32_16x16x32_bf16 v[52:55], v[188:191], v[204:207], v[52:55]
	v_mfma_f32_16x16x32_bf16 v[48:51], v[196:199], v[204:207], v[48:51]
	v_mfma_f32_16x16x32_bf16 v[36:39], v[188:191], v[212:215], v[36:39]
	v_mfma_f32_16x16x32_bf16 v[32:35], v[196:199], v[212:215], v[32:35]
	v_mfma_f32_16x16x32_bf16 v[20:23], v[188:191], v[222:225], v[20:23]
	v_mfma_f32_16x16x32_bf16 v[16:19], v[196:199], v[222:225], v[16:19]
	v_mfma_f32_16x16x32_bf16 v[4:7], v[188:191], v[230:233], v[4:7]
	v_mfma_f32_16x16x32_bf16 v[0:3], v[196:199], v[230:233], v[0:3]
	v_mfma_f32_16x16x32_bf16 v[52:55], v[192:195], v[208:211], v[52:55]
	v_mfma_f32_16x16x32_bf16 v[48:51], v[200:203], v[208:211], v[48:51]
	v_mfma_f32_16x16x32_bf16 v[36:39], v[192:195], v[216:219], v[36:39]
	v_mfma_f32_16x16x32_bf16 v[32:35], v[200:203], v[216:219], v[32:35]
	v_mfma_f32_16x16x32_bf16 v[20:23], v[192:195], v[226:229], v[20:23]
	v_mfma_f32_16x16x32_bf16 v[16:19], v[200:203], v[226:229], v[16:19]
	v_mfma_f32_16x16x32_bf16 v[4:7], v[192:195], v[234:237], v[4:7]
	v_mfma_f32_16x16x32_bf16 v[0:3], v[200:203], v[234:237], v[0:3]
	s_barrier
; #define PG8_STAGE(bufoff, gbase, voff) do { _Pragma("unroll") for (int _i = 0; _i < 2; ++_i) \
;         __builtin_amdgcn_global_load_lds((const unsigned*)((const char*)(gbase) + (voff)[_i]), (PG8_LAS unsigned*)(lds + (bufoff) + ldsw + _i * 8192), 16, 0, 0); } while (0)
; #define PG8_LDA(dst, b, h) do { _Pragma("unroll") for (int m = 0; m < 4; ++m) _Pragma("unroll") for (int k = 0; k < 2; ++k) dst[m][k] = *(const PG8_LAS bf16x8*)(lds + PG8_SA(b, h) + aoff + m * 2048 + k * 1024); } while (0)
; #define PG8_LDB(dst, b, h) do { _Pragma("unroll") for (int n = 0; n < 2; ++n) _Pragma("unroll") for (int k = 0; k < 2; ++k) dst[n][k] = *(const PG8_LAS bf16x8*)(lds + PG8_SB(b, h) + boff + n * 2048 + k * 1024); } while (0)
; #define PG8_MMA(ai, bj, At, Bt) do { __builtin_amdgcn_s_setprio(1); _Pragma("unroll") for (int m = 0; m < 4; ++m) _Pragma("unroll") for (int n = 0; n < 2; ++n) _Pragma("unroll") for (int k = 0; k < 2; ++k) \
;         acc[ai][bj][m][n] = __builtin_amdgcn_mfma_f32_16x16x32_bf16(Bt[n][k], At[m][k], acc[ai][bj][m][n], 0, 0, 0); __builtin_amdgcn_s_setprio(0); } while (0)
; #define PG8_WAIT_V(n) asm volatile("s_waitcnt vmcnt(" #n ")" ::: "memory")
; #define PG8_WAIT_L(n) asm volatile("s_waitcnt lgkmcnt(" #n ")" ::: "memory")
; #define PG8_BAR __builtin_amdgcn_s_barrier()
; #define PG8_SCHED __builtin_amdgcn_sched_barrier(0)
; template <class Epi, class Sched>
; __device__ __forceinline__ void gemm_phase(PG8_LAS unsigned char* lds, PG8_LAS unsigned char* xl, const Gemm g, const Sched& S, const Epi& E) {
;     ...
;             PG8_LDB(B0, 1, 0); PG8_LDB(B1, 1, 1); PG8_SCHED; PG8_LDA(At, 1, 0); PG8_STAGE(PG8_SA(0, 1), a2 + hsA, voffA);
;             PG8_WAIT_V(8); PG8_WAIT_L(0); PG8_BAR; PG8_MMA(0, 0, At, B0); PG8_MMA(0, 1, At, B1); PG8_BAR; PG8_SCHED;
	s_setprio 0
	s_add_i32 s68, 0, 0x18000
	v_add_u32_e32 v179, s68, v147
	s_add_i32 s75, 0, 0x1c000
	ds_read_b128 v[168:171], v179
	ds_read_b128 v[172:175], v179 offset:1024
	ds_read_b128 v[180:183], v179 offset:2048
	ds_read_b128 v[184:187], v179 offset:3072
	v_add_u32_e32 v179, s75, v147
	ds_read_b128 v[188:191], v179
	ds_read_b128 v[192:195], v179 offset:1024
	ds_read_b128 v[196:199], v179 offset:2048
	ds_read_b128 v[200:203], v179 offset:3072
	s_add_u32 s36, s36, 0x40000
	s_addc_u32 s37, s37, 0
	s_mov_b32 m0, s58
	v_lshl_add_u64 v[242:243], s[36:37], 0, v[128:129]
	ds_read_b128 v[204:207], v158 offset:32768
	ds_read_b128 v[208:211], v158 offset:33792
	ds_read_b128 v[212:215], v158 offset:34816
	ds_read_b128 v[216:219], v158 offset:35840
	ds_read_b128 v[222:225], v158 offset:36864
	ds_read_b128 v[226:229], v158 offset:37888
	ds_read_b128 v[230:233], v158 offset:38912
	ds_read_b128 v[234:237], v158 offset:39936
	global_load_lds_dwordx4 v[242:243], off
	v_lshl_add_u64 v[242:243], s[36:37], 0, v[132:133]
	s_mov_b32 m0, s59
	s_nop 0
	global_load_lds_dwordx4 v[242:243], off
	s_waitcnt vmcnt(8) lgkmcnt(0)
	s_setprio 1
	s_barrier
	v_mfma_f32_16x16x32_bf16 v[124:127], v[168:171], v[204:207], v[124:127]
	v_mfma_f32_16x16x32_bf16 v[120:123], v[180:183], v[204:207], v[120:123]
	v_mfma_f32_16x16x32_bf16 v[108:111], v[168:171], v[212:215], v[108:111]
	v_mfma_f32_16x16x32_bf16 v[104:107], v[180:183], v[212:215], v[104:107]
	v_mfma_f32_16x16x32_bf16 v[92:95], v[168:171], v[222:225], v[92:95]
	v_mfma_f32_16x16x32_bf16 v[88:91], v[180:183], v[222:225], v[88:91]
	v_mfma_f32_16x16x32_bf16 v[76:79], v[168:171], v[230:233], v[76:79]
	v_mfma_f32_16x16x32_bf16 v[72:75], v[180:183], v[230:233], v[72:75]
	v_mfma_f32_16x16x32_bf16 v[124:127], v[172:175], v[208:211], v[124:127]
	v_mfma_f32_16x16x32_bf16 v[120:123], v[184:187], v[208:211], v[120:123]
	v_mfma_f32_16x16x32_bf16 v[108:111], v[172:175], v[216:219], v[108:111]
	v_mfma_f32_16x16x32_bf16 v[104:107], v[184:187], v[216:219], v[104:107]
	v_mfma_f32_16x16x32_bf16 v[92:95], v[172:175], v[226:229], v[92:95]
	v_mfma_f32_16x16x32_bf16 v[88:91], v[184:187], v[226:229], v[88:91]
	v_mfma_f32_16x16x32_bf16 v[76:79], v[172:175], v[234:237], v[76:79]
	v_mfma_f32_16x16x32_bf16 v[72:75], v[184:187], v[234:237], v[72:75]
	s_setprio 0
	s_setprio 1
	v_mfma_f32_16x16x32_bf16 v[116:119], v[188:191], v[204:207], v[116:119]
	v_mfma_f32_16x16x32_bf16 v[112:115], v[196:199], v[204:207], v[112:115]
	v_mfma_f32_16x16x32_bf16 v[100:103], v[188:191], v[212:215], v[100:103]
	v_mfma_f32_16x16x32_bf16 v[96:99], v[196:199], v[212:215], v[96:99]
	v_mfma_f32_16x16x32_bf16 v[84:87], v[188:191], v[222:225], v[84:87]
	v_mfma_f32_16x16x32_bf16 v[80:83], v[196:199], v[222:225], v[80:83]
	v_mfma_f32_16x16x32_bf16 v[68:71], v[188:191], v[230:233], v[68:71]
	v_mfma_f32_16x16x32_bf16 v[64:67], v[196:199], v[230:233], v[64:67]
	v_mfma_f32_16x16x32_bf16 v[116:119], v[192:195], v[208:211], v[116:119]
	v_mfma_f32_16x16x32_bf16 v[112:115], v[200:203], v[208:211], v[112:115]
	v_mfma_f32_16x16x32_bf16 v[100:103], v[192:195], v[216:219], v[100:103]
	v_mfma_f32_16x16x32_bf16 v[96:99], v[200:203], v[216:219], v[96:99]
	v_mfma_f32_16x16x32_bf16 v[84:87], v[192:195], v[226:229], v[84:87]
	v_mfma_f32_16x16x32_bf16 v[80:83], v[200:203], v[226:229], v[80:83]
	v_mfma_f32_16x16x32_bf16 v[68:71], v[192:195], v[234:237], v[68:71]
	v_mfma_f32_16x16x32_bf16 v[64:67], v[200:203], v[234:237], v[64:67]
	s_barrier
; #define PG8_STAGE(bufoff, gbase, voff) do { _Pragma("unroll") for (int _i = 0; _i < 2; ++_i) \
;         __builtin_amdgcn_global_load_lds((const unsigned*)((const char*)(gbase) + (voff)[_i]), (PG8_LAS unsigned*)(lds + (bufoff) + ldsw + _i * 8192), 16, 0, 0); } while (0)
; #define PG8_LDA(dst, b, h) do { _Pragma("unroll") for (int m = 0; m < 4; ++m) _Pragma("unroll") for (int k = 0; k < 2; ++k) dst[m][k] = *(const PG8_LAS bf16x8*)(lds + PG8_SA(b, h) + aoff + m * 2048 + k * 1024); } while (0)
; #define PG8_MMA(ai, bj, At, Bt) do { __builtin_amdgcn_s_setprio(1); _Pragma("unroll") for (int m = 0; m < 4; ++m) _Pragma("unroll") for (int n = 0; n < 2; ++n) _Pragma("unroll") for (int k = 0; k < 2; ++k) \
;         acc[ai][bj][m][n] = __builtin_amdgcn_mfma_f32_16x16x32_bf16(Bt[n][k], At[m][k], acc[ai][bj][m][n], 0, 0, 0); __builtin_amdgcn_s_setprio(0); } while (0)
; #define PG8_WAIT_V(n) asm volatile("s_waitcnt vmcnt(" #n ")" ::: "memory")
; #define PG8_WAIT_L(n) asm volatile("s_waitcnt lgkmcnt(" #n ")" ::: "memory")
; #define PG8_BAR __builtin_amdgcn_s_barrier()
; #define PG8_SCHED __builtin_amdgcn_sched_barrier(0)
; template <class Epi, class Sched>
; __device__ __forceinline__ void gemm_phase(PG8_LAS unsigned char* lds, PG8_LAS unsigned char* xl, const Gemm g, const Sched& S, const Epi& E) {
;     ...
;             PG8_LDA(At, 1, 1); PG8_STAGE(PG8_SB(1, 0), b3, voffB); PG8_STAGE(PG8_SB(1, 1), b3 + hsB, voffB); PG8_STAGE(PG8_SA(1, 0), a3, voffA);
;             PG8_WAIT_V(8); PG8_WAIT_L(0); PG8_BAR; PG8_MMA(1, 0, At, B0); PG8_MMA(1, 1, At, B1); PG8_BAR; PG8_SCHED;
;         }
	s_setprio 0
	s_add_i32 s36, s68, s55
	v_lshl_add_u64 v[144:145], v[144:145], 0, s[16:17]
	s_mov_b32 m0, s36
	ds_read_b128 v[204:207], v158 offset:49152
	ds_read_b128 v[208:211], v158 offset:50176
	ds_read_b128 v[212:215], v158 offset:51200
	ds_read_b128 v[216:219], v158 offset:52224
	ds_read_b128 v[222:225], v158 offset:53248
	ds_read_b128 v[226:229], v158 offset:54272
	ds_read_b128 v[230:233], v158 offset:55296
	ds_read_b128 v[234:237], v158 offset:56320
	global_load_lds_dwordx4 v[144:145], off
	s_add_i32 m0, s36, 0x2000
	s_add_u32 s34, s34, 0x40080
	v_lshl_add_u64 v[144:145], v[176:177], 0, s[16:17]
	s_addc_u32 s35, s35, 0
	s_add_i32 s36, s75, s55
	global_load_lds_dwordx4 v[144:145], off
	v_lshl_add_u64 v[144:145], s[34:35], 0, v[130:131]
	s_mov_b32 m0, s36
	s_nop 0
	global_load_lds_dwordx4 v[144:145], off
	v_lshl_add_u64 v[144:145], s[34:35], 0, v[134:135]
	s_add_i32 m0, s36, 0x2000
	s_nop 0
	global_load_lds_dwordx4 v[144:145], off
	v_lshl_add_u64 v[144:145], v[238:239], 0, s[16:17]
	s_mov_b32 m0, s61
	s_nop 0
	global_load_lds_dwordx4 v[144:145], off
	v_lshl_add_u64 v[144:145], v[240:241], 0, s[16:17]
	s_mov_b32 m0, s62
	s_nop 0
	global_load_lds_dwordx4 v[144:145], off
	s_waitcnt vmcnt(8) lgkmcnt(0)
	s_setprio 1
	s_barrier
	v_mfma_f32_16x16x32_bf16 v[60:63], v[168:171], v[204:207], v[60:63]
	v_mfma_f32_16x16x32_bf16 v[56:59], v[180:183], v[204:207], v[56:59]
	v_mfma_f32_16x16x32_bf16 v[44:47], v[168:171], v[212:215], v[44:47]
	v_mfma_f32_16x16x32_bf16 v[40:43], v[180:183], v[212:215], v[40:43]
	v_mfma_f32_16x16x32_bf16 v[28:31], v[168:171], v[222:225], v[28:31]
	v_mfma_f32_16x16x32_bf16 v[24:27], v[180:183], v[222:225], v[24:27]
	v_mfma_f32_16x16x32_bf16 v[12:15], v[168:171], v[230:233], v[12:15]
	v_mfma_f32_16x16x32_bf16 v[8:11], v[180:183], v[230:233], v[8:11]
	v_mfma_f32_16x16x32_bf16 v[60:63], v[172:175], v[208:211], v[60:63]
	v_mfma_f32_16x16x32_bf16 v[56:59], v[184:187], v[208:211], v[56:59]
	v_mfma_f32_16x16x32_bf16 v[44:47], v[172:175], v[216:219], v[44:47]
	v_mfma_f32_16x16x32_bf16 v[40:43], v[184:187], v[216:219], v[40:43]
	v_mfma_f32_16x16x32_bf16 v[28:31], v[172:175], v[226:229], v[28:31]
	v_mfma_f32_16x16x32_bf16 v[24:27], v[184:187], v[226:229], v[24:27]
	v_mfma_f32_16x16x32_bf16 v[12:15], v[172:175], v[234:237], v[12:15]
	v_mfma_f32_16x16x32_bf16 v[8:11], v[184:187], v[234:237], v[8:11]
	s_setprio 0
	s_setprio 1
	v_mfma_f32_16x16x32_bf16 v[52:55], v[188:191], v[204:207], v[52:55]
	s_add_i32 s74, s74, 2
	v_mfma_f32_16x16x32_bf16 v[48:51], v[196:199], v[204:207], v[48:51]
	s_add_u32 s72, s72, 0x100
	v_mfma_f32_16x16x32_bf16 v[36:39], v[188:191], v[212:215], v[36:39]
	s_addc_u32 s73, s73, 0
	v_mfma_f32_16x16x32_bf16 v[32:35], v[196:199], v[212:215], v[32:35]
	s_add_u32 s30, s30, 0x100
	v_mfma_f32_16x16x32_bf16 v[20:23], v[188:191], v[222:225], v[20:23]
	s_addc_u32 s31, s31, 0
	v_mfma_f32_16x16x32_bf16 v[16:19], v[196:199], v[222:225], v[16:19]
	s_cmp_gt_u32 s74, 13
	v_mfma_f32_16x16x32_bf16 v[4:7], v[188:191], v[230:233], v[4:7]
	v_mfma_f32_16x16x32_bf16 v[0:3], v[196:199], v[230:233], v[0:3]
	v_mfma_f32_16x16x32_bf16 v[52:55], v[192:195], v[208:211], v[52:55]
	v_mfma_f32_16x16x32_bf16 v[48:51], v[200:203], v[208:211], v[48:51]
	v_mfma_f32_16x16x32_bf16 v[36:39], v[192:195], v[216:219], v[36:39]
	v_mfma_f32_16x16x32_bf16 v[32:35], v[200:203], v[216:219], v[32:35]
	v_mfma_f32_16x16x32_bf16 v[20:23], v[192:195], v[226:229], v[20:23]
	v_mfma_f32_16x16x32_bf16 v[16:19], v[200:203], v[226:229], v[16:19]
	v_mfma_f32_16x16x32_bf16 v[4:7], v[192:195], v[234:237], v[4:7]
	v_mfma_f32_16x16x32_bf16 v[0:3], v[200:203], v[234:237], v[0:3]
	s_barrier
	s_setprio 0
	s_cbranch_scc0 .LBB0_471

; #define PG8_STAGE(bufoff, gbase, voff) do { _Pragma("unroll") for (int _i = 0; _i < 2; ++_i) \
;         __builtin_amdgcn_global_load_lds((const unsigned*)((const char*)(gbase) + (voff)[_i]), (PG8_LAS unsigned*)(lds + (bufoff) + ldsw + _i * 8192), 16, 0, 0); } while (0)
; #define PG8_LDA(dst, b, h) do { _Pragma("unroll") for (int m = 0; m < 4; ++m) _Pragma("unroll") for (int k = 0; k < 2; ++k) dst[m][k] = *(const PG8_LAS bf16x8*)(lds + PG8_SA(b, h) + aoff + m * 2048 + k * 1024); } while (0)
; #define PG8_LDB(dst, b, h) do { _Pragma("unroll") for (int n = 0; n < 2; ++n) _Pragma("unroll") for (int k = 0; k < 2; ++k) dst[n][k] = *(const PG8_LAS bf16x8*)(lds + PG8_SB(b, h) + boff + n * 2048 + k * 1024); } while (0)
; #define PG8_WAIT_V(n) asm volatile("s_waitcnt vmcnt(" #n ")" ::: "memory")
; #define PG8_WAIT_L(n) asm volatile("s_waitcnt lgkmcnt(" #n ")" ::: "memory")
; template <class Epi, class Sched>
; __device__ __forceinline__ void gemm_phase(PG8_LAS unsigned char* lds, PG8_LAS unsigned char* xl, const Gemm g, const Sched& S, const Epi& E) {
;     ...
;             const bool last = (t == nt - 2);
;             const char* a1 = cA + (size_t)(t + 1) * kstep;
;             const char* a2 = last ? nA : cA + (size_t)(t + 2) * kstep; const char* b2 = last ? nB : cB + (size_t)(t + 2) * kstep;
;             const char* a3 = a2 + kstep; const char* b3 = b2 + kstep;
;             PG8_LDB(B0, 0, 0); PG8_LDB(B1, 0, 1); PG8_SCHED; PG8_LDA(At, 0, 0); PG8_STAGE(PG8_SA(1, 1), a1 + hsA, voffA);
;             PG8_WAIT_V(8); PG8_WAIT_L(0); PG8_BAR; PG8_MMA(0, 0, At, B0); PG8_MMA(0, 1, At, B1); PG8_BAR; PG8_SCHED;
;             PG8_LDA(At, 0, 1); PG8_STAGE(PG8_SB(0, 0), b2, voffB); PG8_STAGE(PG8_SB(0, 1), b2 + hsB, voffB); PG8_STAGE(PG8_SA(0, 0), a2, voffA);
;             PG8_WAIT_V(8); PG8_WAIT_L(0); PG8_BAR; PG8_MMA(1, 0, At, B0); PG8_MMA(1, 1, At, B1); PG8_BAR; PG8_SCHED;
;             PG8_LDB(B0, 1, 0); PG8_LDB(B1, 1, 1); PG8_SCHED; PG8_LDA(At, 1, 0); PG8_STAGE(PG8_SA(0, 1), a2 + hsA, voffA);
;             PG8_WAIT_V(8); PG8_WAIT_L(0); PG8_BAR; PG8_MMA(0, 0, At, B0); PG8_MMA(0, 1, At, B1); PG8_BAR; PG8_SCHED;
;             PG8_LDA(At, 1, 1); PG8_STAGE(PG8_SB(1, 0), b3, voffB); PG8_STAGE(PG8_SB(1, 1), b3 + hsB, voffB); PG8_STAGE(PG8_SA(1, 0), a3, voffA);
;             PG8_WAIT_V(8); PG8_WAIT_L(0); PG8_BAR; PG8_MMA(1, 0, At, B0); PG8_MMA(1, 1, At, B1); PG8_BAR; PG8_SCHED;
.LBB0_576:
	s_add_u32 s34, s43, s28
	s_addc_u32 s35, s55, s29
	s_and_b64 s[36:37], s[10:11], exec
	s_cselect_b32 s13, s35, s51
	s_cselect_b32 s33, s34, s50
	s_add_u32 s36, s56, s30
	s_addc_u32 s37, s57, s31
	s_and_b64 s[46:47], s[10:11], exec
	s_cselect_b32 s46, s37, s3
	s_cselect_b32 s47, s36, s2
	s_add_u32 s79, s2, 0x100
	s_addc_u32 s80, s3, 0
	s_add_u32 s2, s50, 0x40080
	v_mov_b32_e32 v0, 0
	s_addc_u32 s3, s51, 0
	s_mov_b32 s81, -2
	ds_read_b128 v[146:149], v181
	ds_read_b128 v[150:153], v181 offset:1024
	ds_read_b128 v[188:191], v181 offset:2048
	ds_read_b128 v[192:195], v181 offset:3072
	ds_read_b128 v[196:199], v182
	ds_read_b128 v[200:203], v182 offset:1024
	ds_read_b128 v[204:207], v182 offset:2048
	ds_read_b128 v[208:211], v182 offset:3072
	s_add_u32 s50, s2, 0xfffc0080
	s_addc_u32 s51, s3, -1
	s_cmp_eq_u32 s81, 12
	s_cselect_b32 s53, s13, s51
	s_cselect_b32 s52, s33, s50
	s_cselect_b32 s51, s46, s80
	s_cselect_b32 s50, s47, s79
	v_lshl_add_u64 v[246:247], s[2:3], 0, v[140:141]
	s_add_i32 m0, s60, 0xc000
	ds_read_b128 v[212:215], v183
	ds_read_b128 v[216:219], v183 offset:1024
	ds_read_b128 v[222:225], v183 offset:2048
	ds_read_b128 v[226:229], v183 offset:3072
	ds_read_b128 v[230:233], v183 offset:4096
	ds_read_b128 v[234:237], v183 offset:5120
	ds_read_b128 v[238:241], v183 offset:6144
	ds_read_b128 v[242:245], v183 offset:7168
	global_load_lds_dwordx4 v[246:247], off
	v_lshl_add_u64 v[246:247], s[2:3], 0, v[138:139]
	s_add_i32 m0, s60, 0xe000
	s_nop 0
	global_load_lds_dwordx4 v[246:247], off
	s_waitcnt vmcnt(8) lgkmcnt(0)
	s_setprio 1
	s_barrier
	v_mfma_f32_16x16x32_bf16 v[124:127], v[146:149], v[212:215], 0
	v_mfma_f32_16x16x32_bf16 v[120:123], v[188:191], v[212:215], 0
	v_mfma_f32_16x16x32_bf16 v[108:111], v[146:149], v[222:225], 0
	v_mfma_f32_16x16x32_bf16 v[104:107], v[188:191], v[222:225], 0
	v_mfma_f32_16x16x32_bf16 v[92:95], v[146:149], v[230:233], 0
	v_mfma_f32_16x16x32_bf16 v[88:91], v[188:191], v[230:233], 0
	v_mfma_f32_16x16x32_bf16 v[76:79], v[146:149], v[238:241], 0
	v_mfma_f32_16x16x32_bf16 v[72:75], v[188:191], v[238:241], 0
	v_mfma_f32_16x16x32_bf16 v[124:127], v[150:153], v[216:219], v[124:127]
	v_mfma_f32_16x16x32_bf16 v[120:123], v[192:195], v[216:219], v[120:123]
	v_mfma_f32_16x16x32_bf16 v[108:111], v[150:153], v[226:229], v[108:111]
	v_mfma_f32_16x16x32_bf16 v[104:107], v[192:195], v[226:229], v[104:107]
	v_mfma_f32_16x16x32_bf16 v[92:95], v[150:153], v[234:237], v[92:95]
	v_mfma_f32_16x16x32_bf16 v[88:91], v[192:195], v[234:237], v[88:91]
	v_mfma_f32_16x16x32_bf16 v[76:79], v[150:153], v[242:245], v[76:79]
	v_mfma_f32_16x16x32_bf16 v[72:75], v[192:195], v[242:245], v[72:75]
	s_setprio 0
	s_setprio 1
	v_mfma_f32_16x16x32_bf16 v[116:119], v[196:199], v[212:215], 0
	v_mfma_f32_16x16x32_bf16 v[112:115], v[204:207], v[212:215], 0
	v_mfma_f32_16x16x32_bf16 v[100:103], v[196:199], v[222:225], 0
	v_mfma_f32_16x16x32_bf16 v[96:99], v[204:207], v[222:225], 0
	v_mfma_f32_16x16x32_bf16 v[84:87], v[196:199], v[230:233], 0
	v_mfma_f32_16x16x32_bf16 v[80:83], v[204:207], v[230:233], 0
	v_mfma_f32_16x16x32_bf16 v[68:71], v[196:199], v[238:241], 0
	v_mfma_f32_16x16x32_bf16 v[64:67], v[204:207], v[238:241], 0
	v_mfma_f32_16x16x32_bf16 v[116:119], v[200:203], v[216:219], v[116:119]
	v_mfma_f32_16x16x32_bf16 v[112:115], v[208:211], v[216:219], v[112:115]
	v_mfma_f32_16x16x32_bf16 v[100:103], v[200:203], v[226:229], v[100:103]
	v_mfma_f32_16x16x32_bf16 v[96:99], v[208:211], v[226:229], v[96:99]
	v_mfma_f32_16x16x32_bf16 v[84:87], v[200:203], v[234:237], v[84:87]
	v_mfma_f32_16x16x32_bf16 v[80:83], v[208:211], v[234:237], v[80:83]
	v_mfma_f32_16x16x32_bf16 v[68:71], v[200:203], v[242:245], v[68:71]
	v_mfma_f32_16x16x32_bf16 v[64:67], v[208:211], v[242:245], v[64:67]
	s_barrier
	s_setprio 0
	s_add_i32 s68, s72, s59
	v_lshl_add_u64 v[246:247], s[50:51], 0, v[130:131]
	s_mov_b32 m0, s68
	ds_read_b128 v[212:215], v183 offset:16384
	ds_read_b128 v[216:219], v183 offset:17408
	ds_read_b128 v[222:225], v183 offset:18432
	ds_read_b128 v[226:229], v183 offset:19456
	ds_read_b128 v[230:233], v183 offset:20480
	ds_read_b128 v[234:237], v183 offset:21504
	ds_read_b128 v[238:241], v183 offset:22528
	ds_read_b128 v[242:245], v183 offset:23552
	global_load_lds_dwordx4 v[246:247], off
	s_add_i32 m0, s68, 0x2000
	s_add_u32 s82, s50, 0x40000
	v_lshl_add_u64 v[248:249], s[50:51], 0, v[134:135]
	s_addc_u32 s83, s51, 0
	s_add_i32 s68, s73, s59
	global_load_lds_dwordx4 v[248:249], off
	v_lshl_add_u64 v[250:251], s[82:83], 0, v[130:131]
	s_mov_b32 m0, s68
	v_lshl_add_u64 v[252:253], s[52:53], 0, v[132:133]
	global_load_lds_dwordx4 v[250:251], off
	v_lshl_add_u64 v[250:251], s[82:83], 0, v[134:135]
	s_add_i32 m0, s68, 0x2000
	s_nop 0
	global_load_lds_dwordx4 v[250:251], off
	v_lshl_add_u64 v[250:251], s[52:53], 0, v[128:129]
	s_mov_b32 m0, s60
	s_nop 0
	global_load_lds_dwordx4 v[250:251], off
	s_mov_b32 m0, s61
	s_nop 0
	global_load_lds_dwordx4 v[252:253], off
	s_waitcnt vmcnt(8) lgkmcnt(0)
	s_setprio 1
	s_barrier
; #define PG8_STAGE(bufoff, gbase, voff) do { _Pragma("unroll") for (int _i = 0; _i < 2; ++_i) \
;         __builtin_amdgcn_global_load_lds((const unsigned*)((const char*)(gbase) + (voff)[_i]), (PG8_LAS unsigned*)(lds + (bufoff) + ldsw + _i * 8192), 16, 0, 0); } while (0)
; #define PG8_LDA(dst, b, h) do { _Pragma("unroll") for (int m = 0; m < 4; ++m) _Pragma("unroll") for (int k = 0; k < 2; ++k) dst[m][k] = *(const PG8_LAS bf16x8*)(lds + PG8_SA(b, h) + aoff + m * 2048 + k * 1024); } while (0)
; #define PG8_LDB(dst, b, h) do { _Pragma("unroll") for (int n = 0; n < 2; ++n) _Pragma("unroll") for (int k = 0; k < 2; ++k) dst[n][k] = *(const PG8_LAS bf16x8*)(lds + PG8_SB(b, h) + boff + n * 2048 + k * 1024); } while (0)
; #define PG8_MMA(ai, bj, At, Bt) do { __builtin_amdgcn_s_setprio(1); _Pragma("unroll") for (int m = 0; m < 4; ++m) _Pragma("unroll") for (int n = 0; n < 2; ++n) _Pragma("unroll") for (int k = 0; k < 2; ++k) \
;         acc[ai][bj][m][n] = __builtin_amdgcn_mfma_f32_16x16x32_bf16(Bt[n][k], At[m][k], acc[ai][bj][m][n], 0, 0, 0); __builtin_amdgcn_s_setprio(0); } while (0)
; #define PG8_WAIT_V(n) asm volatile("s_waitcnt vmcnt(" #n ")" ::: "memory")
; #define PG8_WAIT_L(n) asm volatile("s_waitcnt lgkmcnt(" #n ")" ::: "memory")
; #define PG8_BAR __builtin_amdgcn_s_barrier()
; #define PG8_SCHED __builtin_amdgcn_sched_barrier(0)
; template <class Epi, class Sched>
; __device__ __forceinline__ void gemm_phase(PG8_LAS unsigned char* lds, PG8_LAS unsigned char* xl, const Gemm g, const Sched& S, const Epi& E) {
;     ...
;             PG8_LDA(At, 0, 1); PG8_STAGE(PG8_SB(0, 0), b2, voffB); PG8_STAGE(PG8_SB(0, 1), b2 + hsB, voffB); PG8_STAGE(PG8_SA(0, 0), a2, voffA);
;             PG8_WAIT_V(8); PG8_WAIT_L(0); PG8_BAR; PG8_MMA(1, 0, At, B0); PG8_MMA(1, 1, At, B1); PG8_BAR; PG8_SCHED;
;             PG8_LDB(B0, 1, 0); PG8_LDB(B1, 1, 1); PG8_SCHED; PG8_LDA(At, 1, 0); PG8_STAGE(PG8_SA(0, 1), a2 + hsA, voffA);
;             PG8_WAIT_V(8); PG8_WAIT_L(0); PG8_BAR; PG8_MMA(0, 0, At, B0); PG8_MMA(0, 1, At, B1); PG8_BAR; PG8_SCHED;
	v_mfma_f32_16x16x32_bf16 v[60:63], v[146:149], v[212:215], 0
	v_mfma_f32_16x16x32_bf16 v[56:59], v[188:191], v[212:215], 0
	v_mfma_f32_16x16x32_bf16 v[44:47], v[146:149], v[222:225], 0
	v_mfma_f32_16x16x32_bf16 v[40:43], v[188:191], v[222:225], 0
	v_mfma_f32_16x16x32_bf16 v[28:31], v[146:149], v[230:233], 0
	v_mfma_f32_16x16x32_bf16 v[24:27], v[188:191], v[230:233], 0
	v_mfma_f32_16x16x32_bf16 v[12:15], v[146:149], v[238:241], 0
	v_mfma_f32_16x16x32_bf16 v[8:11], v[188:191], v[238:241], 0
	v_mfma_f32_16x16x32_bf16 v[60:63], v[150:153], v[216:219], v[60:63]
	v_mfma_f32_16x16x32_bf16 v[56:59], v[192:195], v[216:219], v[56:59]
	v_mfma_f32_16x16x32_bf16 v[44:47], v[150:153], v[226:229], v[44:47]
	v_mfma_f32_16x16x32_bf16 v[40:43], v[192:195], v[226:229], v[40:43]
	v_mfma_f32_16x16x32_bf16 v[28:31], v[150:153], v[234:237], v[28:31]
	v_mfma_f32_16x16x32_bf16 v[24:27], v[192:195], v[234:237], v[24:27]
	v_mfma_f32_16x16x32_bf16 v[12:15], v[150:153], v[242:245], v[12:15]
	v_mfma_f32_16x16x32_bf16 v[8:11], v[192:195], v[242:245], v[8:11]
	s_setprio 0
	s_setprio 1
	v_mfma_f32_16x16x32_bf16 v[52:55], v[196:199], v[212:215], 0
	v_mfma_f32_16x16x32_bf16 v[48:51], v[204:207], v[212:215], 0
	v_mfma_f32_16x16x32_bf16 v[36:39], v[196:199], v[222:225], 0
	v_mfma_f32_16x16x32_bf16 v[32:35], v[204:207], v[222:225], 0
	v_mfma_f32_16x16x32_bf16 v[20:23], v[196:199], v[230:233], 0
	v_mfma_f32_16x16x32_bf16 v[16:19], v[204:207], v[230:233], 0
	v_mfma_f32_16x16x32_bf16 v[4:7], v[196:199], v[238:241], 0
	v_mfma_f32_16x16x32_bf16 v[0:3], v[204:207], v[238:241], 0
	v_mfma_f32_16x16x32_bf16 v[52:55], v[200:203], v[216:219], v[52:55]
	v_mfma_f32_16x16x32_bf16 v[48:51], v[208:211], v[216:219], v[48:51]
	v_mfma_f32_16x16x32_bf16 v[36:39], v[200:203], v[226:229], v[36:39]
	v_mfma_f32_16x16x32_bf16 v[32:35], v[208:211], v[226:229], v[32:35]
	v_mfma_f32_16x16x32_bf16 v[20:23], v[200:203], v[234:237], v[20:23]
	v_mfma_f32_16x16x32_bf16 v[16:19], v[208:211], v[234:237], v[16:19]
	v_mfma_f32_16x16x32_bf16 v[4:7], v[200:203], v[242:245], v[4:7]
	v_mfma_f32_16x16x32_bf16 v[0:3], v[208:211], v[242:245], v[0:3]
	s_barrier
	s_setprio 0
	s_add_i32 s68, 0, 0x18000
	v_add_u32_e32 v184, s68, v156
	s_add_i32 s82, 0, 0x1c000
	ds_read_b128 v[146:149], v184
	ds_read_b128 v[150:153], v184 offset:1024
	ds_read_b128 v[188:191], v184 offset:2048
	ds_read_b128 v[192:195], v184 offset:3072
	v_add_u32_e32 v184, s82, v156
	ds_read_b128 v[196:199], v184
	ds_read_b128 v[200:203], v184 offset:1024
	ds_read_b128 v[204:207], v184 offset:2048
	ds_read_b128 v[208:211], v184 offset:3072
	s_add_u32 s52, s52, 0x40000
	s_addc_u32 s53, s53, 0
	s_mov_b32 m0, s62
	v_lshl_add_u64 v[184:185], s[52:53], 0, v[128:129]
	ds_read_b128 v[212:215], v183 offset:32768
	ds_read_b128 v[216:219], v183 offset:33792
	ds_read_b128 v[222:225], v183 offset:34816
	ds_read_b128 v[226:229], v183 offset:35840
	ds_read_b128 v[230:233], v183 offset:36864
	ds_read_b128 v[234:237], v183 offset:37888
	ds_read_b128 v[238:241], v183 offset:38912
	ds_read_b128 v[242:245], v183 offset:39936
	global_load_lds_dwordx4 v[184:185], off
	v_lshl_add_u64 v[184:185], s[52:53], 0, v[132:133]
	s_mov_b32 m0, s63
	s_nop 0
	global_load_lds_dwordx4 v[184:185], off
	s_waitcnt vmcnt(8) lgkmcnt(0)
	s_setprio 1
	s_barrier
	v_mfma_f32_16x16x32_bf16 v[124:127], v[146:149], v[212:215], v[124:127]
	v_mfma_f32_16x16x32_bf16 v[120:123], v[188:191], v[212:215], v[120:123]
	v_mfma_f32_16x16x32_bf16 v[108:111], v[146:149], v[222:225], v[108:111]
	v_mfma_f32_16x16x32_bf16 v[104:107], v[188:191], v[222:225], v[104:107]
	v_mfma_f32_16x16x32_bf16 v[92:95], v[146:149], v[230:233], v[92:95]
	v_mfma_f32_16x16x32_bf16 v[88:91], v[188:191], v[230:233], v[88:91]
	v_mfma_f32_16x16x32_bf16 v[76:79], v[146:149], v[238:241], v[76:79]
	v_mfma_f32_16x16x32_bf16 v[72:75], v[188:191], v[238:241], v[72:75]
	v_mfma_f32_16x16x32_bf16 v[124:127], v[150:153], v[216:219], v[124:127]
	v_mfma_f32_16x16x32_bf16 v[120:123], v[192:195], v[216:219], v[120:123]
	v_mfma_f32_16x16x32_bf16 v[108:111], v[150:153], v[226:229], v[108:111]
	v_mfma_f32_16x16x32_bf16 v[104:107], v[192:195], v[226:229], v[104:107]
	v_mfma_f32_16x16x32_bf16 v[92:95], v[150:153], v[234:237], v[92:95]
	v_mfma_f32_16x16x32_bf16 v[88:91], v[192:195], v[234:237], v[88:91]
	v_mfma_f32_16x16x32_bf16 v[76:79], v[150:153], v[242:245], v[76:79]
	v_mfma_f32_16x16x32_bf16 v[72:75], v[192:195], v[242:245], v[72:75]
	s_setprio 0
	s_setprio 1
	v_mfma_f32_16x16x32_bf16 v[116:119], v[196:199], v[212:215], v[116:119]
	v_mfma_f32_16x16x32_bf16 v[112:115], v[204:207], v[212:215], v[112:115]
	v_mfma_f32_16x16x32_bf16 v[100:103], v[196:199], v[222:225], v[100:103]
	v_mfma_f32_16x16x32_bf16 v[96:99], v[204:207], v[222:225], v[96:99]
	v_mfma_f32_16x16x32_bf16 v[84:87], v[196:199], v[230:233], v[84:87]
	v_mfma_f32_16x16x32_bf16 v[80:83], v[204:207], v[230:233], v[80:83]
	v_mfma_f32_16x16x32_bf16 v[68:71], v[196:199], v[238:241], v[68:71]
	v_mfma_f32_16x16x32_bf16 v[64:67], v[204:207], v[238:241], v[64:67]
	v_mfma_f32_16x16x32_bf16 v[116:119], v[200:203], v[216:219], v[116:119]
	v_mfma_f32_16x16x32_bf16 v[112:115], v[208:211], v[216:219], v[112:115]
	v_mfma_f32_16x16x32_bf16 v[100:103], v[200:203], v[226:229], v[100:103]
	v_mfma_f32_16x16x32_bf16 v[96:99], v[208:211], v[226:229], v[96:99]
	v_mfma_f32_16x16x32_bf16 v[84:87], v[200:203], v[234:237], v[84:87]
	v_mfma_f32_16x16x32_bf16 v[80:83], v[208:211], v[234:237], v[80:83]
	v_mfma_f32_16x16x32_bf16 v[68:71], v[200:203], v[242:245], v[68:71]
	v_mfma_f32_16x16x32_bf16 v[64:67], v[208:211], v[242:245], v[64:67]
	s_barrier
; #define PG8_STAGE(bufoff, gbase, voff) do { _Pragma("unroll") for (int _i = 0; _i < 2; ++_i) \
;         __builtin_amdgcn_global_load_lds((const unsigned*)((const char*)(gbase) + (voff)[_i]), (PG8_LAS unsigned*)(lds + (bufoff) + ldsw + _i * 8192), 16, 0, 0); } while (0)
; #define PG8_LDA(dst, b, h) do { _Pragma("unroll") for (int m = 0; m < 4; ++m) _Pragma("unroll") for (int k = 0; k < 2; ++k) dst[m][k] = *(const PG8_LAS bf16x8*)(lds + PG8_SA(b, h) + aoff + m * 2048 + k * 1024); } while (0)
; #define PG8_LDB(dst, b, h) do { _Pragma("unroll") for (int n = 0; n < 2; ++n) _Pragma("unroll") for (int k = 0; k < 2; ++k) dst[n][k] = *(const PG8_LAS bf16x8*)(lds + PG8_SB(b, h) + boff + n * 2048 + k * 1024); } while (0)
; #define PG8_MMA(ai, bj, At, Bt) do { __builtin_amdgcn_s_setprio(1); _Pragma("unroll") for (int m = 0; m < 4; ++m) _Pragma("unroll") for (int n = 0; n < 2; ++n) _Pragma("unroll") for (int k = 0; k < 2; ++k) \
;         acc[ai][bj][m][n] = __builtin_amdgcn_mfma_f32_16x16x32_bf16(Bt[n][k], At[m][k], acc[ai][bj][m][n], 0, 0, 0); __builtin_amdgcn_s_setprio(0); } while (0)
; #define PG8_WAIT_V(n) asm volatile("s_waitcnt vmcnt(" #n ")" ::: "memory")
; #define PG8_WAIT_L(n) asm volatile("s_waitcnt lgkmcnt(" #n ")" ::: "memory")
; #define PG8_BAR __builtin_amdgcn_s_barrier()
; #define PG8_SCHED __builtin_amdgcn_sched_barrier(0)
; template <class Epi, class Sched>
; __device__ __forceinline__ void gemm_phase(PG8_LAS unsigned char* lds, PG8_LAS unsigned char* xl, const Gemm g, const Sched& S, const Epi& E) {
;     ...
;             PG8_LDB(B0, 1, 0); PG8_LDB(B1, 1, 1); PG8_SCHED; PG8_LDA(At, 1, 0); PG8_STAGE(PG8_SA(0, 1), a2 + hsA, voffA);
;             PG8_WAIT_V(8); PG8_WAIT_L(0); PG8_BAR; PG8_MMA(0, 0, At, B0); PG8_MMA(0, 1, At, B1); PG8_BAR; PG8_SCHED;
;             PG8_LDA(At, 1, 1); PG8_STAGE(PG8_SB(1, 0), b3, voffB); PG8_STAGE(PG8_SB(1, 1), b3 + hsB, voffB); PG8_STAGE(PG8_SA(1, 0), a3, voffA);
;             PG8_WAIT_V(8); PG8_WAIT_L(0); PG8_BAR; PG8_MMA(1, 0, At, B0); PG8_MMA(1, 1, At, B1); PG8_BAR; PG8_SCHED;
;         }
	s_setprio 0
	s_add_i32 s52, s68, s59
	v_lshl_add_u64 v[184:185], v[246:247], 0, s[20:21]
	s_mov_b32 m0, s52
	ds_read_b128 v[212:215], v183 offset:49152
	ds_read_b128 v[216:219], v183 offset:50176
	ds_read_b128 v[222:225], v183 offset:51200
	ds_read_b128 v[226:229], v183 offset:52224
	ds_read_b128 v[230:233], v183 offset:53248
	ds_read_b128 v[234:237], v183 offset:54272
	ds_read_b128 v[238:241], v183 offset:55296
	ds_read_b128 v[242:245], v183 offset:56320
	global_load_lds_dwordx4 v[184:185], off
	s_add_i32 m0, s52, 0x2000
	s_add_u32 s50, s50, 0x40080
	v_lshl_add_u64 v[184:185], v[248:249], 0, s[20:21]
	s_addc_u32 s51, s51, 0
	s_add_i32 s52, s82, s59
	global_load_lds_dwordx4 v[184:185], off
	v_lshl_add_u64 v[184:185], s[50:51], 0, v[130:131]
	s_mov_b32 m0, s52
	s_nop 0
	global_load_lds_dwordx4 v[184:185], off
	v_lshl_add_u64 v[184:185], s[50:51], 0, v[134:135]
	s_add_i32 m0, s52, 0x2000
	s_nop 0
	global_load_lds_dwordx4 v[184:185], off
	v_lshl_add_u64 v[184:185], v[250:251], 0, s[20:21]
	s_mov_b32 m0, s65
	s_nop 0
	global_load_lds_dwordx4 v[184:185], off
	v_lshl_add_u64 v[184:185], v[252:253], 0, s[20:21]
	s_mov_b32 m0, s66
	s_nop 0
	global_load_lds_dwordx4 v[184:185], off
	s_waitcnt vmcnt(8) lgkmcnt(0)
	s_setprio 1
	s_barrier
	v_mfma_f32_16x16x32_bf16 v[60:63], v[146:149], v[212:215], v[60:63]
	v_mfma_f32_16x16x32_bf16 v[56:59], v[188:191], v[212:215], v[56:59]
	v_mfma_f32_16x16x32_bf16 v[44:47], v[146:149], v[222:225], v[44:47]
	v_mfma_f32_16x16x32_bf16 v[40:43], v[188:191], v[222:225], v[40:43]
	v_mfma_f32_16x16x32_bf16 v[28:31], v[146:149], v[230:233], v[28:31]
	v_mfma_f32_16x16x32_bf16 v[24:27], v[188:191], v[230:233], v[24:27]
	v_mfma_f32_16x16x32_bf16 v[12:15], v[146:149], v[238:241], v[12:15]
	v_mfma_f32_16x16x32_bf16 v[8:11], v[188:191], v[238:241], v[8:11]
	v_mfma_f32_16x16x32_bf16 v[60:63], v[150:153], v[216:219], v[60:63]
	v_mfma_f32_16x16x32_bf16 v[56:59], v[192:195], v[216:219], v[56:59]
	v_mfma_f32_16x16x32_bf16 v[44:47], v[150:153], v[226:229], v[44:47]
	v_mfma_f32_16x16x32_bf16 v[40:43], v[192:195], v[226:229], v[40:43]
	v_mfma_f32_16x16x32_bf16 v[28:31], v[150:153], v[234:237], v[28:31]
	v_mfma_f32_16x16x32_bf16 v[24:27], v[192:195], v[234:237], v[24:27]
	v_mfma_f32_16x16x32_bf16 v[12:15], v[150:153], v[242:245], v[12:15]
	v_mfma_f32_16x16x32_bf16 v[8:11], v[192:195], v[242:245], v[8:11]
	s_setprio 0
	s_setprio 1
	v_mfma_f32_16x16x32_bf16 v[52:55], v[196:199], v[212:215], v[52:55]
	s_add_i32 s81, s81, 2
	v_mfma_f32_16x16x32_bf16 v[48:51], v[204:207], v[212:215], v[48:51]
	s_add_u32 s79, s79, 0x100
	v_mfma_f32_16x16x32_bf16 v[36:39], v[196:199], v[222:225], v[36:39]
	s_addc_u32 s80, s80, 0
	v_mfma_f32_16x16x32_bf16 v[32:35], v[204:207], v[222:225], v[32:35]
	s_add_u32 s2, s2, 0x100
	v_mfma_f32_16x16x32_bf16 v[20:23], v[196:199], v[230:233], v[20:23]
	s_addc_u32 s3, s3, 0
	v_mfma_f32_16x16x32_bf16 v[16:19], v[204:207], v[230:233], v[16:19]
	s_cmp_gt_u32 s81, 13
	v_mfma_f32_16x16x32_bf16 v[4:7], v[196:199], v[238:241], v[4:7]
	v_mfma_f32_16x16x32_bf16 v[0:3], v[204:207], v[238:241], v[0:3]
	v_mfma_f32_16x16x32_bf16 v[52:55], v[200:203], v[216:219], v[52:55]
	v_mfma_f32_16x16x32_bf16 v[48:51], v[208:211], v[216:219], v[48:51]
	v_mfma_f32_16x16x32_bf16 v[36:39], v[200:203], v[226:229], v[36:39]
	v_mfma_f32_16x16x32_bf16 v[32:35], v[208:211], v[226:229], v[32:35]
	v_mfma_f32_16x16x32_bf16 v[20:23], v[200:203], v[234:237], v[20:23]
	v_mfma_f32_16x16x32_bf16 v[16:19], v[208:211], v[234:237], v[16:19]
	v_mfma_f32_16x16x32_bf16 v[4:7], v[200:203], v[242:245], v[4:7]
	v_mfma_f32_16x16x32_bf16 v[0:3], v[208:211], v[242:245], v[0:3]
	s_barrier
	s_setprio 0
	s_cbranch_scc1 .Lpeel_after_P4
.LBB0_577:
	ds_read_b128 v[146:149], v181
	ds_read_b128 v[150:153], v181 offset:1024
	ds_read_b128 v[188:191], v181 offset:2048
	ds_read_b128 v[192:195], v181 offset:3072
	ds_read_b128 v[196:199], v182
	ds_read_b128 v[200:203], v182 offset:1024
	ds_read_b128 v[204:207], v182 offset:2048
	ds_read_b128 v[208:211], v182 offset:3072
	s_add_u32 s50, s2, 0xfffc0080
	s_addc_u32 s51, s3, -1
	s_cmp_eq_u32 s81, 12
	s_cselect_b32 s53, s13, s51
	s_cselect_b32 s52, s33, s50
	s_cselect_b32 s51, s46, s80
	s_cselect_b32 s50, s47, s79
	v_lshl_add_u64 v[246:247], s[2:3], 0, v[140:141]
	s_add_i32 m0, s60, 0xc000
	ds_read_b128 v[212:215], v183
	ds_read_b128 v[216:219], v183 offset:1024
	ds_read_b128 v[222:225], v183 offset:2048
	ds_read_b128 v[226:229], v183 offset:3072
	ds_read_b128 v[230:233], v183 offset:4096
	ds_read_b128 v[234:237], v183 offset:5120
	ds_read_b128 v[238:241], v183 offset:6144
	ds_read_b128 v[242:245], v183 offset:7168
	global_load_lds_dwordx4 v[246:247], off
	v_lshl_add_u64 v[246:247], s[2:3], 0, v[138:139]
	s_add_i32 m0, s60, 0xe000
	s_nop 0
	global_load_lds_dwordx4 v[246:247], off
	s_waitcnt vmcnt(8) lgkmcnt(0)
	s_setprio 1
	s_barrier
; #define PG8_STAGE(bufoff, gbase, voff) do { _Pragma("unroll") for (int _i = 0; _i < 2; ++_i) \
;         __builtin_amdgcn_global_load_lds((const unsigned*)((const char*)(gbase) + (voff)[_i]), (PG8_LAS unsigned*)(lds + (bufoff) + ldsw + _i * 8192), 16, 0, 0); } while (0)
; #define PG8_LDA(dst, b, h) do { _Pragma("unroll") for (int m = 0; m < 4; ++m) _Pragma("unroll") for (int k = 0; k < 2; ++k) dst[m][k] = *(const PG8_LAS bf16x8*)(lds + PG8_SA(b, h) + aoff + m * 2048 + k * 1024); } while (0)
; #define PG8_LDB(dst, b, h) do { _Pragma("unroll") for (int n = 0; n < 2; ++n) _Pragma("unroll") for (int k = 0; k < 2; ++k) dst[n][k] = *(const PG8_LAS bf16x8*)(lds + PG8_SB(b, h) + boff + n * 2048 + k * 1024); } while (0)
; #define PG8_MMA(ai, bj, At, Bt) do { __builtin_amdgcn_s_setprio(1); _Pragma("unroll") for (int m = 0; m < 4; ++m) _Pragma("unroll") for (int n = 0; n < 2; ++n) _Pragma("unroll") for (int k = 0; k < 2; ++k) \
;         acc[ai][bj][m][n] = __builtin_amdgcn_mfma_f32_16x16x32_bf16(Bt[n][k], At[m][k], acc[ai][bj][m][n], 0, 0, 0); __builtin_amdgcn_s_setprio(0); } while (0)
; #define PG8_WAIT_V(n) asm volatile("s_waitcnt vmcnt(" #n ")" ::: "memory")
; #define PG8_WAIT_L(n) asm volatile("s_waitcnt lgkmcnt(" #n ")" ::: "memory")
; #define PG8_BAR __builtin_amdgcn_s_barrier()
; #define PG8_SCHED __builtin_amdgcn_sched_barrier(0)
; template <class Epi, class Sched>
; __device__ __forceinline__ void gemm_phase(PG8_LAS unsigned char* lds, PG8_LAS unsigned char* xl, const Gemm g, const Sched& S, const Epi& E) {
;     ...
;             PG8_WAIT_V(8); PG8_WAIT_L(0); PG8_BAR; PG8_MMA(0, 0, At, B0); PG8_MMA(0, 1, At, B1); PG8_BAR; PG8_SCHED;
;             PG8_LDA(At, 0, 1); PG8_STAGE(PG8_SB(0, 0), b2, voffB); PG8_STAGE(PG8_SB(0, 1), b2 + hsB, voffB); PG8_STAGE(PG8_SA(0, 0), a2, voffA);
;             PG8_WAIT_V(8); PG8_WAIT_L(0); PG8_BAR; PG8_MMA(1, 0, At, B0); PG8_MMA(1, 1, At, B1); PG8_BAR; PG8_SCHED;
;             PG8_LDB(B0, 1, 0); PG8_LDB(B1, 1, 1); PG8_SCHED; PG8_LDA(At, 1, 0); PG8_STAGE(PG8_SA(0, 1), a2 + hsA, voffA);
;             PG8_WAIT_V(8); PG8_WAIT_L(0); PG8_BAR; PG8_MMA(0, 0, At, B0); PG8_MMA(0, 1, At, B1); PG8_BAR; PG8_SCHED;
	v_mfma_f32_16x16x32_bf16 v[124:127], v[146:149], v[212:215], v[124:127]
	v_mfma_f32_16x16x32_bf16 v[120:123], v[188:191], v[212:215], v[120:123]
	v_mfma_f32_16x16x32_bf16 v[108:111], v[146:149], v[222:225], v[108:111]
	v_mfma_f32_16x16x32_bf16 v[104:107], v[188:191], v[222:225], v[104:107]
	v_mfma_f32_16x16x32_bf16 v[92:95], v[146:149], v[230:233], v[92:95]
	v_mfma_f32_16x16x32_bf16 v[88:91], v[188:191], v[230:233], v[88:91]
	v_mfma_f32_16x16x32_bf16 v[76:79], v[146:149], v[238:241], v[76:79]
	v_mfma_f32_16x16x32_bf16 v[72:75], v[188:191], v[238:241], v[72:75]
	v_mfma_f32_16x16x32_bf16 v[124:127], v[150:153], v[216:219], v[124:127]
	v_mfma_f32_16x16x32_bf16 v[120:123], v[192:195], v[216:219], v[120:123]
	v_mfma_f32_16x16x32_bf16 v[108:111], v[150:153], v[226:229], v[108:111]
	v_mfma_f32_16x16x32_bf16 v[104:107], v[192:195], v[226:229], v[104:107]
	v_mfma_f32_16x16x32_bf16 v[92:95], v[150:153], v[234:237], v[92:95]
	v_mfma_f32_16x16x32_bf16 v[88:91], v[192:195], v[234:237], v[88:91]
	v_mfma_f32_16x16x32_bf16 v[76:79], v[150:153], v[242:245], v[76:79]
	v_mfma_f32_16x16x32_bf16 v[72:75], v[192:195], v[242:245], v[72:75]
	s_setprio 0
	s_setprio 1
	v_mfma_f32_16x16x32_bf16 v[116:119], v[196:199], v[212:215], v[116:119]
	v_mfma_f32_16x16x32_bf16 v[112:115], v[204:207], v[212:215], v[112:115]
	v_mfma_f32_16x16x32_bf16 v[100:103], v[196:199], v[222:225], v[100:103]
	v_mfma_f32_16x16x32_bf16 v[96:99], v[204:207], v[222:225], v[96:99]
	v_mfma_f32_16x16x32_bf16 v[84:87], v[196:199], v[230:233], v[84:87]
	v_mfma_f32_16x16x32_bf16 v[80:83], v[204:207], v[230:233], v[80:83]
	v_mfma_f32_16x16x32_bf16 v[68:71], v[196:199], v[238:241], v[68:71]
	v_mfma_f32_16x16x32_bf16 v[64:67], v[204:207], v[238:241], v[64:67]
	v_mfma_f32_16x16x32_bf16 v[116:119], v[200:203], v[216:219], v[116:119]
	v_mfma_f32_16x16x32_bf16 v[112:115], v[208:211], v[216:219], v[112:115]
	v_mfma_f32_16x16x32_bf16 v[100:103], v[200:203], v[226:229], v[100:103]
	v_mfma_f32_16x16x32_bf16 v[96:99], v[208:211], v[226:229], v[96:99]
	v_mfma_f32_16x16x32_bf16 v[84:87], v[200:203], v[234:237], v[84:87]
	v_mfma_f32_16x16x32_bf16 v[80:83], v[208:211], v[234:237], v[80:83]
	v_mfma_f32_16x16x32_bf16 v[68:71], v[200:203], v[242:245], v[68:71]
	v_mfma_f32_16x16x32_bf16 v[64:67], v[208:211], v[242:245], v[64:67]
	s_barrier
	s_setprio 0
	s_add_i32 s68, s72, s59
	v_lshl_add_u64 v[246:247], s[50:51], 0, v[130:131]
	s_mov_b32 m0, s68
	ds_read_b128 v[212:215], v183 offset:16384
	ds_read_b128 v[216:219], v183 offset:17408
	ds_read_b128 v[222:225], v183 offset:18432
	ds_read_b128 v[226:229], v183 offset:19456
	ds_read_b128 v[230:233], v183 offset:20480
	ds_read_b128 v[234:237], v183 offset:21504
	ds_read_b128 v[238:241], v183 offset:22528
	ds_read_b128 v[242:245], v183 offset:23552
	global_load_lds_dwordx4 v[246:247], off
	s_add_i32 m0, s68, 0x2000
	s_add_u32 s82, s50, 0x40000
	v_lshl_add_u64 v[248:249], s[50:51], 0, v[134:135]
	s_addc_u32 s83, s51, 0
	s_add_i32 s68, s73, s59
	global_load_lds_dwordx4 v[248:249], off
	v_lshl_add_u64 v[250:251], s[82:83], 0, v[130:131]
	s_mov_b32 m0, s68
	v_lshl_add_u64 v[252:253], s[52:53], 0, v[132:133]
	global_load_lds_dwordx4 v[250:251], off
	v_lshl_add_u64 v[250:251], s[82:83], 0, v[134:135]
	s_add_i32 m0, s68, 0x2000
	s_nop 0
	global_load_lds_dwordx4 v[250:251], off
	v_lshl_add_u64 v[250:251], s[52:53], 0, v[128:129]
	s_mov_b32 m0, s60
	s_nop 0
	global_load_lds_dwordx4 v[250:251], off
	s_mov_b32 m0, s61
	s_nop 0
	global_load_lds_dwordx4 v[252:253], off
	s_waitcnt vmcnt(8) lgkmcnt(0)
	s_setprio 1
	s_barrier
	v_mfma_f32_16x16x32_bf16 v[60:63], v[146:149], v[212:215], v[60:63]
	v_mfma_f32_16x16x32_bf16 v[56:59], v[188:191], v[212:215], v[56:59]
	v_mfma_f32_16x16x32_bf16 v[44:47], v[146:149], v[222:225], v[44:47]
	v_mfma_f32_16x16x32_bf16 v[40:43], v[188:191], v[222:225], v[40:43]
	v_mfma_f32_16x16x32_bf16 v[28:31], v[146:149], v[230:233], v[28:31]
	v_mfma_f32_16x16x32_bf16 v[24:27], v[188:191], v[230:233], v[24:27]
	v_mfma_f32_16x16x32_bf16 v[12:15], v[146:149], v[238:241], v[12:15]
	v_mfma_f32_16x16x32_bf16 v[8:11], v[188:191], v[238:241], v[8:11]
	v_mfma_f32_16x16x32_bf16 v[60:63], v[150:153], v[216:219], v[60:63]
	v_mfma_f32_16x16x32_bf16 v[56:59], v[192:195], v[216:219], v[56:59]
	v_mfma_f32_16x16x32_bf16 v[44:47], v[150:153], v[226:229], v[44:47]
	v_mfma_f32_16x16x32_bf16 v[40:43], v[192:195], v[226:229], v[40:43]
	v_mfma_f32_16x16x32_bf16 v[28:31], v[150:153], v[234:237], v[28:31]
	v_mfma_f32_16x16x32_bf16 v[24:27], v[192:195], v[234:237], v[24:27]
	v_mfma_f32_16x16x32_bf16 v[12:15], v[150:153], v[242:245], v[12:15]
	v_mfma_f32_16x16x32_bf16 v[8:11], v[192:195], v[242:245], v[8:11]
	s_setprio 0
	s_setprio 1
	v_mfma_f32_16x16x32_bf16 v[52:55], v[196:199], v[212:215], v[52:55]
	v_mfma_f32_16x16x32_bf16 v[48:51], v[204:207], v[212:215], v[48:51]
	v_mfma_f32_16x16x32_bf16 v[36:39], v[196:199], v[222:225], v[36:39]
	v_mfma_f32_16x16x32_bf16 v[32:35], v[204:207], v[222:225], v[32:35]
	v_mfma_f32_16x16x32_bf16 v[20:23], v[196:199], v[230:233], v[20:23]
	v_mfma_f32_16x16x32_bf16 v[16:19], v[204:207], v[230:233], v[16:19]
	v_mfma_f32_16x16x32_bf16 v[4:7], v[196:199], v[238:241], v[4:7]
	v_mfma_f32_16x16x32_bf16 v[0:3], v[204:207], v[238:241], v[0:3]
	v_mfma_f32_16x16x32_bf16 v[52:55], v[200:203], v[216:219], v[52:55]
	v_mfma_f32_16x16x32_bf16 v[48:51], v[208:211], v[216:219], v[48:51]
	v_mfma_f32_16x16x32_bf16 v[36:39], v[200:203], v[226:229], v[36:39]
	v_mfma_f32_16x16x32_bf16 v[32:35], v[208:211], v[226:229], v[32:35]
	v_mfma_f32_16x16x32_bf16 v[20:23], v[200:203], v[234:237], v[20:23]
	v_mfma_f32_16x16x32_bf16 v[16:19], v[208:211], v[234:237], v[16:19]
	v_mfma_f32_16x16x32_bf16 v[4:7], v[200:203], v[242:245], v[4:7]
	v_mfma_f32_16x16x32_bf16 v[0:3], v[208:211], v[242:245], v[0:3]
	s_barrier
; #define PG8_STAGE(bufoff, gbase, voff) do { _Pragma("unroll") for (int _i = 0; _i < 2; ++_i) \
;         __builtin_amdgcn_global_load_lds((const unsigned*)((const char*)(gbase) + (voff)[_i]), (PG8_LAS unsigned*)(lds + (bufoff) + ldsw + _i * 8192), 16, 0, 0); } while (0)
; #define PG8_LDA(dst, b, h) do { _Pragma("unroll") for (int m = 0; m < 4; ++m) _Pragma("unroll") for (int k = 0; k < 2; ++k) dst[m][k] = *(const PG8_LAS bf16x8*)(lds + PG8_SA(b, h) + aoff + m * 2048 + k * 1024); } while (0)
; #define PG8_LDB(dst, b, h) do { _Pragma("unroll") for (int n = 0; n < 2; ++n) _Pragma("unroll") for (int k = 0; k < 2; ++k) dst[n][k] = *(const PG8_LAS bf16x8*)(lds + PG8_SB(b, h) + boff + n * 2048 + k * 1024); } while (0)
; #define PG8_MMA(ai, bj, At, Bt) do { __builtin_amdgcn_s_setprio(1); _Pragma("unroll") for (int m = 0; m < 4; ++m) _Pragma("unroll") for (int n = 0; n < 2; ++n) _Pragma("unroll") for (int k = 0; k < 2; ++k) \
;         acc[ai][bj][m][n] = __builtin_amdgcn_mfma_f32_16x16x32_bf16(Bt[n][k], At[m][k], acc[ai][bj][m][n], 0, 0, 0); __builtin_amdgcn_s_setprio(0); } while (0)
; #define PG8_WAIT_V(n) asm volatile("s_waitcnt vmcnt(" #n ")" ::: "memory")
; #define PG8_WAIT_L(n) asm volatile("s_waitcnt lgkmcnt(" #n ")" ::: "memory")
; #define PG8_BAR __builtin_amdgcn_s_barrier()
; #define PG8_SCHED __builtin_amdgcn_sched_barrier(0)
; template <class Epi, class Sched>
; __device__ __forceinline__ void gemm_phase(PG8_LAS unsigned char* lds, PG8_LAS unsigned char* xl, const Gemm g, const Sched& S, const Epi& E) {
;     ...
;             PG8_LDB(B0, 1, 0); PG8_LDB(B1, 1, 1); PG8_SCHED; PG8_LDA(At, 1, 0); PG8_STAGE(PG8_SA(0, 1), a2 + hsA, voffA);
;             PG8_WAIT_V(8); PG8_WAIT_L(0); PG8_BAR; PG8_MMA(0, 0, At, B0); PG8_MMA(0, 1, At, B1); PG8_BAR; PG8_SCHED;
	s_setprio 0
	s_add_i32 s68, 0, 0x18000
	v_add_u32_e32 v184, s68, v156
	s_add_i32 s82, 0, 0x1c000
	ds_read_b128 v[146:149], v184
	ds_read_b128 v[150:153], v184 offset:1024
	ds_read_b128 v[188:191], v184 offset:2048
	ds_read_b128 v[192:195], v184 offset:3072
	v_add_u32_e32 v184, s82, v156
	ds_read_b128 v[196:199], v184
	ds_read_b128 v[200:203], v184 offset:1024
	ds_read_b128 v[204:207], v184 offset:2048
	ds_read_b128 v[208:211], v184 offset:3072
	s_add_u32 s52, s52, 0x40000
	s_addc_u32 s53, s53, 0
	s_mov_b32 m0, s62
	v_lshl_add_u64 v[184:185], s[52:53], 0, v[128:129]
	ds_read_b128 v[212:215], v183 offset:32768
	ds_read_b128 v[216:219], v183 offset:33792
	ds_read_b128 v[222:225], v183 offset:34816
	ds_read_b128 v[226:229], v183 offset:35840
	ds_read_b128 v[230:233], v183 offset:36864
	ds_read_b128 v[234:237], v183 offset:37888
	ds_read_b128 v[238:241], v183 offset:38912
	ds_read_b128 v[242:245], v183 offset:39936
	global_load_lds_dwordx4 v[184:185], off
	v_lshl_add_u64 v[184:185], s[52:53], 0, v[132:133]
	s_mov_b32 m0, s63
	s_nop 0
	global_load_lds_dwordx4 v[184:185], off
	s_waitcnt vmcnt(8) lgkmcnt(0)
	s_setprio 1
	s_barrier
	v_mfma_f32_16x16x32_bf16 v[124:127], v[146:149], v[212:215], v[124:127]
	v_mfma_f32_16x16x32_bf16 v[120:123], v[188:191], v[212:215], v[120:123]
	v_mfma_f32_16x16x32_bf16 v[108:111], v[146:149], v[222:225], v[108:111]
	v_mfma_f32_16x16x32_bf16 v[104:107], v[188:191], v[222:225], v[104:107]
	v_mfma_f32_16x16x32_bf16 v[92:95], v[146:149], v[230:233], v[92:95]
	v_mfma_f32_16x16x32_bf16 v[88:91], v[188:191], v[230:233], v[88:91]
	v_mfma_f32_16x16x32_bf16 v[76:79], v[146:149], v[238:241], v[76:79]
	v_mfma_f32_16x16x32_bf16 v[72:75], v[188:191], v[238:241], v[72:75]
	v_mfma_f32_16x16x32_bf16 v[124:127], v[150:153], v[216:219], v[124:127]
	v_mfma_f32_16x16x32_bf16 v[120:123], v[192:195], v[216:219], v[120:123]
	v_mfma_f32_16x16x32_bf16 v[108:111], v[150:153], v[226:229], v[108:111]
	v_mfma_f32_16x16x32_bf16 v[104:107], v[192:195], v[226:229], v[104:107]
	v_mfma_f32_16x16x32_bf16 v[92:95], v[150:153], v[234:237], v[92:95]
	v_mfma_f32_16x16x32_bf16 v[88:91], v[192:195], v[234:237], v[88:91]
	v_mfma_f32_16x16x32_bf16 v[76:79], v[150:153], v[242:245], v[76:79]
	v_mfma_f32_16x16x32_bf16 v[72:75], v[192:195], v[242:245], v[72:75]
	s_setprio 0
	s_setprio 1
	v_mfma_f32_16x16x32_bf16 v[116:119], v[196:199], v[212:215], v[116:119]
	v_mfma_f32_16x16x32_bf16 v[112:115], v[204:207], v[212:215], v[112:115]
	v_mfma_f32_16x16x32_bf16 v[100:103], v[196:199], v[222:225], v[100:103]
	v_mfma_f32_16x16x32_bf16 v[96:99], v[204:207], v[222:225], v[96:99]
	v_mfma_f32_16x16x32_bf16 v[84:87], v[196:199], v[230:233], v[84:87]
	v_mfma_f32_16x16x32_bf16 v[80:83], v[204:207], v[230:233], v[80:83]
	v_mfma_f32_16x16x32_bf16 v[68:71], v[196:199], v[238:241], v[68:71]
	v_mfma_f32_16x16x32_bf16 v[64:67], v[204:207], v[238:241], v[64:67]
	v_mfma_f32_16x16x32_bf16 v[116:119], v[200:203], v[216:219], v[116:119]
	v_mfma_f32_16x16x32_bf16 v[112:115], v[208:211], v[216:219], v[112:115]
	v_mfma_f32_16x16x32_bf16 v[100:103], v[200:203], v[226:229], v[100:103]
	v_mfma_f32_16x16x32_bf16 v[96:99], v[208:211], v[226:229], v[96:99]
	v_mfma_f32_16x16x32_bf16 v[84:87], v[200:203], v[234:237], v[84:87]
	v_mfma_f32_16x16x32_bf16 v[80:83], v[208:211], v[234:237], v[80:83]
	v_mfma_f32_16x16x32_bf16 v[68:71], v[200:203], v[242:245], v[68:71]
	v_mfma_f32_16x16x32_bf16 v[64:67], v[208:211], v[242:245], v[64:67]
	s_barrier
; #define PG8_STAGE(bufoff, gbase, voff) do { _Pragma("unroll") for (int _i = 0; _i < 2; ++_i) \
;         __builtin_amdgcn_global_load_lds((const unsigned*)((const char*)(gbase) + (voff)[_i]), (PG8_LAS unsigned*)(lds + (bufoff) + ldsw + _i * 8192), 16, 0, 0); } while (0)
; #define PG8_LDA(dst, b, h) do { _Pragma("unroll") for (int m = 0; m < 4; ++m) _Pragma("unroll") for (int k = 0; k < 2; ++k) dst[m][k] = *(const PG8_LAS bf16x8*)(lds + PG8_SA(b, h) + aoff + m * 2048 + k * 1024); } while (0)
; #define PG8_MMA(ai, bj, At, Bt) do { __builtin_amdgcn_s_setprio(1); _Pragma("unroll") for (int m = 0; m < 4; ++m) _Pragma("unroll") for (int n = 0; n < 2; ++n) _Pragma("unroll") for (int k = 0; k < 2; ++k) \
;         acc[ai][bj][m][n] = __builtin_amdgcn_mfma_f32_16x16x32_bf16(Bt[n][k], At[m][k], acc[ai][bj][m][n], 0, 0, 0); __builtin_amdgcn_s_setprio(0); } while (0)
; #define PG8_WAIT_V(n) asm volatile("s_waitcnt vmcnt(" #n ")" ::: "memory")
; #define PG8_WAIT_L(n) asm volatile("s_waitcnt lgkmcnt(" #n ")" ::: "memory")
; #define PG8_BAR __builtin_amdgcn_s_barrier()
; #define PG8_SCHED __builtin_amdgcn_sched_barrier(0)
; template <class Epi, class Sched>
; __device__ __forceinline__ void gemm_phase(PG8_LAS unsigned char* lds, PG8_LAS unsigned char* xl, const Gemm g, const Sched& S, const Epi& E) {
;     ...
;             PG8_LDA(At, 1, 1); PG8_STAGE(PG8_SB(1, 0), b3, voffB); PG8_STAGE(PG8_SB(1, 1), b3 + hsB, voffB); PG8_STAGE(PG8_SA(1, 0), a3, voffA);
;             PG8_WAIT_V(8); PG8_WAIT_L(0); PG8_BAR; PG8_MMA(1, 0, At, B0); PG8_MMA(1, 1, At, B1); PG8_BAR; PG8_SCHED;
;         }
	s_setprio 0
	s_add_i32 s52, s68, s59
	v_lshl_add_u64 v[184:185], v[246:247], 0, s[20:21]
	s_mov_b32 m0, s52
	ds_read_b128 v[212:215], v183 offset:49152
	ds_read_b128 v[216:219], v183 offset:50176
	ds_read_b128 v[222:225], v183 offset:51200
	ds_read_b128 v[226:229], v183 offset:52224
	ds_read_b128 v[230:233], v183 offset:53248
	ds_read_b128 v[234:237], v183 offset:54272
	ds_read_b128 v[238:241], v183 offset:55296
	ds_read_b128 v[242:245], v183 offset:56320
	global_load_lds_dwordx4 v[184:185], off
	s_add_i32 m0, s52, 0x2000
	s_add_u32 s50, s50, 0x40080
	v_lshl_add_u64 v[184:185], v[248:249], 0, s[20:21]
	s_addc_u32 s51, s51, 0
	s_add_i32 s52, s82, s59
	global_load_lds_dwordx4 v[184:185], off
	v_lshl_add_u64 v[184:185], s[50:51], 0, v[130:131]
	s_mov_b32 m0, s52
	s_nop 0
	global_load_lds_dwordx4 v[184:185], off
	v_lshl_add_u64 v[184:185], s[50:51], 0, v[134:135]
	s_add_i32 m0, s52, 0x2000
	s_nop 0
	global_load_lds_dwordx4 v[184:185], off
	v_lshl_add_u64 v[184:185], v[250:251], 0, s[20:21]
	s_mov_b32 m0, s65
	s_nop 0
	global_load_lds_dwordx4 v[184:185], off
	v_lshl_add_u64 v[184:185], v[252:253], 0, s[20:21]
	s_mov_b32 m0, s66
	s_nop 0
	global_load_lds_dwordx4 v[184:185], off
	s_waitcnt vmcnt(8) lgkmcnt(0)
	s_setprio 1
	s_barrier
	v_mfma_f32_16x16x32_bf16 v[60:63], v[146:149], v[212:215], v[60:63]
	v_mfma_f32_16x16x32_bf16 v[56:59], v[188:191], v[212:215], v[56:59]
	v_mfma_f32_16x16x32_bf16 v[44:47], v[146:149], v[222:225], v[44:47]
	v_mfma_f32_16x16x32_bf16 v[40:43], v[188:191], v[222:225], v[40:43]
	v_mfma_f32_16x16x32_bf16 v[28:31], v[146:149], v[230:233], v[28:31]
	v_mfma_f32_16x16x32_bf16 v[24:27], v[188:191], v[230:233], v[24:27]
	v_mfma_f32_16x16x32_bf16 v[12:15], v[146:149], v[238:241], v[12:15]
	v_mfma_f32_16x16x32_bf16 v[8:11], v[188:191], v[238:241], v[8:11]
	v_mfma_f32_16x16x32_bf16 v[60:63], v[150:153], v[216:219], v[60:63]
	v_mfma_f32_16x16x32_bf16 v[56:59], v[192:195], v[216:219], v[56:59]
	v_mfma_f32_16x16x32_bf16 v[44:47], v[150:153], v[226:229], v[44:47]
	v_mfma_f32_16x16x32_bf16 v[40:43], v[192:195], v[226:229], v[40:43]
	v_mfma_f32_16x16x32_bf16 v[28:31], v[150:153], v[234:237], v[28:31]
	v_mfma_f32_16x16x32_bf16 v[24:27], v[192:195], v[234:237], v[24:27]
	v_mfma_f32_16x16x32_bf16 v[12:15], v[150:153], v[242:245], v[12:15]
	v_mfma_f32_16x16x32_bf16 v[8:11], v[192:195], v[242:245], v[8:11]
	s_setprio 0
	s_setprio 1
	v_mfma_f32_16x16x32_bf16 v[52:55], v[196:199], v[212:215], v[52:55]
	s_add_i32 s81, s81, 2
	v_mfma_f32_16x16x32_bf16 v[48:51], v[204:207], v[212:215], v[48:51]
	s_add_u32 s79, s79, 0x100
	v_mfma_f32_16x16x32_bf16 v[36:39], v[196:199], v[222:225], v[36:39]
	s_addc_u32 s80, s80, 0
	v_mfma_f32_16x16x32_bf16 v[32:35], v[204:207], v[222:225], v[32:35]
	s_add_u32 s2, s2, 0x100
	v_mfma_f32_16x16x32_bf16 v[20:23], v[196:199], v[230:233], v[20:23]
	s_addc_u32 s3, s3, 0
	v_mfma_f32_16x16x32_bf16 v[16:19], v[204:207], v[230:233], v[16:19]
	s_cmp_gt_u32 s81, 13
	v_mfma_f32_16x16x32_bf16 v[4:7], v[196:199], v[238:241], v[4:7]
	v_mfma_f32_16x16x32_bf16 v[0:3], v[204:207], v[238:241], v[0:3]
	v_mfma_f32_16x16x32_bf16 v[52:55], v[200:203], v[216:219], v[52:55]
	v_mfma_f32_16x16x32_bf16 v[48:51], v[208:211], v[216:219], v[48:51]
	v_mfma_f32_16x16x32_bf16 v[36:39], v[200:203], v[226:229], v[36:39]
	v_mfma_f32_16x16x32_bf16 v[32:35], v[208:211], v[226:229], v[32:35]
	v_mfma_f32_16x16x32_bf16 v[20:23], v[200:203], v[234:237], v[20:23]
	v_mfma_f32_16x16x32_bf16 v[16:19], v[208:211], v[234:237], v[16:19]
	v_mfma_f32_16x16x32_bf16 v[4:7], v[200:203], v[242:245], v[4:7]
	v_mfma_f32_16x16x32_bf16 v[0:3], v[208:211], v[242:245], v[0:3]
	s_barrier
	s_setprio 0
	s_cbranch_scc0 .LBB0_577

; #define PG8_STAGE(bufoff, gbase, voff) do { _Pragma("unroll") for (int _i = 0; _i < 2; ++_i) \
;         __builtin_amdgcn_global_load_lds((const unsigned*)((const char*)(gbase) + (voff)[_i]), (PG8_LAS unsigned*)(lds + (bufoff) + ldsw + _i * 8192), 16, 0, 0); } while (0)
; #define PG8_LDA(dst, b, h) do { _Pragma("unroll") for (int m = 0; m < 4; ++m) _Pragma("unroll") for (int k = 0; k < 2; ++k) dst[m][k] = *(const PG8_LAS bf16x8*)(lds + PG8_SA(b, h) + aoff + m * 2048 + k * 1024); } while (0)
; #define PG8_LDB(dst, b, h) do { _Pragma("unroll") for (int n = 0; n < 2; ++n) _Pragma("unroll") for (int k = 0; k < 2; ++k) dst[n][k] = *(const PG8_LAS bf16x8*)(lds + PG8_SB(b, h) + boff + n * 2048 + k * 1024); } while (0)
; #define PG8_WAIT_V(n) asm volatile("s_waitcnt vmcnt(" #n ")" ::: "memory")
; #define PG8_WAIT_L(n) asm volatile("s_waitcnt lgkmcnt(" #n ")" ::: "memory")
; template <class Epi, class Sched>
; __device__ __forceinline__ void gemm_phase(PG8_LAS unsigned char* lds, PG8_LAS unsigned char* xl, const Gemm g, const Sched& S, const Epi& E) {
;     ...
;             const bool last = (t == nt - 2);
;             const char* a1 = cA + (size_t)(t + 1) * kstep;
;             const char* a2 = last ? nA : cA + (size_t)(t + 2) * kstep; const char* b2 = last ? nB : cB + (size_t)(t + 2) * kstep;
;             const char* a3 = a2 + kstep; const char* b3 = b2 + kstep;
;             PG8_LDB(B0, 0, 0); PG8_LDB(B1, 0, 1); PG8_SCHED; PG8_LDA(At, 0, 0); PG8_STAGE(PG8_SA(1, 1), a1 + hsA, voffA);
;             PG8_WAIT_V(8); PG8_WAIT_L(0); PG8_BAR; PG8_MMA(0, 0, At, B0); PG8_MMA(0, 1, At, B1); PG8_BAR; PG8_SCHED;
;             PG8_LDA(At, 0, 1); PG8_STAGE(PG8_SB(0, 0), b2, voffB); PG8_STAGE(PG8_SB(0, 1), b2 + hsB, voffB); PG8_STAGE(PG8_SA(0, 0), a2, voffA);
;             PG8_WAIT_V(8); PG8_WAIT_L(0); PG8_BAR; PG8_MMA(1, 0, At, B0); PG8_MMA(1, 1, At, B1); PG8_BAR; PG8_SCHED;
;             PG8_LDB(B0, 1, 0); PG8_LDB(B1, 1, 1); PG8_SCHED; PG8_LDA(At, 1, 0); PG8_STAGE(PG8_SA(0, 1), a2 + hsA, voffA);
;             PG8_WAIT_V(8); PG8_WAIT_L(0); PG8_BAR; PG8_MMA(0, 0, At, B0); PG8_MMA(0, 1, At, B1); PG8_BAR; PG8_SCHED;
;             PG8_LDA(At, 1, 1); PG8_STAGE(PG8_SB(1, 0), b3, voffB); PG8_STAGE(PG8_SB(1, 1), b3 + hsB, voffB); PG8_STAGE(PG8_SA(1, 0), a3, voffA);
;             PG8_WAIT_V(8); PG8_WAIT_L(0); PG8_BAR; PG8_MMA(1, 0, At, B0); PG8_MMA(1, 1, At, B1); PG8_BAR; PG8_SCHED;
.LBB0_724:
	s_add_u32 s26, s43, s20
	s_addc_u32 s27, s50, s21
	s_and_b64 s[28:29], s[8:9], exec
	s_cselect_b32 s33, s27, s35
	s_cselect_b32 s46, s26, s34
	s_add_u32 s28, s51, s22
	s_addc_u32 s29, s52, s23
	s_and_b64 s[36:37], s[8:9], exec
	s_cselect_b32 s47, s29, s31
	s_cselect_b32 s72, s28, s30
	s_add_u32 s73, s30, 0x100
	s_addc_u32 s74, s31, 0
	s_add_u32 s30, s34, 0x40080
	v_mov_b32_e32 v0, 0
	s_addc_u32 s31, s35, 0
	s_mov_b32 s75, -2
	s_waitcnt lgkmcnt(0)
	ds_read_b128 v[170:173], v157
	ds_read_b128 v[174:177], v157 offset:1024
	ds_read_b128 v[180:183], v157 offset:2048
	ds_read_b128 v[184:187], v157 offset:3072
	ds_read_b128 v[188:191], v158
	ds_read_b128 v[192:195], v158 offset:1024
	ds_read_b128 v[196:199], v158 offset:2048
	ds_read_b128 v[200:203], v158 offset:3072
	s_add_u32 s34, s30, 0xfffc0080
	s_addc_u32 s35, s31, -1
	s_cmp_eq_u32 s75, 12
	s_cselect_b32 s37, s33, s35
	s_cselect_b32 s36, s46, s34
	s_cselect_b32 s35, s47, s74
	s_cselect_b32 s34, s72, s73
	v_lshl_add_u64 v[144:145], s[30:31], 0, v[138:139]
	s_add_i32 m0, s57, 0xc000
	ds_read_b128 v[204:207], v159
	ds_read_b128 v[208:211], v159 offset:1024
	ds_read_b128 v[212:215], v159 offset:2048
	ds_read_b128 v[216:219], v159 offset:3072
	ds_read_b128 v[222:225], v159 offset:4096
	ds_read_b128 v[226:229], v159 offset:5120
	ds_read_b128 v[230:233], v159 offset:6144
	ds_read_b128 v[234:237], v159 offset:7168
	global_load_lds_dwordx4 v[144:145], off
	v_lshl_add_u64 v[144:145], s[30:31], 0, v[136:137]
	s_add_i32 m0, s57, 0xe000
	s_nop 0
	global_load_lds_dwordx4 v[144:145], off
	s_waitcnt vmcnt(8) lgkmcnt(0)
	s_setprio 1
	s_barrier
	v_mfma_f32_16x16x32_bf16 v[124:127], v[170:173], v[204:207], 0
	v_mfma_f32_16x16x32_bf16 v[120:123], v[180:183], v[204:207], 0
	v_mfma_f32_16x16x32_bf16 v[108:111], v[170:173], v[212:215], 0
	v_mfma_f32_16x16x32_bf16 v[104:107], v[180:183], v[212:215], 0
	v_mfma_f32_16x16x32_bf16 v[92:95], v[170:173], v[222:225], 0
	v_mfma_f32_16x16x32_bf16 v[88:91], v[180:183], v[222:225], 0
	v_mfma_f32_16x16x32_bf16 v[76:79], v[170:173], v[230:233], 0
	v_mfma_f32_16x16x32_bf16 v[72:75], v[180:183], v[230:233], 0
	v_mfma_f32_16x16x32_bf16 v[124:127], v[174:177], v[208:211], v[124:127]
	v_mfma_f32_16x16x32_bf16 v[120:123], v[184:187], v[208:211], v[120:123]
	v_mfma_f32_16x16x32_bf16 v[108:111], v[174:177], v[216:219], v[108:111]
	v_mfma_f32_16x16x32_bf16 v[104:107], v[184:187], v[216:219], v[104:107]
	v_mfma_f32_16x16x32_bf16 v[92:95], v[174:177], v[226:229], v[92:95]
	v_mfma_f32_16x16x32_bf16 v[88:91], v[184:187], v[226:229], v[88:91]
	v_mfma_f32_16x16x32_bf16 v[76:79], v[174:177], v[234:237], v[76:79]
	v_mfma_f32_16x16x32_bf16 v[72:75], v[184:187], v[234:237], v[72:75]
	s_setprio 0
	s_setprio 1
	v_mfma_f32_16x16x32_bf16 v[116:119], v[188:191], v[204:207], 0
	v_mfma_f32_16x16x32_bf16 v[112:115], v[196:199], v[204:207], 0
	v_mfma_f32_16x16x32_bf16 v[100:103], v[188:191], v[212:215], 0
	v_mfma_f32_16x16x32_bf16 v[96:99], v[196:199], v[212:215], 0
	v_mfma_f32_16x16x32_bf16 v[84:87], v[188:191], v[222:225], 0
	v_mfma_f32_16x16x32_bf16 v[80:83], v[196:199], v[222:225], 0
	v_mfma_f32_16x16x32_bf16 v[68:71], v[188:191], v[230:233], 0
	v_mfma_f32_16x16x32_bf16 v[64:67], v[196:199], v[230:233], 0
	v_mfma_f32_16x16x32_bf16 v[116:119], v[192:195], v[208:211], v[116:119]
	v_mfma_f32_16x16x32_bf16 v[112:115], v[200:203], v[208:211], v[112:115]
	v_mfma_f32_16x16x32_bf16 v[100:103], v[192:195], v[216:219], v[100:103]
	v_mfma_f32_16x16x32_bf16 v[96:99], v[200:203], v[216:219], v[96:99]
	v_mfma_f32_16x16x32_bf16 v[84:87], v[192:195], v[226:229], v[84:87]
	v_mfma_f32_16x16x32_bf16 v[80:83], v[200:203], v[226:229], v[80:83]
	v_mfma_f32_16x16x32_bf16 v[68:71], v[192:195], v[234:237], v[68:71]
	v_mfma_f32_16x16x32_bf16 v[64:67], v[200:203], v[234:237], v[64:67]
	s_barrier
	s_setprio 0
	s_add_i32 s68, s65, s56
	v_lshl_add_u64 v[144:145], s[34:35], 0, v[130:131]
	s_mov_b32 m0, s68
	ds_read_b128 v[204:207], v159 offset:16384
	ds_read_b128 v[208:211], v159 offset:17408
	ds_read_b128 v[212:215], v159 offset:18432
	ds_read_b128 v[216:219], v159 offset:19456
	ds_read_b128 v[222:225], v159 offset:20480
	ds_read_b128 v[226:229], v159 offset:21504
	ds_read_b128 v[230:233], v159 offset:22528
	ds_read_b128 v[234:237], v159 offset:23552
	global_load_lds_dwordx4 v[144:145], off
	s_add_i32 m0, s68, 0x2000
	s_add_u32 s76, s34, 0x40000
	v_lshl_add_u64 v[238:239], s[34:35], 0, v[134:135]
	s_addc_u32 s77, s35, 0
	s_add_i32 s68, s66, s56
	global_load_lds_dwordx4 v[238:239], off
	v_lshl_add_u64 v[240:241], s[76:77], 0, v[130:131]
	s_mov_b32 m0, s68
	v_lshl_add_u64 v[242:243], s[36:37], 0, v[132:133]
	global_load_lds_dwordx4 v[240:241], off
	v_lshl_add_u64 v[240:241], s[76:77], 0, v[134:135]
	s_add_i32 m0, s68, 0x2000
	s_nop 0
	global_load_lds_dwordx4 v[240:241], off
	v_lshl_add_u64 v[240:241], s[36:37], 0, v[128:129]
	s_mov_b32 m0, s57
	s_nop 0
	global_load_lds_dwordx4 v[240:241], off
	s_mov_b32 m0, s58
	s_nop 0
	global_load_lds_dwordx4 v[242:243], off
	s_waitcnt vmcnt(8) lgkmcnt(0)
	s_setprio 1
	s_barrier
; #define PG8_STAGE(bufoff, gbase, voff) do { _Pragma("unroll") for (int _i = 0; _i < 2; ++_i) \
;         __builtin_amdgcn_global_load_lds((const unsigned*)((const char*)(gbase) + (voff)[_i]), (PG8_LAS unsigned*)(lds + (bufoff) + ldsw + _i * 8192), 16, 0, 0); } while (0)
; #define PG8_LDA(dst, b, h) do { _Pragma("unroll") for (int m = 0; m < 4; ++m) _Pragma("unroll") for (int k = 0; k < 2; ++k) dst[m][k] = *(const PG8_LAS bf16x8*)(lds + PG8_SA(b, h) + aoff + m * 2048 + k * 1024); } while (0)
; #define PG8_LDB(dst, b, h) do { _Pragma("unroll") for (int n = 0; n < 2; ++n) _Pragma("unroll") for (int k = 0; k < 2; ++k) dst[n][k] = *(const PG8_LAS bf16x8*)(lds + PG8_SB(b, h) + boff + n * 2048 + k * 1024); } while (0)
; #define PG8_MMA(ai, bj, At, Bt) do { __builtin_amdgcn_s_setprio(1); _Pragma("unroll") for (int m = 0; m < 4; ++m) _Pragma("unroll") for (int n = 0; n < 2; ++n) _Pragma("unroll") for (int k = 0; k < 2; ++k) \
;         acc[ai][bj][m][n] = __builtin_amdgcn_mfma_f32_16x16x32_bf16(Bt[n][k], At[m][k], acc[ai][bj][m][n], 0, 0, 0); __builtin_amdgcn_s_setprio(0); } while (0)
; #define PG8_WAIT_V(n) asm volatile("s_waitcnt vmcnt(" #n ")" ::: "memory")
; #define PG8_WAIT_L(n) asm volatile("s_waitcnt lgkmcnt(" #n ")" ::: "memory")
; #define PG8_BAR __builtin_amdgcn_s_barrier()
; #define PG8_SCHED __builtin_amdgcn_sched_barrier(0)
; template <class Epi, class Sched>
; __device__ __forceinline__ void gemm_phase(PG8_LAS unsigned char* lds, PG8_LAS unsigned char* xl, const Gemm g, const Sched& S, const Epi& E) {
;     ...
;             PG8_LDA(At, 0, 1); PG8_STAGE(PG8_SB(0, 0), b2, voffB); PG8_STAGE(PG8_SB(0, 1), b2 + hsB, voffB); PG8_STAGE(PG8_SA(0, 0), a2, voffA);
;             PG8_WAIT_V(8); PG8_WAIT_L(0); PG8_BAR; PG8_MMA(1, 0, At, B0); PG8_MMA(1, 1, At, B1); PG8_BAR; PG8_SCHED;
;             PG8_LDB(B0, 1, 0); PG8_LDB(B1, 1, 1); PG8_SCHED; PG8_LDA(At, 1, 0); PG8_STAGE(PG8_SA(0, 1), a2 + hsA, voffA);
;             PG8_WAIT_V(8); PG8_WAIT_L(0); PG8_BAR; PG8_MMA(0, 0, At, B0); PG8_MMA(0, 1, At, B1); PG8_BAR; PG8_SCHED;
	v_mfma_f32_16x16x32_bf16 v[60:63], v[170:173], v[204:207], 0
	v_mfma_f32_16x16x32_bf16 v[56:59], v[180:183], v[204:207], 0
	v_mfma_f32_16x16x32_bf16 v[44:47], v[170:173], v[212:215], 0
	v_mfma_f32_16x16x32_bf16 v[40:43], v[180:183], v[212:215], 0
	v_mfma_f32_16x16x32_bf16 v[28:31], v[170:173], v[222:225], 0
	v_mfma_f32_16x16x32_bf16 v[24:27], v[180:183], v[222:225], 0
	v_mfma_f32_16x16x32_bf16 v[12:15], v[170:173], v[230:233], 0
	v_mfma_f32_16x16x32_bf16 v[8:11], v[180:183], v[230:233], 0
	v_mfma_f32_16x16x32_bf16 v[60:63], v[174:177], v[208:211], v[60:63]
	v_mfma_f32_16x16x32_bf16 v[56:59], v[184:187], v[208:211], v[56:59]
	v_mfma_f32_16x16x32_bf16 v[44:47], v[174:177], v[216:219], v[44:47]
	v_mfma_f32_16x16x32_bf16 v[40:43], v[184:187], v[216:219], v[40:43]
	v_mfma_f32_16x16x32_bf16 v[28:31], v[174:177], v[226:229], v[28:31]
	v_mfma_f32_16x16x32_bf16 v[24:27], v[184:187], v[226:229], v[24:27]
	v_mfma_f32_16x16x32_bf16 v[12:15], v[174:177], v[234:237], v[12:15]
	v_mfma_f32_16x16x32_bf16 v[8:11], v[184:187], v[234:237], v[8:11]
	s_setprio 0
	s_setprio 1
	v_mfma_f32_16x16x32_bf16 v[52:55], v[188:191], v[204:207], 0
	v_mfma_f32_16x16x32_bf16 v[48:51], v[196:199], v[204:207], 0
	v_mfma_f32_16x16x32_bf16 v[36:39], v[188:191], v[212:215], 0
	v_mfma_f32_16x16x32_bf16 v[32:35], v[196:199], v[212:215], 0
	v_mfma_f32_16x16x32_bf16 v[20:23], v[188:191], v[222:225], 0
	v_mfma_f32_16x16x32_bf16 v[16:19], v[196:199], v[222:225], 0
	v_mfma_f32_16x16x32_bf16 v[4:7], v[188:191], v[230:233], 0
	v_mfma_f32_16x16x32_bf16 v[0:3], v[196:199], v[230:233], 0
	v_mfma_f32_16x16x32_bf16 v[52:55], v[192:195], v[208:211], v[52:55]
	v_mfma_f32_16x16x32_bf16 v[48:51], v[200:203], v[208:211], v[48:51]
	v_mfma_f32_16x16x32_bf16 v[36:39], v[192:195], v[216:219], v[36:39]
	v_mfma_f32_16x16x32_bf16 v[32:35], v[200:203], v[216:219], v[32:35]
	v_mfma_f32_16x16x32_bf16 v[20:23], v[192:195], v[226:229], v[20:23]
	v_mfma_f32_16x16x32_bf16 v[16:19], v[200:203], v[226:229], v[16:19]
	v_mfma_f32_16x16x32_bf16 v[4:7], v[192:195], v[234:237], v[4:7]
	v_mfma_f32_16x16x32_bf16 v[0:3], v[200:203], v[234:237], v[0:3]
	s_barrier
	s_setprio 0
	s_add_i32 s68, 0, 0x18000
	v_add_u32_e32 v169, s68, v147
	s_add_i32 s76, 0, 0x1c000
	ds_read_b128 v[170:173], v169
	ds_read_b128 v[174:177], v169 offset:1024
	ds_read_b128 v[180:183], v169 offset:2048
	ds_read_b128 v[184:187], v169 offset:3072
	v_add_u32_e32 v169, s76, v147
	ds_read_b128 v[188:191], v169
	ds_read_b128 v[192:195], v169 offset:1024
	ds_read_b128 v[196:199], v169 offset:2048
	ds_read_b128 v[200:203], v169 offset:3072
	s_add_u32 s36, s36, 0x40000
	s_addc_u32 s37, s37, 0
	s_mov_b32 m0, s59
	v_lshl_add_u64 v[244:245], s[36:37], 0, v[128:129]
	ds_read_b128 v[204:207], v159 offset:32768
	ds_read_b128 v[208:211], v159 offset:33792
	ds_read_b128 v[212:215], v159 offset:34816
	ds_read_b128 v[216:219], v159 offset:35840
	ds_read_b128 v[222:225], v159 offset:36864
	ds_read_b128 v[226:229], v159 offset:37888
	ds_read_b128 v[230:233], v159 offset:38912
	ds_read_b128 v[234:237], v159 offset:39936
	global_load_lds_dwordx4 v[244:245], off
	v_lshl_add_u64 v[244:245], s[36:37], 0, v[132:133]
	s_mov_b32 m0, s60
	s_nop 0
	global_load_lds_dwordx4 v[244:245], off
	s_waitcnt vmcnt(8) lgkmcnt(0)
	s_setprio 1
	s_barrier
	v_mfma_f32_16x16x32_bf16 v[124:127], v[170:173], v[204:207], v[124:127]
	v_mfma_f32_16x16x32_bf16 v[120:123], v[180:183], v[204:207], v[120:123]
	v_mfma_f32_16x16x32_bf16 v[108:111], v[170:173], v[212:215], v[108:111]
	v_mfma_f32_16x16x32_bf16 v[104:107], v[180:183], v[212:215], v[104:107]
	v_mfma_f32_16x16x32_bf16 v[92:95], v[170:173], v[222:225], v[92:95]
	v_mfma_f32_16x16x32_bf16 v[88:91], v[180:183], v[222:225], v[88:91]
	v_mfma_f32_16x16x32_bf16 v[76:79], v[170:173], v[230:233], v[76:79]
	v_mfma_f32_16x16x32_bf16 v[72:75], v[180:183], v[230:233], v[72:75]
	v_mfma_f32_16x16x32_bf16 v[124:127], v[174:177], v[208:211], v[124:127]
	v_mfma_f32_16x16x32_bf16 v[120:123], v[184:187], v[208:211], v[120:123]
	v_mfma_f32_16x16x32_bf16 v[108:111], v[174:177], v[216:219], v[108:111]
	v_mfma_f32_16x16x32_bf16 v[104:107], v[184:187], v[216:219], v[104:107]
	v_mfma_f32_16x16x32_bf16 v[92:95], v[174:177], v[226:229], v[92:95]
	v_mfma_f32_16x16x32_bf16 v[88:91], v[184:187], v[226:229], v[88:91]
	v_mfma_f32_16x16x32_bf16 v[76:79], v[174:177], v[234:237], v[76:79]
	v_mfma_f32_16x16x32_bf16 v[72:75], v[184:187], v[234:237], v[72:75]
	s_setprio 0
	s_setprio 1
	v_mfma_f32_16x16x32_bf16 v[116:119], v[188:191], v[204:207], v[116:119]
	v_mfma_f32_16x16x32_bf16 v[112:115], v[196:199], v[204:207], v[112:115]
	v_mfma_f32_16x16x32_bf16 v[100:103], v[188:191], v[212:215], v[100:103]
	v_mfma_f32_16x16x32_bf16 v[96:99], v[196:199], v[212:215], v[96:99]
	v_mfma_f32_16x16x32_bf16 v[84:87], v[188:191], v[222:225], v[84:87]
	v_mfma_f32_16x16x32_bf16 v[80:83], v[196:199], v[222:225], v[80:83]
	v_mfma_f32_16x16x32_bf16 v[68:71], v[188:191], v[230:233], v[68:71]
	v_mfma_f32_16x16x32_bf16 v[64:67], v[196:199], v[230:233], v[64:67]
	v_mfma_f32_16x16x32_bf16 v[116:119], v[192:195], v[208:211], v[116:119]
	v_mfma_f32_16x16x32_bf16 v[112:115], v[200:203], v[208:211], v[112:115]
	v_mfma_f32_16x16x32_bf16 v[100:103], v[192:195], v[216:219], v[100:103]
	v_mfma_f32_16x16x32_bf16 v[96:99], v[200:203], v[216:219], v[96:99]
	v_mfma_f32_16x16x32_bf16 v[84:87], v[192:195], v[226:229], v[84:87]
	v_mfma_f32_16x16x32_bf16 v[80:83], v[200:203], v[226:229], v[80:83]
	v_mfma_f32_16x16x32_bf16 v[68:71], v[192:195], v[234:237], v[68:71]
	v_mfma_f32_16x16x32_bf16 v[64:67], v[200:203], v[234:237], v[64:67]
	s_barrier
; #define PG8_STAGE(bufoff, gbase, voff) do { _Pragma("unroll") for (int _i = 0; _i < 2; ++_i) \
;         __builtin_amdgcn_global_load_lds((const unsigned*)((const char*)(gbase) + (voff)[_i]), (PG8_LAS unsigned*)(lds + (bufoff) + ldsw + _i * 8192), 16, 0, 0); } while (0)
; #define PG8_LDA(dst, b, h) do { _Pragma("unroll") for (int m = 0; m < 4; ++m) _Pragma("unroll") for (int k = 0; k < 2; ++k) dst[m][k] = *(const PG8_LAS bf16x8*)(lds + PG8_SA(b, h) + aoff + m * 2048 + k * 1024); } while (0)
; #define PG8_LDB(dst, b, h) do { _Pragma("unroll") for (int n = 0; n < 2; ++n) _Pragma("unroll") for (int k = 0; k < 2; ++k) dst[n][k] = *(const PG8_LAS bf16x8*)(lds + PG8_SB(b, h) + boff + n * 2048 + k * 1024); } while (0)
; #define PG8_MMA(ai, bj, At, Bt) do { __builtin_amdgcn_s_setprio(1); _Pragma("unroll") for (int m = 0; m < 4; ++m) _Pragma("unroll") for (int n = 0; n < 2; ++n) _Pragma("unroll") for (int k = 0; k < 2; ++k) \
;         acc[ai][bj][m][n] = __builtin_amdgcn_mfma_f32_16x16x32_bf16(Bt[n][k], At[m][k], acc[ai][bj][m][n], 0, 0, 0); __builtin_amdgcn_s_setprio(0); } while (0)
; #define PG8_WAIT_V(n) asm volatile("s_waitcnt vmcnt(" #n ")" ::: "memory")
; #define PG8_WAIT_L(n) asm volatile("s_waitcnt lgkmcnt(" #n ")" ::: "memory")
; #define PG8_BAR __builtin_amdgcn_s_barrier()
; #define PG8_SCHED __builtin_amdgcn_sched_barrier(0)
; template <class Epi, class Sched>
; __device__ __forceinline__ void gemm_phase(PG8_LAS unsigned char* lds, PG8_LAS unsigned char* xl, const Gemm g, const Sched& S, const Epi& E) {
;     ...
;             PG8_LDB(B0, 1, 0); PG8_LDB(B1, 1, 1); PG8_SCHED; PG8_LDA(At, 1, 0); PG8_STAGE(PG8_SA(0, 1), a2 + hsA, voffA);
;             PG8_WAIT_V(8); PG8_WAIT_L(0); PG8_BAR; PG8_MMA(0, 0, At, B0); PG8_MMA(0, 1, At, B1); PG8_BAR; PG8_SCHED;
;             PG8_LDA(At, 1, 1); PG8_STAGE(PG8_SB(1, 0), b3, voffB); PG8_STAGE(PG8_SB(1, 1), b3 + hsB, voffB); PG8_STAGE(PG8_SA(1, 0), a3, voffA);
;             PG8_WAIT_V(8); PG8_WAIT_L(0); PG8_BAR; PG8_MMA(1, 0, At, B0); PG8_MMA(1, 1, At, B1); PG8_BAR; PG8_SCHED;
;         }
	s_setprio 0
	s_add_i32 s36, s68, s56
	v_lshl_add_u64 v[144:145], v[144:145], 0, s[16:17]
	s_mov_b32 m0, s36
	ds_read_b128 v[204:207], v159 offset:49152
	ds_read_b128 v[208:211], v159 offset:50176
	ds_read_b128 v[212:215], v159 offset:51200
	ds_read_b128 v[216:219], v159 offset:52224
	ds_read_b128 v[222:225], v159 offset:53248
	ds_read_b128 v[226:229], v159 offset:54272
	ds_read_b128 v[230:233], v159 offset:55296
	ds_read_b128 v[234:237], v159 offset:56320
	global_load_lds_dwordx4 v[144:145], off
	s_add_i32 m0, s36, 0x2000
	s_add_u32 s34, s34, 0x40080
	v_lshl_add_u64 v[144:145], v[238:239], 0, s[16:17]
	s_addc_u32 s35, s35, 0
	s_add_i32 s36, s76, s56
	global_load_lds_dwordx4 v[144:145], off
	v_lshl_add_u64 v[144:145], s[34:35], 0, v[130:131]
	s_mov_b32 m0, s36
	s_nop 0
	global_load_lds_dwordx4 v[144:145], off
	v_lshl_add_u64 v[144:145], s[34:35], 0, v[134:135]
	s_add_i32 m0, s36, 0x2000
	s_nop 0
	global_load_lds_dwordx4 v[144:145], off
	v_lshl_add_u64 v[144:145], v[240:241], 0, s[16:17]
	s_mov_b32 m0, s62
	s_nop 0
	global_load_lds_dwordx4 v[144:145], off
	v_lshl_add_u64 v[144:145], v[242:243], 0, s[16:17]
	s_mov_b32 m0, s63
	s_nop 0
	global_load_lds_dwordx4 v[144:145], off
	s_waitcnt vmcnt(8) lgkmcnt(0)
	s_setprio 1
	s_barrier
	v_mfma_f32_16x16x32_bf16 v[60:63], v[170:173], v[204:207], v[60:63]
	v_mfma_f32_16x16x32_bf16 v[56:59], v[180:183], v[204:207], v[56:59]
	v_mfma_f32_16x16x32_bf16 v[44:47], v[170:173], v[212:215], v[44:47]
	v_mfma_f32_16x16x32_bf16 v[40:43], v[180:183], v[212:215], v[40:43]
	v_mfma_f32_16x16x32_bf16 v[28:31], v[170:173], v[222:225], v[28:31]
	v_mfma_f32_16x16x32_bf16 v[24:27], v[180:183], v[222:225], v[24:27]
	v_mfma_f32_16x16x32_bf16 v[12:15], v[170:173], v[230:233], v[12:15]
	v_mfma_f32_16x16x32_bf16 v[8:11], v[180:183], v[230:233], v[8:11]
	v_mfma_f32_16x16x32_bf16 v[60:63], v[174:177], v[208:211], v[60:63]
	v_mfma_f32_16x16x32_bf16 v[56:59], v[184:187], v[208:211], v[56:59]
	v_mfma_f32_16x16x32_bf16 v[44:47], v[174:177], v[216:219], v[44:47]
	v_mfma_f32_16x16x32_bf16 v[40:43], v[184:187], v[216:219], v[40:43]
	v_mfma_f32_16x16x32_bf16 v[28:31], v[174:177], v[226:229], v[28:31]
	v_mfma_f32_16x16x32_bf16 v[24:27], v[184:187], v[226:229], v[24:27]
	v_mfma_f32_16x16x32_bf16 v[12:15], v[174:177], v[234:237], v[12:15]
	v_mfma_f32_16x16x32_bf16 v[8:11], v[184:187], v[234:237], v[8:11]
	s_setprio 0
	s_setprio 1
	v_mfma_f32_16x16x32_bf16 v[52:55], v[188:191], v[204:207], v[52:55]
	s_add_i32 s75, s75, 2
	v_mfma_f32_16x16x32_bf16 v[48:51], v[196:199], v[204:207], v[48:51]
	s_add_u32 s73, s73, 0x100
	v_mfma_f32_16x16x32_bf16 v[36:39], v[188:191], v[212:215], v[36:39]
	s_addc_u32 s74, s74, 0
	v_mfma_f32_16x16x32_bf16 v[32:35], v[196:199], v[212:215], v[32:35]
	s_add_u32 s30, s30, 0x100
	v_mfma_f32_16x16x32_bf16 v[20:23], v[188:191], v[222:225], v[20:23]
	s_addc_u32 s31, s31, 0
	v_mfma_f32_16x16x32_bf16 v[16:19], v[196:199], v[222:225], v[16:19]
	s_cmp_gt_u32 s75, 13
	v_mfma_f32_16x16x32_bf16 v[4:7], v[188:191], v[230:233], v[4:7]
	v_mfma_f32_16x16x32_bf16 v[0:3], v[196:199], v[230:233], v[0:3]
	v_mfma_f32_16x16x32_bf16 v[52:55], v[192:195], v[208:211], v[52:55]
	v_mfma_f32_16x16x32_bf16 v[48:51], v[200:203], v[208:211], v[48:51]
	v_mfma_f32_16x16x32_bf16 v[36:39], v[192:195], v[216:219], v[36:39]
	v_mfma_f32_16x16x32_bf16 v[32:35], v[200:203], v[216:219], v[32:35]
	v_mfma_f32_16x16x32_bf16 v[20:23], v[192:195], v[226:229], v[20:23]
	v_mfma_f32_16x16x32_bf16 v[16:19], v[200:203], v[226:229], v[16:19]
	v_mfma_f32_16x16x32_bf16 v[4:7], v[192:195], v[234:237], v[4:7]
	v_mfma_f32_16x16x32_bf16 v[0:3], v[200:203], v[234:237], v[0:3]
	s_barrier
	s_setprio 0
	s_cbranch_scc1 .Lpeel_after_P7
.LBB0_725:
	ds_read_b128 v[170:173], v157
	ds_read_b128 v[174:177], v157 offset:1024
	ds_read_b128 v[180:183], v157 offset:2048
	ds_read_b128 v[184:187], v157 offset:3072
	ds_read_b128 v[188:191], v158
	ds_read_b128 v[192:195], v158 offset:1024
	ds_read_b128 v[196:199], v158 offset:2048
	ds_read_b128 v[200:203], v158 offset:3072
	s_add_u32 s34, s30, 0xfffc0080
	s_addc_u32 s35, s31, -1
	s_cmp_eq_u32 s75, 12
	s_cselect_b32 s37, s33, s35
	s_cselect_b32 s36, s46, s34
	s_cselect_b32 s35, s47, s74
	s_cselect_b32 s34, s72, s73
	v_lshl_add_u64 v[144:145], s[30:31], 0, v[138:139]
	s_add_i32 m0, s57, 0xc000
	ds_read_b128 v[204:207], v159
	ds_read_b128 v[208:211], v159 offset:1024
	ds_read_b128 v[212:215], v159 offset:2048
	ds_read_b128 v[216:219], v159 offset:3072
	ds_read_b128 v[222:225], v159 offset:4096
	ds_read_b128 v[226:229], v159 offset:5120
	ds_read_b128 v[230:233], v159 offset:6144
	ds_read_b128 v[234:237], v159 offset:7168
	global_load_lds_dwordx4 v[144:145], off
	v_lshl_add_u64 v[144:145], s[30:31], 0, v[136:137]
	s_add_i32 m0, s57, 0xe000
	s_nop 0
	global_load_lds_dwordx4 v[144:145], off
	s_waitcnt vmcnt(8) lgkmcnt(0)
	s_setprio 1
	s_barrier
; #define PG8_STAGE(bufoff, gbase, voff) do { _Pragma("unroll") for (int _i = 0; _i < 2; ++_i) \
;         __builtin_amdgcn_global_load_lds((const unsigned*)((const char*)(gbase) + (voff)[_i]), (PG8_LAS unsigned*)(lds + (bufoff) + ldsw + _i * 8192), 16, 0, 0); } while (0)
; #define PG8_LDA(dst, b, h) do { _Pragma("unroll") for (int m = 0; m < 4; ++m) _Pragma("unroll") for (int k = 0; k < 2; ++k) dst[m][k] = *(const PG8_LAS bf16x8*)(lds + PG8_SA(b, h) + aoff + m * 2048 + k * 1024); } while (0)
; #define PG8_LDB(dst, b, h) do { _Pragma("unroll") for (int n = 0; n < 2; ++n) _Pragma("unroll") for (int k = 0; k < 2; ++k) dst[n][k] = *(const PG8_LAS bf16x8*)(lds + PG8_SB(b, h) + boff + n * 2048 + k * 1024); } while (0)
; #define PG8_MMA(ai, bj, At, Bt) do { __builtin_amdgcn_s_setprio(1); _Pragma("unroll") for (int m = 0; m < 4; ++m) _Pragma("unroll") for (int n = 0; n < 2; ++n) _Pragma("unroll") for (int k = 0; k < 2; ++k) \
;         acc[ai][bj][m][n] = __builtin_amdgcn_mfma_f32_16x16x32_bf16(Bt[n][k], At[m][k], acc[ai][bj][m][n], 0, 0, 0); __builtin_amdgcn_s_setprio(0); } while (0)
; #define PG8_WAIT_V(n) asm volatile("s_waitcnt vmcnt(" #n ")" ::: "memory")
; #define PG8_WAIT_L(n) asm volatile("s_waitcnt lgkmcnt(" #n ")" ::: "memory")
; #define PG8_BAR __builtin_amdgcn_s_barrier()
; #define PG8_SCHED __builtin_amdgcn_sched_barrier(0)
; template <class Epi, class Sched>
; __device__ __forceinline__ void gemm_phase(PG8_LAS unsigned char* lds, PG8_LAS unsigned char* xl, const Gemm g, const Sched& S, const Epi& E) {
;     ...
;             PG8_WAIT_V(8); PG8_WAIT_L(0); PG8_BAR; PG8_MMA(0, 0, At, B0); PG8_MMA(0, 1, At, B1); PG8_BAR; PG8_SCHED;
;             PG8_LDA(At, 0, 1); PG8_STAGE(PG8_SB(0, 0), b2, voffB); PG8_STAGE(PG8_SB(0, 1), b2 + hsB, voffB); PG8_STAGE(PG8_SA(0, 0), a2, voffA);
;             PG8_WAIT_V(8); PG8_WAIT_L(0); PG8_BAR; PG8_MMA(1, 0, At, B0); PG8_MMA(1, 1, At, B1); PG8_BAR; PG8_SCHED;
;             PG8_LDB(B0, 1, 0); PG8_LDB(B1, 1, 1); PG8_SCHED; PG8_LDA(At, 1, 0); PG8_STAGE(PG8_SA(0, 1), a2 + hsA, voffA);
;             PG8_WAIT_V(8); PG8_WAIT_L(0); PG8_BAR; PG8_MMA(0, 0, At, B0); PG8_MMA(0, 1, At, B1); PG8_BAR; PG8_SCHED;
	v_mfma_f32_16x16x32_bf16 v[124:127], v[170:173], v[204:207], v[124:127]
	v_mfma_f32_16x16x32_bf16 v[120:123], v[180:183], v[204:207], v[120:123]
	v_mfma_f32_16x16x32_bf16 v[108:111], v[170:173], v[212:215], v[108:111]
	v_mfma_f32_16x16x32_bf16 v[104:107], v[180:183], v[212:215], v[104:107]
	v_mfma_f32_16x16x32_bf16 v[92:95], v[170:173], v[222:225], v[92:95]
	v_mfma_f32_16x16x32_bf16 v[88:91], v[180:183], v[222:225], v[88:91]
	v_mfma_f32_16x16x32_bf16 v[76:79], v[170:173], v[230:233], v[76:79]
	v_mfma_f32_16x16x32_bf16 v[72:75], v[180:183], v[230:233], v[72:75]
	v_mfma_f32_16x16x32_bf16 v[124:127], v[174:177], v[208:211], v[124:127]
	v_mfma_f32_16x16x32_bf16 v[120:123], v[184:187], v[208:211], v[120:123]
	v_mfma_f32_16x16x32_bf16 v[108:111], v[174:177], v[216:219], v[108:111]
	v_mfma_f32_16x16x32_bf16 v[104:107], v[184:187], v[216:219], v[104:107]
	v_mfma_f32_16x16x32_bf16 v[92:95], v[174:177], v[226:229], v[92:95]
	v_mfma_f32_16x16x32_bf16 v[88:91], v[184:187], v[226:229], v[88:91]
	v_mfma_f32_16x16x32_bf16 v[76:79], v[174:177], v[234:237], v[76:79]
	v_mfma_f32_16x16x32_bf16 v[72:75], v[184:187], v[234:237], v[72:75]
	s_setprio 0
	s_setprio 1
	v_mfma_f32_16x16x32_bf16 v[116:119], v[188:191], v[204:207], v[116:119]
	v_mfma_f32_16x16x32_bf16 v[112:115], v[196:199], v[204:207], v[112:115]
	v_mfma_f32_16x16x32_bf16 v[100:103], v[188:191], v[212:215], v[100:103]
	v_mfma_f32_16x16x32_bf16 v[96:99], v[196:199], v[212:215], v[96:99]
	v_mfma_f32_16x16x32_bf16 v[84:87], v[188:191], v[222:225], v[84:87]
	v_mfma_f32_16x16x32_bf16 v[80:83], v[196:199], v[222:225], v[80:83]
	v_mfma_f32_16x16x32_bf16 v[68:71], v[188:191], v[230:233], v[68:71]
	v_mfma_f32_16x16x32_bf16 v[64:67], v[196:199], v[230:233], v[64:67]
	v_mfma_f32_16x16x32_bf16 v[116:119], v[192:195], v[208:211], v[116:119]
	v_mfma_f32_16x16x32_bf16 v[112:115], v[200:203], v[208:211], v[112:115]
	v_mfma_f32_16x16x32_bf16 v[100:103], v[192:195], v[216:219], v[100:103]
	v_mfma_f32_16x16x32_bf16 v[96:99], v[200:203], v[216:219], v[96:99]
	v_mfma_f32_16x16x32_bf16 v[84:87], v[192:195], v[226:229], v[84:87]
	v_mfma_f32_16x16x32_bf16 v[80:83], v[200:203], v[226:229], v[80:83]
	v_mfma_f32_16x16x32_bf16 v[68:71], v[192:195], v[234:237], v[68:71]
	v_mfma_f32_16x16x32_bf16 v[64:67], v[200:203], v[234:237], v[64:67]
	s_barrier
	s_setprio 0
	s_add_i32 s68, s65, s56
	v_lshl_add_u64 v[144:145], s[34:35], 0, v[130:131]
	s_mov_b32 m0, s68
	ds_read_b128 v[204:207], v159 offset:16384
	ds_read_b128 v[208:211], v159 offset:17408
	ds_read_b128 v[212:215], v159 offset:18432
	ds_read_b128 v[216:219], v159 offset:19456
	ds_read_b128 v[222:225], v159 offset:20480
	ds_read_b128 v[226:229], v159 offset:21504
	ds_read_b128 v[230:233], v159 offset:22528
	ds_read_b128 v[234:237], v159 offset:23552
	global_load_lds_dwordx4 v[144:145], off
	s_add_i32 m0, s68, 0x2000
	s_add_u32 s76, s34, 0x40000
	v_lshl_add_u64 v[238:239], s[34:35], 0, v[134:135]
	s_addc_u32 s77, s35, 0
	s_add_i32 s68, s66, s56
	global_load_lds_dwordx4 v[238:239], off
	v_lshl_add_u64 v[240:241], s[76:77], 0, v[130:131]
	s_mov_b32 m0, s68
	v_lshl_add_u64 v[242:243], s[36:37], 0, v[132:133]
	global_load_lds_dwordx4 v[240:241], off
	v_lshl_add_u64 v[240:241], s[76:77], 0, v[134:135]
	s_add_i32 m0, s68, 0x2000
	s_nop 0
	global_load_lds_dwordx4 v[240:241], off
	v_lshl_add_u64 v[240:241], s[36:37], 0, v[128:129]
	s_mov_b32 m0, s57
	s_nop 0
	global_load_lds_dwordx4 v[240:241], off
	s_mov_b32 m0, s58
	s_nop 0
	global_load_lds_dwordx4 v[242:243], off
	s_waitcnt vmcnt(8) lgkmcnt(0)
	s_setprio 1
	s_barrier
	v_mfma_f32_16x16x32_bf16 v[60:63], v[170:173], v[204:207], v[60:63]
	v_mfma_f32_16x16x32_bf16 v[56:59], v[180:183], v[204:207], v[56:59]
	v_mfma_f32_16x16x32_bf16 v[44:47], v[170:173], v[212:215], v[44:47]
	v_mfma_f32_16x16x32_bf16 v[40:43], v[180:183], v[212:215], v[40:43]
	v_mfma_f32_16x16x32_bf16 v[28:31], v[170:173], v[222:225], v[28:31]
	v_mfma_f32_16x16x32_bf16 v[24:27], v[180:183], v[222:225], v[24:27]
	v_mfma_f32_16x16x32_bf16 v[12:15], v[170:173], v[230:233], v[12:15]
	v_mfma_f32_16x16x32_bf16 v[8:11], v[180:183], v[230:233], v[8:11]
	v_mfma_f32_16x16x32_bf16 v[60:63], v[174:177], v[208:211], v[60:63]
	v_mfma_f32_16x16x32_bf16 v[56:59], v[184:187], v[208:211], v[56:59]
	v_mfma_f32_16x16x32_bf16 v[44:47], v[174:177], v[216:219], v[44:47]
	v_mfma_f32_16x16x32_bf16 v[40:43], v[184:187], v[216:219], v[40:43]
	v_mfma_f32_16x16x32_bf16 v[28:31], v[174:177], v[226:229], v[28:31]
	v_mfma_f32_16x16x32_bf16 v[24:27], v[184:187], v[226:229], v[24:27]
	v_mfma_f32_16x16x32_bf16 v[12:15], v[174:177], v[234:237], v[12:15]
	v_mfma_f32_16x16x32_bf16 v[8:11], v[184:187], v[234:237], v[8:11]
	s_setprio 0
	s_setprio 1
	v_mfma_f32_16x16x32_bf16 v[52:55], v[188:191], v[204:207], v[52:55]
	v_mfma_f32_16x16x32_bf16 v[48:51], v[196:199], v[204:207], v[48:51]
	v_mfma_f32_16x16x32_bf16 v[36:39], v[188:191], v[212:215], v[36:39]
	v_mfma_f32_16x16x32_bf16 v[32:35], v[196:199], v[212:215], v[32:35]
	v_mfma_f32_16x16x32_bf16 v[20:23], v[188:191], v[222:225], v[20:23]
	v_mfma_f32_16x16x32_bf16 v[16:19], v[196:199], v[222:225], v[16:19]
	v_mfma_f32_16x16x32_bf16 v[4:7], v[188:191], v[230:233], v[4:7]
	v_mfma_f32_16x16x32_bf16 v[0:3], v[196:199], v[230:233], v[0:3]
	v_mfma_f32_16x16x32_bf16 v[52:55], v[192:195], v[208:211], v[52:55]
	v_mfma_f32_16x16x32_bf16 v[48:51], v[200:203], v[208:211], v[48:51]
	v_mfma_f32_16x16x32_bf16 v[36:39], v[192:195], v[216:219], v[36:39]
	v_mfma_f32_16x16x32_bf16 v[32:35], v[200:203], v[216:219], v[32:35]
	v_mfma_f32_16x16x32_bf16 v[20:23], v[192:195], v[226:229], v[20:23]
	v_mfma_f32_16x16x32_bf16 v[16:19], v[200:203], v[226:229], v[16:19]
	v_mfma_f32_16x16x32_bf16 v[4:7], v[192:195], v[234:237], v[4:7]
	v_mfma_f32_16x16x32_bf16 v[0:3], v[200:203], v[234:237], v[0:3]
	s_barrier
; #define PG8_STAGE(bufoff, gbase, voff) do { _Pragma("unroll") for (int _i = 0; _i < 2; ++_i) \
;         __builtin_amdgcn_global_load_lds((const unsigned*)((const char*)(gbase) + (voff)[_i]), (PG8_LAS unsigned*)(lds + (bufoff) + ldsw + _i * 8192), 16, 0, 0); } while (0)
; #define PG8_LDA(dst, b, h) do { _Pragma("unroll") for (int m = 0; m < 4; ++m) _Pragma("unroll") for (int k = 0; k < 2; ++k) dst[m][k] = *(const PG8_LAS bf16x8*)(lds + PG8_SA(b, h) + aoff + m * 2048 + k * 1024); } while (0)
; #define PG8_LDB(dst, b, h) do { _Pragma("unroll") for (int n = 0; n < 2; ++n) _Pragma("unroll") for (int k = 0; k < 2; ++k) dst[n][k] = *(const PG8_LAS bf16x8*)(lds + PG8_SB(b, h) + boff + n * 2048 + k * 1024); } while (0)
; #define PG8_MMA(ai, bj, At, Bt) do { __builtin_amdgcn_s_setprio(1); _Pragma("unroll") for (int m = 0; m < 4; ++m) _Pragma("unroll") for (int n = 0; n < 2; ++n) _Pragma("unroll") for (int k = 0; k < 2; ++k) \
;         acc[ai][bj][m][n] = __builtin_amdgcn_mfma_f32_16x16x32_bf16(Bt[n][k], At[m][k], acc[ai][bj][m][n], 0, 0, 0); __builtin_amdgcn_s_setprio(0); } while (0)
; #define PG8_WAIT_V(n) asm volatile("s_waitcnt vmcnt(" #n ")" ::: "memory")
; #define PG8_WAIT_L(n) asm volatile("s_waitcnt lgkmcnt(" #n ")" ::: "memory")
; #define PG8_BAR __builtin_amdgcn_s_barrier()
; #define PG8_SCHED __builtin_amdgcn_sched_barrier(0)
; template <class Epi, class Sched>
; __device__ __forceinline__ void gemm_phase(PG8_LAS unsigned char* lds, PG8_LAS unsigned char* xl, const Gemm g, const Sched& S, const Epi& E) {
;     ...
;             PG8_LDB(B0, 1, 0); PG8_LDB(B1, 1, 1); PG8_SCHED; PG8_LDA(At, 1, 0); PG8_STAGE(PG8_SA(0, 1), a2 + hsA, voffA);
;             PG8_WAIT_V(8); PG8_WAIT_L(0); PG8_BAR; PG8_MMA(0, 0, At, B0); PG8_MMA(0, 1, At, B1); PG8_BAR; PG8_SCHED;
	s_setprio 0
	s_add_i32 s68, 0, 0x18000
	v_add_u32_e32 v169, s68, v147
	s_add_i32 s76, 0, 0x1c000
	ds_read_b128 v[170:173], v169
	ds_read_b128 v[174:177], v169 offset:1024
	ds_read_b128 v[180:183], v169 offset:2048
	ds_read_b128 v[184:187], v169 offset:3072
	v_add_u32_e32 v169, s76, v147
	ds_read_b128 v[188:191], v169
	ds_read_b128 v[192:195], v169 offset:1024
	ds_read_b128 v[196:199], v169 offset:2048
	ds_read_b128 v[200:203], v169 offset:3072
	s_add_u32 s36, s36, 0x40000
	s_addc_u32 s37, s37, 0
	s_mov_b32 m0, s59
	v_lshl_add_u64 v[244:245], s[36:37], 0, v[128:129]
	ds_read_b128 v[204:207], v159 offset:32768
	ds_read_b128 v[208:211], v159 offset:33792
	ds_read_b128 v[212:215], v159 offset:34816
	ds_read_b128 v[216:219], v159 offset:35840
	ds_read_b128 v[222:225], v159 offset:36864
	ds_read_b128 v[226:229], v159 offset:37888
	ds_read_b128 v[230:233], v159 offset:38912
	ds_read_b128 v[234:237], v159 offset:39936
	global_load_lds_dwordx4 v[244:245], off
	v_lshl_add_u64 v[244:245], s[36:37], 0, v[132:133]
	s_mov_b32 m0, s60
	s_nop 0
	global_load_lds_dwordx4 v[244:245], off
	s_waitcnt vmcnt(8) lgkmcnt(0)
	s_setprio 1
	s_barrier
	v_mfma_f32_16x16x32_bf16 v[124:127], v[170:173], v[204:207], v[124:127]
	v_mfma_f32_16x16x32_bf16 v[120:123], v[180:183], v[204:207], v[120:123]
	v_mfma_f32_16x16x32_bf16 v[108:111], v[170:173], v[212:215], v[108:111]
	v_mfma_f32_16x16x32_bf16 v[104:107], v[180:183], v[212:215], v[104:107]
	v_mfma_f32_16x16x32_bf16 v[92:95], v[170:173], v[222:225], v[92:95]
	v_mfma_f32_16x16x32_bf16 v[88:91], v[180:183], v[222:225], v[88:91]
	v_mfma_f32_16x16x32_bf16 v[76:79], v[170:173], v[230:233], v[76:79]
	v_mfma_f32_16x16x32_bf16 v[72:75], v[180:183], v[230:233], v[72:75]
	v_mfma_f32_16x16x32_bf16 v[124:127], v[174:177], v[208:211], v[124:127]
	v_mfma_f32_16x16x32_bf16 v[120:123], v[184:187], v[208:211], v[120:123]
	v_mfma_f32_16x16x32_bf16 v[108:111], v[174:177], v[216:219], v[108:111]
	v_mfma_f32_16x16x32_bf16 v[104:107], v[184:187], v[216:219], v[104:107]
	v_mfma_f32_16x16x32_bf16 v[92:95], v[174:177], v[226:229], v[92:95]
	v_mfma_f32_16x16x32_bf16 v[88:91], v[184:187], v[226:229], v[88:91]
	v_mfma_f32_16x16x32_bf16 v[76:79], v[174:177], v[234:237], v[76:79]
	v_mfma_f32_16x16x32_bf16 v[72:75], v[184:187], v[234:237], v[72:75]
	s_setprio 0
	s_setprio 1
	v_mfma_f32_16x16x32_bf16 v[116:119], v[188:191], v[204:207], v[116:119]
	v_mfma_f32_16x16x32_bf16 v[112:115], v[196:199], v[204:207], v[112:115]
	v_mfma_f32_16x16x32_bf16 v[100:103], v[188:191], v[212:215], v[100:103]
	v_mfma_f32_16x16x32_bf16 v[96:99], v[196:199], v[212:215], v[96:99]
	v_mfma_f32_16x16x32_bf16 v[84:87], v[188:191], v[222:225], v[84:87]
	v_mfma_f32_16x16x32_bf16 v[80:83], v[196:199], v[222:225], v[80:83]
	v_mfma_f32_16x16x32_bf16 v[68:71], v[188:191], v[230:233], v[68:71]
	v_mfma_f32_16x16x32_bf16 v[64:67], v[196:199], v[230:233], v[64:67]
	v_mfma_f32_16x16x32_bf16 v[116:119], v[192:195], v[208:211], v[116:119]
	v_mfma_f32_16x16x32_bf16 v[112:115], v[200:203], v[208:211], v[112:115]
	v_mfma_f32_16x16x32_bf16 v[100:103], v[192:195], v[216:219], v[100:103]
	v_mfma_f32_16x16x32_bf16 v[96:99], v[200:203], v[216:219], v[96:99]
	v_mfma_f32_16x16x32_bf16 v[84:87], v[192:195], v[226:229], v[84:87]
	v_mfma_f32_16x16x32_bf16 v[80:83], v[200:203], v[226:229], v[80:83]
	v_mfma_f32_16x16x32_bf16 v[68:71], v[192:195], v[234:237], v[68:71]
	v_mfma_f32_16x16x32_bf16 v[64:67], v[200:203], v[234:237], v[64:67]
	s_barrier
; #define PG8_STAGE(bufoff, gbase, voff) do { _Pragma("unroll") for (int _i = 0; _i < 2; ++_i) \
;         __builtin_amdgcn_global_load_lds((const unsigned*)((const char*)(gbase) + (voff)[_i]), (PG8_LAS unsigned*)(lds + (bufoff) + ldsw + _i * 8192), 16, 0, 0); } while (0)
; #define PG8_LDA(dst, b, h) do { _Pragma("unroll") for (int m = 0; m < 4; ++m) _Pragma("unroll") for (int k = 0; k < 2; ++k) dst[m][k] = *(const PG8_LAS bf16x8*)(lds + PG8_SA(b, h) + aoff + m * 2048 + k * 1024); } while (0)
; #define PG8_MMA(ai, bj, At, Bt) do { __builtin_amdgcn_s_setprio(1); _Pragma("unroll") for (int m = 0; m < 4; ++m) _Pragma("unroll") for (int n = 0; n < 2; ++n) _Pragma("unroll") for (int k = 0; k < 2; ++k) \
;         acc[ai][bj][m][n] = __builtin_amdgcn_mfma_f32_16x16x32_bf16(Bt[n][k], At[m][k], acc[ai][bj][m][n], 0, 0, 0); __builtin_amdgcn_s_setprio(0); } while (0)
; #define PG8_WAIT_V(n) asm volatile("s_waitcnt vmcnt(" #n ")" ::: "memory")
; #define PG8_WAIT_L(n) asm volatile("s_waitcnt lgkmcnt(" #n ")" ::: "memory")
; #define PG8_BAR __builtin_amdgcn_s_barrier()
; #define PG8_SCHED __builtin_amdgcn_sched_barrier(0)
; template <class Epi, class Sched>
; __device__ __forceinline__ void gemm_phase(PG8_LAS unsigned char* lds, PG8_LAS unsigned char* xl, const Gemm g, const Sched& S, const Epi& E) {
;     ...
;             PG8_LDA(At, 1, 1); PG8_STAGE(PG8_SB(1, 0), b3, voffB); PG8_STAGE(PG8_SB(1, 1), b3 + hsB, voffB); PG8_STAGE(PG8_SA(1, 0), a3, voffA);
;             PG8_WAIT_V(8); PG8_WAIT_L(0); PG8_BAR; PG8_MMA(1, 0, At, B0); PG8_MMA(1, 1, At, B1); PG8_BAR; PG8_SCHED;
;         }
	s_setprio 0
	s_add_i32 s36, s68, s56
	v_lshl_add_u64 v[144:145], v[144:145], 0, s[16:17]
	s_mov_b32 m0, s36
	ds_read_b128 v[204:207], v159 offset:49152
	ds_read_b128 v[208:211], v159 offset:50176
	ds_read_b128 v[212:215], v159 offset:51200
	ds_read_b128 v[216:219], v159 offset:52224
	ds_read_b128 v[222:225], v159 offset:53248
	ds_read_b128 v[226:229], v159 offset:54272
	ds_read_b128 v[230:233], v159 offset:55296
	ds_read_b128 v[234:237], v159 offset:56320
	global_load_lds_dwordx4 v[144:145], off
	s_add_i32 m0, s36, 0x2000
	s_add_u32 s34, s34, 0x40080
	v_lshl_add_u64 v[144:145], v[238:239], 0, s[16:17]
	s_addc_u32 s35, s35, 0
	s_add_i32 s36, s76, s56
	global_load_lds_dwordx4 v[144:145], off
	v_lshl_add_u64 v[144:145], s[34:35], 0, v[130:131]
	s_mov_b32 m0, s36
	s_nop 0
	global_load_lds_dwordx4 v[144:145], off
	v_lshl_add_u64 v[144:145], s[34:35], 0, v[134:135]
	s_add_i32 m0, s36, 0x2000
	s_nop 0
	global_load_lds_dwordx4 v[144:145], off
	v_lshl_add_u64 v[144:145], v[240:241], 0, s[16:17]
	s_mov_b32 m0, s62
	s_nop 0
	global_load_lds_dwordx4 v[144:145], off
	v_lshl_add_u64 v[144:145], v[242:243], 0, s[16:17]
	s_mov_b32 m0, s63
	s_nop 0
	global_load_lds_dwordx4 v[144:145], off
	s_waitcnt vmcnt(8) lgkmcnt(0)
	s_setprio 1
	s_barrier
	v_mfma_f32_16x16x32_bf16 v[60:63], v[170:173], v[204:207], v[60:63]
	v_mfma_f32_16x16x32_bf16 v[56:59], v[180:183], v[204:207], v[56:59]
	v_mfma_f32_16x16x32_bf16 v[44:47], v[170:173], v[212:215], v[44:47]
	v_mfma_f32_16x16x32_bf16 v[40:43], v[180:183], v[212:215], v[40:43]
	v_mfma_f32_16x16x32_bf16 v[28:31], v[170:173], v[222:225], v[28:31]
	v_mfma_f32_16x16x32_bf16 v[24:27], v[180:183], v[222:225], v[24:27]
	v_mfma_f32_16x16x32_bf16 v[12:15], v[170:173], v[230:233], v[12:15]
	v_mfma_f32_16x16x32_bf16 v[8:11], v[180:183], v[230:233], v[8:11]
	v_mfma_f32_16x16x32_bf16 v[60:63], v[174:177], v[208:211], v[60:63]
	v_mfma_f32_16x16x32_bf16 v[56:59], v[184:187], v[208:211], v[56:59]
	v_mfma_f32_16x16x32_bf16 v[44:47], v[174:177], v[216:219], v[44:47]
	v_mfma_f32_16x16x32_bf16 v[40:43], v[184:187], v[216:219], v[40:43]
	v_mfma_f32_16x16x32_bf16 v[28:31], v[174:177], v[226:229], v[28:31]
	v_mfma_f32_16x16x32_bf16 v[24:27], v[184:187], v[226:229], v[24:27]
	v_mfma_f32_16x16x32_bf16 v[12:15], v[174:177], v[234:237], v[12:15]
	v_mfma_f32_16x16x32_bf16 v[8:11], v[184:187], v[234:237], v[8:11]
	s_setprio 0
	s_setprio 1
	v_mfma_f32_16x16x32_bf16 v[52:55], v[188:191], v[204:207], v[52:55]
	s_add_i32 s75, s75, 2
	v_mfma_f32_16x16x32_bf16 v[48:51], v[196:199], v[204:207], v[48:51]
	s_add_u32 s73, s73, 0x100
	v_mfma_f32_16x16x32_bf16 v[36:39], v[188:191], v[212:215], v[36:39]
	s_addc_u32 s74, s74, 0
	v_mfma_f32_16x16x32_bf16 v[32:35], v[196:199], v[212:215], v[32:35]
	s_add_u32 s30, s30, 0x100
	v_mfma_f32_16x16x32_bf16 v[20:23], v[188:191], v[222:225], v[20:23]
	s_addc_u32 s31, s31, 0
	v_mfma_f32_16x16x32_bf16 v[16:19], v[196:199], v[222:225], v[16:19]
	s_cmp_gt_u32 s75, 13
	v_mfma_f32_16x16x32_bf16 v[4:7], v[188:191], v[230:233], v[4:7]
	v_mfma_f32_16x16x32_bf16 v[0:3], v[196:199], v[230:233], v[0:3]
	v_mfma_f32_16x16x32_bf16 v[52:55], v[192:195], v[208:211], v[52:55]
	v_mfma_f32_16x16x32_bf16 v[48:51], v[200:203], v[208:211], v[48:51]
	v_mfma_f32_16x16x32_bf16 v[36:39], v[192:195], v[216:219], v[36:39]
	v_mfma_f32_16x16x32_bf16 v[32:35], v[200:203], v[216:219], v[32:35]
	v_mfma_f32_16x16x32_bf16 v[20:23], v[192:195], v[226:229], v[20:23]
	v_mfma_f32_16x16x32_bf16 v[16:19], v[200:203], v[226:229], v[16:19]
	v_mfma_f32_16x16x32_bf16 v[4:7], v[192:195], v[234:237], v[4:7]
	v_mfma_f32_16x16x32_bf16 v[0:3], v[200:203], v[234:237], v[0:3]
	s_barrier
	s_setprio 0
	s_cbranch_scc0 .LBB0_725

; #define PG8_STAGE(bufoff, gbase, voff) do { _Pragma("unroll") for (int _i = 0; _i < 2; ++_i) \
;         __builtin_amdgcn_global_load_lds((const unsigned*)((const char*)(gbase) + (voff)[_i]), (PG8_LAS unsigned*)(lds + (bufoff) + ldsw + _i * 8192), 16, 0, 0); } while (0)
; #define PG8_LDA(dst, b, h) do { _Pragma("unroll") for (int m = 0; m < 4; ++m) _Pragma("unroll") for (int k = 0; k < 2; ++k) dst[m][k] = *(const PG8_LAS bf16x8*)(lds + PG8_SA(b, h) + aoff + m * 2048 + k * 1024); } while (0)
; #define PG8_LDB(dst, b, h) do { _Pragma("unroll") for (int n = 0; n < 2; ++n) _Pragma("unroll") for (int k = 0; k < 2; ++k) dst[n][k] = *(const PG8_LAS bf16x8*)(lds + PG8_SB(b, h) + boff + n * 2048 + k * 1024); } while (0)
; #define PG8_WAIT_V(n) asm volatile("s_waitcnt vmcnt(" #n ")" ::: "memory")
; #define PG8_WAIT_L(n) asm volatile("s_waitcnt lgkmcnt(" #n ")" ::: "memory")
; template <class Epi, class Sched>
; __device__ __forceinline__ void gemm_phase(PG8_LAS unsigned char* lds, PG8_LAS unsigned char* xl, const Gemm g, const Sched& S, const Epi& E) {
;     ...
;             const bool last = (t == nt - 2);
;             const char* a1 = cA + (size_t)(t + 1) * kstep;
;             const char* a2 = last ? nA : cA + (size_t)(t + 2) * kstep; const char* b2 = last ? nB : cB + (size_t)(t + 2) * kstep;
;             const char* a3 = a2 + kstep; const char* b3 = b2 + kstep;
;             PG8_LDB(B0, 0, 0); PG8_LDB(B1, 0, 1); PG8_SCHED; PG8_LDA(At, 0, 0); PG8_STAGE(PG8_SA(1, 1), a1 + hsA, voffA);
;             PG8_WAIT_V(8); PG8_WAIT_L(0); PG8_BAR; PG8_MMA(0, 0, At, B0); PG8_MMA(0, 1, At, B1); PG8_BAR; PG8_SCHED;
;             PG8_LDA(At, 0, 1); PG8_STAGE(PG8_SB(0, 0), b2, voffB); PG8_STAGE(PG8_SB(0, 1), b2 + hsB, voffB); PG8_STAGE(PG8_SA(0, 0), a2, voffA);
;             PG8_WAIT_V(8); PG8_WAIT_L(0); PG8_BAR; PG8_MMA(1, 0, At, B0); PG8_MMA(1, 1, At, B1); PG8_BAR; PG8_SCHED;
;             PG8_LDB(B0, 1, 0); PG8_LDB(B1, 1, 1); PG8_SCHED; PG8_LDA(At, 1, 0); PG8_STAGE(PG8_SA(0, 1), a2 + hsA, voffA);
;             PG8_WAIT_V(8); PG8_WAIT_L(0); PG8_BAR; PG8_MMA(0, 0, At, B0); PG8_MMA(0, 1, At, B1); PG8_BAR; PG8_SCHED;
;             PG8_LDA(At, 1, 1); PG8_STAGE(PG8_SB(1, 0), b3, voffB); PG8_STAGE(PG8_SB(1, 1), b3 + hsB, voffB); PG8_STAGE(PG8_SA(1, 0), a3, voffA);
;             PG8_WAIT_V(8); PG8_WAIT_L(0); PG8_BAR; PG8_MMA(1, 0, At, B0); PG8_MMA(1, 1, At, B1); PG8_BAR; PG8_SCHED;
.LBB0_824:
	s_add_u32 s26, s37, s20
	s_addc_u32 s27, s42, s21
	s_and_b64 s[28:29], s[6:7], exec
	s_cselect_b32 s46, s27, s31
	s_cselect_b32 s47, s26, s30
	s_add_u32 s28, s43, s22
	s_addc_u32 s29, s50, s23
	s_and_b64 s[34:35], s[6:7], exec
	s_cselect_b32 s70, s29, s3
	s_cselect_b32 s72, s28, s2
	s_add_u32 s73, s2, 0x100
	s_addc_u32 s74, s3, 0
	s_add_u32 s2, s30, 0x40080
	v_mov_b32_e32 v0, 0
	s_addc_u32 s3, s31, 0
	s_mov_b32 s75, -2
	ds_read_b128 v[170:173], v164
	ds_read_b128 v[174:177], v164 offset:1024
	ds_read_b128 v[180:183], v164 offset:2048
	ds_read_b128 v[184:187], v164 offset:3072
	ds_read_b128 v[188:191], v165
	ds_read_b128 v[192:195], v165 offset:1024
	ds_read_b128 v[196:199], v165 offset:2048
	ds_read_b128 v[200:203], v165 offset:3072
	s_add_u32 s30, s2, 0xfffc0080
	s_addc_u32 s31, s3, -1
	s_cmp_eq_u32 s75, 12
	s_cselect_b32 s35, s46, s31
	s_cselect_b32 s34, s47, s30
	s_cselect_b32 s31, s70, s74
	s_cselect_b32 s30, s72, s73
	v_lshl_add_u64 v[238:239], s[2:3], 0, v[140:141]
	s_add_i32 m0, s55, 0xc000
	ds_read_b128 v[204:207], v166
	ds_read_b128 v[208:211], v166 offset:1024
	ds_read_b128 v[212:215], v166 offset:2048
	ds_read_b128 v[216:219], v166 offset:3072
	ds_read_b128 v[222:225], v166 offset:4096
	ds_read_b128 v[226:229], v166 offset:5120
	ds_read_b128 v[230:233], v166 offset:6144
	ds_read_b128 v[234:237], v166 offset:7168
	global_load_lds_dwordx4 v[238:239], off
	v_lshl_add_u64 v[238:239], s[2:3], 0, v[138:139]
	s_add_i32 m0, s55, 0xe000
	s_nop 0
	global_load_lds_dwordx4 v[238:239], off
	s_waitcnt vmcnt(8) lgkmcnt(0)
	s_setprio 1
	s_barrier
	v_mfma_f32_16x16x32_bf16 v[124:127], v[170:173], v[204:207], 0
	v_mfma_f32_16x16x32_bf16 v[116:119], v[180:183], v[204:207], 0
	v_mfma_f32_16x16x32_bf16 v[108:111], v[170:173], v[212:215], 0
	v_mfma_f32_16x16x32_bf16 v[100:103], v[180:183], v[212:215], 0
	v_mfma_f32_16x16x32_bf16 v[92:95], v[170:173], v[222:225], 0
	v_mfma_f32_16x16x32_bf16 v[84:87], v[180:183], v[222:225], 0
	v_mfma_f32_16x16x32_bf16 v[76:79], v[170:173], v[230:233], 0
	v_mfma_f32_16x16x32_bf16 v[68:71], v[180:183], v[230:233], 0
	v_mfma_f32_16x16x32_bf16 v[124:127], v[174:177], v[208:211], v[124:127]
	v_mfma_f32_16x16x32_bf16 v[116:119], v[184:187], v[208:211], v[116:119]
	v_mfma_f32_16x16x32_bf16 v[108:111], v[174:177], v[216:219], v[108:111]
	v_mfma_f32_16x16x32_bf16 v[100:103], v[184:187], v[216:219], v[100:103]
	v_mfma_f32_16x16x32_bf16 v[92:95], v[174:177], v[226:229], v[92:95]
	v_mfma_f32_16x16x32_bf16 v[84:87], v[184:187], v[226:229], v[84:87]
	v_mfma_f32_16x16x32_bf16 v[76:79], v[174:177], v[234:237], v[76:79]
	v_mfma_f32_16x16x32_bf16 v[68:71], v[184:187], v[234:237], v[68:71]
	s_setprio 0
	s_setprio 1
	v_mfma_f32_16x16x32_bf16 v[120:123], v[188:191], v[204:207], 0
	v_mfma_f32_16x16x32_bf16 v[112:115], v[196:199], v[204:207], 0
	v_mfma_f32_16x16x32_bf16 v[104:107], v[188:191], v[212:215], 0
	v_mfma_f32_16x16x32_bf16 v[96:99], v[196:199], v[212:215], 0
	v_mfma_f32_16x16x32_bf16 v[88:91], v[188:191], v[222:225], 0
	v_mfma_f32_16x16x32_bf16 v[80:83], v[196:199], v[222:225], 0
	v_mfma_f32_16x16x32_bf16 v[72:75], v[188:191], v[230:233], 0
	v_mfma_f32_16x16x32_bf16 v[64:67], v[196:199], v[230:233], 0
	v_mfma_f32_16x16x32_bf16 v[120:123], v[192:195], v[208:211], v[120:123]
	v_mfma_f32_16x16x32_bf16 v[112:115], v[200:203], v[208:211], v[112:115]
	v_mfma_f32_16x16x32_bf16 v[104:107], v[192:195], v[216:219], v[104:107]
	v_mfma_f32_16x16x32_bf16 v[96:99], v[200:203], v[216:219], v[96:99]
	v_mfma_f32_16x16x32_bf16 v[88:91], v[192:195], v[226:229], v[88:91]
	v_mfma_f32_16x16x32_bf16 v[80:83], v[200:203], v[226:229], v[80:83]
	v_mfma_f32_16x16x32_bf16 v[72:75], v[192:195], v[234:237], v[72:75]
	v_mfma_f32_16x16x32_bf16 v[64:67], v[200:203], v[234:237], v[64:67]
	s_barrier
	s_setprio 0
	s_add_i32 s68, s54, s51
	v_lshl_add_u64 v[238:239], s[30:31], 0, v[132:133]
	s_mov_b32 m0, s68
	ds_read_b128 v[204:207], v166 offset:16384
	ds_read_b128 v[208:211], v166 offset:17408
	ds_read_b128 v[212:215], v166 offset:18432
	ds_read_b128 v[216:219], v166 offset:19456
	ds_read_b128 v[222:225], v166 offset:20480
	ds_read_b128 v[226:229], v166 offset:21504
	ds_read_b128 v[230:233], v166 offset:22528
	ds_read_b128 v[234:237], v166 offset:23552
	global_load_lds_dwordx4 v[238:239], off
	s_add_i32 m0, s68, 0x2000
	s_add_u32 s76, s30, 0x40000
	v_lshl_add_u64 v[240:241], s[30:31], 0, v[128:129]
	s_addc_u32 s77, s31, 0
	s_add_i32 s68, s62, s51
	global_load_lds_dwordx4 v[240:241], off
	v_lshl_add_u64 v[242:243], s[76:77], 0, v[132:133]
	s_mov_b32 m0, s68
	v_lshl_add_u64 v[244:245], s[34:35], 0, v[130:131]
	global_load_lds_dwordx4 v[242:243], off
	v_lshl_add_u64 v[242:243], s[76:77], 0, v[128:129]
	s_add_i32 m0, s68, 0x2000
	s_nop 0
	global_load_lds_dwordx4 v[242:243], off
	v_lshl_add_u64 v[242:243], s[34:35], 0, v[134:135]
	s_mov_b32 m0, s55
	s_nop 0
	global_load_lds_dwordx4 v[242:243], off
	s_mov_b32 m0, s56
	s_nop 0
	global_load_lds_dwordx4 v[244:245], off
	s_waitcnt vmcnt(8) lgkmcnt(0)
	s_setprio 1
	s_barrier
; #define PG8_STAGE(bufoff, gbase, voff) do { _Pragma("unroll") for (int _i = 0; _i < 2; ++_i) \
;         __builtin_amdgcn_global_load_lds((const unsigned*)((const char*)(gbase) + (voff)[_i]), (PG8_LAS unsigned*)(lds + (bufoff) + ldsw + _i * 8192), 16, 0, 0); } while (0)
; #define PG8_LDA(dst, b, h) do { _Pragma("unroll") for (int m = 0; m < 4; ++m) _Pragma("unroll") for (int k = 0; k < 2; ++k) dst[m][k] = *(const PG8_LAS bf16x8*)(lds + PG8_SA(b, h) + aoff + m * 2048 + k * 1024); } while (0)
; #define PG8_LDB(dst, b, h) do { _Pragma("unroll") for (int n = 0; n < 2; ++n) _Pragma("unroll") for (int k = 0; k < 2; ++k) dst[n][k] = *(const PG8_LAS bf16x8*)(lds + PG8_SB(b, h) + boff + n * 2048 + k * 1024); } while (0)
; #define PG8_MMA(ai, bj, At, Bt) do { __builtin_amdgcn_s_setprio(1); _Pragma("unroll") for (int m = 0; m < 4; ++m) _Pragma("unroll") for (int n = 0; n < 2; ++n) _Pragma("unroll") for (int k = 0; k < 2; ++k) \
;         acc[ai][bj][m][n] = __builtin_amdgcn_mfma_f32_16x16x32_bf16(Bt[n][k], At[m][k], acc[ai][bj][m][n], 0, 0, 0); __builtin_amdgcn_s_setprio(0); } while (0)
; #define PG8_WAIT_V(n) asm volatile("s_waitcnt vmcnt(" #n ")" ::: "memory")
; #define PG8_WAIT_L(n) asm volatile("s_waitcnt lgkmcnt(" #n ")" ::: "memory")
; #define PG8_BAR __builtin_amdgcn_s_barrier()
; #define PG8_SCHED __builtin_amdgcn_sched_barrier(0)
; template <class Epi, class Sched>
; __device__ __forceinline__ void gemm_phase(PG8_LAS unsigned char* lds, PG8_LAS unsigned char* xl, const Gemm g, const Sched& S, const Epi& E) {
;     ...
;             PG8_LDA(At, 0, 1); PG8_STAGE(PG8_SB(0, 0), b2, voffB); PG8_STAGE(PG8_SB(0, 1), b2 + hsB, voffB); PG8_STAGE(PG8_SA(0, 0), a2, voffA);
;             PG8_WAIT_V(8); PG8_WAIT_L(0); PG8_BAR; PG8_MMA(1, 0, At, B0); PG8_MMA(1, 1, At, B1); PG8_BAR; PG8_SCHED;
;             PG8_LDB(B0, 1, 0); PG8_LDB(B1, 1, 1); PG8_SCHED; PG8_LDA(At, 1, 0); PG8_STAGE(PG8_SA(0, 1), a2 + hsA, voffA);
;             PG8_WAIT_V(8); PG8_WAIT_L(0); PG8_BAR; PG8_MMA(0, 0, At, B0); PG8_MMA(0, 1, At, B1); PG8_BAR; PG8_SCHED;
	v_mfma_f32_16x16x32_bf16 v[60:63], v[170:173], v[204:207], 0
	v_mfma_f32_16x16x32_bf16 v[52:55], v[180:183], v[204:207], 0
	v_mfma_f32_16x16x32_bf16 v[44:47], v[170:173], v[212:215], 0
	v_mfma_f32_16x16x32_bf16 v[36:39], v[180:183], v[212:215], 0
	v_mfma_f32_16x16x32_bf16 v[28:31], v[170:173], v[222:225], 0
	v_mfma_f32_16x16x32_bf16 v[20:23], v[180:183], v[222:225], 0
	v_mfma_f32_16x16x32_bf16 v[12:15], v[170:173], v[230:233], 0
	v_mfma_f32_16x16x32_bf16 v[4:7], v[180:183], v[230:233], 0
	v_mfma_f32_16x16x32_bf16 v[60:63], v[174:177], v[208:211], v[60:63]
	v_mfma_f32_16x16x32_bf16 v[52:55], v[184:187], v[208:211], v[52:55]
	v_mfma_f32_16x16x32_bf16 v[44:47], v[174:177], v[216:219], v[44:47]
	v_mfma_f32_16x16x32_bf16 v[36:39], v[184:187], v[216:219], v[36:39]
	v_mfma_f32_16x16x32_bf16 v[28:31], v[174:177], v[226:229], v[28:31]
	v_mfma_f32_16x16x32_bf16 v[20:23], v[184:187], v[226:229], v[20:23]
	v_mfma_f32_16x16x32_bf16 v[12:15], v[174:177], v[234:237], v[12:15]
	v_mfma_f32_16x16x32_bf16 v[4:7], v[184:187], v[234:237], v[4:7]
	s_setprio 0
	s_setprio 1
	v_mfma_f32_16x16x32_bf16 v[56:59], v[188:191], v[204:207], 0
	v_mfma_f32_16x16x32_bf16 v[48:51], v[196:199], v[204:207], 0
	v_mfma_f32_16x16x32_bf16 v[40:43], v[188:191], v[212:215], 0
	v_mfma_f32_16x16x32_bf16 v[32:35], v[196:199], v[212:215], 0
	v_mfma_f32_16x16x32_bf16 v[24:27], v[188:191], v[222:225], 0
	v_mfma_f32_16x16x32_bf16 v[16:19], v[196:199], v[222:225], 0
	v_mfma_f32_16x16x32_bf16 v[8:11], v[188:191], v[230:233], 0
	v_mfma_f32_16x16x32_bf16 v[0:3], v[196:199], v[230:233], 0
	v_mfma_f32_16x16x32_bf16 v[56:59], v[192:195], v[208:211], v[56:59]
	v_mfma_f32_16x16x32_bf16 v[48:51], v[200:203], v[208:211], v[48:51]
	v_mfma_f32_16x16x32_bf16 v[40:43], v[192:195], v[216:219], v[40:43]
	v_mfma_f32_16x16x32_bf16 v[32:35], v[200:203], v[216:219], v[32:35]
	v_mfma_f32_16x16x32_bf16 v[24:27], v[192:195], v[226:229], v[24:27]
	v_mfma_f32_16x16x32_bf16 v[16:19], v[200:203], v[226:229], v[16:19]
	v_mfma_f32_16x16x32_bf16 v[8:11], v[192:195], v[234:237], v[8:11]
	v_mfma_f32_16x16x32_bf16 v[0:3], v[200:203], v[234:237], v[0:3]
	s_barrier
	s_setprio 0
	s_add_i32 s68, 0, 0x18000
	v_add_u32_e32 v169, s68, v147
	s_add_i32 s76, 0, 0x1c000
	ds_read_b128 v[170:173], v169
	ds_read_b128 v[174:177], v169 offset:1024
	ds_read_b128 v[180:183], v169 offset:2048
	ds_read_b128 v[184:187], v169 offset:3072
	v_add_u32_e32 v169, s76, v147
	ds_read_b128 v[188:191], v169
	ds_read_b128 v[192:195], v169 offset:1024
	ds_read_b128 v[196:199], v169 offset:2048
	ds_read_b128 v[200:203], v169 offset:3072
	s_add_u32 s34, s34, 0x40000
	s_addc_u32 s35, s35, 0
	s_mov_b32 m0, s57
	v_lshl_add_u64 v[246:247], s[34:35], 0, v[134:135]
	ds_read_b128 v[204:207], v166 offset:32768
	ds_read_b128 v[208:211], v166 offset:33792
	ds_read_b128 v[212:215], v166 offset:34816
	ds_read_b128 v[216:219], v166 offset:35840
	ds_read_b128 v[222:225], v166 offset:36864
	ds_read_b128 v[226:229], v166 offset:37888
	ds_read_b128 v[230:233], v166 offset:38912
	ds_read_b128 v[234:237], v166 offset:39936
	global_load_lds_dwordx4 v[246:247], off
	v_lshl_add_u64 v[246:247], s[34:35], 0, v[130:131]
	s_mov_b32 m0, s58
	s_nop 0
	global_load_lds_dwordx4 v[246:247], off
	s_waitcnt vmcnt(8) lgkmcnt(0)
	s_setprio 1
	s_barrier
	v_mfma_f32_16x16x32_bf16 v[124:127], v[170:173], v[204:207], v[124:127]
	v_mfma_f32_16x16x32_bf16 v[116:119], v[180:183], v[204:207], v[116:119]
	v_mfma_f32_16x16x32_bf16 v[108:111], v[170:173], v[212:215], v[108:111]
	v_mfma_f32_16x16x32_bf16 v[100:103], v[180:183], v[212:215], v[100:103]
	v_mfma_f32_16x16x32_bf16 v[92:95], v[170:173], v[222:225], v[92:95]
	v_mfma_f32_16x16x32_bf16 v[84:87], v[180:183], v[222:225], v[84:87]
	v_mfma_f32_16x16x32_bf16 v[76:79], v[170:173], v[230:233], v[76:79]
	v_mfma_f32_16x16x32_bf16 v[68:71], v[180:183], v[230:233], v[68:71]
	v_mfma_f32_16x16x32_bf16 v[124:127], v[174:177], v[208:211], v[124:127]
	v_mfma_f32_16x16x32_bf16 v[116:119], v[184:187], v[208:211], v[116:119]
	v_mfma_f32_16x16x32_bf16 v[108:111], v[174:177], v[216:219], v[108:111]
	v_mfma_f32_16x16x32_bf16 v[100:103], v[184:187], v[216:219], v[100:103]
	v_mfma_f32_16x16x32_bf16 v[92:95], v[174:177], v[226:229], v[92:95]
	v_mfma_f32_16x16x32_bf16 v[84:87], v[184:187], v[226:229], v[84:87]
	v_mfma_f32_16x16x32_bf16 v[76:79], v[174:177], v[234:237], v[76:79]
	v_mfma_f32_16x16x32_bf16 v[68:71], v[184:187], v[234:237], v[68:71]
	s_setprio 0
	s_setprio 1
	v_mfma_f32_16x16x32_bf16 v[120:123], v[188:191], v[204:207], v[120:123]
	v_mfma_f32_16x16x32_bf16 v[112:115], v[196:199], v[204:207], v[112:115]
	v_mfma_f32_16x16x32_bf16 v[104:107], v[188:191], v[212:215], v[104:107]
	v_mfma_f32_16x16x32_bf16 v[96:99], v[196:199], v[212:215], v[96:99]
	v_mfma_f32_16x16x32_bf16 v[88:91], v[188:191], v[222:225], v[88:91]
	v_mfma_f32_16x16x32_bf16 v[80:83], v[196:199], v[222:225], v[80:83]
	v_mfma_f32_16x16x32_bf16 v[72:75], v[188:191], v[230:233], v[72:75]
	v_mfma_f32_16x16x32_bf16 v[64:67], v[196:199], v[230:233], v[64:67]
	v_mfma_f32_16x16x32_bf16 v[120:123], v[192:195], v[208:211], v[120:123]
	v_mfma_f32_16x16x32_bf16 v[112:115], v[200:203], v[208:211], v[112:115]
	v_mfma_f32_16x16x32_bf16 v[104:107], v[192:195], v[216:219], v[104:107]
	v_mfma_f32_16x16x32_bf16 v[96:99], v[200:203], v[216:219], v[96:99]
	v_mfma_f32_16x16x32_bf16 v[88:91], v[192:195], v[226:229], v[88:91]
	v_mfma_f32_16x16x32_bf16 v[80:83], v[200:203], v[226:229], v[80:83]
	v_mfma_f32_16x16x32_bf16 v[72:75], v[192:195], v[234:237], v[72:75]
	v_mfma_f32_16x16x32_bf16 v[64:67], v[200:203], v[234:237], v[64:67]
	s_barrier
; #define PG8_STAGE(bufoff, gbase, voff) do { _Pragma("unroll") for (int _i = 0; _i < 2; ++_i) \
;         __builtin_amdgcn_global_load_lds((const unsigned*)((const char*)(gbase) + (voff)[_i]), (PG8_LAS unsigned*)(lds + (bufoff) + ldsw + _i * 8192), 16, 0, 0); } while (0)
; #define PG8_LDA(dst, b, h) do { _Pragma("unroll") for (int m = 0; m < 4; ++m) _Pragma("unroll") for (int k = 0; k < 2; ++k) dst[m][k] = *(const PG8_LAS bf16x8*)(lds + PG8_SA(b, h) + aoff + m * 2048 + k * 1024); } while (0)
; #define PG8_LDB(dst, b, h) do { _Pragma("unroll") for (int n = 0; n < 2; ++n) _Pragma("unroll") for (int k = 0; k < 2; ++k) dst[n][k] = *(const PG8_LAS bf16x8*)(lds + PG8_SB(b, h) + boff + n * 2048 + k * 1024); } while (0)
; #define PG8_WAIT_V(n) asm volatile("s_waitcnt vmcnt(" #n ")" ::: "memory")
; #define PG8_WAIT_L(n) asm volatile("s_waitcnt lgkmcnt(" #n ")" ::: "memory")
; template <class Epi, class Sched>
; __device__ __forceinline__ void gemm_phase(PG8_LAS unsigned char* lds, PG8_LAS unsigned char* xl, const Gemm g, const Sched& S, const Epi& E) {
;     ...
;             const bool last = (t == nt - 2);
;             const char* a1 = cA + (size_t)(t + 1) * kstep;
;             const char* a2 = last ? nA : cA + (size_t)(t + 2) * kstep; const char* b2 = last ? nB : cB + (size_t)(t + 2) * kstep;
;             const char* a3 = a2 + kstep; const char* b3 = b2 + kstep;
;             PG8_LDB(B0, 0, 0); PG8_LDB(B1, 0, 1); PG8_SCHED; PG8_LDA(At, 0, 0); PG8_STAGE(PG8_SA(1, 1), a1 + hsA, voffA);
;             PG8_WAIT_V(8); PG8_WAIT_L(0); PG8_BAR; PG8_MMA(0, 0, At, B0); PG8_MMA(0, 1, At, B1); PG8_BAR; PG8_SCHED;
;             PG8_LDA(At, 0, 1); PG8_STAGE(PG8_SB(0, 0), b2, voffB); PG8_STAGE(PG8_SB(0, 1), b2 + hsB, voffB); PG8_STAGE(PG8_SA(0, 0), a2, voffA);
;             PG8_WAIT_V(8); PG8_WAIT_L(0); PG8_BAR; PG8_MMA(1, 0, At, B0); PG8_MMA(1, 1, At, B1); PG8_BAR; PG8_SCHED;
;             PG8_LDB(B0, 1, 0); PG8_LDB(B1, 1, 1); PG8_SCHED; PG8_LDA(At, 1, 0); PG8_STAGE(PG8_SA(0, 1), a2 + hsA, voffA);
;             PG8_WAIT_V(8); PG8_WAIT_L(0); PG8_BAR; PG8_MMA(0, 0, At, B0); PG8_MMA(0, 1, At, B1); PG8_BAR; PG8_SCHED;
;             PG8_LDA(At, 1, 1); PG8_STAGE(PG8_SB(1, 0), b3, voffB); PG8_STAGE(PG8_SB(1, 1), b3 + hsB, voffB); PG8_STAGE(PG8_SA(1, 0), a3, voffA);
;             PG8_WAIT_V(8); PG8_WAIT_L(0); PG8_BAR; PG8_MMA(1, 0, At, B0); PG8_MMA(1, 1, At, B1); PG8_BAR; PG8_SCHED;
	s_setprio 0
	s_add_i32 s34, s68, s51
	v_lshl_add_u64 v[238:239], v[238:239], 0, s[16:17]
	s_mov_b32 m0, s34
	ds_read_b128 v[204:207], v166 offset:49152
	ds_read_b128 v[208:211], v166 offset:50176
	ds_read_b128 v[212:215], v166 offset:51200
	ds_read_b128 v[216:219], v166 offset:52224
	ds_read_b128 v[222:225], v166 offset:53248
	ds_read_b128 v[226:229], v166 offset:54272
	ds_read_b128 v[230:233], v166 offset:55296
	ds_read_b128 v[234:237], v166 offset:56320
	global_load_lds_dwordx4 v[238:239], off
	s_add_i32 m0, s34, 0x2000
	s_add_u32 s30, s30, 0x40080
	v_lshl_add_u64 v[238:239], v[240:241], 0, s[16:17]
	s_addc_u32 s31, s31, 0
	s_add_i32 s34, s76, s51
	global_load_lds_dwordx4 v[238:239], off
	v_lshl_add_u64 v[238:239], s[30:31], 0, v[132:133]
	s_mov_b32 m0, s34
	s_nop 0
	global_load_lds_dwordx4 v[238:239], off
	v_lshl_add_u64 v[238:239], s[30:31], 0, v[128:129]
	s_add_i32 m0, s34, 0x2000
	s_nop 0
	global_load_lds_dwordx4 v[238:239], off
	v_lshl_add_u64 v[238:239], v[242:243], 0, s[16:17]
	s_mov_b32 m0, s59
	s_nop 0
	global_load_lds_dwordx4 v[238:239], off
	v_lshl_add_u64 v[238:239], v[244:245], 0, s[16:17]
	s_mov_b32 m0, s61
	s_nop 0
	global_load_lds_dwordx4 v[238:239], off
	s_waitcnt vmcnt(8) lgkmcnt(0)
	s_setprio 1
	s_barrier
	v_mfma_f32_16x16x32_bf16 v[60:63], v[170:173], v[204:207], v[60:63]
	v_mfma_f32_16x16x32_bf16 v[52:55], v[180:183], v[204:207], v[52:55]
	v_mfma_f32_16x16x32_bf16 v[44:47], v[170:173], v[212:215], v[44:47]
	v_mfma_f32_16x16x32_bf16 v[36:39], v[180:183], v[212:215], v[36:39]
	v_mfma_f32_16x16x32_bf16 v[28:31], v[170:173], v[222:225], v[28:31]
	v_mfma_f32_16x16x32_bf16 v[20:23], v[180:183], v[222:225], v[20:23]
	v_mfma_f32_16x16x32_bf16 v[12:15], v[170:173], v[230:233], v[12:15]
	v_mfma_f32_16x16x32_bf16 v[4:7], v[180:183], v[230:233], v[4:7]
	v_mfma_f32_16x16x32_bf16 v[60:63], v[174:177], v[208:211], v[60:63]
	v_mfma_f32_16x16x32_bf16 v[52:55], v[184:187], v[208:211], v[52:55]
	v_mfma_f32_16x16x32_bf16 v[44:47], v[174:177], v[216:219], v[44:47]
	v_mfma_f32_16x16x32_bf16 v[36:39], v[184:187], v[216:219], v[36:39]
	v_mfma_f32_16x16x32_bf16 v[28:31], v[174:177], v[226:229], v[28:31]
	v_mfma_f32_16x16x32_bf16 v[20:23], v[184:187], v[226:229], v[20:23]
	v_mfma_f32_16x16x32_bf16 v[12:15], v[174:177], v[234:237], v[12:15]
	v_mfma_f32_16x16x32_bf16 v[4:7], v[184:187], v[234:237], v[4:7]
	s_setprio 0
	s_setprio 1
	v_mfma_f32_16x16x32_bf16 v[56:59], v[188:191], v[204:207], v[56:59]
	s_add_i32 s75, s75, 2
	v_mfma_f32_16x16x32_bf16 v[48:51], v[196:199], v[204:207], v[48:51]
	s_add_u32 s73, s73, 0x100
	v_mfma_f32_16x16x32_bf16 v[40:43], v[188:191], v[212:215], v[40:43]
	s_addc_u32 s74, s74, 0
	v_mfma_f32_16x16x32_bf16 v[32:35], v[196:199], v[212:215], v[32:35]
	s_add_u32 s2, s2, 0x100
	v_mfma_f32_16x16x32_bf16 v[24:27], v[188:191], v[222:225], v[24:27]
	s_addc_u32 s3, s3, 0
	v_mfma_f32_16x16x32_bf16 v[16:19], v[196:199], v[222:225], v[16:19]
	s_cmp_gt_u32 s75, 13
	v_mfma_f32_16x16x32_bf16 v[8:11], v[188:191], v[230:233], v[8:11]
	v_mfma_f32_16x16x32_bf16 v[0:3], v[196:199], v[230:233], v[0:3]
	v_mfma_f32_16x16x32_bf16 v[56:59], v[192:195], v[208:211], v[56:59]
	v_mfma_f32_16x16x32_bf16 v[48:51], v[200:203], v[208:211], v[48:51]
	v_mfma_f32_16x16x32_bf16 v[40:43], v[192:195], v[216:219], v[40:43]
	v_mfma_f32_16x16x32_bf16 v[32:35], v[200:203], v[216:219], v[32:35]
	v_mfma_f32_16x16x32_bf16 v[24:27], v[192:195], v[226:229], v[24:27]
	v_mfma_f32_16x16x32_bf16 v[16:19], v[200:203], v[226:229], v[16:19]
	v_mfma_f32_16x16x32_bf16 v[8:11], v[192:195], v[234:237], v[8:11]
	v_mfma_f32_16x16x32_bf16 v[0:3], v[200:203], v[234:237], v[0:3]
	s_barrier
	s_setprio 0
	s_cbranch_scc1 .Lpeel_after_P8
.LBB0_825:
	ds_read_b128 v[170:173], v164
	ds_read_b128 v[174:177], v164 offset:1024
	ds_read_b128 v[180:183], v164 offset:2048
	ds_read_b128 v[184:187], v164 offset:3072
	ds_read_b128 v[188:191], v165
	ds_read_b128 v[192:195], v165 offset:1024
	ds_read_b128 v[196:199], v165 offset:2048
	ds_read_b128 v[200:203], v165 offset:3072
	s_add_u32 s30, s2, 0xfffc0080
	s_addc_u32 s31, s3, -1
	s_cmp_eq_u32 s75, 12
	s_cselect_b32 s35, s46, s31
	s_cselect_b32 s34, s47, s30
	s_cselect_b32 s31, s70, s74
	s_cselect_b32 s30, s72, s73
	v_lshl_add_u64 v[238:239], s[2:3], 0, v[140:141]
	s_add_i32 m0, s55, 0xc000
	ds_read_b128 v[204:207], v166
	ds_read_b128 v[208:211], v166 offset:1024
	ds_read_b128 v[212:215], v166 offset:2048
	ds_read_b128 v[216:219], v166 offset:3072
	ds_read_b128 v[222:225], v166 offset:4096
	ds_read_b128 v[226:229], v166 offset:5120
	ds_read_b128 v[230:233], v166 offset:6144
	ds_read_b128 v[234:237], v166 offset:7168
	global_load_lds_dwordx4 v[238:239], off
	v_lshl_add_u64 v[238:239], s[2:3], 0, v[138:139]
	s_add_i32 m0, s55, 0xe000
	s_nop 0
	global_load_lds_dwordx4 v[238:239], off
	s_waitcnt vmcnt(8) lgkmcnt(0)
	s_setprio 1
	s_barrier
; #define PG8_STAGE(bufoff, gbase, voff) do { _Pragma("unroll") for (int _i = 0; _i < 2; ++_i) \
;         __builtin_amdgcn_global_load_lds((const unsigned*)((const char*)(gbase) + (voff)[_i]), (PG8_LAS unsigned*)(lds + (bufoff) + ldsw + _i * 8192), 16, 0, 0); } while (0)
; #define PG8_LDA(dst, b, h) do { _Pragma("unroll") for (int m = 0; m < 4; ++m) _Pragma("unroll") for (int k = 0; k < 2; ++k) dst[m][k] = *(const PG8_LAS bf16x8*)(lds + PG8_SA(b, h) + aoff + m * 2048 + k * 1024); } while (0)
; #define PG8_LDB(dst, b, h) do { _Pragma("unroll") for (int n = 0; n < 2; ++n) _Pragma("unroll") for (int k = 0; k < 2; ++k) dst[n][k] = *(const PG8_LAS bf16x8*)(lds + PG8_SB(b, h) + boff + n * 2048 + k * 1024); } while (0)
; #define PG8_WAIT_V(n) asm volatile("s_waitcnt vmcnt(" #n ")" ::: "memory")
; #define PG8_WAIT_L(n) asm volatile("s_waitcnt lgkmcnt(" #n ")" ::: "memory")
; template <class Epi, class Sched>
; __device__ __forceinline__ void gemm_phase(PG8_LAS unsigned char* lds, PG8_LAS unsigned char* xl, const Gemm g, const Sched& S, const Epi& E) {
;     ...
;             const bool last = (t == nt - 2);
;             const char* a1 = cA + (size_t)(t + 1) * kstep;
;             const char* a2 = last ? nA : cA + (size_t)(t + 2) * kstep; const char* b2 = last ? nB : cB + (size_t)(t + 2) * kstep;
;             const char* a3 = a2 + kstep; const char* b3 = b2 + kstep;
;             PG8_LDB(B0, 0, 0); PG8_LDB(B1, 0, 1); PG8_SCHED; PG8_LDA(At, 0, 0); PG8_STAGE(PG8_SA(1, 1), a1 + hsA, voffA);
;             PG8_WAIT_V(8); PG8_WAIT_L(0); PG8_BAR; PG8_MMA(0, 0, At, B0); PG8_MMA(0, 1, At, B1); PG8_BAR; PG8_SCHED;
;             PG8_LDA(At, 0, 1); PG8_STAGE(PG8_SB(0, 0), b2, voffB); PG8_STAGE(PG8_SB(0, 1), b2 + hsB, voffB); PG8_STAGE(PG8_SA(0, 0), a2, voffA);
;             PG8_WAIT_V(8); PG8_WAIT_L(0); PG8_BAR; PG8_MMA(1, 0, At, B0); PG8_MMA(1, 1, At, B1); PG8_BAR; PG8_SCHED;
;             PG8_LDB(B0, 1, 0); PG8_LDB(B1, 1, 1); PG8_SCHED; PG8_LDA(At, 1, 0); PG8_STAGE(PG8_SA(0, 1), a2 + hsA, voffA);
;             PG8_WAIT_V(8); PG8_WAIT_L(0); PG8_BAR; PG8_MMA(0, 0, At, B0); PG8_MMA(0, 1, At, B1); PG8_BAR; PG8_SCHED;
;             PG8_LDA(At, 1, 1); PG8_STAGE(PG8_SB(1, 0), b3, voffB); PG8_STAGE(PG8_SB(1, 1), b3 + hsB, voffB); PG8_STAGE(PG8_SA(1, 0), a3, voffA);
;             PG8_WAIT_V(8); PG8_WAIT_L(0); PG8_BAR; PG8_MMA(1, 0, At, B0); PG8_MMA(1, 1, At, B1); PG8_BAR; PG8_SCHED;
	v_mfma_f32_16x16x32_bf16 v[124:127], v[170:173], v[204:207], v[124:127]
	v_mfma_f32_16x16x32_bf16 v[116:119], v[180:183], v[204:207], v[116:119]
	v_mfma_f32_16x16x32_bf16 v[108:111], v[170:173], v[212:215], v[108:111]
	v_mfma_f32_16x16x32_bf16 v[100:103], v[180:183], v[212:215], v[100:103]
	v_mfma_f32_16x16x32_bf16 v[92:95], v[170:173], v[222:225], v[92:95]
	v_mfma_f32_16x16x32_bf16 v[84:87], v[180:183], v[222:225], v[84:87]
	v_mfma_f32_16x16x32_bf16 v[76:79], v[170:173], v[230:233], v[76:79]
	v_mfma_f32_16x16x32_bf16 v[68:71], v[180:183], v[230:233], v[68:71]
	v_mfma_f32_16x16x32_bf16 v[124:127], v[174:177], v[208:211], v[124:127]
	v_mfma_f32_16x16x32_bf16 v[116:119], v[184:187], v[208:211], v[116:119]
	v_mfma_f32_16x16x32_bf16 v[108:111], v[174:177], v[216:219], v[108:111]
	v_mfma_f32_16x16x32_bf16 v[100:103], v[184:187], v[216:219], v[100:103]
	v_mfma_f32_16x16x32_bf16 v[92:95], v[174:177], v[226:229], v[92:95]
	v_mfma_f32_16x16x32_bf16 v[84:87], v[184:187], v[226:229], v[84:87]
	v_mfma_f32_16x16x32_bf16 v[76:79], v[174:177], v[234:237], v[76:79]
	v_mfma_f32_16x16x32_bf16 v[68:71], v[184:187], v[234:237], v[68:71]
	s_setprio 0
	s_setprio 1
	v_mfma_f32_16x16x32_bf16 v[120:123], v[188:191], v[204:207], v[120:123]
	v_mfma_f32_16x16x32_bf16 v[112:115], v[196:199], v[204:207], v[112:115]
	v_mfma_f32_16x16x32_bf16 v[104:107], v[188:191], v[212:215], v[104:107]
	v_mfma_f32_16x16x32_bf16 v[96:99], v[196:199], v[212:215], v[96:99]
	v_mfma_f32_16x16x32_bf16 v[88:91], v[188:191], v[222:225], v[88:91]
	v_mfma_f32_16x16x32_bf16 v[80:83], v[196:199], v[222:225], v[80:83]
	v_mfma_f32_16x16x32_bf16 v[72:75], v[188:191], v[230:233], v[72:75]
	v_mfma_f32_16x16x32_bf16 v[64:67], v[196:199], v[230:233], v[64:67]
	v_mfma_f32_16x16x32_bf16 v[120:123], v[192:195], v[208:211], v[120:123]
	v_mfma_f32_16x16x32_bf16 v[112:115], v[200:203], v[208:211], v[112:115]
	v_mfma_f32_16x16x32_bf16 v[104:107], v[192:195], v[216:219], v[104:107]
	v_mfma_f32_16x16x32_bf16 v[96:99], v[200:203], v[216:219], v[96:99]
	v_mfma_f32_16x16x32_bf16 v[88:91], v[192:195], v[226:229], v[88:91]
	v_mfma_f32_16x16x32_bf16 v[80:83], v[200:203], v[226:229], v[80:83]
	v_mfma_f32_16x16x32_bf16 v[72:75], v[192:195], v[234:237], v[72:75]
	v_mfma_f32_16x16x32_bf16 v[64:67], v[200:203], v[234:237], v[64:67]
	s_barrier
	s_setprio 0
	s_add_i32 s68, s54, s51
	v_lshl_add_u64 v[238:239], s[30:31], 0, v[132:133]
	s_mov_b32 m0, s68
	ds_read_b128 v[204:207], v166 offset:16384
	ds_read_b128 v[208:211], v166 offset:17408
	ds_read_b128 v[212:215], v166 offset:18432
	ds_read_b128 v[216:219], v166 offset:19456
	ds_read_b128 v[222:225], v166 offset:20480
	ds_read_b128 v[226:229], v166 offset:21504
	ds_read_b128 v[230:233], v166 offset:22528
	ds_read_b128 v[234:237], v166 offset:23552
	global_load_lds_dwordx4 v[238:239], off
	s_add_i32 m0, s68, 0x2000
	s_add_u32 s76, s30, 0x40000
	v_lshl_add_u64 v[240:241], s[30:31], 0, v[128:129]
	s_addc_u32 s77, s31, 0
	s_add_i32 s68, s62, s51
	global_load_lds_dwordx4 v[240:241], off
	v_lshl_add_u64 v[242:243], s[76:77], 0, v[132:133]
	s_mov_b32 m0, s68
	v_lshl_add_u64 v[244:245], s[34:35], 0, v[130:131]
	global_load_lds_dwordx4 v[242:243], off
	v_lshl_add_u64 v[242:243], s[76:77], 0, v[128:129]
	s_add_i32 m0, s68, 0x2000
	s_nop 0
	global_load_lds_dwordx4 v[242:243], off
	v_lshl_add_u64 v[242:243], s[34:35], 0, v[134:135]
	s_mov_b32 m0, s55
	s_nop 0
	global_load_lds_dwordx4 v[242:243], off
	s_mov_b32 m0, s56
	s_nop 0
	global_load_lds_dwordx4 v[244:245], off
	s_waitcnt vmcnt(8) lgkmcnt(0)
	s_setprio 1
	s_barrier
	v_mfma_f32_16x16x32_bf16 v[60:63], v[170:173], v[204:207], v[60:63]
	v_mfma_f32_16x16x32_bf16 v[52:55], v[180:183], v[204:207], v[52:55]
	v_mfma_f32_16x16x32_bf16 v[44:47], v[170:173], v[212:215], v[44:47]
	v_mfma_f32_16x16x32_bf16 v[36:39], v[180:183], v[212:215], v[36:39]
	v_mfma_f32_16x16x32_bf16 v[28:31], v[170:173], v[222:225], v[28:31]
	v_mfma_f32_16x16x32_bf16 v[20:23], v[180:183], v[222:225], v[20:23]
	v_mfma_f32_16x16x32_bf16 v[12:15], v[170:173], v[230:233], v[12:15]
	v_mfma_f32_16x16x32_bf16 v[4:7], v[180:183], v[230:233], v[4:7]
	v_mfma_f32_16x16x32_bf16 v[60:63], v[174:177], v[208:211], v[60:63]
	v_mfma_f32_16x16x32_bf16 v[52:55], v[184:187], v[208:211], v[52:55]
	v_mfma_f32_16x16x32_bf16 v[44:47], v[174:177], v[216:219], v[44:47]
	v_mfma_f32_16x16x32_bf16 v[36:39], v[184:187], v[216:219], v[36:39]
	v_mfma_f32_16x16x32_bf16 v[28:31], v[174:177], v[226:229], v[28:31]
	v_mfma_f32_16x16x32_bf16 v[20:23], v[184:187], v[226:229], v[20:23]
	v_mfma_f32_16x16x32_bf16 v[12:15], v[174:177], v[234:237], v[12:15]
	v_mfma_f32_16x16x32_bf16 v[4:7], v[184:187], v[234:237], v[4:7]
	s_setprio 0
	s_setprio 1
	v_mfma_f32_16x16x32_bf16 v[56:59], v[188:191], v[204:207], v[56:59]
	v_mfma_f32_16x16x32_bf16 v[48:51], v[196:199], v[204:207], v[48:51]
	v_mfma_f32_16x16x32_bf16 v[40:43], v[188:191], v[212:215], v[40:43]
	v_mfma_f32_16x16x32_bf16 v[32:35], v[196:199], v[212:215], v[32:35]
	v_mfma_f32_16x16x32_bf16 v[24:27], v[188:191], v[222:225], v[24:27]
	v_mfma_f32_16x16x32_bf16 v[16:19], v[196:199], v[222:225], v[16:19]
	v_mfma_f32_16x16x32_bf16 v[8:11], v[188:191], v[230:233], v[8:11]
	v_mfma_f32_16x16x32_bf16 v[0:3], v[196:199], v[230:233], v[0:3]
	v_mfma_f32_16x16x32_bf16 v[56:59], v[192:195], v[208:211], v[56:59]
	v_mfma_f32_16x16x32_bf16 v[48:51], v[200:203], v[208:211], v[48:51]
	v_mfma_f32_16x16x32_bf16 v[40:43], v[192:195], v[216:219], v[40:43]
	v_mfma_f32_16x16x32_bf16 v[32:35], v[200:203], v[216:219], v[32:35]
	v_mfma_f32_16x16x32_bf16 v[24:27], v[192:195], v[226:229], v[24:27]
	v_mfma_f32_16x16x32_bf16 v[16:19], v[200:203], v[226:229], v[16:19]
	v_mfma_f32_16x16x32_bf16 v[8:11], v[192:195], v[234:237], v[8:11]
	v_mfma_f32_16x16x32_bf16 v[0:3], v[200:203], v[234:237], v[0:3]
	s_barrier
; #define PG8_STAGE(bufoff, gbase, voff) do { _Pragma("unroll") for (int _i = 0; _i < 2; ++_i) \
;         __builtin_amdgcn_global_load_lds((const unsigned*)((const char*)(gbase) + (voff)[_i]), (PG8_LAS unsigned*)(lds + (bufoff) + ldsw + _i * 8192), 16, 0, 0); } while (0)
; #define PG8_LDA(dst, b, h) do { _Pragma("unroll") for (int m = 0; m < 4; ++m) _Pragma("unroll") for (int k = 0; k < 2; ++k) dst[m][k] = *(const PG8_LAS bf16x8*)(lds + PG8_SA(b, h) + aoff + m * 2048 + k * 1024); } while (0)
; #define PG8_LDB(dst, b, h) do { _Pragma("unroll") for (int n = 0; n < 2; ++n) _Pragma("unroll") for (int k = 0; k < 2; ++k) dst[n][k] = *(const PG8_LAS bf16x8*)(lds + PG8_SB(b, h) + boff + n * 2048 + k * 1024); } while (0)
; #define PG8_MMA(ai, bj, At, Bt) do { __builtin_amdgcn_s_setprio(1); _Pragma("unroll") for (int m = 0; m < 4; ++m) _Pragma("unroll") for (int n = 0; n < 2; ++n) _Pragma("unroll") for (int k = 0; k < 2; ++k) \
;         acc[ai][bj][m][n] = __builtin_amdgcn_mfma_f32_16x16x32_bf16(Bt[n][k], At[m][k], acc[ai][bj][m][n], 0, 0, 0); __builtin_amdgcn_s_setprio(0); } while (0)
; #define PG8_WAIT_V(n) asm volatile("s_waitcnt vmcnt(" #n ")" ::: "memory")
; #define PG8_WAIT_L(n) asm volatile("s_waitcnt lgkmcnt(" #n ")" ::: "memory")
; #define PG8_BAR __builtin_amdgcn_s_barrier()
; #define PG8_SCHED __builtin_amdgcn_sched_barrier(0)
; template <class Epi, class Sched>
; __device__ __forceinline__ void gemm_phase(PG8_LAS unsigned char* lds, PG8_LAS unsigned char* xl, const Gemm g, const Sched& S, const Epi& E) {
;     ...
;             PG8_LDB(B0, 1, 0); PG8_LDB(B1, 1, 1); PG8_SCHED; PG8_LDA(At, 1, 0); PG8_STAGE(PG8_SA(0, 1), a2 + hsA, voffA);
;             PG8_WAIT_V(8); PG8_WAIT_L(0); PG8_BAR; PG8_MMA(0, 0, At, B0); PG8_MMA(0, 1, At, B1); PG8_BAR; PG8_SCHED;
	s_setprio 0
	s_add_i32 s68, 0, 0x18000
	v_add_u32_e32 v169, s68, v147
	s_add_i32 s76, 0, 0x1c000
	ds_read_b128 v[170:173], v169
	ds_read_b128 v[174:177], v169 offset:1024
	ds_read_b128 v[180:183], v169 offset:2048
	ds_read_b128 v[184:187], v169 offset:3072
	v_add_u32_e32 v169, s76, v147
	ds_read_b128 v[188:191], v169
	ds_read_b128 v[192:195], v169 offset:1024
	ds_read_b128 v[196:199], v169 offset:2048
	ds_read_b128 v[200:203], v169 offset:3072
	s_add_u32 s34, s34, 0x40000
	s_addc_u32 s35, s35, 0
	s_mov_b32 m0, s57
	v_lshl_add_u64 v[246:247], s[34:35], 0, v[134:135]
	ds_read_b128 v[204:207], v166 offset:32768
	ds_read_b128 v[208:211], v166 offset:33792
	ds_read_b128 v[212:215], v166 offset:34816
	ds_read_b128 v[216:219], v166 offset:35840
	ds_read_b128 v[222:225], v166 offset:36864
	ds_read_b128 v[226:229], v166 offset:37888
	ds_read_b128 v[230:233], v166 offset:38912
	ds_read_b128 v[234:237], v166 offset:39936
	global_load_lds_dwordx4 v[246:247], off
	v_lshl_add_u64 v[246:247], s[34:35], 0, v[130:131]
	s_mov_b32 m0, s58
	s_nop 0
	global_load_lds_dwordx4 v[246:247], off
	s_waitcnt vmcnt(8) lgkmcnt(0)
	s_setprio 1
	s_barrier
	v_mfma_f32_16x16x32_bf16 v[124:127], v[170:173], v[204:207], v[124:127]
	v_mfma_f32_16x16x32_bf16 v[116:119], v[180:183], v[204:207], v[116:119]
	v_mfma_f32_16x16x32_bf16 v[108:111], v[170:173], v[212:215], v[108:111]
	v_mfma_f32_16x16x32_bf16 v[100:103], v[180:183], v[212:215], v[100:103]
	v_mfma_f32_16x16x32_bf16 v[92:95], v[170:173], v[222:225], v[92:95]
	v_mfma_f32_16x16x32_bf16 v[84:87], v[180:183], v[222:225], v[84:87]
	v_mfma_f32_16x16x32_bf16 v[76:79], v[170:173], v[230:233], v[76:79]
	v_mfma_f32_16x16x32_bf16 v[68:71], v[180:183], v[230:233], v[68:71]
	v_mfma_f32_16x16x32_bf16 v[124:127], v[174:177], v[208:211], v[124:127]
	v_mfma_f32_16x16x32_bf16 v[116:119], v[184:187], v[208:211], v[116:119]
	v_mfma_f32_16x16x32_bf16 v[108:111], v[174:177], v[216:219], v[108:111]
	v_mfma_f32_16x16x32_bf16 v[100:103], v[184:187], v[216:219], v[100:103]
	v_mfma_f32_16x16x32_bf16 v[92:95], v[174:177], v[226:229], v[92:95]
	v_mfma_f32_16x16x32_bf16 v[84:87], v[184:187], v[226:229], v[84:87]
	v_mfma_f32_16x16x32_bf16 v[76:79], v[174:177], v[234:237], v[76:79]
	v_mfma_f32_16x16x32_bf16 v[68:71], v[184:187], v[234:237], v[68:71]
	s_setprio 0
	s_setprio 1
	v_mfma_f32_16x16x32_bf16 v[120:123], v[188:191], v[204:207], v[120:123]
	v_mfma_f32_16x16x32_bf16 v[112:115], v[196:199], v[204:207], v[112:115]
	v_mfma_f32_16x16x32_bf16 v[104:107], v[188:191], v[212:215], v[104:107]
	v_mfma_f32_16x16x32_bf16 v[96:99], v[196:199], v[212:215], v[96:99]
	v_mfma_f32_16x16x32_bf16 v[88:91], v[188:191], v[222:225], v[88:91]
	v_mfma_f32_16x16x32_bf16 v[80:83], v[196:199], v[222:225], v[80:83]
	v_mfma_f32_16x16x32_bf16 v[72:75], v[188:191], v[230:233], v[72:75]
	v_mfma_f32_16x16x32_bf16 v[64:67], v[196:199], v[230:233], v[64:67]
	v_mfma_f32_16x16x32_bf16 v[120:123], v[192:195], v[208:211], v[120:123]
	v_mfma_f32_16x16x32_bf16 v[112:115], v[200:203], v[208:211], v[112:115]
	v_mfma_f32_16x16x32_bf16 v[104:107], v[192:195], v[216:219], v[104:107]
	v_mfma_f32_16x16x32_bf16 v[96:99], v[200:203], v[216:219], v[96:99]
	v_mfma_f32_16x16x32_bf16 v[88:91], v[192:195], v[226:229], v[88:91]
	v_mfma_f32_16x16x32_bf16 v[80:83], v[200:203], v[226:229], v[80:83]
	v_mfma_f32_16x16x32_bf16 v[72:75], v[192:195], v[234:237], v[72:75]
	v_mfma_f32_16x16x32_bf16 v[64:67], v[200:203], v[234:237], v[64:67]
	s_barrier
; #define PG8_STAGE(bufoff, gbase, voff) do { _Pragma("unroll") for (int _i = 0; _i < 2; ++_i) \
;         __builtin_amdgcn_global_load_lds((const unsigned*)((const char*)(gbase) + (voff)[_i]), (PG8_LAS unsigned*)(lds + (bufoff) + ldsw + _i * 8192), 16, 0, 0); } while (0)
; #define PG8_LDA(dst, b, h) do { _Pragma("unroll") for (int m = 0; m < 4; ++m) _Pragma("unroll") for (int k = 0; k < 2; ++k) dst[m][k] = *(const PG8_LAS bf16x8*)(lds + PG8_SA(b, h) + aoff + m * 2048 + k * 1024); } while (0)
; #define PG8_MMA(ai, bj, At, Bt) do { __builtin_amdgcn_s_setprio(1); _Pragma("unroll") for (int m = 0; m < 4; ++m) _Pragma("unroll") for (int n = 0; n < 2; ++n) _Pragma("unroll") for (int k = 0; k < 2; ++k) \
;         acc[ai][bj][m][n] = __builtin_amdgcn_mfma_f32_16x16x32_bf16(Bt[n][k], At[m][k], acc[ai][bj][m][n], 0, 0, 0); __builtin_amdgcn_s_setprio(0); } while (0)
; #define PG8_WAIT_V(n) asm volatile("s_waitcnt vmcnt(" #n ")" ::: "memory")
; #define PG8_WAIT_L(n) asm volatile("s_waitcnt lgkmcnt(" #n ")" ::: "memory")
; #define PG8_BAR __builtin_amdgcn_s_barrier()
; #define PG8_SCHED __builtin_amdgcn_sched_barrier(0)
; template <class Epi, class Sched>
; __device__ __forceinline__ void gemm_phase(PG8_LAS unsigned char* lds, PG8_LAS unsigned char* xl, const Gemm g, const Sched& S, const Epi& E) {
;     ...
;             PG8_LDA(At, 1, 1); PG8_STAGE(PG8_SB(1, 0), b3, voffB); PG8_STAGE(PG8_SB(1, 1), b3 + hsB, voffB); PG8_STAGE(PG8_SA(1, 0), a3, voffA);
;             PG8_WAIT_V(8); PG8_WAIT_L(0); PG8_BAR; PG8_MMA(1, 0, At, B0); PG8_MMA(1, 1, At, B1); PG8_BAR; PG8_SCHED;
	s_setprio 0
	s_add_i32 s34, s68, s51
	v_lshl_add_u64 v[238:239], v[238:239], 0, s[16:17]
	s_mov_b32 m0, s34
	ds_read_b128 v[204:207], v166 offset:49152
	ds_read_b128 v[208:211], v166 offset:50176
	ds_read_b128 v[212:215], v166 offset:51200
	ds_read_b128 v[216:219], v166 offset:52224
	ds_read_b128 v[222:225], v166 offset:53248
	ds_read_b128 v[226:229], v166 offset:54272
	ds_read_b128 v[230:233], v166 offset:55296
	ds_read_b128 v[234:237], v166 offset:56320
	global_load_lds_dwordx4 v[238:239], off
	s_add_i32 m0, s34, 0x2000
	s_add_u32 s30, s30, 0x40080
	v_lshl_add_u64 v[238:239], v[240:241], 0, s[16:17]
	s_addc_u32 s31, s31, 0
	s_add_i32 s34, s76, s51
	global_load_lds_dwordx4 v[238:239], off
	v_lshl_add_u64 v[238:239], s[30:31], 0, v[132:133]
	s_mov_b32 m0, s34
	s_nop 0
	global_load_lds_dwordx4 v[238:239], off
	v_lshl_add_u64 v[238:239], s[30:31], 0, v[128:129]
	s_add_i32 m0, s34, 0x2000
	s_nop 0
	global_load_lds_dwordx4 v[238:239], off
	v_lshl_add_u64 v[238:239], v[242:243], 0, s[16:17]
	s_mov_b32 m0, s59
	s_nop 0
	global_load_lds_dwordx4 v[238:239], off
	v_lshl_add_u64 v[238:239], v[244:245], 0, s[16:17]
	s_mov_b32 m0, s61
	s_nop 0
	global_load_lds_dwordx4 v[238:239], off
	s_waitcnt vmcnt(8) lgkmcnt(0)
	s_setprio 1
	s_barrier
	v_mfma_f32_16x16x32_bf16 v[60:63], v[170:173], v[204:207], v[60:63]
	v_mfma_f32_16x16x32_bf16 v[52:55], v[180:183], v[204:207], v[52:55]
	v_mfma_f32_16x16x32_bf16 v[44:47], v[170:173], v[212:215], v[44:47]
	v_mfma_f32_16x16x32_bf16 v[36:39], v[180:183], v[212:215], v[36:39]
	v_mfma_f32_16x16x32_bf16 v[28:31], v[170:173], v[222:225], v[28:31]
	v_mfma_f32_16x16x32_bf16 v[20:23], v[180:183], v[222:225], v[20:23]
	v_mfma_f32_16x16x32_bf16 v[12:15], v[170:173], v[230:233], v[12:15]
	v_mfma_f32_16x16x32_bf16 v[4:7], v[180:183], v[230:233], v[4:7]
	v_mfma_f32_16x16x32_bf16 v[60:63], v[174:177], v[208:211], v[60:63]
	v_mfma_f32_16x16x32_bf16 v[52:55], v[184:187], v[208:211], v[52:55]
	v_mfma_f32_16x16x32_bf16 v[44:47], v[174:177], v[216:219], v[44:47]
	v_mfma_f32_16x16x32_bf16 v[36:39], v[184:187], v[216:219], v[36:39]
	v_mfma_f32_16x16x32_bf16 v[28:31], v[174:177], v[226:229], v[28:31]
	v_mfma_f32_16x16x32_bf16 v[20:23], v[184:187], v[226:229], v[20:23]
	v_mfma_f32_16x16x32_bf16 v[12:15], v[174:177], v[234:237], v[12:15]
	v_mfma_f32_16x16x32_bf16 v[4:7], v[184:187], v[234:237], v[4:7]
	s_setprio 0
	s_setprio 1
	v_mfma_f32_16x16x32_bf16 v[56:59], v[188:191], v[204:207], v[56:59]
	s_add_i32 s75, s75, 2
	v_mfma_f32_16x16x32_bf16 v[48:51], v[196:199], v[204:207], v[48:51]
	s_add_u32 s73, s73, 0x100
	v_mfma_f32_16x16x32_bf16 v[40:43], v[188:191], v[212:215], v[40:43]
	s_addc_u32 s74, s74, 0
	v_mfma_f32_16x16x32_bf16 v[32:35], v[196:199], v[212:215], v[32:35]
	s_add_u32 s2, s2, 0x100
	v_mfma_f32_16x16x32_bf16 v[24:27], v[188:191], v[222:225], v[24:27]
	s_addc_u32 s3, s3, 0
	v_mfma_f32_16x16x32_bf16 v[16:19], v[196:199], v[222:225], v[16:19]
	s_cmp_gt_u32 s75, 13
	v_mfma_f32_16x16x32_bf16 v[8:11], v[188:191], v[230:233], v[8:11]
	v_mfma_f32_16x16x32_bf16 v[0:3], v[196:199], v[230:233], v[0:3]
	v_mfma_f32_16x16x32_bf16 v[56:59], v[192:195], v[208:211], v[56:59]
	v_mfma_f32_16x16x32_bf16 v[48:51], v[200:203], v[208:211], v[48:51]
	v_mfma_f32_16x16x32_bf16 v[40:43], v[192:195], v[216:219], v[40:43]
	v_mfma_f32_16x16x32_bf16 v[32:35], v[200:203], v[216:219], v[32:35]
	v_mfma_f32_16x16x32_bf16 v[24:27], v[192:195], v[226:229], v[24:27]
	v_mfma_f32_16x16x32_bf16 v[16:19], v[200:203], v[226:229], v[16:19]
	v_mfma_f32_16x16x32_bf16 v[8:11], v[192:195], v[234:237], v[8:11]
	v_mfma_f32_16x16x32_bf16 v[0:3], v[200:203], v[234:237], v[0:3]
	s_barrier
	s_setprio 0
	s_cbranch_scc0 .LBB0_825

; #define PG8_STAGE(bufoff, gbase, voff) do { _Pragma("unroll") for (int _i = 0; _i < 2; ++_i) \
;         __builtin_amdgcn_global_load_lds((const unsigned*)((const char*)(gbase) + (voff)[_i]), (PG8_LAS unsigned*)(lds + (bufoff) + ldsw + _i * 8192), 16, 0, 0); } while (0)
; #define PG8_LDA(dst, b, h) do { _Pragma("unroll") for (int m = 0; m < 4; ++m) _Pragma("unroll") for (int k = 0; k < 2; ++k) dst[m][k] = *(const PG8_LAS bf16x8*)(lds + PG8_SA(b, h) + aoff + m * 2048 + k * 1024); } while (0)
; #define PG8_LDB(dst, b, h) do { _Pragma("unroll") for (int n = 0; n < 2; ++n) _Pragma("unroll") for (int k = 0; k < 2; ++k) dst[n][k] = *(const PG8_LAS bf16x8*)(lds + PG8_SB(b, h) + boff + n * 2048 + k * 1024); } while (0)
; #define PG8_MMA(ai, bj, At, Bt) do { __builtin_amdgcn_s_setprio(1); _Pragma("unroll") for (int m = 0; m < 4; ++m) _Pragma("unroll") for (int n = 0; n < 2; ++n) _Pragma("unroll") for (int k = 0; k < 2; ++k) \
;         acc[ai][bj][m][n] = __builtin_amdgcn_mfma_f32_16x16x32_bf16(Bt[n][k], At[m][k], acc[ai][bj][m][n], 0, 0, 0); __builtin_amdgcn_s_setprio(0); } while (0)
; #define PG8_BAR __builtin_amdgcn_s_barrier()
; template <class Epi, class Sched>
; __device__ __forceinline__ void gemm_phase(PG8_LAS unsigned char* lds, PG8_LAS unsigned char* xl, const Gemm g, const Sched& S, const Epi& E) {
;     ...
;             const bool last = (t == nt - 2);
;             const char* a1 = cA + (size_t)(t + 1) * kstep;
;             const char* a2 = last ? nA : cA + (size_t)(t + 2) * kstep; const char* b2 = last ? nB : cB + (size_t)(t + 2) * kstep;
;             const char* a3 = a2 + kstep; const char* b3 = b2 + kstep;
;             PG8_LDB(B0, 0, 0); PG8_LDB(B1, 0, 1); PG8_SCHED; PG8_LDA(At, 0, 0); PG8_STAGE(PG8_SA(1, 1), a1 + hsA, voffA);
;             PG8_WAIT_V(8); PG8_WAIT_L(0); PG8_BAR; PG8_MMA(0, 0, At, B0); PG8_MMA(0, 1, At, B1); PG8_BAR; PG8_SCHED;
;             PG8_LDA(At, 0, 1); PG8_STAGE(PG8_SB(0, 0), b2, voffB); PG8_STAGE(PG8_SB(0, 1), b2 + hsB, voffB); PG8_STAGE(PG8_SA(0, 0), a2, voffA);
;             PG8_WAIT_V(8); PG8_WAIT_L(0); PG8_BAR; PG8_MMA(1, 0, At, B0); PG8_MMA(1, 1, At, B1); PG8_BAR; PG8_SCHED;
;             PG8_LDB(B0, 1, 0); PG8_LDB(B1, 1, 1); PG8_SCHED; PG8_LDA(At, 1, 0); PG8_STAGE(PG8_SA(0, 1), a2 + hsA, voffA);
;             PG8_WAIT_V(8); PG8_WAIT_L(0); PG8_BAR; PG8_MMA(0, 0, At, B0); PG8_MMA(0, 1, At, B1); PG8_BAR; PG8_SCHED;
.LBB0_914:
	ds_read_b128 v[144:147], v151
	ds_read_b128 v[154:157], v151 offset:1024
	ds_read_b128 v[158:161], v151 offset:2048
	ds_read_b128 v[162:165], v151 offset:3072
	ds_read_b128 v[166:169], v152
	ds_read_b128 v[170:173], v152 offset:1024
	ds_read_b128 v[174:177], v152 offset:2048
	ds_read_b128 v[180:183], v152 offset:3072
	s_add_u32 s28, s26, 0x100
	s_addc_u32 s29, s27, 0
	s_cmp_eq_u32 s67, 40
	s_cselect_b32 s35, s61, s29
	s_cselect_b32 s34, s62, s28
	s_cselect_b32 s31, s63, s66
	s_cselect_b32 s30, s64, s65
	v_lshl_add_u64 v[216:217], s[26:27], 0, v[138:139]
	s_add_i32 m0, s42, 0xc000
	ds_read_b128 v[184:187], v153
	ds_read_b128 v[188:191], v153 offset:1024
	ds_read_b128 v[192:195], v153 offset:2048
	ds_read_b128 v[196:199], v153 offset:3072
	ds_read_b128 v[200:203], v153 offset:4096
	ds_read_b128 v[204:207], v153 offset:5120
	ds_read_b128 v[208:211], v153 offset:6144
	ds_read_b128 v[212:215], v153 offset:7168
	global_load_lds_dwordx4 v[216:217], off
	v_lshl_add_u64 v[216:217], s[26:27], 0, v[136:137]
	s_add_i32 m0, s42, 0xe000
	s_nop 0
	global_load_lds_dwordx4 v[216:217], off
	s_waitcnt vmcnt(8) lgkmcnt(0)
	s_setprio 1
	s_barrier
	v_mfma_f32_16x16x32_bf16 v[124:127], v[144:147], v[184:187], v[124:127]
	v_mfma_f32_16x16x32_bf16 v[120:123], v[158:161], v[184:187], v[120:123]
	v_mfma_f32_16x16x32_bf16 v[108:111], v[144:147], v[192:195], v[108:111]
	v_mfma_f32_16x16x32_bf16 v[104:107], v[158:161], v[192:195], v[104:107]
	v_mfma_f32_16x16x32_bf16 v[92:95], v[144:147], v[200:203], v[92:95]
	v_mfma_f32_16x16x32_bf16 v[88:91], v[158:161], v[200:203], v[88:91]
	v_mfma_f32_16x16x32_bf16 v[76:79], v[144:147], v[208:211], v[76:79]
	v_mfma_f32_16x16x32_bf16 v[72:75], v[158:161], v[208:211], v[72:75]
	v_mfma_f32_16x16x32_bf16 v[124:127], v[154:157], v[188:191], v[124:127]
	v_mfma_f32_16x16x32_bf16 v[120:123], v[162:165], v[188:191], v[120:123]
	v_mfma_f32_16x16x32_bf16 v[108:111], v[154:157], v[196:199], v[108:111]
	v_mfma_f32_16x16x32_bf16 v[104:107], v[162:165], v[196:199], v[104:107]
	v_mfma_f32_16x16x32_bf16 v[92:95], v[154:157], v[204:207], v[92:95]
	v_mfma_f32_16x16x32_bf16 v[88:91], v[162:165], v[204:207], v[88:91]
	v_mfma_f32_16x16x32_bf16 v[76:79], v[154:157], v[212:215], v[76:79]
	v_mfma_f32_16x16x32_bf16 v[72:75], v[162:165], v[212:215], v[72:75]
	s_setprio 0
	s_setprio 1
	v_mfma_f32_16x16x32_bf16 v[116:119], v[166:169], v[184:187], v[116:119]
	v_mfma_f32_16x16x32_bf16 v[112:115], v[174:177], v[184:187], v[112:115]
	v_mfma_f32_16x16x32_bf16 v[100:103], v[166:169], v[192:195], v[100:103]
	v_mfma_f32_16x16x32_bf16 v[96:99], v[174:177], v[192:195], v[96:99]
	v_mfma_f32_16x16x32_bf16 v[84:87], v[166:169], v[200:203], v[84:87]
	v_mfma_f32_16x16x32_bf16 v[80:83], v[174:177], v[200:203], v[80:83]
	v_mfma_f32_16x16x32_bf16 v[68:71], v[166:169], v[208:211], v[68:71]
	v_mfma_f32_16x16x32_bf16 v[64:67], v[174:177], v[208:211], v[64:67]
	v_mfma_f32_16x16x32_bf16 v[116:119], v[170:173], v[188:191], v[116:119]
	v_mfma_f32_16x16x32_bf16 v[112:115], v[180:183], v[188:191], v[112:115]
	v_mfma_f32_16x16x32_bf16 v[100:103], v[170:173], v[196:199], v[100:103]
	v_mfma_f32_16x16x32_bf16 v[96:99], v[180:183], v[196:199], v[96:99]
	v_mfma_f32_16x16x32_bf16 v[84:87], v[170:173], v[204:207], v[84:87]
	v_mfma_f32_16x16x32_bf16 v[80:83], v[180:183], v[204:207], v[80:83]
	v_mfma_f32_16x16x32_bf16 v[68:71], v[170:173], v[212:215], v[68:71]
	v_mfma_f32_16x16x32_bf16 v[64:67], v[180:183], v[212:215], v[64:67]
	s_barrier
	s_setprio 0
	s_add_i32 s26, s51, s37
	v_lshl_add_u64 v[216:217], s[30:31], 0, v[130:131]
	s_mov_b32 m0, s26
	ds_read_b128 v[184:187], v153 offset:16384
	ds_read_b128 v[188:191], v153 offset:17408
	ds_read_b128 v[192:195], v153 offset:18432
	ds_read_b128 v[196:199], v153 offset:19456
	ds_read_b128 v[200:203], v153 offset:20480
	ds_read_b128 v[204:207], v153 offset:21504
	ds_read_b128 v[208:211], v153 offset:22528
	ds_read_b128 v[212:215], v153 offset:23552
	global_load_lds_dwordx4 v[216:217], off
	s_add_i32 m0, s26, 0x2000
	s_add_u32 s26, s30, 0xb0000
	v_lshl_add_u64 v[218:219], s[30:31], 0, v[134:135]
	s_addc_u32 s27, s31, 0
	s_add_i32 s68, s52, s37
	global_load_lds_dwordx4 v[218:219], off
	v_lshl_add_u64 v[222:223], s[26:27], 0, v[130:131]
	s_mov_b32 m0, s68
	v_lshl_add_u64 v[224:225], s[34:35], 0, v[132:133]
	global_load_lds_dwordx4 v[222:223], off
	v_lshl_add_u64 v[222:223], s[26:27], 0, v[134:135]
	s_add_i32 m0, s68, 0x2000
	s_nop 0
	global_load_lds_dwordx4 v[222:223], off
	v_lshl_add_u64 v[222:223], s[34:35], 0, v[128:129]
	s_mov_b32 m0, s42
	s_nop 0
	global_load_lds_dwordx4 v[222:223], off
	s_mov_b32 m0, s43
	s_nop 0
	global_load_lds_dwordx4 v[224:225], off
	s_waitcnt vmcnt(8) lgkmcnt(0)
	s_setprio 1
	s_barrier
; #define PG8_STAGE(bufoff, gbase, voff) do { _Pragma("unroll") for (int _i = 0; _i < 2; ++_i) \
;         __builtin_amdgcn_global_load_lds((const unsigned*)((const char*)(gbase) + (voff)[_i]), (PG8_LAS unsigned*)(lds + (bufoff) + ldsw + _i * 8192), 16, 0, 0); } while (0)
; #define PG8_LDA(dst, b, h) do { _Pragma("unroll") for (int m = 0; m < 4; ++m) _Pragma("unroll") for (int k = 0; k < 2; ++k) dst[m][k] = *(const PG8_LAS bf16x8*)(lds + PG8_SA(b, h) + aoff + m * 2048 + k * 1024); } while (0)
; #define PG8_LDB(dst, b, h) do { _Pragma("unroll") for (int n = 0; n < 2; ++n) _Pragma("unroll") for (int k = 0; k < 2; ++k) dst[n][k] = *(const PG8_LAS bf16x8*)(lds + PG8_SB(b, h) + boff + n * 2048 + k * 1024); } while (0)
; #define PG8_MMA(ai, bj, At, Bt) do { __builtin_amdgcn_s_setprio(1); _Pragma("unroll") for (int m = 0; m < 4; ++m) _Pragma("unroll") for (int n = 0; n < 2; ++n) _Pragma("unroll") for (int k = 0; k < 2; ++k) \
;         acc[ai][bj][m][n] = __builtin_amdgcn_mfma_f32_16x16x32_bf16(Bt[n][k], At[m][k], acc[ai][bj][m][n], 0, 0, 0); __builtin_amdgcn_s_setprio(0); } while (0)
; #define PG8_WAIT_V(n) asm volatile("s_waitcnt vmcnt(" #n ")" ::: "memory")
; #define PG8_WAIT_L(n) asm volatile("s_waitcnt lgkmcnt(" #n ")" ::: "memory")
; #define PG8_BAR __builtin_amdgcn_s_barrier()
; #define PG8_SCHED __builtin_amdgcn_sched_barrier(0)
; template <class Epi, class Sched>
; __device__ __forceinline__ void gemm_phase(PG8_LAS unsigned char* lds, PG8_LAS unsigned char* xl, const Gemm g, const Sched& S, const Epi& E) {
;     ...
;             PG8_LDA(At, 0, 1); PG8_STAGE(PG8_SB(0, 0), b2, voffB); PG8_STAGE(PG8_SB(0, 1), b2 + hsB, voffB); PG8_STAGE(PG8_SA(0, 0), a2, voffA);
;             PG8_WAIT_V(8); PG8_WAIT_L(0); PG8_BAR; PG8_MMA(1, 0, At, B0); PG8_MMA(1, 1, At, B1); PG8_BAR; PG8_SCHED;
;             PG8_LDB(B0, 1, 0); PG8_LDB(B1, 1, 1); PG8_SCHED; PG8_LDA(At, 1, 0); PG8_STAGE(PG8_SA(0, 1), a2 + hsA, voffA);
;             PG8_WAIT_V(8); PG8_WAIT_L(0); PG8_BAR; PG8_MMA(0, 0, At, B0); PG8_MMA(0, 1, At, B1); PG8_BAR; PG8_SCHED;
	v_mfma_f32_16x16x32_bf16 v[60:63], v[144:147], v[184:187], v[60:63]
	v_mfma_f32_16x16x32_bf16 v[56:59], v[158:161], v[184:187], v[56:59]
	v_mfma_f32_16x16x32_bf16 v[44:47], v[144:147], v[192:195], v[44:47]
	v_mfma_f32_16x16x32_bf16 v[40:43], v[158:161], v[192:195], v[40:43]
	v_mfma_f32_16x16x32_bf16 v[28:31], v[144:147], v[200:203], v[28:31]
	v_mfma_f32_16x16x32_bf16 v[24:27], v[158:161], v[200:203], v[24:27]
	v_mfma_f32_16x16x32_bf16 v[12:15], v[144:147], v[208:211], v[12:15]
	v_mfma_f32_16x16x32_bf16 v[8:11], v[158:161], v[208:211], v[8:11]
	v_mfma_f32_16x16x32_bf16 v[60:63], v[154:157], v[188:191], v[60:63]
	v_mfma_f32_16x16x32_bf16 v[56:59], v[162:165], v[188:191], v[56:59]
	v_mfma_f32_16x16x32_bf16 v[44:47], v[154:157], v[196:199], v[44:47]
	v_mfma_f32_16x16x32_bf16 v[40:43], v[162:165], v[196:199], v[40:43]
	v_mfma_f32_16x16x32_bf16 v[28:31], v[154:157], v[204:207], v[28:31]
	v_mfma_f32_16x16x32_bf16 v[24:27], v[162:165], v[204:207], v[24:27]
	v_mfma_f32_16x16x32_bf16 v[12:15], v[154:157], v[212:215], v[12:15]
	v_mfma_f32_16x16x32_bf16 v[8:11], v[162:165], v[212:215], v[8:11]
	s_setprio 0
	s_setprio 1
	v_mfma_f32_16x16x32_bf16 v[52:55], v[166:169], v[184:187], v[52:55]
	v_mfma_f32_16x16x32_bf16 v[48:51], v[174:177], v[184:187], v[48:51]
	v_mfma_f32_16x16x32_bf16 v[36:39], v[166:169], v[192:195], v[36:39]
	v_mfma_f32_16x16x32_bf16 v[32:35], v[174:177], v[192:195], v[32:35]
	v_mfma_f32_16x16x32_bf16 v[20:23], v[166:169], v[200:203], v[20:23]
	v_mfma_f32_16x16x32_bf16 v[16:19], v[174:177], v[200:203], v[16:19]
	v_mfma_f32_16x16x32_bf16 v[4:7], v[166:169], v[208:211], v[4:7]
	v_mfma_f32_16x16x32_bf16 v[0:3], v[174:177], v[208:211], v[0:3]
	v_mfma_f32_16x16x32_bf16 v[52:55], v[170:173], v[188:191], v[52:55]
	v_mfma_f32_16x16x32_bf16 v[48:51], v[180:183], v[188:191], v[48:51]
	v_mfma_f32_16x16x32_bf16 v[36:39], v[170:173], v[196:199], v[36:39]
	v_mfma_f32_16x16x32_bf16 v[32:35], v[180:183], v[196:199], v[32:35]
	v_mfma_f32_16x16x32_bf16 v[20:23], v[170:173], v[204:207], v[20:23]
	v_mfma_f32_16x16x32_bf16 v[16:19], v[180:183], v[204:207], v[16:19]
	v_mfma_f32_16x16x32_bf16 v[4:7], v[170:173], v[212:215], v[4:7]
	v_mfma_f32_16x16x32_bf16 v[0:3], v[180:183], v[212:215], v[0:3]
	s_barrier
	s_setprio 0
	s_add_i32 s68, 0, 0x18000
	s_add_i32 s70, 0, 0x1c000
	v_add_u32_e32 v162, s68, v149
	v_add_u32_e32 v179, s70, v149
	ds_read_b128 v[144:147], v162
	ds_read_b128 v[154:157], v162 offset:1024
	ds_read_b128 v[158:161], v162 offset:2048
	ds_read_b128 v[162:165], v162 offset:3072
	ds_read_b128 v[166:169], v179
	ds_read_b128 v[170:173], v179 offset:1024
	ds_read_b128 v[174:177], v179 offset:2048
	ds_read_b128 v[180:183], v179 offset:3072
	s_add_u32 s26, s34, 0xb0000
	s_addc_u32 s27, s35, 0
	s_mov_b32 m0, s46
	v_lshl_add_u64 v[226:227], s[26:27], 0, v[128:129]
	ds_read_b128 v[184:187], v153 offset:32768
	ds_read_b128 v[188:191], v153 offset:33792
	ds_read_b128 v[192:195], v153 offset:34816
	ds_read_b128 v[196:199], v153 offset:35840
	ds_read_b128 v[200:203], v153 offset:36864
	ds_read_b128 v[204:207], v153 offset:37888
	ds_read_b128 v[208:211], v153 offset:38912
	ds_read_b128 v[212:215], v153 offset:39936
	global_load_lds_dwordx4 v[226:227], off
	v_lshl_add_u64 v[226:227], s[26:27], 0, v[132:133]
	s_mov_b32 m0, s47
	s_nop 0
	global_load_lds_dwordx4 v[226:227], off
	s_waitcnt vmcnt(8) lgkmcnt(0)
	s_setprio 1
	s_barrier
	v_mfma_f32_16x16x32_bf16 v[124:127], v[144:147], v[184:187], v[124:127]
	v_mfma_f32_16x16x32_bf16 v[120:123], v[158:161], v[184:187], v[120:123]
	v_mfma_f32_16x16x32_bf16 v[108:111], v[144:147], v[192:195], v[108:111]
	v_mfma_f32_16x16x32_bf16 v[104:107], v[158:161], v[192:195], v[104:107]
	v_mfma_f32_16x16x32_bf16 v[92:95], v[144:147], v[200:203], v[92:95]
	v_mfma_f32_16x16x32_bf16 v[88:91], v[158:161], v[200:203], v[88:91]
	v_mfma_f32_16x16x32_bf16 v[76:79], v[144:147], v[208:211], v[76:79]
	v_mfma_f32_16x16x32_bf16 v[72:75], v[158:161], v[208:211], v[72:75]
	v_mfma_f32_16x16x32_bf16 v[124:127], v[154:157], v[188:191], v[124:127]
	v_mfma_f32_16x16x32_bf16 v[120:123], v[162:165], v[188:191], v[120:123]
	v_mfma_f32_16x16x32_bf16 v[108:111], v[154:157], v[196:199], v[108:111]
	v_mfma_f32_16x16x32_bf16 v[104:107], v[162:165], v[196:199], v[104:107]
	v_mfma_f32_16x16x32_bf16 v[92:95], v[154:157], v[204:207], v[92:95]
	v_mfma_f32_16x16x32_bf16 v[88:91], v[162:165], v[204:207], v[88:91]
	v_mfma_f32_16x16x32_bf16 v[76:79], v[154:157], v[212:215], v[76:79]
	v_mfma_f32_16x16x32_bf16 v[72:75], v[162:165], v[212:215], v[72:75]
	s_setprio 0
	s_setprio 1
	v_mfma_f32_16x16x32_bf16 v[116:119], v[166:169], v[184:187], v[116:119]
	v_mfma_f32_16x16x32_bf16 v[112:115], v[174:177], v[184:187], v[112:115]
	v_mfma_f32_16x16x32_bf16 v[100:103], v[166:169], v[192:195], v[100:103]
	v_mfma_f32_16x16x32_bf16 v[96:99], v[174:177], v[192:195], v[96:99]
	v_mfma_f32_16x16x32_bf16 v[84:87], v[166:169], v[200:203], v[84:87]
	v_mfma_f32_16x16x32_bf16 v[80:83], v[174:177], v[200:203], v[80:83]
	v_mfma_f32_16x16x32_bf16 v[68:71], v[166:169], v[208:211], v[68:71]
	v_mfma_f32_16x16x32_bf16 v[64:67], v[174:177], v[208:211], v[64:67]
	v_mfma_f32_16x16x32_bf16 v[116:119], v[170:173], v[188:191], v[116:119]
	v_mfma_f32_16x16x32_bf16 v[112:115], v[180:183], v[188:191], v[112:115]
	v_mfma_f32_16x16x32_bf16 v[100:103], v[170:173], v[196:199], v[100:103]
	v_mfma_f32_16x16x32_bf16 v[96:99], v[180:183], v[196:199], v[96:99]
	v_mfma_f32_16x16x32_bf16 v[84:87], v[170:173], v[204:207], v[84:87]
	v_mfma_f32_16x16x32_bf16 v[80:83], v[180:183], v[204:207], v[80:83]
	v_mfma_f32_16x16x32_bf16 v[68:71], v[170:173], v[212:215], v[68:71]
	v_mfma_f32_16x16x32_bf16 v[64:67], v[180:183], v[212:215], v[64:67]
	s_barrier
; #define PG8_STAGE(bufoff, gbase, voff) do { _Pragma("unroll") for (int _i = 0; _i < 2; ++_i) \
;         __builtin_amdgcn_global_load_lds((const unsigned*)((const char*)(gbase) + (voff)[_i]), (PG8_LAS unsigned*)(lds + (bufoff) + ldsw + _i * 8192), 16, 0, 0); } while (0)
; #define PG8_LDA(dst, b, h) do { _Pragma("unroll") for (int m = 0; m < 4; ++m) _Pragma("unroll") for (int k = 0; k < 2; ++k) dst[m][k] = *(const PG8_LAS bf16x8*)(lds + PG8_SA(b, h) + aoff + m * 2048 + k * 1024); } while (0)
; #define PG8_MMA(ai, bj, At, Bt) do { __builtin_amdgcn_s_setprio(1); _Pragma("unroll") for (int m = 0; m < 4; ++m) _Pragma("unroll") for (int n = 0; n < 2; ++n) _Pragma("unroll") for (int k = 0; k < 2; ++k) \
;         acc[ai][bj][m][n] = __builtin_amdgcn_mfma_f32_16x16x32_bf16(Bt[n][k], At[m][k], acc[ai][bj][m][n], 0, 0, 0); __builtin_amdgcn_s_setprio(0); } while (0)
; #define PG8_WAIT_V(n) asm volatile("s_waitcnt vmcnt(" #n ")" ::: "memory")
; #define PG8_WAIT_L(n) asm volatile("s_waitcnt lgkmcnt(" #n ")" ::: "memory")
; #define PG8_BAR __builtin_amdgcn_s_barrier()
; #define PG8_SCHED __builtin_amdgcn_sched_barrier(0)
; template <class Epi, class Sched>
; __device__ __forceinline__ void gemm_phase(PG8_LAS unsigned char* lds, PG8_LAS unsigned char* xl, const Gemm g, const Sched& S, const Epi& E) {
;     ...
;             PG8_LDA(At, 1, 1); PG8_STAGE(PG8_SB(1, 0), b3, voffB); PG8_STAGE(PG8_SB(1, 1), b3 + hsB, voffB); PG8_STAGE(PG8_SA(1, 0), a3, voffA);
;             PG8_WAIT_V(8); PG8_WAIT_L(0); PG8_BAR; PG8_MMA(1, 0, At, B0); PG8_MMA(1, 1, At, B1); PG8_BAR; PG8_SCHED;
;         }
;         if (wr == 0) PG8_BAR;
	s_setprio 0
	s_add_i32 s26, s68, s37
	v_lshl_add_u64 v[216:217], v[216:217], 0, s[12:13]
	s_mov_b32 m0, s26
	ds_read_b128 v[184:187], v153 offset:49152
	ds_read_b128 v[188:191], v153 offset:50176
	ds_read_b128 v[192:195], v153 offset:51200
	ds_read_b128 v[196:199], v153 offset:52224
	ds_read_b128 v[200:203], v153 offset:53248
	ds_read_b128 v[204:207], v153 offset:54272
	ds_read_b128 v[208:211], v153 offset:55296
	ds_read_b128 v[212:215], v153 offset:56320
	global_load_lds_dwordx4 v[216:217], off
	s_add_i32 m0, s26, 0x2000
	s_add_u32 s26, s30, 0xb0080
	v_lshl_add_u64 v[216:217], v[218:219], 0, s[12:13]
	s_addc_u32 s27, s31, 0
	s_add_i32 s30, s70, s37
	global_load_lds_dwordx4 v[216:217], off
	v_lshl_add_u64 v[216:217], s[26:27], 0, v[130:131]
	s_mov_b32 m0, s30
	s_nop 0
	global_load_lds_dwordx4 v[216:217], off
	v_lshl_add_u64 v[216:217], s[26:27], 0, v[134:135]
	s_add_i32 m0, s30, 0x2000
	s_nop 0
	global_load_lds_dwordx4 v[216:217], off
	v_lshl_add_u64 v[216:217], v[222:223], 0, s[12:13]
	s_mov_b32 m0, s49
	s_nop 0
	global_load_lds_dwordx4 v[216:217], off
	v_lshl_add_u64 v[216:217], v[224:225], 0, s[12:13]
	s_mov_b32 m0, s50
	s_nop 0
	global_load_lds_dwordx4 v[216:217], off
	s_waitcnt vmcnt(8) lgkmcnt(0)
	s_setprio 1
	s_barrier
	v_mfma_f32_16x16x32_bf16 v[60:63], v[144:147], v[184:187], v[60:63]
	v_mfma_f32_16x16x32_bf16 v[56:59], v[158:161], v[184:187], v[56:59]
	v_mfma_f32_16x16x32_bf16 v[44:47], v[144:147], v[192:195], v[44:47]
	v_mfma_f32_16x16x32_bf16 v[40:43], v[158:161], v[192:195], v[40:43]
	v_mfma_f32_16x16x32_bf16 v[28:31], v[144:147], v[200:203], v[28:31]
	v_mfma_f32_16x16x32_bf16 v[24:27], v[158:161], v[200:203], v[24:27]
	v_mfma_f32_16x16x32_bf16 v[12:15], v[144:147], v[208:211], v[12:15]
	v_mfma_f32_16x16x32_bf16 v[8:11], v[158:161], v[208:211], v[8:11]
	v_mfma_f32_16x16x32_bf16 v[60:63], v[154:157], v[188:191], v[60:63]
	v_mfma_f32_16x16x32_bf16 v[56:59], v[162:165], v[188:191], v[56:59]
	v_mfma_f32_16x16x32_bf16 v[44:47], v[154:157], v[196:199], v[44:47]
	v_mfma_f32_16x16x32_bf16 v[40:43], v[162:165], v[196:199], v[40:43]
	v_mfma_f32_16x16x32_bf16 v[28:31], v[154:157], v[204:207], v[28:31]
	v_mfma_f32_16x16x32_bf16 v[24:27], v[162:165], v[204:207], v[24:27]
	v_mfma_f32_16x16x32_bf16 v[12:15], v[154:157], v[212:215], v[12:15]
	v_mfma_f32_16x16x32_bf16 v[8:11], v[162:165], v[212:215], v[8:11]
	s_setprio 0
	s_setprio 1
	v_mfma_f32_16x16x32_bf16 v[52:55], v[166:169], v[184:187], v[52:55]
	s_add_i32 s67, s67, 2
	v_mfma_f32_16x16x32_bf16 v[48:51], v[174:177], v[184:187], v[48:51]
	s_add_u32 s65, s65, 0x100
	v_mfma_f32_16x16x32_bf16 v[36:39], v[166:169], v[192:195], v[36:39]
	s_addc_u32 s66, s66, 0
	v_mfma_f32_16x16x32_bf16 v[32:35], v[174:177], v[192:195], v[32:35]
	s_cmp_gt_u32 s67, 41
	v_mfma_f32_16x16x32_bf16 v[20:23], v[166:169], v[200:203], v[20:23]
	s_mov_b64 s[26:27], s[28:29]
	v_mfma_f32_16x16x32_bf16 v[16:19], v[174:177], v[200:203], v[16:19]
	v_mfma_f32_16x16x32_bf16 v[4:7], v[166:169], v[208:211], v[4:7]
	v_mfma_f32_16x16x32_bf16 v[0:3], v[174:177], v[208:211], v[0:3]
	v_mfma_f32_16x16x32_bf16 v[52:55], v[170:173], v[188:191], v[52:55]
	v_mfma_f32_16x16x32_bf16 v[48:51], v[180:183], v[188:191], v[48:51]
	v_mfma_f32_16x16x32_bf16 v[36:39], v[170:173], v[196:199], v[36:39]
	v_mfma_f32_16x16x32_bf16 v[32:35], v[180:183], v[196:199], v[32:35]
	v_mfma_f32_16x16x32_bf16 v[20:23], v[170:173], v[204:207], v[20:23]
	v_mfma_f32_16x16x32_bf16 v[16:19], v[180:183], v[204:207], v[16:19]
	v_mfma_f32_16x16x32_bf16 v[4:7], v[170:173], v[212:215], v[4:7]
	v_mfma_f32_16x16x32_bf16 v[0:3], v[180:183], v[212:215], v[0:3]
	s_barrier
	s_setprio 0
	s_cbranch_scc0 .LBB0_914
	s_and_b64 vcc, exec, s[14:15]
	s_cbranch_vccz .LBB0_917
	s_barrier

; #define PG8_STAGE(bufoff, gbase, voff) do { _Pragma("unroll") for (int _i = 0; _i < 2; ++_i) \
;         __builtin_amdgcn_global_load_lds((const unsigned*)((const char*)(gbase) + (voff)[_i]), (PG8_LAS unsigned*)(lds + (bufoff) + ldsw + _i * 8192), 16, 0, 0); } while (0)
; #define PG8_LDA(dst, b, h) do { _Pragma("unroll") for (int m = 0; m < 4; ++m) _Pragma("unroll") for (int k = 0; k < 2; ++k) dst[m][k] = *(const PG8_LAS bf16x8*)(lds + PG8_SA(b, h) + aoff + m * 2048 + k * 1024); } while (0)
; #define PG8_LDB(dst, b, h) do { _Pragma("unroll") for (int n = 0; n < 2; ++n) _Pragma("unroll") for (int k = 0; k < 2; ++k) dst[n][k] = *(const PG8_LAS bf16x8*)(lds + PG8_SB(b, h) + boff + n * 2048 + k * 1024); } while (0)
; #define PG8_MMA(ai, bj, At, Bt) do { __builtin_amdgcn_s_setprio(1); _Pragma("unroll") for (int m = 0; m < 4; ++m) _Pragma("unroll") for (int n = 0; n < 2; ++n) _Pragma("unroll") for (int k = 0; k < 2; ++k) \
;         acc[ai][bj][m][n] = __builtin_amdgcn_mfma_f32_16x16x32_bf16(Bt[n][k], At[m][k], acc[ai][bj][m][n], 0, 0, 0); __builtin_amdgcn_s_setprio(0); } while (0)
; #define PG8_BAR __builtin_amdgcn_s_barrier()
; template <class Epi, class Sched>
; __device__ __forceinline__ void gemm_phase(PG8_LAS unsigned char* lds, PG8_LAS unsigned char* xl, const Gemm g, const Sched& S, const Epi& E) {
;     ...
;         const bool has_next = S.next(ui + 1, nxt);
;         const char* nA = has_next ? (const char*)g.A + nxt.aoff : cA; const char* nB = has_next ? (const char*)g.Bt + nxt.boff : cB;
; #pragma unroll 1
;         for (int t = 0; t < nt; t += 2) {
;             const bool last = (t == nt - 2);
;             const char* a1 = cA + (size_t)(t + 1) * kstep;
;             const char* a2 = last ? nA : cA + (size_t)(t + 2) * kstep; const char* b2 = last ? nB : cB + (size_t)(t + 2) * kstep;
;             const char* a3 = a2 + kstep; const char* b3 = b2 + kstep;
;             PG8_LDB(B0, 0, 0); PG8_LDB(B1, 0, 1); PG8_SCHED; PG8_LDA(At, 0, 0); PG8_STAGE(PG8_SA(1, 1), a1 + hsA, voffA);
;             PG8_WAIT_V(8); PG8_WAIT_L(0); PG8_BAR; PG8_MMA(0, 0, At, B0); PG8_MMA(0, 1, At, B1); PG8_BAR; PG8_SCHED;
;             PG8_LDA(At, 0, 1); PG8_STAGE(PG8_SB(0, 0), b2, voffB); PG8_STAGE(PG8_SB(0, 1), b2 + hsB, voffB); PG8_STAGE(PG8_SA(0, 0), a2, voffA);
;             PG8_WAIT_V(8); PG8_WAIT_L(0); PG8_BAR; PG8_MMA(1, 0, At, B0); PG8_MMA(1, 1, At, B1); PG8_BAR; PG8_SCHED;
.LBB0_941:
	s_add_u32 s34, s55, s28
	s_addc_u32 s35, s56, s29
	s_and_b64 s[36:37], s[10:11], exec
	s_cselect_b32 s33, s35, s3
	s_cselect_b32 s46, s34, s2
	s_add_u32 s36, s57, s30
	s_addc_u32 s37, s58, s31
	s_and_b64 s[50:51], s[10:11], exec
	s_cselect_b32 s47, s37, s49
	s_cselect_b32 s77, s36, s48
	s_add_u32 s78, s48, 0x100
	v_mov_b32_e32 v0, 0
	s_addc_u32 s79, s49, 0
	s_mov_b32 s80, -2
	ds_read_b128 v[144:147], v199
	ds_read_b128 v[148:151], v199 offset:1024
	ds_read_b128 v[152:155], v199 offset:2048
	ds_read_b128 v[156:159], v199 offset:3072
	ds_read_b128 v[160:163], v200
	ds_read_b128 v[164:167], v200 offset:1024
	ds_read_b128 v[168:171], v200 offset:2048
	ds_read_b128 v[172:175], v200 offset:3072
	s_add_u32 s48, s2, 0x100
	s_addc_u32 s49, s3, 0
	s_cmp_eq_u32 s80, 40
	s_cselect_b32 s53, s33, s49
	s_cselect_b32 s52, s46, s48
	s_cselect_b32 s51, s47, s79
	s_cselect_b32 s50, s77, s78
	v_lshl_add_u64 v[176:177], s[2:3], 0, v[138:139]
	s_add_i32 m0, s43, 0xc000
	ds_read_b128 v[214:217], v201
	ds_read_b128 v[222:225], v201 offset:1024
	ds_read_b128 v[226:229], v201 offset:2048
	ds_read_b128 v[230:233], v201 offset:3072
	ds_read_b128 v[234:237], v201 offset:4096
	ds_read_b128 v[238:241], v201 offset:5120
	ds_read_b128 v[242:245], v201 offset:6144
	ds_read_b128 v[246:249], v201 offset:7168
	global_load_lds_dwordx4 v[176:177], off
	v_lshl_add_u64 v[176:177], s[2:3], 0, v[136:137]
	s_add_i32 m0, s43, 0xe000
	s_nop 0
	global_load_lds_dwordx4 v[176:177], off
	s_waitcnt vmcnt(8) lgkmcnt(0)
	s_setprio 1
	s_barrier
	v_mfma_f32_16x16x32_bf16 v[124:127], v[144:147], v[214:217], 0
	v_mfma_f32_16x16x32_bf16 v[120:123], v[152:155], v[214:217], 0
	v_mfma_f32_16x16x32_bf16 v[108:111], v[144:147], v[226:229], 0
	v_mfma_f32_16x16x32_bf16 v[104:107], v[152:155], v[226:229], 0
	v_mfma_f32_16x16x32_bf16 v[92:95], v[144:147], v[234:237], 0
	v_mfma_f32_16x16x32_bf16 v[88:91], v[152:155], v[234:237], 0
	v_mfma_f32_16x16x32_bf16 v[76:79], v[144:147], v[242:245], 0
	v_mfma_f32_16x16x32_bf16 v[72:75], v[152:155], v[242:245], 0
	v_mfma_f32_16x16x32_bf16 v[124:127], v[148:151], v[222:225], v[124:127]
	v_mfma_f32_16x16x32_bf16 v[120:123], v[156:159], v[222:225], v[120:123]
	v_mfma_f32_16x16x32_bf16 v[108:111], v[148:151], v[230:233], v[108:111]
	v_mfma_f32_16x16x32_bf16 v[104:107], v[156:159], v[230:233], v[104:107]
	v_mfma_f32_16x16x32_bf16 v[92:95], v[148:151], v[238:241], v[92:95]
	v_mfma_f32_16x16x32_bf16 v[88:91], v[156:159], v[238:241], v[88:91]
	v_mfma_f32_16x16x32_bf16 v[76:79], v[148:151], v[246:249], v[76:79]
	v_mfma_f32_16x16x32_bf16 v[72:75], v[156:159], v[246:249], v[72:75]
	s_setprio 0
	s_setprio 1
	v_mfma_f32_16x16x32_bf16 v[116:119], v[160:163], v[214:217], 0
	v_mfma_f32_16x16x32_bf16 v[112:115], v[168:171], v[214:217], 0
	v_mfma_f32_16x16x32_bf16 v[100:103], v[160:163], v[226:229], 0
	v_mfma_f32_16x16x32_bf16 v[96:99], v[168:171], v[226:229], 0
	v_mfma_f32_16x16x32_bf16 v[84:87], v[160:163], v[234:237], 0
	v_mfma_f32_16x16x32_bf16 v[80:83], v[168:171], v[234:237], 0
	v_mfma_f32_16x16x32_bf16 v[68:71], v[160:163], v[242:245], 0
	v_mfma_f32_16x16x32_bf16 v[64:67], v[168:171], v[242:245], 0
	v_mfma_f32_16x16x32_bf16 v[116:119], v[164:167], v[222:225], v[116:119]
	v_mfma_f32_16x16x32_bf16 v[112:115], v[172:175], v[222:225], v[112:115]
	v_mfma_f32_16x16x32_bf16 v[100:103], v[164:167], v[230:233], v[100:103]
	v_mfma_f32_16x16x32_bf16 v[96:99], v[172:175], v[230:233], v[96:99]
	v_mfma_f32_16x16x32_bf16 v[84:87], v[164:167], v[238:241], v[84:87]
	v_mfma_f32_16x16x32_bf16 v[80:83], v[172:175], v[238:241], v[80:83]
	v_mfma_f32_16x16x32_bf16 v[68:71], v[164:167], v[246:249], v[68:71]
	v_mfma_f32_16x16x32_bf16 v[64:67], v[172:175], v[246:249], v[64:67]
	s_barrier
	s_setprio 0
	s_add_i32 s2, s70, s42
	v_lshl_add_u64 v[176:177], s[50:51], 0, v[130:131]
	s_mov_b32 m0, s2
	ds_read_b128 v[214:217], v201 offset:16384
	ds_read_b128 v[222:225], v201 offset:17408
	ds_read_b128 v[226:229], v201 offset:18432
	ds_read_b128 v[230:233], v201 offset:19456
	ds_read_b128 v[234:237], v201 offset:20480
	ds_read_b128 v[238:241], v201 offset:21504
	ds_read_b128 v[242:245], v201 offset:22528
	ds_read_b128 v[246:249], v201 offset:23552
	global_load_lds_dwordx4 v[176:177], off
	s_add_i32 m0, s2, 0x2000
	s_add_u32 s2, s50, 0xb0000
	v_lshl_add_u64 v[218:219], s[50:51], 0, v[134:135]
	s_addc_u32 s3, s51, 0
	s_add_i32 s68, s71, s42
	global_load_lds_dwordx4 v[218:219], off
	v_lshl_add_u64 v[250:251], s[2:3], 0, v[130:131]
	s_mov_b32 m0, s68
	v_lshl_add_u64 v[252:253], s[52:53], 0, v[132:133]
	global_load_lds_dwordx4 v[250:251], off
	v_lshl_add_u64 v[250:251], s[2:3], 0, v[134:135]
	s_add_i32 m0, s68, 0x2000
	s_nop 0
	global_load_lds_dwordx4 v[250:251], off
	v_lshl_add_u64 v[250:251], s[52:53], 0, v[128:129]
	s_mov_b32 m0, s43
	s_nop 0
	global_load_lds_dwordx4 v[250:251], off
	s_mov_b32 m0, s59
	s_nop 0
	global_load_lds_dwordx4 v[252:253], off
	s_waitcnt vmcnt(8) lgkmcnt(0)
	s_setprio 1
	s_barrier
; #define PG8_STAGE(bufoff, gbase, voff) do { _Pragma("unroll") for (int _i = 0; _i < 2; ++_i) \
;         __builtin_amdgcn_global_load_lds((const unsigned*)((const char*)(gbase) + (voff)[_i]), (PG8_LAS unsigned*)(lds + (bufoff) + ldsw + _i * 8192), 16, 0, 0); } while (0)
; #define PG8_LDA(dst, b, h) do { _Pragma("unroll") for (int m = 0; m < 4; ++m) _Pragma("unroll") for (int k = 0; k < 2; ++k) dst[m][k] = *(const PG8_LAS bf16x8*)(lds + PG8_SA(b, h) + aoff + m * 2048 + k * 1024); } while (0)
; #define PG8_LDB(dst, b, h) do { _Pragma("unroll") for (int n = 0; n < 2; ++n) _Pragma("unroll") for (int k = 0; k < 2; ++k) dst[n][k] = *(const PG8_LAS bf16x8*)(lds + PG8_SB(b, h) + boff + n * 2048 + k * 1024); } while (0)
; #define PG8_MMA(ai, bj, At, Bt) do { __builtin_amdgcn_s_setprio(1); _Pragma("unroll") for (int m = 0; m < 4; ++m) _Pragma("unroll") for (int n = 0; n < 2; ++n) _Pragma("unroll") for (int k = 0; k < 2; ++k) \
;         acc[ai][bj][m][n] = __builtin_amdgcn_mfma_f32_16x16x32_bf16(Bt[n][k], At[m][k], acc[ai][bj][m][n], 0, 0, 0); __builtin_amdgcn_s_setprio(0); } while (0)
; #define PG8_WAIT_V(n) asm volatile("s_waitcnt vmcnt(" #n ")" ::: "memory")
; #define PG8_WAIT_L(n) asm volatile("s_waitcnt lgkmcnt(" #n ")" ::: "memory")
; #define PG8_BAR __builtin_amdgcn_s_barrier()
; #define PG8_SCHED __builtin_amdgcn_sched_barrier(0)
; template <class Epi, class Sched>
; __device__ __forceinline__ void gemm_phase(PG8_LAS unsigned char* lds, PG8_LAS unsigned char* xl, const Gemm g, const Sched& S, const Epi& E) {
;     ...
;             PG8_LDA(At, 0, 1); PG8_STAGE(PG8_SB(0, 0), b2, voffB); PG8_STAGE(PG8_SB(0, 1), b2 + hsB, voffB); PG8_STAGE(PG8_SA(0, 0), a2, voffA);
;             PG8_WAIT_V(8); PG8_WAIT_L(0); PG8_BAR; PG8_MMA(1, 0, At, B0); PG8_MMA(1, 1, At, B1); PG8_BAR; PG8_SCHED;
;             PG8_LDB(B0, 1, 0); PG8_LDB(B1, 1, 1); PG8_SCHED; PG8_LDA(At, 1, 0); PG8_STAGE(PG8_SA(0, 1), a2 + hsA, voffA);
;             PG8_WAIT_V(8); PG8_WAIT_L(0); PG8_BAR; PG8_MMA(0, 0, At, B0); PG8_MMA(0, 1, At, B1); PG8_BAR; PG8_SCHED;
	v_mfma_f32_16x16x32_bf16 v[60:63], v[144:147], v[214:217], 0
	v_mfma_f32_16x16x32_bf16 v[56:59], v[152:155], v[214:217], 0
	v_mfma_f32_16x16x32_bf16 v[44:47], v[144:147], v[226:229], 0
	v_mfma_f32_16x16x32_bf16 v[40:43], v[152:155], v[226:229], 0
	v_mfma_f32_16x16x32_bf16 v[28:31], v[144:147], v[234:237], 0
	v_mfma_f32_16x16x32_bf16 v[24:27], v[152:155], v[234:237], 0
	v_mfma_f32_16x16x32_bf16 v[12:15], v[144:147], v[242:245], 0
	v_mfma_f32_16x16x32_bf16 v[8:11], v[152:155], v[242:245], 0
	v_mfma_f32_16x16x32_bf16 v[60:63], v[148:151], v[222:225], v[60:63]
	v_mfma_f32_16x16x32_bf16 v[56:59], v[156:159], v[222:225], v[56:59]
	v_mfma_f32_16x16x32_bf16 v[44:47], v[148:151], v[230:233], v[44:47]
	v_mfma_f32_16x16x32_bf16 v[40:43], v[156:159], v[230:233], v[40:43]
	v_mfma_f32_16x16x32_bf16 v[28:31], v[148:151], v[238:241], v[28:31]
	v_mfma_f32_16x16x32_bf16 v[24:27], v[156:159], v[238:241], v[24:27]
	v_mfma_f32_16x16x32_bf16 v[12:15], v[148:151], v[246:249], v[12:15]
	v_mfma_f32_16x16x32_bf16 v[8:11], v[156:159], v[246:249], v[8:11]
	s_setprio 0
	s_setprio 1
	v_mfma_f32_16x16x32_bf16 v[52:55], v[160:163], v[214:217], 0
	v_mfma_f32_16x16x32_bf16 v[48:51], v[168:171], v[214:217], 0
	v_mfma_f32_16x16x32_bf16 v[36:39], v[160:163], v[226:229], 0
	v_mfma_f32_16x16x32_bf16 v[32:35], v[168:171], v[226:229], 0
	v_mfma_f32_16x16x32_bf16 v[20:23], v[160:163], v[234:237], 0
	v_mfma_f32_16x16x32_bf16 v[16:19], v[168:171], v[234:237], 0
	v_mfma_f32_16x16x32_bf16 v[4:7], v[160:163], v[242:245], 0
	v_mfma_f32_16x16x32_bf16 v[0:3], v[168:171], v[242:245], 0
	v_mfma_f32_16x16x32_bf16 v[52:55], v[164:167], v[222:225], v[52:55]
	v_mfma_f32_16x16x32_bf16 v[48:51], v[172:175], v[222:225], v[48:51]
	v_mfma_f32_16x16x32_bf16 v[36:39], v[164:167], v[230:233], v[36:39]
	v_mfma_f32_16x16x32_bf16 v[32:35], v[172:175], v[230:233], v[32:35]
	v_mfma_f32_16x16x32_bf16 v[20:23], v[164:167], v[238:241], v[20:23]
	v_mfma_f32_16x16x32_bf16 v[16:19], v[172:175], v[238:241], v[16:19]
	v_mfma_f32_16x16x32_bf16 v[4:7], v[164:167], v[246:249], v[4:7]
	v_mfma_f32_16x16x32_bf16 v[0:3], v[172:175], v[246:249], v[0:3]
	s_barrier
	s_setprio 0
	s_add_i32 s68, 0, 0x18000
	s_add_i32 s81, 0, 0x1c000
	v_add_u32_e32 v156, s68, v181
	v_add_u32_e32 v172, s81, v181
	ds_read_b128 v[144:147], v156
	ds_read_b128 v[148:151], v156 offset:1024
	ds_read_b128 v[152:155], v156 offset:2048
	ds_read_b128 v[156:159], v156 offset:3072
	ds_read_b128 v[160:163], v172
	ds_read_b128 v[164:167], v172 offset:1024
	ds_read_b128 v[168:171], v172 offset:2048
	ds_read_b128 v[172:175], v172 offset:3072
	s_add_u32 s2, s52, 0xb0000
	s_addc_u32 s3, s53, 0
	s_mov_b32 m0, s60
	v_lshl_add_u64 v[212:213], s[2:3], 0, v[128:129]
	ds_read_b128 v[214:217], v201 offset:32768
	ds_read_b128 v[222:225], v201 offset:33792
	ds_read_b128 v[226:229], v201 offset:34816
	ds_read_b128 v[230:233], v201 offset:35840
	ds_read_b128 v[234:237], v201 offset:36864
	ds_read_b128 v[238:241], v201 offset:37888
	ds_read_b128 v[242:245], v201 offset:38912
	ds_read_b128 v[246:249], v201 offset:39936
	global_load_lds_dwordx4 v[212:213], off
	v_lshl_add_u64 v[212:213], s[2:3], 0, v[132:133]
	s_mov_b32 m0, s61
	s_nop 0
	global_load_lds_dwordx4 v[212:213], off
	s_waitcnt vmcnt(8) lgkmcnt(0)
	s_setprio 1
	s_barrier
	v_mfma_f32_16x16x32_bf16 v[124:127], v[144:147], v[214:217], v[124:127]
	v_mfma_f32_16x16x32_bf16 v[120:123], v[152:155], v[214:217], v[120:123]
	v_mfma_f32_16x16x32_bf16 v[108:111], v[144:147], v[226:229], v[108:111]
	v_mfma_f32_16x16x32_bf16 v[104:107], v[152:155], v[226:229], v[104:107]
	v_mfma_f32_16x16x32_bf16 v[92:95], v[144:147], v[234:237], v[92:95]
	v_mfma_f32_16x16x32_bf16 v[88:91], v[152:155], v[234:237], v[88:91]
	v_mfma_f32_16x16x32_bf16 v[76:79], v[144:147], v[242:245], v[76:79]
	v_mfma_f32_16x16x32_bf16 v[72:75], v[152:155], v[242:245], v[72:75]
	v_mfma_f32_16x16x32_bf16 v[124:127], v[148:151], v[222:225], v[124:127]
	v_mfma_f32_16x16x32_bf16 v[120:123], v[156:159], v[222:225], v[120:123]
	v_mfma_f32_16x16x32_bf16 v[108:111], v[148:151], v[230:233], v[108:111]
	v_mfma_f32_16x16x32_bf16 v[104:107], v[156:159], v[230:233], v[104:107]
	v_mfma_f32_16x16x32_bf16 v[92:95], v[148:151], v[238:241], v[92:95]
	v_mfma_f32_16x16x32_bf16 v[88:91], v[156:159], v[238:241], v[88:91]
	v_mfma_f32_16x16x32_bf16 v[76:79], v[148:151], v[246:249], v[76:79]
	v_mfma_f32_16x16x32_bf16 v[72:75], v[156:159], v[246:249], v[72:75]
	s_setprio 0
	s_setprio 1
	v_mfma_f32_16x16x32_bf16 v[116:119], v[160:163], v[214:217], v[116:119]
	v_mfma_f32_16x16x32_bf16 v[112:115], v[168:171], v[214:217], v[112:115]
	v_mfma_f32_16x16x32_bf16 v[100:103], v[160:163], v[226:229], v[100:103]
	v_mfma_f32_16x16x32_bf16 v[96:99], v[168:171], v[226:229], v[96:99]
	v_mfma_f32_16x16x32_bf16 v[84:87], v[160:163], v[234:237], v[84:87]
	v_mfma_f32_16x16x32_bf16 v[80:83], v[168:171], v[234:237], v[80:83]
	v_mfma_f32_16x16x32_bf16 v[68:71], v[160:163], v[242:245], v[68:71]
	v_mfma_f32_16x16x32_bf16 v[64:67], v[168:171], v[242:245], v[64:67]
	v_mfma_f32_16x16x32_bf16 v[116:119], v[164:167], v[222:225], v[116:119]
	v_mfma_f32_16x16x32_bf16 v[112:115], v[172:175], v[222:225], v[112:115]
	v_mfma_f32_16x16x32_bf16 v[100:103], v[164:167], v[230:233], v[100:103]
	v_mfma_f32_16x16x32_bf16 v[96:99], v[172:175], v[230:233], v[96:99]
	v_mfma_f32_16x16x32_bf16 v[84:87], v[164:167], v[238:241], v[84:87]
	v_mfma_f32_16x16x32_bf16 v[80:83], v[172:175], v[238:241], v[80:83]
	v_mfma_f32_16x16x32_bf16 v[68:71], v[164:167], v[246:249], v[68:71]
	v_mfma_f32_16x16x32_bf16 v[64:67], v[172:175], v[246:249], v[64:67]
	s_barrier
; #define PG8_STAGE(bufoff, gbase, voff) do { _Pragma("unroll") for (int _i = 0; _i < 2; ++_i) \
;         __builtin_amdgcn_global_load_lds((const unsigned*)((const char*)(gbase) + (voff)[_i]), (PG8_LAS unsigned*)(lds + (bufoff) + ldsw + _i * 8192), 16, 0, 0); } while (0)
; #define PG8_LDA(dst, b, h) do { _Pragma("unroll") for (int m = 0; m < 4; ++m) _Pragma("unroll") for (int k = 0; k < 2; ++k) dst[m][k] = *(const PG8_LAS bf16x8*)(lds + PG8_SA(b, h) + aoff + m * 2048 + k * 1024); } while (0)
; #define PG8_LDB(dst, b, h) do { _Pragma("unroll") for (int n = 0; n < 2; ++n) _Pragma("unroll") for (int k = 0; k < 2; ++k) dst[n][k] = *(const PG8_LAS bf16x8*)(lds + PG8_SB(b, h) + boff + n * 2048 + k * 1024); } while (0)
; #define PG8_MMA(ai, bj, At, Bt) do { __builtin_amdgcn_s_setprio(1); _Pragma("unroll") for (int m = 0; m < 4; ++m) _Pragma("unroll") for (int n = 0; n < 2; ++n) _Pragma("unroll") for (int k = 0; k < 2; ++k) \
;         acc[ai][bj][m][n] = __builtin_amdgcn_mfma_f32_16x16x32_bf16(Bt[n][k], At[m][k], acc[ai][bj][m][n], 0, 0, 0); __builtin_amdgcn_s_setprio(0); } while (0)
; #define PG8_WAIT_V(n) asm volatile("s_waitcnt vmcnt(" #n ")" ::: "memory")
; #define PG8_WAIT_L(n) asm volatile("s_waitcnt lgkmcnt(" #n ")" ::: "memory")
; #define PG8_BAR __builtin_amdgcn_s_barrier()
; #define PG8_SCHED __builtin_amdgcn_sched_barrier(0)
; template <class Epi, class Sched>
; __device__ __forceinline__ void gemm_phase(PG8_LAS unsigned char* lds, PG8_LAS unsigned char* xl, const Gemm g, const Sched& S, const Epi& E) {
;     ...
;             const bool last = (t == nt - 2);
;             const char* a1 = cA + (size_t)(t + 1) * kstep;
;             const char* a2 = last ? nA : cA + (size_t)(t + 2) * kstep; const char* b2 = last ? nB : cB + (size_t)(t + 2) * kstep;
;             const char* a3 = a2 + kstep; const char* b3 = b2 + kstep;
;             PG8_LDB(B0, 0, 0); PG8_LDB(B1, 0, 1); PG8_SCHED; PG8_LDA(At, 0, 0); PG8_STAGE(PG8_SA(1, 1), a1 + hsA, voffA);
;     ...
;             PG8_LDA(At, 1, 1); PG8_STAGE(PG8_SB(1, 0), b3, voffB); PG8_STAGE(PG8_SB(1, 1), b3 + hsB, voffB); PG8_STAGE(PG8_SA(1, 0), a3, voffA);
;             PG8_WAIT_V(8); PG8_WAIT_L(0); PG8_BAR; PG8_MMA(1, 0, At, B0); PG8_MMA(1, 1, At, B1); PG8_BAR; PG8_SCHED;
	s_setprio 0
	s_add_i32 s2, s68, s42
	v_lshl_add_u64 v[176:177], v[176:177], 0, s[22:23]
	s_mov_b32 m0, s2
	ds_read_b128 v[214:217], v201 offset:49152
	ds_read_b128 v[222:225], v201 offset:50176
	ds_read_b128 v[226:229], v201 offset:51200
	ds_read_b128 v[230:233], v201 offset:52224
	ds_read_b128 v[234:237], v201 offset:53248
	ds_read_b128 v[238:241], v201 offset:54272
	ds_read_b128 v[242:245], v201 offset:55296
	ds_read_b128 v[246:249], v201 offset:56320
	global_load_lds_dwordx4 v[176:177], off
	s_add_i32 m0, s2, 0x2000
	s_add_u32 s2, s50, 0xb0080
	v_lshl_add_u64 v[176:177], v[218:219], 0, s[22:23]
	s_addc_u32 s3, s51, 0
	s_add_i32 s50, s81, s42
	global_load_lds_dwordx4 v[176:177], off
	v_lshl_add_u64 v[176:177], s[2:3], 0, v[130:131]
	s_mov_b32 m0, s50
	s_nop 0
	global_load_lds_dwordx4 v[176:177], off
	v_lshl_add_u64 v[176:177], s[2:3], 0, v[134:135]
	s_add_i32 m0, s50, 0x2000
	s_nop 0
	global_load_lds_dwordx4 v[176:177], off
	v_lshl_add_u64 v[176:177], v[250:251], 0, s[22:23]
	s_mov_b32 m0, s65
	s_nop 0
	global_load_lds_dwordx4 v[176:177], off
	v_lshl_add_u64 v[176:177], v[252:253], 0, s[22:23]
	s_mov_b32 m0, s66
	s_nop 0
	global_load_lds_dwordx4 v[176:177], off
	s_waitcnt vmcnt(8) lgkmcnt(0)
	s_setprio 1
	s_barrier
	v_mfma_f32_16x16x32_bf16 v[60:63], v[144:147], v[214:217], v[60:63]
	v_mfma_f32_16x16x32_bf16 v[56:59], v[152:155], v[214:217], v[56:59]
	v_mfma_f32_16x16x32_bf16 v[44:47], v[144:147], v[226:229], v[44:47]
	v_mfma_f32_16x16x32_bf16 v[40:43], v[152:155], v[226:229], v[40:43]
	v_mfma_f32_16x16x32_bf16 v[28:31], v[144:147], v[234:237], v[28:31]
	v_mfma_f32_16x16x32_bf16 v[24:27], v[152:155], v[234:237], v[24:27]
	v_mfma_f32_16x16x32_bf16 v[12:15], v[144:147], v[242:245], v[12:15]
	v_mfma_f32_16x16x32_bf16 v[8:11], v[152:155], v[242:245], v[8:11]
	v_mfma_f32_16x16x32_bf16 v[60:63], v[148:151], v[222:225], v[60:63]
	v_mfma_f32_16x16x32_bf16 v[56:59], v[156:159], v[222:225], v[56:59]
	v_mfma_f32_16x16x32_bf16 v[44:47], v[148:151], v[230:233], v[44:47]
	v_mfma_f32_16x16x32_bf16 v[40:43], v[156:159], v[230:233], v[40:43]
	v_mfma_f32_16x16x32_bf16 v[28:31], v[148:151], v[238:241], v[28:31]
	v_mfma_f32_16x16x32_bf16 v[24:27], v[156:159], v[238:241], v[24:27]
	v_mfma_f32_16x16x32_bf16 v[12:15], v[148:151], v[246:249], v[12:15]
	v_mfma_f32_16x16x32_bf16 v[8:11], v[156:159], v[246:249], v[8:11]
	s_setprio 0
	s_setprio 1
	v_mfma_f32_16x16x32_bf16 v[52:55], v[160:163], v[214:217], v[52:55]
	s_add_i32 s80, s80, 2
	v_mfma_f32_16x16x32_bf16 v[48:51], v[168:171], v[214:217], v[48:51]
	s_add_u32 s78, s78, 0x100
	v_mfma_f32_16x16x32_bf16 v[36:39], v[160:163], v[226:229], v[36:39]
	s_addc_u32 s79, s79, 0
	v_mfma_f32_16x16x32_bf16 v[32:35], v[168:171], v[226:229], v[32:35]
	s_cmp_gt_u32 s80, 41
	v_mfma_f32_16x16x32_bf16 v[20:23], v[160:163], v[234:237], v[20:23]
	s_mov_b64 s[2:3], s[48:49]
	v_mfma_f32_16x16x32_bf16 v[16:19], v[168:171], v[234:237], v[16:19]
	v_mfma_f32_16x16x32_bf16 v[4:7], v[160:163], v[242:245], v[4:7]
	v_mfma_f32_16x16x32_bf16 v[0:3], v[168:171], v[242:245], v[0:3]
	v_mfma_f32_16x16x32_bf16 v[52:55], v[164:167], v[222:225], v[52:55]
	v_mfma_f32_16x16x32_bf16 v[48:51], v[172:175], v[222:225], v[48:51]
	v_mfma_f32_16x16x32_bf16 v[36:39], v[164:167], v[230:233], v[36:39]
	v_mfma_f32_16x16x32_bf16 v[32:35], v[172:175], v[230:233], v[32:35]
	v_mfma_f32_16x16x32_bf16 v[20:23], v[164:167], v[238:241], v[20:23]
	v_mfma_f32_16x16x32_bf16 v[16:19], v[172:175], v[238:241], v[16:19]
	v_mfma_f32_16x16x32_bf16 v[4:7], v[164:167], v[246:249], v[4:7]
	v_mfma_f32_16x16x32_bf16 v[0:3], v[172:175], v[246:249], v[0:3]
	s_barrier
	s_setprio 0
	s_cbranch_scc1 .Lpeel_after_P9
.LBB0_942:
	ds_read_b128 v[144:147], v199
	ds_read_b128 v[148:151], v199 offset:1024
	ds_read_b128 v[152:155], v199 offset:2048
	ds_read_b128 v[156:159], v199 offset:3072
	ds_read_b128 v[160:163], v200
	ds_read_b128 v[164:167], v200 offset:1024
	ds_read_b128 v[168:171], v200 offset:2048
	ds_read_b128 v[172:175], v200 offset:3072
	s_add_u32 s48, s2, 0x100
	s_addc_u32 s49, s3, 0
	s_cmp_eq_u32 s80, 40
	s_cselect_b32 s53, s33, s49
	s_cselect_b32 s52, s46, s48
	s_cselect_b32 s51, s47, s79
	s_cselect_b32 s50, s77, s78
	v_lshl_add_u64 v[176:177], s[2:3], 0, v[138:139]
	s_add_i32 m0, s43, 0xc000
	ds_read_b128 v[214:217], v201
	ds_read_b128 v[222:225], v201 offset:1024
	ds_read_b128 v[226:229], v201 offset:2048
	ds_read_b128 v[230:233], v201 offset:3072
	ds_read_b128 v[234:237], v201 offset:4096
	ds_read_b128 v[238:241], v201 offset:5120
	ds_read_b128 v[242:245], v201 offset:6144
	ds_read_b128 v[246:249], v201 offset:7168
	global_load_lds_dwordx4 v[176:177], off
	v_lshl_add_u64 v[176:177], s[2:3], 0, v[136:137]
	s_add_i32 m0, s43, 0xe000
	s_nop 0
	global_load_lds_dwordx4 v[176:177], off
	s_waitcnt vmcnt(8) lgkmcnt(0)
	s_setprio 1
	s_barrier
; #define PG8_STAGE(bufoff, gbase, voff) do { _Pragma("unroll") for (int _i = 0; _i < 2; ++_i) \
;         __builtin_amdgcn_global_load_lds((const unsigned*)((const char*)(gbase) + (voff)[_i]), (PG8_LAS unsigned*)(lds + (bufoff) + ldsw + _i * 8192), 16, 0, 0); } while (0)
; #define PG8_LDA(dst, b, h) do { _Pragma("unroll") for (int m = 0; m < 4; ++m) _Pragma("unroll") for (int k = 0; k < 2; ++k) dst[m][k] = *(const PG8_LAS bf16x8*)(lds + PG8_SA(b, h) + aoff + m * 2048 + k * 1024); } while (0)
; #define PG8_LDB(dst, b, h) do { _Pragma("unroll") for (int n = 0; n < 2; ++n) _Pragma("unroll") for (int k = 0; k < 2; ++k) dst[n][k] = *(const PG8_LAS bf16x8*)(lds + PG8_SB(b, h) + boff + n * 2048 + k * 1024); } while (0)
; #define PG8_MMA(ai, bj, At, Bt) do { __builtin_amdgcn_s_setprio(1); _Pragma("unroll") for (int m = 0; m < 4; ++m) _Pragma("unroll") for (int n = 0; n < 2; ++n) _Pragma("unroll") for (int k = 0; k < 2; ++k) \
;         acc[ai][bj][m][n] = __builtin_amdgcn_mfma_f32_16x16x32_bf16(Bt[n][k], At[m][k], acc[ai][bj][m][n], 0, 0, 0); __builtin_amdgcn_s_setprio(0); } while (0)
; #define PG8_WAIT_V(n) asm volatile("s_waitcnt vmcnt(" #n ")" ::: "memory")
; #define PG8_WAIT_L(n) asm volatile("s_waitcnt lgkmcnt(" #n ")" ::: "memory")
; #define PG8_BAR __builtin_amdgcn_s_barrier()
; #define PG8_SCHED __builtin_amdgcn_sched_barrier(0)
; template <class Epi, class Sched>
; __device__ __forceinline__ void gemm_phase(PG8_LAS unsigned char* lds, PG8_LAS unsigned char* xl, const Gemm g, const Sched& S, const Epi& E) {
;     ...
;             PG8_LDB(B0, 0, 0); PG8_LDB(B1, 0, 1); PG8_SCHED; PG8_LDA(At, 0, 0); PG8_STAGE(PG8_SA(1, 1), a1 + hsA, voffA);
;             PG8_WAIT_V(8); PG8_WAIT_L(0); PG8_BAR; PG8_MMA(0, 0, At, B0); PG8_MMA(0, 1, At, B1); PG8_BAR; PG8_SCHED;
;             PG8_LDA(At, 0, 1); PG8_STAGE(PG8_SB(0, 0), b2, voffB); PG8_STAGE(PG8_SB(0, 1), b2 + hsB, voffB); PG8_STAGE(PG8_SA(0, 0), a2, voffA);
;             PG8_WAIT_V(8); PG8_WAIT_L(0); PG8_BAR; PG8_MMA(1, 0, At, B0); PG8_MMA(1, 1, At, B1); PG8_BAR; PG8_SCHED;
;             PG8_LDB(B0, 1, 0); PG8_LDB(B1, 1, 1); PG8_SCHED; PG8_LDA(At, 1, 0); PG8_STAGE(PG8_SA(0, 1), a2 + hsA, voffA);
;             PG8_WAIT_V(8); PG8_WAIT_L(0); PG8_BAR; PG8_MMA(0, 0, At, B0); PG8_MMA(0, 1, At, B1); PG8_BAR; PG8_SCHED;
	v_mfma_f32_16x16x32_bf16 v[124:127], v[144:147], v[214:217], v[124:127]
	v_mfma_f32_16x16x32_bf16 v[120:123], v[152:155], v[214:217], v[120:123]
	v_mfma_f32_16x16x32_bf16 v[108:111], v[144:147], v[226:229], v[108:111]
	v_mfma_f32_16x16x32_bf16 v[104:107], v[152:155], v[226:229], v[104:107]
	v_mfma_f32_16x16x32_bf16 v[92:95], v[144:147], v[234:237], v[92:95]
	v_mfma_f32_16x16x32_bf16 v[88:91], v[152:155], v[234:237], v[88:91]
	v_mfma_f32_16x16x32_bf16 v[76:79], v[144:147], v[242:245], v[76:79]
	v_mfma_f32_16x16x32_bf16 v[72:75], v[152:155], v[242:245], v[72:75]
	v_mfma_f32_16x16x32_bf16 v[124:127], v[148:151], v[222:225], v[124:127]
	v_mfma_f32_16x16x32_bf16 v[120:123], v[156:159], v[222:225], v[120:123]
	v_mfma_f32_16x16x32_bf16 v[108:111], v[148:151], v[230:233], v[108:111]
	v_mfma_f32_16x16x32_bf16 v[104:107], v[156:159], v[230:233], v[104:107]
	v_mfma_f32_16x16x32_bf16 v[92:95], v[148:151], v[238:241], v[92:95]
	v_mfma_f32_16x16x32_bf16 v[88:91], v[156:159], v[238:241], v[88:91]
	v_mfma_f32_16x16x32_bf16 v[76:79], v[148:151], v[246:249], v[76:79]
	v_mfma_f32_16x16x32_bf16 v[72:75], v[156:159], v[246:249], v[72:75]
	s_setprio 0
	s_setprio 1
	v_mfma_f32_16x16x32_bf16 v[116:119], v[160:163], v[214:217], v[116:119]
	v_mfma_f32_16x16x32_bf16 v[112:115], v[168:171], v[214:217], v[112:115]
	v_mfma_f32_16x16x32_bf16 v[100:103], v[160:163], v[226:229], v[100:103]
	v_mfma_f32_16x16x32_bf16 v[96:99], v[168:171], v[226:229], v[96:99]
	v_mfma_f32_16x16x32_bf16 v[84:87], v[160:163], v[234:237], v[84:87]
	v_mfma_f32_16x16x32_bf16 v[80:83], v[168:171], v[234:237], v[80:83]
	v_mfma_f32_16x16x32_bf16 v[68:71], v[160:163], v[242:245], v[68:71]
	v_mfma_f32_16x16x32_bf16 v[64:67], v[168:171], v[242:245], v[64:67]
	v_mfma_f32_16x16x32_bf16 v[116:119], v[164:167], v[222:225], v[116:119]
	v_mfma_f32_16x16x32_bf16 v[112:115], v[172:175], v[222:225], v[112:115]
	v_mfma_f32_16x16x32_bf16 v[100:103], v[164:167], v[230:233], v[100:103]
	v_mfma_f32_16x16x32_bf16 v[96:99], v[172:175], v[230:233], v[96:99]
	v_mfma_f32_16x16x32_bf16 v[84:87], v[164:167], v[238:241], v[84:87]
	v_mfma_f32_16x16x32_bf16 v[80:83], v[172:175], v[238:241], v[80:83]
	v_mfma_f32_16x16x32_bf16 v[68:71], v[164:167], v[246:249], v[68:71]
	v_mfma_f32_16x16x32_bf16 v[64:67], v[172:175], v[246:249], v[64:67]
	s_barrier
	s_setprio 0
	s_add_i32 s2, s70, s42
	v_lshl_add_u64 v[176:177], s[50:51], 0, v[130:131]
	s_mov_b32 m0, s2
	ds_read_b128 v[214:217], v201 offset:16384
	ds_read_b128 v[222:225], v201 offset:17408
	ds_read_b128 v[226:229], v201 offset:18432
	ds_read_b128 v[230:233], v201 offset:19456
	ds_read_b128 v[234:237], v201 offset:20480
	ds_read_b128 v[238:241], v201 offset:21504
	ds_read_b128 v[242:245], v201 offset:22528
	ds_read_b128 v[246:249], v201 offset:23552
	global_load_lds_dwordx4 v[176:177], off
	s_add_i32 m0, s2, 0x2000
	s_add_u32 s2, s50, 0xb0000
	v_lshl_add_u64 v[218:219], s[50:51], 0, v[134:135]
	s_addc_u32 s3, s51, 0
	s_add_i32 s68, s71, s42
	global_load_lds_dwordx4 v[218:219], off
	v_lshl_add_u64 v[250:251], s[2:3], 0, v[130:131]
	s_mov_b32 m0, s68
	v_lshl_add_u64 v[252:253], s[52:53], 0, v[132:133]
	global_load_lds_dwordx4 v[250:251], off
	v_lshl_add_u64 v[250:251], s[2:3], 0, v[134:135]
	s_add_i32 m0, s68, 0x2000
	s_nop 0
	global_load_lds_dwordx4 v[250:251], off
	v_lshl_add_u64 v[250:251], s[52:53], 0, v[128:129]
	s_mov_b32 m0, s43
	s_nop 0
	global_load_lds_dwordx4 v[250:251], off
	s_mov_b32 m0, s59
	s_nop 0
	global_load_lds_dwordx4 v[252:253], off
	s_waitcnt vmcnt(8) lgkmcnt(0)
	s_setprio 1
	s_barrier
	v_mfma_f32_16x16x32_bf16 v[60:63], v[144:147], v[214:217], v[60:63]
	v_mfma_f32_16x16x32_bf16 v[56:59], v[152:155], v[214:217], v[56:59]
	v_mfma_f32_16x16x32_bf16 v[44:47], v[144:147], v[226:229], v[44:47]
	v_mfma_f32_16x16x32_bf16 v[40:43], v[152:155], v[226:229], v[40:43]
	v_mfma_f32_16x16x32_bf16 v[28:31], v[144:147], v[234:237], v[28:31]
	v_mfma_f32_16x16x32_bf16 v[24:27], v[152:155], v[234:237], v[24:27]
	v_mfma_f32_16x16x32_bf16 v[12:15], v[144:147], v[242:245], v[12:15]
	v_mfma_f32_16x16x32_bf16 v[8:11], v[152:155], v[242:245], v[8:11]
	v_mfma_f32_16x16x32_bf16 v[60:63], v[148:151], v[222:225], v[60:63]
	v_mfma_f32_16x16x32_bf16 v[56:59], v[156:159], v[222:225], v[56:59]
	v_mfma_f32_16x16x32_bf16 v[44:47], v[148:151], v[230:233], v[44:47]
	v_mfma_f32_16x16x32_bf16 v[40:43], v[156:159], v[230:233], v[40:43]
	v_mfma_f32_16x16x32_bf16 v[28:31], v[148:151], v[238:241], v[28:31]
	v_mfma_f32_16x16x32_bf16 v[24:27], v[156:159], v[238:241], v[24:27]
	v_mfma_f32_16x16x32_bf16 v[12:15], v[148:151], v[246:249], v[12:15]
	v_mfma_f32_16x16x32_bf16 v[8:11], v[156:159], v[246:249], v[8:11]
	s_setprio 0
	s_setprio 1
	v_mfma_f32_16x16x32_bf16 v[52:55], v[160:163], v[214:217], v[52:55]
	v_mfma_f32_16x16x32_bf16 v[48:51], v[168:171], v[214:217], v[48:51]
	v_mfma_f32_16x16x32_bf16 v[36:39], v[160:163], v[226:229], v[36:39]
	v_mfma_f32_16x16x32_bf16 v[32:35], v[168:171], v[226:229], v[32:35]
	v_mfma_f32_16x16x32_bf16 v[20:23], v[160:163], v[234:237], v[20:23]
	v_mfma_f32_16x16x32_bf16 v[16:19], v[168:171], v[234:237], v[16:19]
	v_mfma_f32_16x16x32_bf16 v[4:7], v[160:163], v[242:245], v[4:7]
	v_mfma_f32_16x16x32_bf16 v[0:3], v[168:171], v[242:245], v[0:3]
	v_mfma_f32_16x16x32_bf16 v[52:55], v[164:167], v[222:225], v[52:55]
	v_mfma_f32_16x16x32_bf16 v[48:51], v[172:175], v[222:225], v[48:51]
	v_mfma_f32_16x16x32_bf16 v[36:39], v[164:167], v[230:233], v[36:39]
	v_mfma_f32_16x16x32_bf16 v[32:35], v[172:175], v[230:233], v[32:35]
	v_mfma_f32_16x16x32_bf16 v[20:23], v[164:167], v[238:241], v[20:23]
	v_mfma_f32_16x16x32_bf16 v[16:19], v[172:175], v[238:241], v[16:19]
	v_mfma_f32_16x16x32_bf16 v[4:7], v[164:167], v[246:249], v[4:7]
	v_mfma_f32_16x16x32_bf16 v[0:3], v[172:175], v[246:249], v[0:3]
	s_barrier
; #define PG8_STAGE(bufoff, gbase, voff) do { _Pragma("unroll") for (int _i = 0; _i < 2; ++_i) \
;         __builtin_amdgcn_global_load_lds((const unsigned*)((const char*)(gbase) + (voff)[_i]), (PG8_LAS unsigned*)(lds + (bufoff) + ldsw + _i * 8192), 16, 0, 0); } while (0)
; #define PG8_LDA(dst, b, h) do { _Pragma("unroll") for (int m = 0; m < 4; ++m) _Pragma("unroll") for (int k = 0; k < 2; ++k) dst[m][k] = *(const PG8_LAS bf16x8*)(lds + PG8_SA(b, h) + aoff + m * 2048 + k * 1024); } while (0)
; #define PG8_LDB(dst, b, h) do { _Pragma("unroll") for (int n = 0; n < 2; ++n) _Pragma("unroll") for (int k = 0; k < 2; ++k) dst[n][k] = *(const PG8_LAS bf16x8*)(lds + PG8_SB(b, h) + boff + n * 2048 + k * 1024); } while (0)
; #define PG8_MMA(ai, bj, At, Bt) do { __builtin_amdgcn_s_setprio(1); _Pragma("unroll") for (int m = 0; m < 4; ++m) _Pragma("unroll") for (int n = 0; n < 2; ++n) _Pragma("unroll") for (int k = 0; k < 2; ++k) \
;         acc[ai][bj][m][n] = __builtin_amdgcn_mfma_f32_16x16x32_bf16(Bt[n][k], At[m][k], acc[ai][bj][m][n], 0, 0, 0); __builtin_amdgcn_s_setprio(0); } while (0)
; #define PG8_WAIT_V(n) asm volatile("s_waitcnt vmcnt(" #n ")" ::: "memory")
; #define PG8_WAIT_L(n) asm volatile("s_waitcnt lgkmcnt(" #n ")" ::: "memory")
; #define PG8_BAR __builtin_amdgcn_s_barrier()
; #define PG8_SCHED __builtin_amdgcn_sched_barrier(0)
; template <class Epi, class Sched>
; __device__ __forceinline__ void gemm_phase(PG8_LAS unsigned char* lds, PG8_LAS unsigned char* xl, const Gemm g, const Sched& S, const Epi& E) {
;     ...
;             PG8_LDB(B0, 1, 0); PG8_LDB(B1, 1, 1); PG8_SCHED; PG8_LDA(At, 1, 0); PG8_STAGE(PG8_SA(0, 1), a2 + hsA, voffA);
;             PG8_WAIT_V(8); PG8_WAIT_L(0); PG8_BAR; PG8_MMA(0, 0, At, B0); PG8_MMA(0, 1, At, B1); PG8_BAR; PG8_SCHED;
	s_setprio 0
	s_add_i32 s68, 0, 0x18000
	s_add_i32 s81, 0, 0x1c000
	v_add_u32_e32 v156, s68, v181
	v_add_u32_e32 v172, s81, v181
	ds_read_b128 v[144:147], v156
	ds_read_b128 v[148:151], v156 offset:1024
	ds_read_b128 v[152:155], v156 offset:2048
	ds_read_b128 v[156:159], v156 offset:3072
	ds_read_b128 v[160:163], v172
	ds_read_b128 v[164:167], v172 offset:1024
	ds_read_b128 v[168:171], v172 offset:2048
	ds_read_b128 v[172:175], v172 offset:3072
	s_add_u32 s2, s52, 0xb0000
	s_addc_u32 s3, s53, 0
	s_mov_b32 m0, s60
	v_lshl_add_u64 v[212:213], s[2:3], 0, v[128:129]
	ds_read_b128 v[214:217], v201 offset:32768
	ds_read_b128 v[222:225], v201 offset:33792
	ds_read_b128 v[226:229], v201 offset:34816
	ds_read_b128 v[230:233], v201 offset:35840
	ds_read_b128 v[234:237], v201 offset:36864
	ds_read_b128 v[238:241], v201 offset:37888
	ds_read_b128 v[242:245], v201 offset:38912
	ds_read_b128 v[246:249], v201 offset:39936
	global_load_lds_dwordx4 v[212:213], off
	v_lshl_add_u64 v[212:213], s[2:3], 0, v[132:133]
	s_mov_b32 m0, s61
	s_nop 0
	global_load_lds_dwordx4 v[212:213], off
	s_waitcnt vmcnt(8) lgkmcnt(0)
	s_setprio 1
	s_barrier
	v_mfma_f32_16x16x32_bf16 v[124:127], v[144:147], v[214:217], v[124:127]
	v_mfma_f32_16x16x32_bf16 v[120:123], v[152:155], v[214:217], v[120:123]
	v_mfma_f32_16x16x32_bf16 v[108:111], v[144:147], v[226:229], v[108:111]
	v_mfma_f32_16x16x32_bf16 v[104:107], v[152:155], v[226:229], v[104:107]
	v_mfma_f32_16x16x32_bf16 v[92:95], v[144:147], v[234:237], v[92:95]
	v_mfma_f32_16x16x32_bf16 v[88:91], v[152:155], v[234:237], v[88:91]
	v_mfma_f32_16x16x32_bf16 v[76:79], v[144:147], v[242:245], v[76:79]
	v_mfma_f32_16x16x32_bf16 v[72:75], v[152:155], v[242:245], v[72:75]
	v_mfma_f32_16x16x32_bf16 v[124:127], v[148:151], v[222:225], v[124:127]
	v_mfma_f32_16x16x32_bf16 v[120:123], v[156:159], v[222:225], v[120:123]
	v_mfma_f32_16x16x32_bf16 v[108:111], v[148:151], v[230:233], v[108:111]
	v_mfma_f32_16x16x32_bf16 v[104:107], v[156:159], v[230:233], v[104:107]
	v_mfma_f32_16x16x32_bf16 v[92:95], v[148:151], v[238:241], v[92:95]
	v_mfma_f32_16x16x32_bf16 v[88:91], v[156:159], v[238:241], v[88:91]
	v_mfma_f32_16x16x32_bf16 v[76:79], v[148:151], v[246:249], v[76:79]
	v_mfma_f32_16x16x32_bf16 v[72:75], v[156:159], v[246:249], v[72:75]
	s_setprio 0
	s_setprio 1
	v_mfma_f32_16x16x32_bf16 v[116:119], v[160:163], v[214:217], v[116:119]
	v_mfma_f32_16x16x32_bf16 v[112:115], v[168:171], v[214:217], v[112:115]
	v_mfma_f32_16x16x32_bf16 v[100:103], v[160:163], v[226:229], v[100:103]
	v_mfma_f32_16x16x32_bf16 v[96:99], v[168:171], v[226:229], v[96:99]
	v_mfma_f32_16x16x32_bf16 v[84:87], v[160:163], v[234:237], v[84:87]
	v_mfma_f32_16x16x32_bf16 v[80:83], v[168:171], v[234:237], v[80:83]
	v_mfma_f32_16x16x32_bf16 v[68:71], v[160:163], v[242:245], v[68:71]
	v_mfma_f32_16x16x32_bf16 v[64:67], v[168:171], v[242:245], v[64:67]
	v_mfma_f32_16x16x32_bf16 v[116:119], v[164:167], v[222:225], v[116:119]
	v_mfma_f32_16x16x32_bf16 v[112:115], v[172:175], v[222:225], v[112:115]
	v_mfma_f32_16x16x32_bf16 v[100:103], v[164:167], v[230:233], v[100:103]
	v_mfma_f32_16x16x32_bf16 v[96:99], v[172:175], v[230:233], v[96:99]
	v_mfma_f32_16x16x32_bf16 v[84:87], v[164:167], v[238:241], v[84:87]
	v_mfma_f32_16x16x32_bf16 v[80:83], v[172:175], v[238:241], v[80:83]
	v_mfma_f32_16x16x32_bf16 v[68:71], v[164:167], v[246:249], v[68:71]
	v_mfma_f32_16x16x32_bf16 v[64:67], v[172:175], v[246:249], v[64:67]
	s_barrier
; #define PG8_STAGE(bufoff, gbase, voff) do { _Pragma("unroll") for (int _i = 0; _i < 2; ++_i) \
;         __builtin_amdgcn_global_load_lds((const unsigned*)((const char*)(gbase) + (voff)[_i]), (PG8_LAS unsigned*)(lds + (bufoff) + ldsw + _i * 8192), 16, 0, 0); } while (0)
; #define PG8_LDA(dst, b, h) do { _Pragma("unroll") for (int m = 0; m < 4; ++m) _Pragma("unroll") for (int k = 0; k < 2; ++k) dst[m][k] = *(const PG8_LAS bf16x8*)(lds + PG8_SA(b, h) + aoff + m * 2048 + k * 1024); } while (0)
; #define PG8_MMA(ai, bj, At, Bt) do { __builtin_amdgcn_s_setprio(1); _Pragma("unroll") for (int m = 0; m < 4; ++m) _Pragma("unroll") for (int n = 0; n < 2; ++n) _Pragma("unroll") for (int k = 0; k < 2; ++k) \
;         acc[ai][bj][m][n] = __builtin_amdgcn_mfma_f32_16x16x32_bf16(Bt[n][k], At[m][k], acc[ai][bj][m][n], 0, 0, 0); __builtin_amdgcn_s_setprio(0); } while (0)
; #define PG8_WAIT_V(n) asm volatile("s_waitcnt vmcnt(" #n ")" ::: "memory")
; #define PG8_WAIT_L(n) asm volatile("s_waitcnt lgkmcnt(" #n ")" ::: "memory")
; #define PG8_BAR __builtin_amdgcn_s_barrier()
; #define PG8_SCHED __builtin_amdgcn_sched_barrier(0)
; template <class Epi, class Sched>
; __device__ __forceinline__ void gemm_phase(PG8_LAS unsigned char* lds, PG8_LAS unsigned char* xl, const Gemm g, const Sched& S, const Epi& E) {
;     ...
;             PG8_LDA(At, 1, 1); PG8_STAGE(PG8_SB(1, 0), b3, voffB); PG8_STAGE(PG8_SB(1, 1), b3 + hsB, voffB); PG8_STAGE(PG8_SA(1, 0), a3, voffA);
;             PG8_WAIT_V(8); PG8_WAIT_L(0); PG8_BAR; PG8_MMA(1, 0, At, B0); PG8_MMA(1, 1, At, B1); PG8_BAR; PG8_SCHED;
	s_setprio 0
	s_add_i32 s2, s68, s42
	v_lshl_add_u64 v[176:177], v[176:177], 0, s[22:23]
	s_mov_b32 m0, s2
	ds_read_b128 v[214:217], v201 offset:49152
	ds_read_b128 v[222:225], v201 offset:50176
	ds_read_b128 v[226:229], v201 offset:51200
	ds_read_b128 v[230:233], v201 offset:52224
	ds_read_b128 v[234:237], v201 offset:53248
	ds_read_b128 v[238:241], v201 offset:54272
	ds_read_b128 v[242:245], v201 offset:55296
	ds_read_b128 v[246:249], v201 offset:56320
	global_load_lds_dwordx4 v[176:177], off
	s_add_i32 m0, s2, 0x2000
	s_add_u32 s2, s50, 0xb0080
	v_lshl_add_u64 v[176:177], v[218:219], 0, s[22:23]
	s_addc_u32 s3, s51, 0
	s_add_i32 s50, s81, s42
	global_load_lds_dwordx4 v[176:177], off
	v_lshl_add_u64 v[176:177], s[2:3], 0, v[130:131]
	s_mov_b32 m0, s50
	s_nop 0
	global_load_lds_dwordx4 v[176:177], off
	v_lshl_add_u64 v[176:177], s[2:3], 0, v[134:135]
	s_add_i32 m0, s50, 0x2000
	s_nop 0
	global_load_lds_dwordx4 v[176:177], off
	v_lshl_add_u64 v[176:177], v[250:251], 0, s[22:23]
	s_mov_b32 m0, s65
	s_nop 0
	global_load_lds_dwordx4 v[176:177], off
	v_lshl_add_u64 v[176:177], v[252:253], 0, s[22:23]
	s_mov_b32 m0, s66
	s_nop 0
	global_load_lds_dwordx4 v[176:177], off
	s_waitcnt vmcnt(8) lgkmcnt(0)
	s_setprio 1
	s_barrier
	v_mfma_f32_16x16x32_bf16 v[60:63], v[144:147], v[214:217], v[60:63]
	v_mfma_f32_16x16x32_bf16 v[56:59], v[152:155], v[214:217], v[56:59]
	v_mfma_f32_16x16x32_bf16 v[44:47], v[144:147], v[226:229], v[44:47]
	v_mfma_f32_16x16x32_bf16 v[40:43], v[152:155], v[226:229], v[40:43]
	v_mfma_f32_16x16x32_bf16 v[28:31], v[144:147], v[234:237], v[28:31]
	v_mfma_f32_16x16x32_bf16 v[24:27], v[152:155], v[234:237], v[24:27]
	v_mfma_f32_16x16x32_bf16 v[12:15], v[144:147], v[242:245], v[12:15]
	v_mfma_f32_16x16x32_bf16 v[8:11], v[152:155], v[242:245], v[8:11]
	v_mfma_f32_16x16x32_bf16 v[60:63], v[148:151], v[222:225], v[60:63]
	v_mfma_f32_16x16x32_bf16 v[56:59], v[156:159], v[222:225], v[56:59]
	v_mfma_f32_16x16x32_bf16 v[44:47], v[148:151], v[230:233], v[44:47]
	v_mfma_f32_16x16x32_bf16 v[40:43], v[156:159], v[230:233], v[40:43]
	v_mfma_f32_16x16x32_bf16 v[28:31], v[148:151], v[238:241], v[28:31]
	v_mfma_f32_16x16x32_bf16 v[24:27], v[156:159], v[238:241], v[24:27]
	v_mfma_f32_16x16x32_bf16 v[12:15], v[148:151], v[246:249], v[12:15]
	v_mfma_f32_16x16x32_bf16 v[8:11], v[156:159], v[246:249], v[8:11]
	s_setprio 0
	s_setprio 1
	v_mfma_f32_16x16x32_bf16 v[52:55], v[160:163], v[214:217], v[52:55]
	s_add_i32 s80, s80, 2
	v_mfma_f32_16x16x32_bf16 v[48:51], v[168:171], v[214:217], v[48:51]
	s_add_u32 s78, s78, 0x100
	v_mfma_f32_16x16x32_bf16 v[36:39], v[160:163], v[226:229], v[36:39]
	s_addc_u32 s79, s79, 0
	v_mfma_f32_16x16x32_bf16 v[32:35], v[168:171], v[226:229], v[32:35]
	s_cmp_gt_u32 s80, 41
	v_mfma_f32_16x16x32_bf16 v[20:23], v[160:163], v[234:237], v[20:23]
	s_mov_b64 s[2:3], s[48:49]
	v_mfma_f32_16x16x32_bf16 v[16:19], v[168:171], v[234:237], v[16:19]
	v_mfma_f32_16x16x32_bf16 v[4:7], v[160:163], v[242:245], v[4:7]
	v_mfma_f32_16x16x32_bf16 v[0:3], v[168:171], v[242:245], v[0:3]
	v_mfma_f32_16x16x32_bf16 v[52:55], v[164:167], v[222:225], v[52:55]
	v_mfma_f32_16x16x32_bf16 v[48:51], v[172:175], v[222:225], v[48:51]
	v_mfma_f32_16x16x32_bf16 v[36:39], v[164:167], v[230:233], v[36:39]
	v_mfma_f32_16x16x32_bf16 v[32:35], v[172:175], v[230:233], v[32:35]
	v_mfma_f32_16x16x32_bf16 v[20:23], v[164:167], v[238:241], v[20:23]
	v_mfma_f32_16x16x32_bf16 v[16:19], v[172:175], v[238:241], v[16:19]
	v_mfma_f32_16x16x32_bf16 v[4:7], v[164:167], v[246:249], v[4:7]
	v_mfma_f32_16x16x32_bf16 v[0:3], v[172:175], v[246:249], v[0:3]
	s_barrier
	s_setprio 0
	s_cbranch_scc0 .LBB0_942
